# v40
# baseline (speedup 1.0000x reference)
.LBB0_189:
	s_add_u32 s36, s34, 0xfffc0080
	s_addc_u32 s37, s35, -1
	s_add_i32 s75, 0, 0x10000
	v_add_u32_e32 v140, s75, v161
	ds_read_b128 v[164:167], v140
	ds_read_b128 v[168:171], v140 offset:1024
	ds_read_b128 v[172:175], v140 offset:2048
	ds_read_b128 v[176:179], v140 offset:3072
	s_cmp_eq_u32 s74, 12
	s_cselect_b32 s39, s25, s37
	s_cselect_b32 s38, s69, s36
	s_cselect_b32 s37, s23, s73
	s_cselect_b32 s36, s70, s71
	s_add_i32 m0, s31, 0xc000
	ds_read_b128 v[180:183], v163
	ds_read_b128 v[184:187], v163 offset:1024
	ds_read_b128 v[188:191], v163 offset:2048
	ds_read_b128 v[192:195], v163 offset:3072
	ds_read_b128 v[196:199], v163 offset:4096
	ds_read_b128 v[200:203], v163 offset:5120
	ds_read_b128 v[204:207], v163 offset:6144
	global_load_lds_dwordx4 v136, s[34:35]
	s_add_i32 m0, s31, 0xe000
	ds_read_b128 v[208:211], v163 offset:7168
	global_load_lds_dwordx4 v138, s[34:35]
	s_waitcnt lgkmcnt(8)
	s_barrier
	s_waitcnt lgkmcnt(0)
	v_mfma_f32_16x16x32_bf16 v[124:127], v[164:167], v[180:183], v[124:127]
	v_mfma_f32_16x16x32_bf16 v[120:123], v[172:175], v[180:183], v[120:123]
	v_mfma_f32_16x16x32_bf16 v[116:119], v[164:167], v[188:191], v[116:119]
	v_mfma_f32_16x16x32_bf16 v[108:111], v[172:175], v[188:191], v[108:111]
	v_mfma_f32_16x16x32_bf16 v[100:103], v[164:167], v[196:199], v[100:103]
	v_mfma_f32_16x16x32_bf16 v[92:95], v[172:175], v[196:199], v[92:95]
	v_mfma_f32_16x16x32_bf16 v[84:87], v[164:167], v[204:207], v[84:87]
	v_mfma_f32_16x16x32_bf16 v[76:79], v[172:175], v[204:207], v[76:79]
	v_mfma_f32_16x16x32_bf16 v[124:127], v[168:171], v[184:187], v[124:127]
	v_mfma_f32_16x16x32_bf16 v[120:123], v[176:179], v[184:187], v[120:123]
	v_mfma_f32_16x16x32_bf16 v[116:119], v[168:171], v[192:195], v[116:119]
	v_mfma_f32_16x16x32_bf16 v[108:111], v[176:179], v[192:195], v[108:111]
	v_mfma_f32_16x16x32_bf16 v[100:103], v[168:171], v[200:203], v[100:103]
	v_mfma_f32_16x16x32_bf16 v[92:95], v[176:179], v[200:203], v[92:95]
	v_mfma_f32_16x16x32_bf16 v[84:87], v[168:171], v[208:211], v[84:87]
	v_mfma_f32_16x16x32_bf16 v[76:79], v[176:179], v[208:211], v[76:79]
	s_barrier
	s_add_i32 s78, 0, 0x14000
	v_add_u32_e32 v140, s78, v161
	s_add_i32 s75, s75, s57
	ds_read_b128 v[212:215], v140
	ds_read_b128 v[216:219], v140 offset:1024
	ds_read_b128 v[220:223], v140 offset:2048
	ds_read_b128 v[224:227], v140 offset:3072
	s_add_u32 s98, s36, s14
	s_addc_u32 s99, s37, s15
	s_mov_b32 m0, s75
	s_nop 0
	global_load_lds_dwordx4 v128, s[36:37]
	s_add_i32 m0, s75, 0x2000
	s_nop 0
	global_load_lds_dwordx4 v130, s[36:37]
	s_barrier
	s_waitcnt lgkmcnt(0)
	v_mfma_f32_16x16x32_bf16 v[112:115], v[212:215], v[180:183], v[112:115]
	v_mfma_f32_16x16x32_bf16 v[104:107], v[220:223], v[180:183], v[104:107]
	v_mfma_f32_16x16x32_bf16 v[96:99], v[212:215], v[188:191], v[96:99]
	v_mfma_f32_16x16x32_bf16 v[88:91], v[220:223], v[188:191], v[88:91]
	v_mfma_f32_16x16x32_bf16 v[80:83], v[212:215], v[196:199], v[80:83]
	v_mfma_f32_16x16x32_bf16 v[72:75], v[220:223], v[196:199], v[72:75]
	v_mfma_f32_16x16x32_bf16 v[68:71], v[212:215], v[204:207], v[68:71]
	v_mfma_f32_16x16x32_bf16 v[64:67], v[220:223], v[204:207], v[64:67]
	v_mfma_f32_16x16x32_bf16 v[112:115], v[216:219], v[184:187], v[112:115]
	v_mfma_f32_16x16x32_bf16 v[104:107], v[224:227], v[184:187], v[104:107]
	v_mfma_f32_16x16x32_bf16 v[96:99], v[216:219], v[192:195], v[96:99]
	v_mfma_f32_16x16x32_bf16 v[88:91], v[224:227], v[192:195], v[88:91]
	v_mfma_f32_16x16x32_bf16 v[80:83], v[216:219], v[200:203], v[80:83]
	v_mfma_f32_16x16x32_bf16 v[72:75], v[224:227], v[200:203], v[72:75]
	v_mfma_f32_16x16x32_bf16 v[68:71], v[216:219], v[208:211], v[68:71]
	v_mfma_f32_16x16x32_bf16 v[64:67], v[224:227], v[208:211], v[64:67]
	s_mov_b32 m0, s31
	s_add_u32 s100, s38, s14
	s_addc_u32 s101, s39, s15
	s_barrier
	ds_read_b128 v[180:183], v163 offset:16384
	ds_read_b128 v[184:187], v163 offset:17408
	ds_read_b128 v[188:191], v163 offset:18432
	ds_read_b128 v[192:195], v163 offset:19456
	ds_read_b128 v[196:199], v163 offset:20480
	ds_read_b128 v[200:203], v163 offset:21504
	ds_read_b128 v[204:207], v163 offset:22528
	global_load_lds_dwordx4 v134, s[38:39]
	s_mov_b32 m0, s60
	ds_read_b128 v[208:211], v163 offset:23552
	global_load_lds_dwordx4 v132, s[38:39]
	s_barrier
	s_waitcnt lgkmcnt(0)
	v_mfma_f32_16x16x32_bf16 v[60:63], v[164:167], v[180:183], v[60:63]
	v_mfma_f32_16x16x32_bf16 v[56:59], v[172:175], v[180:183], v[56:59]
	v_mfma_f32_16x16x32_bf16 v[52:55], v[164:167], v[188:191], v[52:55]
	v_mfma_f32_16x16x32_bf16 v[44:47], v[172:175], v[188:191], v[44:47]
	v_mfma_f32_16x16x32_bf16 v[36:39], v[164:167], v[196:199], v[36:39]
	v_mfma_f32_16x16x32_bf16 v[28:31], v[172:175], v[196:199], v[28:31]
	v_mfma_f32_16x16x32_bf16 v[20:23], v[164:167], v[204:207], v[20:23]
	v_mfma_f32_16x16x32_bf16 v[12:15], v[172:175], v[204:207], v[12:15]
	v_mfma_f32_16x16x32_bf16 v[60:63], v[168:171], v[184:187], v[60:63]
	v_mfma_f32_16x16x32_bf16 v[56:59], v[176:179], v[184:187], v[56:59]
	v_mfma_f32_16x16x32_bf16 v[52:55], v[168:171], v[192:195], v[52:55]
	v_mfma_f32_16x16x32_bf16 v[44:47], v[176:179], v[192:195], v[44:47]
	v_mfma_f32_16x16x32_bf16 v[36:39], v[168:171], v[200:203], v[36:39]
	v_mfma_f32_16x16x32_bf16 v[28:31], v[176:179], v[200:203], v[28:31]
	v_mfma_f32_16x16x32_bf16 v[20:23], v[168:171], v[208:211], v[20:23]
	v_mfma_f32_16x16x32_bf16 v[12:15], v[176:179], v[208:211], v[12:15]
	s_barrier
	s_add_u32 s76, s36, 0x40000
	s_addc_u32 s77, s37, 0
	s_add_i32 s75, s78, s57
	s_mov_b32 m0, s75
	s_nop 0
	global_load_lds_dwordx4 v128, s[76:77]
	s_add_i32 m0, s75, 0x2000
	s_nop 0
	global_load_lds_dwordx4 v130, s[76:77]
	s_waitcnt vmcnt(6)
	s_barrier
	v_mfma_f32_16x16x32_bf16 v[48:51], v[212:215], v[180:183], v[48:51]
	v_mfma_f32_16x16x32_bf16 v[40:43], v[220:223], v[180:183], v[40:43]
	v_mfma_f32_16x16x32_bf16 v[32:35], v[212:215], v[188:191], v[32:35]
	v_mfma_f32_16x16x32_bf16 v[24:27], v[220:223], v[188:191], v[24:27]
	v_mfma_f32_16x16x32_bf16 v[16:19], v[212:215], v[196:199], v[16:19]
	v_mfma_f32_16x16x32_bf16 v[8:11], v[220:223], v[196:199], v[8:11]
	v_mfma_f32_16x16x32_bf16 v[4:7], v[212:215], v[204:207], v[4:7]
	v_mfma_f32_16x16x32_bf16 v[0:3], v[220:223], v[204:207], v[0:3]
	v_mfma_f32_16x16x32_bf16 v[48:51], v[216:219], v[184:187], v[48:51]
	v_mfma_f32_16x16x32_bf16 v[40:43], v[224:227], v[184:187], v[40:43]
	v_mfma_f32_16x16x32_bf16 v[32:35], v[216:219], v[192:195], v[32:35]
	v_mfma_f32_16x16x32_bf16 v[24:27], v[224:227], v[192:195], v[24:27]
	v_mfma_f32_16x16x32_bf16 v[16:19], v[216:219], v[200:203], v[16:19]
	v_mfma_f32_16x16x32_bf16 v[8:11], v[224:227], v[200:203], v[8:11]
	v_mfma_f32_16x16x32_bf16 v[4:7], v[216:219], v[208:211], v[4:7]
	v_mfma_f32_16x16x32_bf16 v[0:3], v[224:227], v[208:211], v[0:3]
	s_add_i32 s75, 0, 0x18000
	v_add_u32_e32 v176, s75, v161
	s_barrier
	ds_read_b128 v[164:167], v176
	ds_read_b128 v[168:171], v176 offset:1024
	ds_read_b128 v[172:175], v176 offset:2048
	ds_read_b128 v[176:179], v176 offset:3072
	s_add_u32 s38, s38, 0x40000
	s_addc_u32 s39, s39, 0
	s_mov_b32 m0, s61
	ds_read_b128 v[180:183], v163 offset:32768
	ds_read_b128 v[184:187], v163 offset:33792
	ds_read_b128 v[188:191], v163 offset:34816
	ds_read_b128 v[192:195], v163 offset:35840
	ds_read_b128 v[196:199], v163 offset:36864
	ds_read_b128 v[200:203], v163 offset:37888
	ds_read_b128 v[204:207], v163 offset:38912
	global_load_lds_dwordx4 v134, s[38:39]
	s_mov_b32 m0, s62
	ds_read_b128 v[208:211], v163 offset:39936
	global_load_lds_dwordx4 v132, s[38:39]
	s_waitcnt lgkmcnt(8)
	s_barrier
	s_waitcnt lgkmcnt(0)
	v_mfma_f32_16x16x32_bf16 v[124:127], v[164:167], v[180:183], v[124:127]
	v_mfma_f32_16x16x32_bf16 v[120:123], v[172:175], v[180:183], v[120:123]
	v_mfma_f32_16x16x32_bf16 v[116:119], v[164:167], v[188:191], v[116:119]
	v_mfma_f32_16x16x32_bf16 v[108:111], v[172:175], v[188:191], v[108:111]
	v_mfma_f32_16x16x32_bf16 v[100:103], v[164:167], v[196:199], v[100:103]
	v_mfma_f32_16x16x32_bf16 v[92:95], v[172:175], v[196:199], v[92:95]
	v_mfma_f32_16x16x32_bf16 v[84:87], v[164:167], v[204:207], v[84:87]
	v_mfma_f32_16x16x32_bf16 v[76:79], v[172:175], v[204:207], v[76:79]
	v_mfma_f32_16x16x32_bf16 v[124:127], v[168:171], v[184:187], v[124:127]
	v_mfma_f32_16x16x32_bf16 v[120:123], v[176:179], v[184:187], v[120:123]
	v_mfma_f32_16x16x32_bf16 v[116:119], v[168:171], v[192:195], v[116:119]
	v_mfma_f32_16x16x32_bf16 v[108:111], v[176:179], v[192:195], v[108:111]
	v_mfma_f32_16x16x32_bf16 v[100:103], v[168:171], v[200:203], v[100:103]
	v_mfma_f32_16x16x32_bf16 v[92:95], v[176:179], v[200:203], v[92:95]
	v_mfma_f32_16x16x32_bf16 v[84:87], v[168:171], v[208:211], v[84:87]
	v_mfma_f32_16x16x32_bf16 v[76:79], v[176:179], v[208:211], v[76:79]
	s_barrier
	s_add_i32 s38, 0, 0x1c000
	s_add_i32 s39, s75, s57
	v_add_u32_e32 v224, s38, v161
	s_mov_b32 m0, s39
	ds_read_b128 v[212:215], v224
	ds_read_b128 v[216:219], v224 offset:1024
	ds_read_b128 v[220:223], v224 offset:2048
	global_load_lds_dwordx4 v128, s[98:99]
	s_add_i32 m0, s39, 0x2000
	ds_read_b128 v[224:227], v224 offset:3072
	global_load_lds_dwordx4 v130, s[98:99]
	s_barrier
	s_waitcnt lgkmcnt(0)
	v_mfma_f32_16x16x32_bf16 v[112:115], v[212:215], v[180:183], v[112:115]
	v_mfma_f32_16x16x32_bf16 v[104:107], v[220:223], v[180:183], v[104:107]
	v_mfma_f32_16x16x32_bf16 v[96:99], v[212:215], v[188:191], v[96:99]
	v_mfma_f32_16x16x32_bf16 v[88:91], v[220:223], v[188:191], v[88:91]
	v_mfma_f32_16x16x32_bf16 v[80:83], v[212:215], v[196:199], v[80:83]
	v_mfma_f32_16x16x32_bf16 v[72:75], v[220:223], v[196:199], v[72:75]
	v_mfma_f32_16x16x32_bf16 v[68:71], v[212:215], v[204:207], v[68:71]
	v_mfma_f32_16x16x32_bf16 v[64:67], v[220:223], v[204:207], v[64:67]
	v_mfma_f32_16x16x32_bf16 v[112:115], v[216:219], v[184:187], v[112:115]
	v_mfma_f32_16x16x32_bf16 v[104:107], v[224:227], v[184:187], v[104:107]
	v_mfma_f32_16x16x32_bf16 v[96:99], v[216:219], v[192:195], v[96:99]
	v_mfma_f32_16x16x32_bf16 v[88:91], v[224:227], v[192:195], v[88:91]
	v_mfma_f32_16x16x32_bf16 v[80:83], v[216:219], v[200:203], v[80:83]
	v_mfma_f32_16x16x32_bf16 v[72:75], v[224:227], v[200:203], v[72:75]
	v_mfma_f32_16x16x32_bf16 v[68:71], v[216:219], v[208:211], v[68:71]
	v_mfma_f32_16x16x32_bf16 v[64:67], v[224:227], v[208:211], v[64:67]
	s_mov_b32 m0, s63
	s_barrier
	ds_read_b128 v[180:183], v163 offset:49152
	ds_read_b128 v[184:187], v163 offset:50176
	ds_read_b128 v[188:191], v163 offset:51200
	ds_read_b128 v[192:195], v163 offset:52224
	ds_read_b128 v[196:199], v163 offset:53248
	ds_read_b128 v[200:203], v163 offset:54272
	ds_read_b128 v[204:207], v163 offset:55296
	global_load_lds_dwordx4 v134, s[100:101]
	s_mov_b32 m0, s64
	ds_read_b128 v[208:211], v163 offset:56320
	global_load_lds_dwordx4 v132, s[100:101]
	s_barrier
	s_waitcnt lgkmcnt(0)
	v_mfma_f32_16x16x32_bf16 v[60:63], v[164:167], v[180:183], v[60:63]
	v_mfma_f32_16x16x32_bf16 v[56:59], v[172:175], v[180:183], v[56:59]
	v_mfma_f32_16x16x32_bf16 v[52:55], v[164:167], v[188:191], v[52:55]
	v_mfma_f32_16x16x32_bf16 v[44:47], v[172:175], v[188:191], v[44:47]
	v_mfma_f32_16x16x32_bf16 v[36:39], v[164:167], v[196:199], v[36:39]
	v_mfma_f32_16x16x32_bf16 v[28:31], v[172:175], v[196:199], v[28:31]
	v_mfma_f32_16x16x32_bf16 v[20:23], v[164:167], v[204:207], v[20:23]
	v_mfma_f32_16x16x32_bf16 v[12:15], v[172:175], v[204:207], v[12:15]
	v_mfma_f32_16x16x32_bf16 v[60:63], v[168:171], v[184:187], v[60:63]
	v_mfma_f32_16x16x32_bf16 v[56:59], v[176:179], v[184:187], v[56:59]
	v_mfma_f32_16x16x32_bf16 v[52:55], v[168:171], v[192:195], v[52:55]
	v_mfma_f32_16x16x32_bf16 v[44:47], v[176:179], v[192:195], v[44:47]
	v_mfma_f32_16x16x32_bf16 v[36:39], v[168:171], v[200:203], v[36:39]
	v_mfma_f32_16x16x32_bf16 v[28:31], v[176:179], v[200:203], v[28:31]
	v_mfma_f32_16x16x32_bf16 v[20:23], v[168:171], v[208:211], v[20:23]
	v_mfma_f32_16x16x32_bf16 v[12:15], v[176:179], v[208:211], v[12:15]
	s_barrier
	s_add_u32 s36, s36, 0x40080
	s_addc_u32 s37, s37, 0
	s_add_i32 s38, s38, s57
	s_mov_b32 m0, s38
	s_nop 0
	global_load_lds_dwordx4 v128, s[36:37]
	s_add_i32 m0, s38, 0x2000
	s_nop 0
	global_load_lds_dwordx4 v130, s[36:37]
	s_waitcnt vmcnt(6)
	s_barrier
	v_mfma_f32_16x16x32_bf16 v[48:51], v[212:215], v[180:183], v[48:51]
	v_mfma_f32_16x16x32_bf16 v[40:43], v[220:223], v[180:183], v[40:43]
	v_mfma_f32_16x16x32_bf16 v[32:35], v[212:215], v[188:191], v[32:35]
	v_mfma_f32_16x16x32_bf16 v[24:27], v[220:223], v[188:191], v[24:27]
	v_mfma_f32_16x16x32_bf16 v[16:19], v[212:215], v[196:199], v[16:19]
	v_mfma_f32_16x16x32_bf16 v[8:11], v[220:223], v[196:199], v[8:11]
	v_mfma_f32_16x16x32_bf16 v[4:7], v[212:215], v[204:207], v[4:7]
	v_mfma_f32_16x16x32_bf16 v[0:3], v[220:223], v[204:207], v[0:3]
	v_mfma_f32_16x16x32_bf16 v[48:51], v[216:219], v[184:187], v[48:51]
	v_mfma_f32_16x16x32_bf16 v[40:43], v[224:227], v[184:187], v[40:43]
	v_mfma_f32_16x16x32_bf16 v[32:35], v[216:219], v[192:195], v[32:35]
	v_mfma_f32_16x16x32_bf16 v[24:27], v[224:227], v[192:195], v[24:27]
	v_mfma_f32_16x16x32_bf16 v[16:19], v[216:219], v[200:203], v[16:19]
	v_mfma_f32_16x16x32_bf16 v[8:11], v[224:227], v[200:203], v[8:11]
	v_mfma_f32_16x16x32_bf16 v[4:7], v[216:219], v[208:211], v[4:7]
	v_mfma_f32_16x16x32_bf16 v[0:3], v[224:227], v[208:211], v[0:3]
	s_add_i32 s74, s74, 2
	s_add_u32 s34, s34, 0x100
	s_addc_u32 s35, s35, 0
	s_add_u32 s71, s71, 0x100
	s_addc_u32 s73, s73, 0
	s_cmp_gt_u32 s74, 13
	s_barrier
	s_cbranch_scc0 .LBB0_189
	v_lshl_or_b32 v140, s68, 8, v162
	v_lshl_add_u32 v166, s30, 8, v159
	v_ashrrev_i32_e32 v141, 31, v140
	v_lshl_add_u64 v[140:141], v[140:141], 1, s[20:21]
	v_mad_i64_i32 v[164:165], s[34:35], v166, s52, 0
	v_lshl_add_u64 v[164:165], v[164:165], 1, v[140:141]
	v_cvt_pk_bf16_f32 v124, v124, v125
	v_cvt_pk_bf16_f32 v125, v126, v127
	v_cvt_pk_bf16_f32 v126, v120, v121
	v_cvt_pk_bf16_f32 v127, v122, v123
	global_store_dwordx4 v[164:165], v[124:127], off
	v_cvt_pk_bf16_f32 v112, v112, v113
	v_cvt_pk_bf16_f32 v113, v114, v115
	v_cvt_pk_bf16_f32 v114, v104, v105
	v_or_b32_e32 v104, 16, v166
	v_mad_i64_i32 v[104:105], s[34:35], v104, s52, 0
	v_cvt_pk_bf16_f32 v115, v106, v107
	global_store_dwordx4 v[164:165], v[112:115], off offset:256
	s_and_b64 vcc, exec, s[4:5]
	s_mov_b32 s68, s22
	v_lshl_add_u64 v[112:113], v[104:105], 1, v[140:141]
	v_cvt_pk_bf16_f32 v104, v116, v117
	v_cvt_pk_bf16_f32 v105, v118, v119
	v_cvt_pk_bf16_f32 v106, v108, v109
	v_cvt_pk_bf16_f32 v107, v110, v111
	global_store_dwordx4 v[112:113], v[104:107], off
	v_cvt_pk_bf16_f32 v96, v96, v97
	v_cvt_pk_bf16_f32 v97, v98, v99
	v_cvt_pk_bf16_f32 v98, v88, v89
	v_or_b32_e32 v88, 32, v166
	v_mad_i64_i32 v[88:89], s[34:35], v88, s52, 0
	v_cvt_pk_bf16_f32 v99, v90, v91
	global_store_dwordx4 v[112:113], v[96:99], off offset:256
	s_mov_b32 s30, s24
	s_mov_b64 s[36:37], s[28:29]
	v_lshl_add_u64 v[96:97], v[88:89], 1, v[140:141]
	v_cvt_pk_bf16_f32 v88, v100, v101
	v_cvt_pk_bf16_f32 v89, v102, v103
	v_cvt_pk_bf16_f32 v90, v92, v93
	v_cvt_pk_bf16_f32 v91, v94, v95
	global_store_dwordx4 v[96:97], v[88:91], off
	v_cvt_pk_bf16_f32 v80, v80, v81
	v_cvt_pk_bf16_f32 v81, v82, v83
	v_cvt_pk_bf16_f32 v82, v72, v73
	v_or_b32_e32 v72, 48, v166
	v_mad_i64_i32 v[72:73], s[34:35], v72, s52, 0
	v_cvt_pk_bf16_f32 v83, v74, v75
	global_store_dwordx4 v[96:97], v[80:83], off offset:256
	s_nop 1
	v_lshl_add_u64 v[80:81], v[72:73], 1, v[140:141]
	v_cvt_pk_bf16_f32 v72, v84, v85
	v_cvt_pk_bf16_f32 v73, v86, v87
	v_cvt_pk_bf16_f32 v74, v76, v77
	v_cvt_pk_bf16_f32 v75, v78, v79
	global_store_dwordx4 v[80:81], v[72:75], off
	v_cvt_pk_bf16_f32 v68, v68, v69
	v_cvt_pk_bf16_f32 v69, v70, v71
	v_cvt_pk_bf16_f32 v70, v64, v65
	v_add_u32_e32 v64, 0x80, v166
	v_mad_i64_i32 v[64:65], s[34:35], v64, s52, 0
	v_lshl_add_u64 v[64:65], v[64:65], 1, v[140:141]
	v_cvt_pk_bf16_f32 v71, v66, v67
	global_store_dwordx4 v[80:81], v[68:71], off offset:256
	v_cvt_pk_bf16_f32 v60, v60, v61
	v_cvt_pk_bf16_f32 v61, v62, v63
	v_cvt_pk_bf16_f32 v62, v56, v57
	v_cvt_pk_bf16_f32 v63, v58, v59
	global_store_dwordx4 v[64:65], v[60:63], off
	v_cvt_pk_bf16_f32 v48, v48, v49
	v_cvt_pk_bf16_f32 v49, v50, v51
	v_cvt_pk_bf16_f32 v50, v40, v41
	v_add_u32_e32 v40, 0x90, v166
	v_mad_i64_i32 v[40:41], s[34:35], v40, s52, 0
	v_cvt_pk_bf16_f32 v51, v42, v43
	global_store_dwordx4 v[64:65], v[48:51], off offset:256
	s_nop 1
	v_lshl_add_u64 v[48:49], v[40:41], 1, v[140:141]
	v_cvt_pk_bf16_f32 v40, v52, v53
	v_cvt_pk_bf16_f32 v41, v54, v55
	v_cvt_pk_bf16_f32 v42, v44, v45
	v_cvt_pk_bf16_f32 v43, v46, v47
	global_store_dwordx4 v[48:49], v[40:43], off
	v_cvt_pk_bf16_f32 v32, v32, v33
	v_cvt_pk_bf16_f32 v33, v34, v35
	v_cvt_pk_bf16_f32 v34, v24, v25
	v_add_u32_e32 v24, 0xa0, v166
	v_mad_i64_i32 v[24:25], s[34:35], v24, s52, 0
	v_cvt_pk_bf16_f32 v35, v26, v27
	global_store_dwordx4 v[48:49], v[32:35], off offset:256
	s_nop 1
	v_lshl_add_u64 v[32:33], v[24:25], 1, v[140:141]
	v_cvt_pk_bf16_f32 v24, v36, v37
	v_cvt_pk_bf16_f32 v25, v38, v39
	v_cvt_pk_bf16_f32 v26, v28, v29
	v_cvt_pk_bf16_f32 v27, v30, v31
	global_store_dwordx4 v[32:33], v[24:27], off
	v_cvt_pk_bf16_f32 v16, v16, v17
	v_cvt_pk_bf16_f32 v17, v18, v19
	v_cvt_pk_bf16_f32 v18, v8, v9
	v_add_u32_e32 v8, 0xb0, v166
	v_mad_i64_i32 v[8:9], s[34:35], v8, s52, 0
	v_cvt_pk_bf16_f32 v19, v10, v11
	global_store_dwordx4 v[32:33], v[16:19], off offset:256
	s_mov_b64 s[34:35], s[26:27]
	s_nop 0
	v_lshl_add_u64 v[16:17], v[8:9], 1, v[140:141]
	v_cvt_pk_bf16_f32 v8, v20, v21
	v_cvt_pk_bf16_f32 v9, v22, v23
	v_cvt_pk_bf16_f32 v10, v12, v13
	v_cvt_pk_bf16_f32 v11, v14, v15
	global_store_dwordx4 v[16:17], v[8:11], off
	v_cvt_pk_bf16_f32 v4, v4, v5
	v_cvt_pk_bf16_f32 v5, v6, v7
	v_cvt_pk_bf16_f32 v6, v0, v1
	v_cvt_pk_bf16_f32 v7, v2, v3
	global_store_dwordx4 v[16:17], v[4:7], off offset:256
	s_cbranch_vccz .LBB0_186
	s_waitcnt vmcnt(0)
	s_cmpk_gt_u32 s56, 0xff
	s_cbranch_scc1 .LBB0_174
	s_barrier
	s_branch .LBB0_174

.LBB0_203:
	ds_read_b128 v[144:147], v153
	ds_read_b128 v[156:159], v153 offset:1024
	ds_read_b128 v[162:165], v153 offset:2048
	ds_read_b128 v[166:169], v153 offset:3072
	s_add_u32 s26, s24, 0xfffc0080
	s_addc_u32 s27, s25, -1
	s_cmp_eq_u32 s54, 12
	s_cselect_b32 s29, s5, s27
	s_cselect_b32 s28, s17, s26
	s_cselect_b32 s27, s15, s53
	s_cselect_b32 s26, s23, s52
	s_add_i32 m0, s36, 0xc000
	ds_read_b128 v[170:173], v154
	ds_read_b128 v[174:177], v154 offset:1024
	ds_read_b128 v[178:181], v154 offset:2048
	ds_read_b128 v[182:185], v154 offset:3072
	ds_read_b128 v[186:189], v154 offset:4096
	ds_read_b128 v[190:193], v154 offset:5120
	ds_read_b128 v[194:197], v154 offset:6144
	global_load_lds_dwordx4 v136, s[24:25]
	s_add_i32 m0, s36, 0xe000
	ds_read_b128 v[198:201], v154 offset:7168
	global_load_lds_dwordx4 v138, s[24:25]
	s_waitcnt lgkmcnt(8)
	s_barrier
	s_waitcnt lgkmcnt(0)
	v_mfma_f32_16x16x32_bf16 v[124:127], v[144:147], v[170:173], v[124:127]
	v_mfma_f32_16x16x32_bf16 v[120:123], v[162:165], v[170:173], v[120:123]
	v_mfma_f32_16x16x32_bf16 v[108:111], v[144:147], v[178:181], v[108:111]
	v_mfma_f32_16x16x32_bf16 v[104:107], v[162:165], v[178:181], v[104:107]
	v_mfma_f32_16x16x32_bf16 v[92:95], v[144:147], v[186:189], v[92:95]
	v_mfma_f32_16x16x32_bf16 v[88:91], v[162:165], v[186:189], v[88:91]
	v_mfma_f32_16x16x32_bf16 v[76:79], v[144:147], v[194:197], v[76:79]
	v_mfma_f32_16x16x32_bf16 v[72:75], v[162:165], v[194:197], v[72:75]
	v_mfma_f32_16x16x32_bf16 v[124:127], v[156:159], v[174:177], v[124:127]
	v_mfma_f32_16x16x32_bf16 v[120:123], v[166:169], v[174:177], v[120:123]
	v_mfma_f32_16x16x32_bf16 v[108:111], v[156:159], v[182:185], v[108:111]
	v_mfma_f32_16x16x32_bf16 v[104:107], v[166:169], v[182:185], v[104:107]
	v_mfma_f32_16x16x32_bf16 v[92:95], v[156:159], v[190:193], v[92:95]
	v_mfma_f32_16x16x32_bf16 v[88:91], v[166:169], v[190:193], v[88:91]
	v_mfma_f32_16x16x32_bf16 v[76:79], v[156:159], v[198:201], v[76:79]
	v_mfma_f32_16x16x32_bf16 v[72:75], v[166:169], v[198:201], v[72:75]
	s_barrier
	s_add_i32 s55, s48, s35
	s_add_u32 s98, s26, s12
	s_addc_u32 s99, s27, s13
	s_mov_b32 m0, s55
	ds_read_b128 v[202:205], v155
	ds_read_b128 v[206:209], v155 offset:1024
	ds_read_b128 v[210:213], v155 offset:2048
	global_load_lds_dwordx4 v130, s[26:27]
	s_add_i32 m0, s55, 0x2000
	ds_read_b128 v[214:217], v155 offset:3072
	global_load_lds_dwordx4 v134, s[26:27]
	s_barrier
	s_waitcnt lgkmcnt(0)
	v_mfma_f32_16x16x32_bf16 v[116:119], v[202:205], v[170:173], v[116:119]
	v_mfma_f32_16x16x32_bf16 v[112:115], v[210:213], v[170:173], v[112:115]
	v_mfma_f32_16x16x32_bf16 v[100:103], v[202:205], v[178:181], v[100:103]
	v_mfma_f32_16x16x32_bf16 v[96:99], v[210:213], v[178:181], v[96:99]
	v_mfma_f32_16x16x32_bf16 v[84:87], v[202:205], v[186:189], v[84:87]
	v_mfma_f32_16x16x32_bf16 v[80:83], v[210:213], v[186:189], v[80:83]
	v_mfma_f32_16x16x32_bf16 v[68:71], v[202:205], v[194:197], v[68:71]
	v_mfma_f32_16x16x32_bf16 v[64:67], v[210:213], v[194:197], v[64:67]
	v_mfma_f32_16x16x32_bf16 v[116:119], v[206:209], v[174:177], v[116:119]
	v_mfma_f32_16x16x32_bf16 v[112:115], v[214:217], v[174:177], v[112:115]
	v_mfma_f32_16x16x32_bf16 v[100:103], v[206:209], v[182:185], v[100:103]
	v_mfma_f32_16x16x32_bf16 v[96:99], v[214:217], v[182:185], v[96:99]
	v_mfma_f32_16x16x32_bf16 v[84:87], v[206:209], v[190:193], v[84:87]
	v_mfma_f32_16x16x32_bf16 v[80:83], v[214:217], v[190:193], v[80:83]
	v_mfma_f32_16x16x32_bf16 v[68:71], v[206:209], v[198:201], v[68:71]
	v_mfma_f32_16x16x32_bf16 v[64:67], v[214:217], v[198:201], v[64:67]
	s_mov_b32 m0, s36
	s_add_u32 s100, s28, s12
	s_addc_u32 s101, s29, s13
	s_barrier
	ds_read_b128 v[170:173], v154 offset:16384
	ds_read_b128 v[174:177], v154 offset:17408
	ds_read_b128 v[178:181], v154 offset:18432
	ds_read_b128 v[182:185], v154 offset:19456
	ds_read_b128 v[186:189], v154 offset:20480
	ds_read_b128 v[190:193], v154 offset:21504
	ds_read_b128 v[194:197], v154 offset:22528
	global_load_lds_dwordx4 v128, s[28:29]
	s_mov_b32 m0, s37
	ds_read_b128 v[198:201], v154 offset:23552
	global_load_lds_dwordx4 v132, s[28:29]
	s_barrier
	s_waitcnt lgkmcnt(0)
	v_mfma_f32_16x16x32_bf16 v[60:63], v[144:147], v[170:173], v[60:63]
	v_mfma_f32_16x16x32_bf16 v[56:59], v[162:165], v[170:173], v[56:59]
	v_mfma_f32_16x16x32_bf16 v[44:47], v[144:147], v[178:181], v[44:47]
	v_mfma_f32_16x16x32_bf16 v[40:43], v[162:165], v[178:181], v[40:43]
	v_mfma_f32_16x16x32_bf16 v[28:31], v[144:147], v[186:189], v[28:31]
	v_mfma_f32_16x16x32_bf16 v[24:27], v[162:165], v[186:189], v[24:27]
	v_mfma_f32_16x16x32_bf16 v[12:15], v[144:147], v[194:197], v[12:15]
	v_mfma_f32_16x16x32_bf16 v[8:11], v[162:165], v[194:197], v[8:11]
	v_mfma_f32_16x16x32_bf16 v[60:63], v[156:159], v[174:177], v[60:63]
	v_mfma_f32_16x16x32_bf16 v[56:59], v[166:169], v[174:177], v[56:59]
	v_mfma_f32_16x16x32_bf16 v[44:47], v[156:159], v[182:185], v[44:47]
	v_mfma_f32_16x16x32_bf16 v[40:43], v[166:169], v[182:185], v[40:43]
	v_mfma_f32_16x16x32_bf16 v[28:31], v[156:159], v[190:193], v[28:31]
	v_mfma_f32_16x16x32_bf16 v[24:27], v[166:169], v[190:193], v[24:27]
	v_mfma_f32_16x16x32_bf16 v[12:15], v[156:159], v[198:201], v[12:15]
	v_mfma_f32_16x16x32_bf16 v[8:11], v[166:169], v[198:201], v[8:11]
	s_barrier
	s_add_u32 s56, s26, 0x40000
	s_addc_u32 s57, s27, 0
	s_add_i32 s55, s49, s35
	s_mov_b32 m0, s55
	s_nop 0
	global_load_lds_dwordx4 v130, s[56:57]
	s_add_i32 m0, s55, 0x2000
	s_nop 0
	global_load_lds_dwordx4 v134, s[56:57]
	s_waitcnt vmcnt(6)
	s_barrier
	v_mfma_f32_16x16x32_bf16 v[52:55], v[202:205], v[170:173], v[52:55]
	v_mfma_f32_16x16x32_bf16 v[48:51], v[210:213], v[170:173], v[48:51]
	v_mfma_f32_16x16x32_bf16 v[36:39], v[202:205], v[178:181], v[36:39]
	v_mfma_f32_16x16x32_bf16 v[32:35], v[210:213], v[178:181], v[32:35]
	v_mfma_f32_16x16x32_bf16 v[20:23], v[202:205], v[186:189], v[20:23]
	v_mfma_f32_16x16x32_bf16 v[16:19], v[210:213], v[186:189], v[16:19]
	v_mfma_f32_16x16x32_bf16 v[4:7], v[202:205], v[194:197], v[4:7]
	v_mfma_f32_16x16x32_bf16 v[0:3], v[210:213], v[194:197], v[0:3]
	v_mfma_f32_16x16x32_bf16 v[52:55], v[206:209], v[174:177], v[52:55]
	v_mfma_f32_16x16x32_bf16 v[48:51], v[214:217], v[174:177], v[48:51]
	v_mfma_f32_16x16x32_bf16 v[36:39], v[206:209], v[182:185], v[36:39]
	v_mfma_f32_16x16x32_bf16 v[32:35], v[214:217], v[182:185], v[32:35]
	v_mfma_f32_16x16x32_bf16 v[20:23], v[206:209], v[190:193], v[20:23]
	v_mfma_f32_16x16x32_bf16 v[16:19], v[214:217], v[190:193], v[16:19]
	v_mfma_f32_16x16x32_bf16 v[4:7], v[206:209], v[198:201], v[4:7]
	v_mfma_f32_16x16x32_bf16 v[0:3], v[214:217], v[198:201], v[0:3]
	s_add_i32 s55, 0, 0x18000
	v_add_u32_e32 v161, s55, v151
	s_barrier
	ds_read_b128 v[144:147], v161
	ds_read_b128 v[156:159], v161 offset:1024
	ds_read_b128 v[162:165], v161 offset:2048
	ds_read_b128 v[166:169], v161 offset:3072
	s_add_u32 s28, s28, 0x40000
	s_addc_u32 s29, s29, 0
	s_mov_b32 m0, s38
	ds_read_b128 v[170:173], v154 offset:32768
	ds_read_b128 v[174:177], v154 offset:33792
	ds_read_b128 v[178:181], v154 offset:34816
	ds_read_b128 v[182:185], v154 offset:35840
	ds_read_b128 v[186:189], v154 offset:36864
	ds_read_b128 v[190:193], v154 offset:37888
	ds_read_b128 v[194:197], v154 offset:38912
	global_load_lds_dwordx4 v128, s[28:29]
	s_mov_b32 m0, s39
	ds_read_b128 v[198:201], v154 offset:39936
	global_load_lds_dwordx4 v132, s[28:29]
	s_waitcnt lgkmcnt(8)
	s_barrier
	s_waitcnt lgkmcnt(0)
	v_mfma_f32_16x16x32_bf16 v[124:127], v[144:147], v[170:173], v[124:127]
	v_mfma_f32_16x16x32_bf16 v[120:123], v[162:165], v[170:173], v[120:123]
	v_mfma_f32_16x16x32_bf16 v[108:111], v[144:147], v[178:181], v[108:111]
	v_mfma_f32_16x16x32_bf16 v[104:107], v[162:165], v[178:181], v[104:107]
	v_mfma_f32_16x16x32_bf16 v[92:95], v[144:147], v[186:189], v[92:95]
	v_mfma_f32_16x16x32_bf16 v[88:91], v[162:165], v[186:189], v[88:91]
	v_mfma_f32_16x16x32_bf16 v[76:79], v[144:147], v[194:197], v[76:79]
	v_mfma_f32_16x16x32_bf16 v[72:75], v[162:165], v[194:197], v[72:75]
	v_mfma_f32_16x16x32_bf16 v[124:127], v[156:159], v[174:177], v[124:127]
	v_mfma_f32_16x16x32_bf16 v[120:123], v[166:169], v[174:177], v[120:123]
	v_mfma_f32_16x16x32_bf16 v[108:111], v[156:159], v[182:185], v[108:111]
	v_mfma_f32_16x16x32_bf16 v[104:107], v[166:169], v[182:185], v[104:107]
	v_mfma_f32_16x16x32_bf16 v[92:95], v[156:159], v[190:193], v[92:95]
	v_mfma_f32_16x16x32_bf16 v[88:91], v[166:169], v[190:193], v[88:91]
	v_mfma_f32_16x16x32_bf16 v[76:79], v[156:159], v[198:201], v[76:79]
	v_mfma_f32_16x16x32_bf16 v[72:75], v[166:169], v[198:201], v[72:75]
	s_barrier
	s_add_i32 s28, 0, 0x1c000
	s_add_i32 s29, s55, s35
	v_add_u32_e32 v161, s28, v151
	s_mov_b32 m0, s29
	ds_read_b128 v[202:205], v161
	ds_read_b128 v[206:209], v161 offset:1024
	ds_read_b128 v[210:213], v161 offset:2048
	global_load_lds_dwordx4 v130, s[98:99]
	s_add_i32 m0, s29, 0x2000
	ds_read_b128 v[214:217], v161 offset:3072
	global_load_lds_dwordx4 v134, s[98:99]
	s_barrier
	s_waitcnt lgkmcnt(0)
	v_mfma_f32_16x16x32_bf16 v[116:119], v[202:205], v[170:173], v[116:119]
	v_mfma_f32_16x16x32_bf16 v[112:115], v[210:213], v[170:173], v[112:115]
	v_mfma_f32_16x16x32_bf16 v[100:103], v[202:205], v[178:181], v[100:103]
	v_mfma_f32_16x16x32_bf16 v[96:99], v[210:213], v[178:181], v[96:99]
	v_mfma_f32_16x16x32_bf16 v[84:87], v[202:205], v[186:189], v[84:87]
	v_mfma_f32_16x16x32_bf16 v[80:83], v[210:213], v[186:189], v[80:83]
	v_mfma_f32_16x16x32_bf16 v[68:71], v[202:205], v[194:197], v[68:71]
	v_mfma_f32_16x16x32_bf16 v[64:67], v[210:213], v[194:197], v[64:67]
	v_mfma_f32_16x16x32_bf16 v[116:119], v[206:209], v[174:177], v[116:119]
	v_mfma_f32_16x16x32_bf16 v[112:115], v[214:217], v[174:177], v[112:115]
	v_mfma_f32_16x16x32_bf16 v[100:103], v[206:209], v[182:185], v[100:103]
	v_mfma_f32_16x16x32_bf16 v[96:99], v[214:217], v[182:185], v[96:99]
	v_mfma_f32_16x16x32_bf16 v[84:87], v[206:209], v[190:193], v[84:87]
	v_mfma_f32_16x16x32_bf16 v[80:83], v[214:217], v[190:193], v[80:83]
	v_mfma_f32_16x16x32_bf16 v[68:71], v[206:209], v[198:201], v[68:71]
	v_mfma_f32_16x16x32_bf16 v[64:67], v[214:217], v[198:201], v[64:67]
	s_mov_b32 m0, s44
	s_barrier
	ds_read_b128 v[170:173], v154 offset:49152
	ds_read_b128 v[174:177], v154 offset:50176
	ds_read_b128 v[178:181], v154 offset:51200
	ds_read_b128 v[182:185], v154 offset:52224
	ds_read_b128 v[186:189], v154 offset:53248
	ds_read_b128 v[190:193], v154 offset:54272
	ds_read_b128 v[194:197], v154 offset:55296
	global_load_lds_dwordx4 v128, s[100:101]
	s_mov_b32 m0, s46
	ds_read_b128 v[198:201], v154 offset:56320
	global_load_lds_dwordx4 v132, s[100:101]
	s_barrier
	s_waitcnt lgkmcnt(0)
	v_mfma_f32_16x16x32_bf16 v[60:63], v[144:147], v[170:173], v[60:63]
	v_mfma_f32_16x16x32_bf16 v[56:59], v[162:165], v[170:173], v[56:59]
	v_mfma_f32_16x16x32_bf16 v[44:47], v[144:147], v[178:181], v[44:47]
	v_mfma_f32_16x16x32_bf16 v[40:43], v[162:165], v[178:181], v[40:43]
	v_mfma_f32_16x16x32_bf16 v[28:31], v[144:147], v[186:189], v[28:31]
	v_mfma_f32_16x16x32_bf16 v[24:27], v[162:165], v[186:189], v[24:27]
	v_mfma_f32_16x16x32_bf16 v[12:15], v[144:147], v[194:197], v[12:15]
	v_mfma_f32_16x16x32_bf16 v[8:11], v[162:165], v[194:197], v[8:11]
	v_mfma_f32_16x16x32_bf16 v[60:63], v[156:159], v[174:177], v[60:63]
	v_mfma_f32_16x16x32_bf16 v[56:59], v[166:169], v[174:177], v[56:59]
	v_mfma_f32_16x16x32_bf16 v[44:47], v[156:159], v[182:185], v[44:47]
	v_mfma_f32_16x16x32_bf16 v[40:43], v[166:169], v[182:185], v[40:43]
	v_mfma_f32_16x16x32_bf16 v[28:31], v[156:159], v[190:193], v[28:31]
	v_mfma_f32_16x16x32_bf16 v[24:27], v[166:169], v[190:193], v[24:27]
	v_mfma_f32_16x16x32_bf16 v[12:15], v[156:159], v[198:201], v[12:15]
	v_mfma_f32_16x16x32_bf16 v[8:11], v[166:169], v[198:201], v[8:11]
	s_barrier
	s_add_u32 s26, s26, 0x40080
	s_addc_u32 s27, s27, 0
	s_add_i32 s28, s28, s35
	s_mov_b32 m0, s28
	s_nop 0
	global_load_lds_dwordx4 v130, s[26:27]
	s_add_i32 m0, s28, 0x2000
	s_nop 0
	global_load_lds_dwordx4 v134, s[26:27]
	s_waitcnt vmcnt(6)
	s_barrier
	v_mfma_f32_16x16x32_bf16 v[52:55], v[202:205], v[170:173], v[52:55]
	v_mfma_f32_16x16x32_bf16 v[48:51], v[210:213], v[170:173], v[48:51]
	v_mfma_f32_16x16x32_bf16 v[36:39], v[202:205], v[178:181], v[36:39]
	v_mfma_f32_16x16x32_bf16 v[32:35], v[210:213], v[178:181], v[32:35]
	v_mfma_f32_16x16x32_bf16 v[20:23], v[202:205], v[186:189], v[20:23]
	v_mfma_f32_16x16x32_bf16 v[16:19], v[210:213], v[186:189], v[16:19]
	v_mfma_f32_16x16x32_bf16 v[4:7], v[202:205], v[194:197], v[4:7]
	v_mfma_f32_16x16x32_bf16 v[0:3], v[210:213], v[194:197], v[0:3]
	v_mfma_f32_16x16x32_bf16 v[52:55], v[206:209], v[174:177], v[52:55]
	v_mfma_f32_16x16x32_bf16 v[48:51], v[214:217], v[174:177], v[48:51]
	v_mfma_f32_16x16x32_bf16 v[36:39], v[206:209], v[182:185], v[36:39]
	v_mfma_f32_16x16x32_bf16 v[32:35], v[214:217], v[182:185], v[32:35]
	v_mfma_f32_16x16x32_bf16 v[20:23], v[206:209], v[190:193], v[20:23]
	v_mfma_f32_16x16x32_bf16 v[16:19], v[214:217], v[190:193], v[16:19]
	v_mfma_f32_16x16x32_bf16 v[4:7], v[206:209], v[198:201], v[4:7]
	v_mfma_f32_16x16x32_bf16 v[0:3], v[214:217], v[198:201], v[0:3]
	s_add_i32 s54, s54, 2
	s_add_u32 s24, s24, 0x100
	s_addc_u32 s25, s25, 0
	s_add_u32 s52, s52, 0x100
	s_addc_u32 s53, s53, 0
	s_cmp_gt_u32 s54, 13
	s_barrier
	s_cbranch_scc0 .LBB0_203
	v_lshl_or_b32 v148, s22, 8, v152
	v_cmp_lt_i32_e32 vcc, s50, v148
	s_and_saveexec_b64 s[22:23], vcc
	s_cbranch_execz .LBB0_206
	v_mul_f32_e32 v149, 0x3d372713, v126
	v_mul_f32_e32 v145, 0x3d372713, v120
	v_mul_f32_e32 v149, v126, v149
	v_mul_f32_e32 v156, 0x3d372713, v122
	v_mul_f32_e32 v145, v120, v145
	v_mul_f32_e32 v146, 0x3d372713, v125
	v_fma_f32 v149, v126, v149, v126
	v_mul_f32_e32 v156, v122, v156
	v_fma_f32 v145, v120, v145, v120
	v_mul_f32_e32 v146, v125, v146
	v_mul_f32_e32 v149, 0xc0135761, v149
	v_fma_f32 v156, v122, v156, v122
	v_mul_f32_e32 v145, 0xc0135761, v145
	v_fma_f32 v146, v125, v146, v125
	v_exp_f32_e32 v149, v149
	v_mul_f32_e32 v156, 0xc0135761, v156
	v_exp_f32_e32 v145, v145
	v_mul_f32_e32 v146, 0xc0135761, v146
	v_exp_f32_e32 v157, v156
	v_exp_f32_e32 v147, v146
	v_add_f32_e32 v149, 1.0, v149
	v_add_f32_e32 v145, 1.0, v145
	v_rcp_f32_e32 v156, v149
	v_add_f32_e32 v149, 1.0, v157
	v_mul_f32_e32 v157, 0x3d372713, v127
	v_mul_f32_e32 v144, 0x3d372713, v124
	v_rcp_f32_e32 v146, v145
	v_add_f32_e32 v145, 1.0, v147
	v_mul_f32_e32 v147, 0x3d372713, v121
	v_mul_f32_e32 v157, v127, v157
	v_mul_f32_e32 v158, 0x3d372713, v123
	v_mul_f32_e32 v144, v124, v144
	v_mul_f32_e32 v147, v121, v147
	v_fma_f32 v157, v127, v157, v127
	v_mul_f32_e32 v158, v123, v158
	v_fma_f32 v144, v124, v144, v124
	v_fma_f32 v147, v121, v147, v121
	v_mul_f32_e32 v157, 0xc0135761, v157
	v_fma_f32 v158, v123, v158, v123
	v_mul_f32_e32 v144, 0xc0135761, v144
	v_mul_f32_e32 v147, 0xc0135761, v147
	v_exp_f32_e32 v157, v157
	v_mul_f32_e32 v158, 0xc0135761, v158
	v_exp_f32_e32 v144, v144
	v_exp_f32_e32 v147, v147
	v_exp_f32_e32 v159, v158
	v_rcp_f32_e32 v158, v149
	v_add_f32_e32 v149, 1.0, v157
	v_add_f32_e32 v144, 1.0, v144
	v_add_f32_e32 v147, 1.0, v147
	v_rcp_f32_e32 v157, v149
	v_add_f32_e32 v149, 1.0, v159
	v_rcp_f32_e32 v144, v144
	v_rcp_f32_e32 v145, v145
	v_rcp_f32_e32 v159, v149
	v_rcp_f32_e32 v147, v147
	v_pk_mul_f32 v[126:127], v[126:127], v[156:157]
	v_pk_mul_f32 v[124:125], v[124:125], v[144:145]
	v_pk_mul_f32 v[122:123], v[122:123], v[158:159]
	v_pk_mul_f32 v[120:121], v[120:121], v[146:147]

.LBB0_321:
	ds_read_b128 v[144:147], v157
	ds_read_b128 v[148:151], v157 offset:1024
	ds_read_b128 v[164:167], v157 offset:2048
	ds_read_b128 v[168:171], v157 offset:3072
	s_add_u32 s4, s8, 0x100
	s_addc_u32 s5, s9, 0
	s_cmp_eq_u32 s60, 2
	s_cselect_b32 s11, s29, s5
	s_cselect_b32 s10, s28, s4
	s_cselect_b32 s7, s31, s37
	s_cselect_b32 s6, s30, s35
	s_add_i32 m0, s46, 0xc000
	ds_read_b128 v[172:175], v158
	ds_read_b128 v[176:179], v158 offset:1024
	ds_read_b128 v[180:183], v158 offset:2048
	ds_read_b128 v[184:187], v158 offset:3072
	ds_read_b128 v[188:191], v158 offset:4096
	ds_read_b128 v[192:195], v158 offset:5120
	ds_read_b128 v[196:199], v158 offset:6144
	global_load_lds_dwordx4 v136, s[8:9]
	s_add_i32 m0, s46, 0xe000
	ds_read_b128 v[200:203], v158 offset:7168
	global_load_lds_dwordx4 v138, s[8:9]
	s_waitcnt lgkmcnt(8)
	s_barrier
	s_waitcnt lgkmcnt(0)
	v_mfma_f32_16x16x32_bf16 v[124:127], v[144:147], v[172:175], v[124:127]
	v_mfma_f32_16x16x32_bf16 v[120:123], v[164:167], v[172:175], v[120:123]
	v_mfma_f32_16x16x32_bf16 v[116:119], v[144:147], v[180:183], v[116:119]
	v_mfma_f32_16x16x32_bf16 v[112:115], v[164:167], v[180:183], v[112:115]
	v_mfma_f32_16x16x32_bf16 v[108:111], v[144:147], v[188:191], v[108:111]
	v_mfma_f32_16x16x32_bf16 v[104:107], v[164:167], v[188:191], v[104:107]
	v_mfma_f32_16x16x32_bf16 v[100:103], v[144:147], v[196:199], v[100:103]
	v_mfma_f32_16x16x32_bf16 v[96:99], v[164:167], v[196:199], v[96:99]
	v_mfma_f32_16x16x32_bf16 v[124:127], v[148:151], v[176:179], v[124:127]
	v_mfma_f32_16x16x32_bf16 v[120:123], v[168:171], v[176:179], v[120:123]
	v_mfma_f32_16x16x32_bf16 v[116:119], v[148:151], v[184:187], v[116:119]
	v_mfma_f32_16x16x32_bf16 v[112:115], v[168:171], v[184:187], v[112:115]
	v_mfma_f32_16x16x32_bf16 v[108:111], v[148:151], v[192:195], v[108:111]
	v_mfma_f32_16x16x32_bf16 v[104:107], v[168:171], v[192:195], v[104:107]
	v_mfma_f32_16x16x32_bf16 v[100:103], v[148:151], v[200:203], v[100:103]
	v_mfma_f32_16x16x32_bf16 v[96:99], v[168:171], v[200:203], v[96:99]
	s_barrier
	s_add_i32 s8, s54, s44
	s_add_u32 s98, s6, s26
	s_addc_u32 s99, s7, s27
	s_mov_b32 m0, s8
	ds_read_b128 v[204:207], v159
	ds_read_b128 v[208:211], v159 offset:1024
	ds_read_b128 v[212:215], v159 offset:2048
	global_load_lds_dwordx4 v130, s[6:7]
	s_add_i32 m0, s8, 0x2000
	ds_read_b128 v[216:219], v159 offset:3072
	global_load_lds_dwordx4 v134, s[6:7]
	s_barrier
	s_waitcnt lgkmcnt(0)
	v_mfma_f32_16x16x32_bf16 v[60:63], v[204:207], v[172:175], v[60:63]
	v_mfma_f32_16x16x32_bf16 v[56:59], v[212:215], v[172:175], v[56:59]
	v_mfma_f32_16x16x32_bf16 v[52:55], v[204:207], v[180:183], v[52:55]
	v_mfma_f32_16x16x32_bf16 v[48:51], v[212:215], v[180:183], v[48:51]
	v_mfma_f32_16x16x32_bf16 v[44:47], v[204:207], v[188:191], v[44:47]
	v_mfma_f32_16x16x32_bf16 v[40:43], v[212:215], v[188:191], v[40:43]
	v_mfma_f32_16x16x32_bf16 v[36:39], v[204:207], v[196:199], v[36:39]
	v_mfma_f32_16x16x32_bf16 v[32:35], v[212:215], v[196:199], v[32:35]
	v_mfma_f32_16x16x32_bf16 v[60:63], v[208:211], v[176:179], v[60:63]
	v_mfma_f32_16x16x32_bf16 v[56:59], v[216:219], v[176:179], v[56:59]
	v_mfma_f32_16x16x32_bf16 v[52:55], v[208:211], v[184:187], v[52:55]
	v_mfma_f32_16x16x32_bf16 v[48:51], v[216:219], v[184:187], v[48:51]
	v_mfma_f32_16x16x32_bf16 v[44:47], v[208:211], v[192:195], v[44:47]
	v_mfma_f32_16x16x32_bf16 v[40:43], v[216:219], v[192:195], v[40:43]
	v_mfma_f32_16x16x32_bf16 v[36:39], v[208:211], v[200:203], v[36:39]
	v_mfma_f32_16x16x32_bf16 v[32:35], v[216:219], v[200:203], v[32:35]
	s_mov_b32 m0, s46
	s_add_u32 s100, s10, s26
	s_addc_u32 s101, s11, s27
	s_barrier
	ds_read_b128 v[172:175], v158 offset:16384
	ds_read_b128 v[176:179], v158 offset:17408
	ds_read_b128 v[180:183], v158 offset:18432
	ds_read_b128 v[184:187], v158 offset:19456
	ds_read_b128 v[188:191], v158 offset:20480
	ds_read_b128 v[192:195], v158 offset:21504
	ds_read_b128 v[196:199], v158 offset:22528
	global_load_lds_dwordx4 v128, s[10:11]
	s_mov_b32 m0, s47
	ds_read_b128 v[200:203], v158 offset:23552
	global_load_lds_dwordx4 v132, s[10:11]
	s_barrier
	s_waitcnt lgkmcnt(0)
	v_mfma_f32_16x16x32_bf16 v[92:95], v[144:147], v[172:175], v[92:95]
	v_mfma_f32_16x16x32_bf16 v[88:91], v[164:167], v[172:175], v[88:91]
	v_mfma_f32_16x16x32_bf16 v[84:87], v[144:147], v[180:183], v[84:87]
	v_mfma_f32_16x16x32_bf16 v[80:83], v[164:167], v[180:183], v[80:83]
	v_mfma_f32_16x16x32_bf16 v[76:79], v[144:147], v[188:191], v[76:79]
	v_mfma_f32_16x16x32_bf16 v[72:75], v[164:167], v[188:191], v[72:75]
	v_mfma_f32_16x16x32_bf16 v[68:71], v[144:147], v[196:199], v[68:71]
	v_mfma_f32_16x16x32_bf16 v[64:67], v[164:167], v[196:199], v[64:67]
	v_mfma_f32_16x16x32_bf16 v[92:95], v[148:151], v[176:179], v[92:95]
	v_mfma_f32_16x16x32_bf16 v[88:91], v[168:171], v[176:179], v[88:91]
	v_mfma_f32_16x16x32_bf16 v[84:87], v[148:151], v[184:187], v[84:87]
	v_mfma_f32_16x16x32_bf16 v[80:83], v[168:171], v[184:187], v[80:83]
	v_mfma_f32_16x16x32_bf16 v[76:79], v[148:151], v[192:195], v[76:79]
	v_mfma_f32_16x16x32_bf16 v[72:75], v[168:171], v[192:195], v[72:75]
	v_mfma_f32_16x16x32_bf16 v[68:71], v[148:151], v[200:203], v[68:71]
	v_mfma_f32_16x16x32_bf16 v[64:67], v[168:171], v[200:203], v[64:67]
	s_barrier
	s_add_u32 s8, s6, 0x18000
	s_addc_u32 s9, s7, 0
	s_add_i32 s61, s55, s44
	s_mov_b32 m0, s61
	s_nop 0
	global_load_lds_dwordx4 v130, s[8:9]
	s_add_i32 m0, s61, 0x2000
	s_nop 0
	global_load_lds_dwordx4 v134, s[8:9]
	s_waitcnt vmcnt(6)
	s_barrier
	v_mfma_f32_16x16x32_bf16 v[28:31], v[204:207], v[172:175], v[28:31]
	v_mfma_f32_16x16x32_bf16 v[24:27], v[212:215], v[172:175], v[24:27]
	v_mfma_f32_16x16x32_bf16 v[20:23], v[204:207], v[180:183], v[20:23]
	v_mfma_f32_16x16x32_bf16 v[16:19], v[212:215], v[180:183], v[16:19]
	v_mfma_f32_16x16x32_bf16 v[12:15], v[204:207], v[188:191], v[12:15]
	v_mfma_f32_16x16x32_bf16 v[8:11], v[212:215], v[188:191], v[8:11]
	v_mfma_f32_16x16x32_bf16 v[4:7], v[204:207], v[196:199], v[4:7]
	v_mfma_f32_16x16x32_bf16 v[0:3], v[212:215], v[196:199], v[0:3]
	v_mfma_f32_16x16x32_bf16 v[28:31], v[208:211], v[176:179], v[28:31]
	v_mfma_f32_16x16x32_bf16 v[24:27], v[216:219], v[176:179], v[24:27]
	v_mfma_f32_16x16x32_bf16 v[20:23], v[208:211], v[184:187], v[20:23]
	v_mfma_f32_16x16x32_bf16 v[16:19], v[216:219], v[184:187], v[16:19]
	v_mfma_f32_16x16x32_bf16 v[12:15], v[208:211], v[192:195], v[12:15]
	v_mfma_f32_16x16x32_bf16 v[8:11], v[216:219], v[192:195], v[8:11]
	v_mfma_f32_16x16x32_bf16 v[4:7], v[208:211], v[200:203], v[4:7]
	v_mfma_f32_16x16x32_bf16 v[0:3], v[216:219], v[200:203], v[0:3]
	s_add_i32 s61, 0, 0x18000
	v_add_u32_e32 v163, s61, v155
	s_barrier
	ds_read_b128 v[144:147], v163
	ds_read_b128 v[148:151], v163 offset:1024
	ds_read_b128 v[164:167], v163 offset:2048
	ds_read_b128 v[168:171], v163 offset:3072
	s_add_u32 s8, s10, 0x18000
	s_addc_u32 s9, s11, 0
	s_mov_b32 m0, s48
	ds_read_b128 v[172:175], v158 offset:32768
	ds_read_b128 v[176:179], v158 offset:33792
	ds_read_b128 v[180:183], v158 offset:34816
	ds_read_b128 v[184:187], v158 offset:35840
	ds_read_b128 v[188:191], v158 offset:36864
	ds_read_b128 v[192:195], v158 offset:37888
	ds_read_b128 v[196:199], v158 offset:38912
	global_load_lds_dwordx4 v128, s[8:9]
	s_mov_b32 m0, s49
	ds_read_b128 v[200:203], v158 offset:39936
	global_load_lds_dwordx4 v132, s[8:9]
	s_waitcnt lgkmcnt(8)
	s_barrier
	s_waitcnt lgkmcnt(0)
	v_mfma_f32_16x16x32_bf16 v[124:127], v[144:147], v[172:175], v[124:127]
	v_mfma_f32_16x16x32_bf16 v[120:123], v[164:167], v[172:175], v[120:123]
	v_mfma_f32_16x16x32_bf16 v[116:119], v[144:147], v[180:183], v[116:119]
	v_mfma_f32_16x16x32_bf16 v[112:115], v[164:167], v[180:183], v[112:115]
	v_mfma_f32_16x16x32_bf16 v[108:111], v[144:147], v[188:191], v[108:111]
	v_mfma_f32_16x16x32_bf16 v[104:107], v[164:167], v[188:191], v[104:107]
	v_mfma_f32_16x16x32_bf16 v[100:103], v[144:147], v[196:199], v[100:103]
	v_mfma_f32_16x16x32_bf16 v[96:99], v[164:167], v[196:199], v[96:99]
	v_mfma_f32_16x16x32_bf16 v[124:127], v[148:151], v[176:179], v[124:127]
	v_mfma_f32_16x16x32_bf16 v[120:123], v[168:171], v[176:179], v[120:123]
	v_mfma_f32_16x16x32_bf16 v[116:119], v[148:151], v[184:187], v[116:119]
	v_mfma_f32_16x16x32_bf16 v[112:115], v[168:171], v[184:187], v[112:115]
	v_mfma_f32_16x16x32_bf16 v[108:111], v[148:151], v[192:195], v[108:111]
	v_mfma_f32_16x16x32_bf16 v[104:107], v[168:171], v[192:195], v[104:107]
	v_mfma_f32_16x16x32_bf16 v[100:103], v[148:151], v[200:203], v[100:103]
	v_mfma_f32_16x16x32_bf16 v[96:99], v[168:171], v[200:203], v[96:99]
	s_barrier
	s_add_i32 s8, 0, 0x1c000
	s_add_i32 s9, s61, s44
	v_add_u32_e32 v163, s8, v155
	s_mov_b32 m0, s9
	ds_read_b128 v[204:207], v163
	ds_read_b128 v[208:211], v163 offset:1024
	ds_read_b128 v[212:215], v163 offset:2048
	global_load_lds_dwordx4 v130, s[98:99]
	s_add_i32 m0, s9, 0x2000
	ds_read_b128 v[216:219], v163 offset:3072
	global_load_lds_dwordx4 v134, s[98:99]
	s_barrier
	s_waitcnt lgkmcnt(0)
	v_mfma_f32_16x16x32_bf16 v[60:63], v[204:207], v[172:175], v[60:63]
	v_mfma_f32_16x16x32_bf16 v[56:59], v[212:215], v[172:175], v[56:59]
	v_mfma_f32_16x16x32_bf16 v[52:55], v[204:207], v[180:183], v[52:55]
	v_mfma_f32_16x16x32_bf16 v[48:51], v[212:215], v[180:183], v[48:51]
	v_mfma_f32_16x16x32_bf16 v[44:47], v[204:207], v[188:191], v[44:47]
	v_mfma_f32_16x16x32_bf16 v[40:43], v[212:215], v[188:191], v[40:43]
	v_mfma_f32_16x16x32_bf16 v[36:39], v[204:207], v[196:199], v[36:39]
	v_mfma_f32_16x16x32_bf16 v[32:35], v[212:215], v[196:199], v[32:35]
	v_mfma_f32_16x16x32_bf16 v[60:63], v[208:211], v[176:179], v[60:63]
	v_mfma_f32_16x16x32_bf16 v[56:59], v[216:219], v[176:179], v[56:59]
	v_mfma_f32_16x16x32_bf16 v[52:55], v[208:211], v[184:187], v[52:55]
	v_mfma_f32_16x16x32_bf16 v[48:51], v[216:219], v[184:187], v[48:51]
	v_mfma_f32_16x16x32_bf16 v[44:47], v[208:211], v[192:195], v[44:47]
	v_mfma_f32_16x16x32_bf16 v[40:43], v[216:219], v[192:195], v[40:43]
	v_mfma_f32_16x16x32_bf16 v[36:39], v[208:211], v[200:203], v[36:39]
	v_mfma_f32_16x16x32_bf16 v[32:35], v[216:219], v[200:203], v[32:35]
	s_mov_b32 m0, s51
	s_barrier
	ds_read_b128 v[172:175], v158 offset:49152
	ds_read_b128 v[176:179], v158 offset:50176
	ds_read_b128 v[180:183], v158 offset:51200
	ds_read_b128 v[184:187], v158 offset:52224
	ds_read_b128 v[188:191], v158 offset:53248
	ds_read_b128 v[192:195], v158 offset:54272
	ds_read_b128 v[196:199], v158 offset:55296
	global_load_lds_dwordx4 v128, s[100:101]
	s_mov_b32 m0, s52
	ds_read_b128 v[200:203], v158 offset:56320
	global_load_lds_dwordx4 v132, s[100:101]
	s_barrier
	s_waitcnt lgkmcnt(0)
	v_mfma_f32_16x16x32_bf16 v[92:95], v[144:147], v[172:175], v[92:95]
	v_mfma_f32_16x16x32_bf16 v[88:91], v[164:167], v[172:175], v[88:91]
	v_mfma_f32_16x16x32_bf16 v[84:87], v[144:147], v[180:183], v[84:87]
	v_mfma_f32_16x16x32_bf16 v[80:83], v[164:167], v[180:183], v[80:83]
	v_mfma_f32_16x16x32_bf16 v[76:79], v[144:147], v[188:191], v[76:79]
	v_mfma_f32_16x16x32_bf16 v[72:75], v[164:167], v[188:191], v[72:75]
	v_mfma_f32_16x16x32_bf16 v[68:71], v[144:147], v[196:199], v[68:71]
	v_mfma_f32_16x16x32_bf16 v[64:67], v[164:167], v[196:199], v[64:67]
	v_mfma_f32_16x16x32_bf16 v[92:95], v[148:151], v[176:179], v[92:95]
	v_mfma_f32_16x16x32_bf16 v[88:91], v[168:171], v[176:179], v[88:91]
	v_mfma_f32_16x16x32_bf16 v[84:87], v[148:151], v[184:187], v[84:87]
	v_mfma_f32_16x16x32_bf16 v[80:83], v[168:171], v[184:187], v[80:83]
	v_mfma_f32_16x16x32_bf16 v[76:79], v[148:151], v[192:195], v[76:79]
	v_mfma_f32_16x16x32_bf16 v[72:75], v[168:171], v[192:195], v[72:75]
	v_mfma_f32_16x16x32_bf16 v[68:71], v[148:151], v[200:203], v[68:71]
	v_mfma_f32_16x16x32_bf16 v[64:67], v[168:171], v[200:203], v[64:67]
	s_barrier
	s_add_u32 s6, s6, 0x18080
	s_addc_u32 s7, s7, 0
	s_add_i32 s8, s8, s44
	s_mov_b32 m0, s8
	s_nop 0
	global_load_lds_dwordx4 v130, s[6:7]
	s_add_i32 m0, s8, 0x2000
	s_nop 0
	global_load_lds_dwordx4 v134, s[6:7]
	s_waitcnt vmcnt(6)
	s_barrier
	v_mfma_f32_16x16x32_bf16 v[28:31], v[204:207], v[172:175], v[28:31]
	v_mfma_f32_16x16x32_bf16 v[24:27], v[212:215], v[172:175], v[24:27]
	v_mfma_f32_16x16x32_bf16 v[20:23], v[204:207], v[180:183], v[20:23]
	v_mfma_f32_16x16x32_bf16 v[16:19], v[212:215], v[180:183], v[16:19]
	v_mfma_f32_16x16x32_bf16 v[12:15], v[204:207], v[188:191], v[12:15]
	v_mfma_f32_16x16x32_bf16 v[8:11], v[212:215], v[188:191], v[8:11]
	v_mfma_f32_16x16x32_bf16 v[4:7], v[204:207], v[196:199], v[4:7]
	v_mfma_f32_16x16x32_bf16 v[0:3], v[212:215], v[196:199], v[0:3]
	v_mfma_f32_16x16x32_bf16 v[28:31], v[208:211], v[176:179], v[28:31]
	v_mfma_f32_16x16x32_bf16 v[24:27], v[216:219], v[176:179], v[24:27]
	v_mfma_f32_16x16x32_bf16 v[20:23], v[208:211], v[184:187], v[20:23]
	v_mfma_f32_16x16x32_bf16 v[16:19], v[216:219], v[184:187], v[16:19]
	v_mfma_f32_16x16x32_bf16 v[12:15], v[208:211], v[192:195], v[12:15]
	v_mfma_f32_16x16x32_bf16 v[8:11], v[216:219], v[192:195], v[8:11]
	v_mfma_f32_16x16x32_bf16 v[4:7], v[208:211], v[200:203], v[4:7]
	v_mfma_f32_16x16x32_bf16 v[0:3], v[216:219], v[200:203], v[0:3]
	s_add_i32 s60, s60, 2
	s_add_u32 s35, s35, 0x100
	s_addc_u32 s37, s37, 0
	s_cmp_gt_u32 s60, 3
	s_mov_b64 s[8:9], s[4:5]
	s_barrier
	s_cbranch_scc0 .LBB0_321
	s_lshl_b32 s37, s34, 8
	s_ashr_i32 s6, s34, 1
	s_cmp_lt_i32 s6, 2
	s_cselect_b64 s[8:9], -1, 0
	s_cmp_gt_i32 s6, 1
	s_cselect_b64 s[34:35], -1, 0
	s_lshl_b32 s60, s6, 9
	s_add_i32 s61, s60, 0xfffffc00
	v_bitop3_b32 v144, s37, v161, v156 bitop3:0xc8
	v_or_b32_e32 v146, s61, v144
	v_or_b32_e32 v144, s60, v144
	v_mov_b32_e32 v145, 0
	s_cmp_lt_i32 s6, 4
	v_cndmask_b32_e64 v152, v146, v144, s[8:9]
	s_cselect_b64 s[4:5], -1, 0
	s_cmp_gt_i32 s6, 3
	v_ashrrev_i32_e32 v153, 31, v152
	v_mov_b32_e32 v144, v145
	s_cbranch_scc1 .LBB0_330
	s_and_b64 s[10:11], s[8:9], exec
	s_cselect_b32 s7, s21, s23
	s_cselect_b32 s10, s20, s22
	v_mov_b32_e32 v146, s10
	v_mov_b32_e32 v147, s7
	v_lshl_add_u64 v[146:147], v[152:153], 2, v[146:147]
	global_load_dword v144, v[146:147], off
	v_cndmask_b32_e64 v146, 0, 1, s[4:5]
	v_cmp_ne_u32_e64 s[10:11], 1, v146
	s_andn2_b64 vcc, exec, s[4:5]
	s_cbranch_vccz .LBB0_331

.LBB0_583:
	ds_read_b128 v[128:131], v164
	ds_read_b128 v[132:135], v164 offset:1024
	ds_read_b128 v[152:155], v164 offset:2048
	ds_read_b128 v[156:159], v164 offset:3072
	s_add_u32 s38, s36, 0xfffc0080
	s_addc_u32 s39, s37, -1
	s_cmp_eq_u32 s63, 12
	s_cselect_b32 s41, s9, s39
	s_cselect_b32 s40, s29, s38
	s_cselect_b32 s39, s27, s62
	s_cselect_b32 s38, s60, s61
	s_add_i32 m0, s50, 0xc000
	ds_read_b128 v[168:171], v165
	ds_read_b128 v[172:175], v165 offset:1024
	ds_read_b128 v[176:179], v165 offset:2048
	ds_read_b128 v[180:183], v165 offset:3072
	ds_read_b128 v[184:187], v165 offset:4096
	ds_read_b128 v[188:191], v165 offset:5120
	ds_read_b128 v[192:195], v165 offset:6144
	global_load_lds_dwordx4 v144, s[36:37]
	s_add_i32 m0, s50, 0xe000
	ds_read_b128 v[196:199], v165 offset:7168
	global_load_lds_dwordx4 v146, s[36:37]
	s_waitcnt lgkmcnt(8)
	s_barrier
	s_waitcnt lgkmcnt(0)
	v_mfma_f32_16x16x32_bf16 v[120:123], v[128:131], v[168:171], v[120:123]
	v_mfma_f32_16x16x32_bf16 v[124:127], v[152:155], v[168:171], v[124:127]
	v_mfma_f32_16x16x32_bf16 v[104:107], v[128:131], v[176:179], v[104:107]
	v_mfma_f32_16x16x32_bf16 v[108:111], v[152:155], v[176:179], v[108:111]
	v_mfma_f32_16x16x32_bf16 v[88:91], v[128:131], v[184:187], v[88:91]
	v_mfma_f32_16x16x32_bf16 v[92:95], v[152:155], v[184:187], v[92:95]
	v_mfma_f32_16x16x32_bf16 v[72:75], v[128:131], v[192:195], v[72:75]
	v_mfma_f32_16x16x32_bf16 v[76:79], v[152:155], v[192:195], v[76:79]
	v_mfma_f32_16x16x32_bf16 v[120:123], v[132:135], v[172:175], v[120:123]
	v_mfma_f32_16x16x32_bf16 v[124:127], v[156:159], v[172:175], v[124:127]
	v_mfma_f32_16x16x32_bf16 v[104:107], v[132:135], v[180:183], v[104:107]
	v_mfma_f32_16x16x32_bf16 v[108:111], v[156:159], v[180:183], v[108:111]
	v_mfma_f32_16x16x32_bf16 v[88:91], v[132:135], v[188:191], v[88:91]
	v_mfma_f32_16x16x32_bf16 v[92:95], v[156:159], v[188:191], v[92:95]
	v_mfma_f32_16x16x32_bf16 v[72:75], v[132:135], v[196:199], v[72:75]
	v_mfma_f32_16x16x32_bf16 v[76:79], v[156:159], v[196:199], v[76:79]
	s_barrier
	s_add_i32 s64, s57, s49
	s_add_u32 s98, s38, s22
	s_addc_u32 s99, s39, s23
	s_mov_b32 m0, s64
	ds_read_b128 v[200:203], v166
	ds_read_b128 v[204:207], v166 offset:1024
	ds_read_b128 v[208:211], v166 offset:2048
	global_load_lds_dwordx4 v138, s[38:39]
	s_add_i32 m0, s64, 0x2000
	ds_read_b128 v[212:215], v166 offset:3072
	global_load_lds_dwordx4 v142, s[38:39]
	s_barrier
	s_waitcnt lgkmcnt(0)
	v_mfma_f32_16x16x32_bf16 v[112:115], v[200:203], v[168:171], v[112:115]
	v_mfma_f32_16x16x32_bf16 v[116:119], v[208:211], v[168:171], v[116:119]
	v_mfma_f32_16x16x32_bf16 v[96:99], v[200:203], v[176:179], v[96:99]
	v_mfma_f32_16x16x32_bf16 v[100:103], v[208:211], v[176:179], v[100:103]
	v_mfma_f32_16x16x32_bf16 v[80:83], v[200:203], v[184:187], v[80:83]
	v_mfma_f32_16x16x32_bf16 v[84:87], v[208:211], v[184:187], v[84:87]
	v_mfma_f32_16x16x32_bf16 v[64:67], v[200:203], v[192:195], v[64:67]
	v_mfma_f32_16x16x32_bf16 v[68:71], v[208:211], v[192:195], v[68:71]
	v_mfma_f32_16x16x32_bf16 v[112:115], v[204:207], v[172:175], v[112:115]
	v_mfma_f32_16x16x32_bf16 v[116:119], v[212:215], v[172:175], v[116:119]
	v_mfma_f32_16x16x32_bf16 v[96:99], v[204:207], v[180:183], v[96:99]
	v_mfma_f32_16x16x32_bf16 v[100:103], v[212:215], v[180:183], v[100:103]
	v_mfma_f32_16x16x32_bf16 v[80:83], v[204:207], v[188:191], v[80:83]
	v_mfma_f32_16x16x32_bf16 v[84:87], v[212:215], v[188:191], v[84:87]
	v_mfma_f32_16x16x32_bf16 v[64:67], v[204:207], v[196:199], v[64:67]
	v_mfma_f32_16x16x32_bf16 v[68:71], v[212:215], v[196:199], v[68:71]
	s_mov_b32 m0, s50
	s_add_u32 s100, s40, s22
	s_addc_u32 s101, s41, s23
	s_barrier
	ds_read_b128 v[168:171], v165 offset:16384
	ds_read_b128 v[172:175], v165 offset:17408
	ds_read_b128 v[176:179], v165 offset:18432
	ds_read_b128 v[180:183], v165 offset:19456
	ds_read_b128 v[184:187], v165 offset:20480
	ds_read_b128 v[188:191], v165 offset:21504
	ds_read_b128 v[192:195], v165 offset:22528
	global_load_lds_dwordx4 v136, s[40:41]
	s_mov_b32 m0, s51
	ds_read_b128 v[196:199], v165 offset:23552
	global_load_lds_dwordx4 v140, s[40:41]
	s_barrier
	s_waitcnt lgkmcnt(0)
	v_mfma_f32_16x16x32_bf16 v[56:59], v[128:131], v[168:171], v[56:59]
	v_mfma_f32_16x16x32_bf16 v[60:63], v[152:155], v[168:171], v[60:63]
	v_mfma_f32_16x16x32_bf16 v[40:43], v[128:131], v[176:179], v[40:43]
	v_mfma_f32_16x16x32_bf16 v[44:47], v[152:155], v[176:179], v[44:47]
	v_mfma_f32_16x16x32_bf16 v[24:27], v[128:131], v[184:187], v[24:27]
	v_mfma_f32_16x16x32_bf16 v[28:31], v[152:155], v[184:187], v[28:31]
	v_mfma_f32_16x16x32_bf16 v[8:11], v[128:131], v[192:195], v[8:11]
	v_mfma_f32_16x16x32_bf16 v[12:15], v[152:155], v[192:195], v[12:15]
	v_mfma_f32_16x16x32_bf16 v[56:59], v[132:135], v[172:175], v[56:59]
	v_mfma_f32_16x16x32_bf16 v[60:63], v[156:159], v[172:175], v[60:63]
	v_mfma_f32_16x16x32_bf16 v[40:43], v[132:135], v[180:183], v[40:43]
	v_mfma_f32_16x16x32_bf16 v[44:47], v[156:159], v[180:183], v[44:47]
	v_mfma_f32_16x16x32_bf16 v[24:27], v[132:135], v[188:191], v[24:27]
	v_mfma_f32_16x16x32_bf16 v[28:31], v[156:159], v[188:191], v[28:31]
	v_mfma_f32_16x16x32_bf16 v[8:11], v[132:135], v[196:199], v[8:11]
	v_mfma_f32_16x16x32_bf16 v[12:15], v[156:159], v[196:199], v[12:15]
	s_barrier
	s_add_u32 s64, s38, 0x40000
	s_addc_u32 s65, s39, 0
	s_add_i32 s66, s58, s49
	s_mov_b32 m0, s66
	s_nop 0
	global_load_lds_dwordx4 v138, s[64:65]
	s_add_i32 m0, s66, 0x2000
	s_nop 0
	global_load_lds_dwordx4 v142, s[64:65]
	s_waitcnt vmcnt(6)
	s_barrier
	v_mfma_f32_16x16x32_bf16 v[48:51], v[200:203], v[168:171], v[48:51]
	v_mfma_f32_16x16x32_bf16 v[52:55], v[208:211], v[168:171], v[52:55]
	v_mfma_f32_16x16x32_bf16 v[32:35], v[200:203], v[176:179], v[32:35]
	v_mfma_f32_16x16x32_bf16 v[36:39], v[208:211], v[176:179], v[36:39]
	v_mfma_f32_16x16x32_bf16 v[16:19], v[200:203], v[184:187], v[16:19]
	v_mfma_f32_16x16x32_bf16 v[20:23], v[208:211], v[184:187], v[20:23]
	v_mfma_f32_16x16x32_bf16 v[4:7], v[200:203], v[192:195], v[4:7]
	v_mfma_f32_16x16x32_bf16 v[0:3], v[208:211], v[192:195], v[0:3]
	v_mfma_f32_16x16x32_bf16 v[48:51], v[204:207], v[172:175], v[48:51]
	v_mfma_f32_16x16x32_bf16 v[52:55], v[212:215], v[172:175], v[52:55]
	v_mfma_f32_16x16x32_bf16 v[32:35], v[204:207], v[180:183], v[32:35]
	v_mfma_f32_16x16x32_bf16 v[36:39], v[212:215], v[180:183], v[36:39]
	v_mfma_f32_16x16x32_bf16 v[16:19], v[204:207], v[188:191], v[16:19]
	v_mfma_f32_16x16x32_bf16 v[20:23], v[212:215], v[188:191], v[20:23]
	v_mfma_f32_16x16x32_bf16 v[4:7], v[204:207], v[196:199], v[4:7]
	v_mfma_f32_16x16x32_bf16 v[0:3], v[212:215], v[196:199], v[0:3]
	s_add_i32 s64, 0, 0x18000
	v_add_u32_e32 v156, s64, v162
	s_barrier
	ds_read_b128 v[128:131], v156
	ds_read_b128 v[132:135], v156 offset:1024
	ds_read_b128 v[152:155], v156 offset:2048
	ds_read_b128 v[156:159], v156 offset:3072
	s_add_u32 s40, s40, 0x40000
	s_addc_u32 s41, s41, 0
	s_mov_b32 m0, s52
	ds_read_b128 v[168:171], v165 offset:32768
	ds_read_b128 v[172:175], v165 offset:33792
	ds_read_b128 v[176:179], v165 offset:34816
	ds_read_b128 v[180:183], v165 offset:35840
	ds_read_b128 v[184:187], v165 offset:36864
	ds_read_b128 v[188:191], v165 offset:37888
	ds_read_b128 v[192:195], v165 offset:38912
	global_load_lds_dwordx4 v136, s[40:41]
	s_mov_b32 m0, s53
	ds_read_b128 v[196:199], v165 offset:39936
	global_load_lds_dwordx4 v140, s[40:41]
	s_waitcnt lgkmcnt(8)
	s_barrier
	s_waitcnt lgkmcnt(0)
	v_mfma_f32_16x16x32_bf16 v[120:123], v[128:131], v[168:171], v[120:123]
	v_mfma_f32_16x16x32_bf16 v[124:127], v[152:155], v[168:171], v[124:127]
	v_mfma_f32_16x16x32_bf16 v[104:107], v[128:131], v[176:179], v[104:107]
	v_mfma_f32_16x16x32_bf16 v[108:111], v[152:155], v[176:179], v[108:111]
	v_mfma_f32_16x16x32_bf16 v[88:91], v[128:131], v[184:187], v[88:91]
	v_mfma_f32_16x16x32_bf16 v[92:95], v[152:155], v[184:187], v[92:95]
	v_mfma_f32_16x16x32_bf16 v[72:75], v[128:131], v[192:195], v[72:75]
	v_mfma_f32_16x16x32_bf16 v[76:79], v[152:155], v[192:195], v[76:79]
	v_mfma_f32_16x16x32_bf16 v[120:123], v[132:135], v[172:175], v[120:123]
	v_mfma_f32_16x16x32_bf16 v[124:127], v[156:159], v[172:175], v[124:127]
	v_mfma_f32_16x16x32_bf16 v[104:107], v[132:135], v[180:183], v[104:107]
	v_mfma_f32_16x16x32_bf16 v[108:111], v[156:159], v[180:183], v[108:111]
	v_mfma_f32_16x16x32_bf16 v[88:91], v[132:135], v[188:191], v[88:91]
	v_mfma_f32_16x16x32_bf16 v[92:95], v[156:159], v[188:191], v[92:95]
	v_mfma_f32_16x16x32_bf16 v[72:75], v[132:135], v[196:199], v[72:75]
	v_mfma_f32_16x16x32_bf16 v[76:79], v[156:159], v[196:199], v[76:79]
	s_barrier
	s_add_i32 s40, 0, 0x1c000
	s_add_i32 s41, s64, s49
	v_add_u32_e32 v212, s40, v162
	s_mov_b32 m0, s41
	ds_read_b128 v[200:203], v212
	ds_read_b128 v[204:207], v212 offset:1024
	ds_read_b128 v[208:211], v212 offset:2048
	global_load_lds_dwordx4 v138, s[98:99]
	s_add_i32 m0, s41, 0x2000
	ds_read_b128 v[212:215], v212 offset:3072
	global_load_lds_dwordx4 v142, s[98:99]
	s_barrier
	s_waitcnt lgkmcnt(0)
	v_mfma_f32_16x16x32_bf16 v[112:115], v[200:203], v[168:171], v[112:115]
	v_mfma_f32_16x16x32_bf16 v[116:119], v[208:211], v[168:171], v[116:119]
	v_mfma_f32_16x16x32_bf16 v[96:99], v[200:203], v[176:179], v[96:99]
	v_mfma_f32_16x16x32_bf16 v[100:103], v[208:211], v[176:179], v[100:103]
	v_mfma_f32_16x16x32_bf16 v[80:83], v[200:203], v[184:187], v[80:83]
	v_mfma_f32_16x16x32_bf16 v[84:87], v[208:211], v[184:187], v[84:87]
	v_mfma_f32_16x16x32_bf16 v[64:67], v[200:203], v[192:195], v[64:67]
	v_mfma_f32_16x16x32_bf16 v[68:71], v[208:211], v[192:195], v[68:71]
	v_mfma_f32_16x16x32_bf16 v[112:115], v[204:207], v[172:175], v[112:115]
	v_mfma_f32_16x16x32_bf16 v[116:119], v[212:215], v[172:175], v[116:119]
	v_mfma_f32_16x16x32_bf16 v[96:99], v[204:207], v[180:183], v[96:99]
	v_mfma_f32_16x16x32_bf16 v[100:103], v[212:215], v[180:183], v[100:103]
	v_mfma_f32_16x16x32_bf16 v[80:83], v[204:207], v[188:191], v[80:83]
	v_mfma_f32_16x16x32_bf16 v[84:87], v[212:215], v[188:191], v[84:87]
	v_mfma_f32_16x16x32_bf16 v[64:67], v[204:207], v[196:199], v[64:67]
	v_mfma_f32_16x16x32_bf16 v[68:71], v[212:215], v[196:199], v[68:71]
	s_mov_b32 m0, s55
	s_barrier
	ds_read_b128 v[168:171], v165 offset:49152
	ds_read_b128 v[172:175], v165 offset:50176
	ds_read_b128 v[176:179], v165 offset:51200
	ds_read_b128 v[180:183], v165 offset:52224
	ds_read_b128 v[184:187], v165 offset:53248
	ds_read_b128 v[188:191], v165 offset:54272
	ds_read_b128 v[192:195], v165 offset:55296
	global_load_lds_dwordx4 v136, s[100:101]
	s_mov_b32 m0, s56
	ds_read_b128 v[196:199], v165 offset:56320
	global_load_lds_dwordx4 v140, s[100:101]
	s_barrier
	s_waitcnt lgkmcnt(0)
	v_mfma_f32_16x16x32_bf16 v[56:59], v[128:131], v[168:171], v[56:59]
	v_mfma_f32_16x16x32_bf16 v[60:63], v[152:155], v[168:171], v[60:63]
	v_mfma_f32_16x16x32_bf16 v[40:43], v[128:131], v[176:179], v[40:43]
	v_mfma_f32_16x16x32_bf16 v[44:47], v[152:155], v[176:179], v[44:47]
	v_mfma_f32_16x16x32_bf16 v[24:27], v[128:131], v[184:187], v[24:27]
	v_mfma_f32_16x16x32_bf16 v[28:31], v[152:155], v[184:187], v[28:31]
	v_mfma_f32_16x16x32_bf16 v[8:11], v[128:131], v[192:195], v[8:11]
	v_mfma_f32_16x16x32_bf16 v[12:15], v[152:155], v[192:195], v[12:15]
	v_mfma_f32_16x16x32_bf16 v[56:59], v[132:135], v[172:175], v[56:59]
	v_mfma_f32_16x16x32_bf16 v[60:63], v[156:159], v[172:175], v[60:63]
	v_mfma_f32_16x16x32_bf16 v[40:43], v[132:135], v[180:183], v[40:43]
	v_mfma_f32_16x16x32_bf16 v[44:47], v[156:159], v[180:183], v[44:47]
	v_mfma_f32_16x16x32_bf16 v[24:27], v[132:135], v[188:191], v[24:27]
	v_mfma_f32_16x16x32_bf16 v[28:31], v[156:159], v[188:191], v[28:31]
	v_mfma_f32_16x16x32_bf16 v[8:11], v[132:135], v[196:199], v[8:11]
	v_mfma_f32_16x16x32_bf16 v[12:15], v[156:159], v[196:199], v[12:15]
	s_barrier
	s_add_u32 s38, s38, 0x40080
	s_addc_u32 s39, s39, 0
	s_add_i32 s40, s40, s49
	s_mov_b32 m0, s40
	s_nop 0
	global_load_lds_dwordx4 v138, s[38:39]
	s_add_i32 m0, s40, 0x2000
	s_nop 0
	global_load_lds_dwordx4 v142, s[38:39]
	s_waitcnt vmcnt(6)
	s_barrier
	v_mfma_f32_16x16x32_bf16 v[48:51], v[200:203], v[168:171], v[48:51]
	v_mfma_f32_16x16x32_bf16 v[52:55], v[208:211], v[168:171], v[52:55]
	v_mfma_f32_16x16x32_bf16 v[32:35], v[200:203], v[176:179], v[32:35]
	v_mfma_f32_16x16x32_bf16 v[36:39], v[208:211], v[176:179], v[36:39]
	v_mfma_f32_16x16x32_bf16 v[16:19], v[200:203], v[184:187], v[16:19]
	v_mfma_f32_16x16x32_bf16 v[20:23], v[208:211], v[184:187], v[20:23]
	v_mfma_f32_16x16x32_bf16 v[4:7], v[200:203], v[192:195], v[4:7]
	v_mfma_f32_16x16x32_bf16 v[0:3], v[208:211], v[192:195], v[0:3]
	v_mfma_f32_16x16x32_bf16 v[48:51], v[204:207], v[172:175], v[48:51]
	v_mfma_f32_16x16x32_bf16 v[52:55], v[212:215], v[172:175], v[52:55]
	v_mfma_f32_16x16x32_bf16 v[32:35], v[204:207], v[180:183], v[32:35]
	v_mfma_f32_16x16x32_bf16 v[36:39], v[212:215], v[180:183], v[36:39]
	v_mfma_f32_16x16x32_bf16 v[16:19], v[204:207], v[188:191], v[16:19]
	v_mfma_f32_16x16x32_bf16 v[20:23], v[212:215], v[188:191], v[20:23]
	v_mfma_f32_16x16x32_bf16 v[4:7], v[204:207], v[196:199], v[4:7]
	v_mfma_f32_16x16x32_bf16 v[0:3], v[212:215], v[196:199], v[0:3]
	s_add_i32 s63, s63, 2
	s_add_u32 s36, s36, 0x100
	s_addc_u32 s37, s37, 0
	s_add_u32 s61, s61, 0x100
	s_addc_u32 s62, s62, 0
	s_cmp_gt_u32 s63, 13
	s_barrier
	s_cbranch_scc0 .LBB0_583
	v_lshl_add_u32 v152, s8, 8, v161
	v_lshl_or_b32 v153, s16, 8, v163
	s_lshl_b32 s36, s16, 2
	s_ashr_i32 s37, s36, 31
	s_lshl_b32 s16, s54, 2
	v_lshl_add_u32 v154, v152, 10, v153
	v_lshl_add_u32 v156, v152, 6, s16
	v_lshl_add_u32 v156, s36, 2, v156
	v_lshlrev_b32_e32 v155, 1, v154
	v_lshlrev_b32_e32 v154, 2, v154
	global_load_dwordx4 v[168:171], v154, s[14:15]
	global_load_dwordx4 v[172:175], v154, s[14:15] offset:16
	global_load_dwordx4 v[176:179], v154, s[14:15] offset:512
	global_load_dwordx4 v[180:183], v154, s[14:15] offset:528
	v_add_u32_e32 v154, 0x10000, v154
	global_load_dwordx4 v[184:187], v154, s[14:15]
	global_load_dwordx4 v[188:191], v154, s[14:15] offset:16
	global_load_dwordx4 v[192:195], v154, s[14:15] offset:512
	global_load_dwordx4 v[196:199], v154, s[14:15] offset:528
	v_add_u32_e32 v154, 0x10000, v154
	global_load_dwordx4 v[200:203], v154, s[14:15]
	global_load_dwordx4 v[204:207], v154, s[14:15] offset:16
	global_load_dwordx4 v[208:211], v154, s[14:15] offset:512
	global_load_dwordx4 v[212:215], v154, s[14:15] offset:528
	v_add_u32_e32 v154, 0x10000, v154
	global_load_dwordx4 v[216:219], v154, s[14:15]
	global_load_dwordx4 v[220:223], v154, s[14:15] offset:16
	global_load_dwordx4 v[128:131], v154, s[14:15] offset:512
	global_load_dwordx4 v[132:135], v154, s[14:15] offset:528
	v_add_u32_e32 v154, 0x50000, v154
	s_waitcnt vmcnt(12)
	v_pk_add_f32 v[120:121], v[120:121], v[168:169]
	v_pk_add_f32 v[122:123], v[122:123], v[170:171]
	v_pk_add_f32 v[124:125], v[124:125], v[172:173]
	v_pk_add_f32 v[126:127], v[126:127], v[174:175]
	v_cvt_pk_bf16_f32 v168, v120, v121
	v_cvt_pk_bf16_f32 v169, v122, v123
	v_cvt_pk_bf16_f32 v170, v124, v125
	v_cvt_pk_bf16_f32 v171, v126, v127
	v_pk_mul_f32 v[172:173], v[120:121], v[120:121]
	global_store_dwordx4 v155, v[168:171], s[18:19]
	v_pk_fma_f32 v[172:173], v[122:123], v[122:123], v[172:173]
	v_pk_fma_f32 v[172:173], v[124:125], v[124:125], v[172:173]
	v_pk_fma_f32 v[172:173], v[126:127], v[126:127], v[172:173]
	v_pk_add_f32 v[112:113], v[112:113], v[176:177]
	v_pk_add_f32 v[114:115], v[114:115], v[178:179]
	v_pk_add_f32 v[116:117], v[116:117], v[180:181]
	v_pk_add_f32 v[118:119], v[118:119], v[182:183]
	v_cvt_pk_bf16_f32 v176, v112, v113
	v_cvt_pk_bf16_f32 v177, v114, v115
	v_cvt_pk_bf16_f32 v178, v116, v117
	v_cvt_pk_bf16_f32 v179, v118, v119
	v_pk_fma_f32 v[172:173], v[112:113], v[112:113], v[172:173]
	global_store_dwordx4 v155, v[176:179], s[18:19] offset:256
	v_pk_fma_f32 v[172:173], v[114:115], v[114:115], v[172:173]
	v_pk_fma_f32 v[172:173], v[116:117], v[116:117], v[172:173]
	v_pk_fma_f32 v[172:173], v[118:119], v[118:119], v[172:173]
	v_add_f32_e32 v157, v172, v173
	v_add_u32_e32 v155, 0x8000, v155
	v_mov_b32_e32 v158, v157
	s_nop 1
	v_permlane16_swap_b32_e32 v157, v158
	s_nop 0
	v_add_f32_e32 v157, v157, v158
	v_mov_b32_e32 v158, v157
	s_nop 1
	v_permlane32_swap_b32_e32 v157, v158
	s_nop 0
	v_add_f32_e32 v157, v157, v158
	s_and_saveexec_b64 s[38:39], s[4:5]
	global_store_dword v156, v157, s[20:21]
	s_mov_b64 exec, s[38:39]
	global_load_dwordx4 v[168:171], v154, s[14:15]
	global_load_dwordx4 v[172:175], v154, s[14:15] offset:16
	global_load_dwordx4 v[176:179], v154, s[14:15] offset:512
	global_load_dwordx4 v[180:183], v154, s[14:15] offset:528
	v_add_u32_e32 v154, 0x10000, v154
	s_waitcnt vmcnt(15)
	v_pk_add_f32 v[104:105], v[104:105], v[184:185]
	v_pk_add_f32 v[106:107], v[106:107], v[186:187]
	v_pk_add_f32 v[108:109], v[108:109], v[188:189]
	v_pk_add_f32 v[110:111], v[110:111], v[190:191]
	v_cvt_pk_bf16_f32 v184, v104, v105
	v_cvt_pk_bf16_f32 v185, v106, v107
	v_cvt_pk_bf16_f32 v186, v108, v109
	v_cvt_pk_bf16_f32 v187, v110, v111
	v_pk_mul_f32 v[188:189], v[104:105], v[104:105]
	global_store_dwordx4 v155, v[184:187], s[18:19]
	v_pk_fma_f32 v[188:189], v[106:107], v[106:107], v[188:189]
	v_pk_fma_f32 v[188:189], v[108:109], v[108:109], v[188:189]
	v_pk_fma_f32 v[188:189], v[110:111], v[110:111], v[188:189]
	v_pk_add_f32 v[96:97], v[96:97], v[192:193]
	v_pk_add_f32 v[98:99], v[98:99], v[194:195]
	v_pk_add_f32 v[100:101], v[100:101], v[196:197]
	v_pk_add_f32 v[102:103], v[102:103], v[198:199]
	v_cvt_pk_bf16_f32 v192, v96, v97
	v_cvt_pk_bf16_f32 v193, v98, v99
	v_cvt_pk_bf16_f32 v194, v100, v101
	v_cvt_pk_bf16_f32 v195, v102, v103
	v_pk_fma_f32 v[188:189], v[96:97], v[96:97], v[188:189]
	global_store_dwordx4 v155, v[192:195], s[18:19] offset:256
	v_pk_fma_f32 v[188:189], v[98:99], v[98:99], v[188:189]
	v_pk_fma_f32 v[188:189], v[100:101], v[100:101], v[188:189]
	v_pk_fma_f32 v[188:189], v[102:103], v[102:103], v[188:189]
	v_add_f32_e32 v157, v188, v189
	v_add_u32_e32 v155, 0x8000, v155
	v_mov_b32_e32 v158, v157
	s_nop 1
	v_permlane16_swap_b32_e32 v157, v158
	s_nop 0
	v_add_f32_e32 v157, v157, v158
	v_mov_b32_e32 v158, v157
	s_nop 1
	v_permlane32_swap_b32_e32 v157, v158
	s_nop 0
	v_add_f32_e32 v157, v157, v158
	s_and_saveexec_b64 s[38:39], s[4:5]
	global_store_dword v156, v157, s[20:21] offset:1024
	s_mov_b64 exec, s[38:39]
	global_load_dwordx4 v[184:187], v154, s[14:15]
	global_load_dwordx4 v[188:191], v154, s[14:15] offset:16
	global_load_dwordx4 v[192:195], v154, s[14:15] offset:512
	global_load_dwordx4 v[196:199], v154, s[14:15] offset:528
	v_add_u32_e32 v154, 0x10000, v154
	s_waitcnt vmcnt(18)
	v_pk_add_f32 v[88:89], v[88:89], v[200:201]
	v_pk_add_f32 v[90:91], v[90:91], v[202:203]
	v_pk_add_f32 v[92:93], v[92:93], v[204:205]
	v_pk_add_f32 v[94:95], v[94:95], v[206:207]
	v_cvt_pk_bf16_f32 v200, v88, v89
	v_cvt_pk_bf16_f32 v201, v90, v91
	v_cvt_pk_bf16_f32 v202, v92, v93
	v_cvt_pk_bf16_f32 v203, v94, v95
	v_pk_mul_f32 v[204:205], v[88:89], v[88:89]
	global_store_dwordx4 v155, v[200:203], s[18:19]
	v_pk_fma_f32 v[204:205], v[90:91], v[90:91], v[204:205]
	v_pk_fma_f32 v[204:205], v[92:93], v[92:93], v[204:205]
	v_pk_fma_f32 v[204:205], v[94:95], v[94:95], v[204:205]
	v_pk_add_f32 v[80:81], v[80:81], v[208:209]
	v_pk_add_f32 v[82:83], v[82:83], v[210:211]
	v_pk_add_f32 v[84:85], v[84:85], v[212:213]
	v_pk_add_f32 v[86:87], v[86:87], v[214:215]
	v_cvt_pk_bf16_f32 v208, v80, v81
	v_cvt_pk_bf16_f32 v209, v82, v83
	v_cvt_pk_bf16_f32 v210, v84, v85
	v_cvt_pk_bf16_f32 v211, v86, v87
	v_pk_fma_f32 v[204:205], v[80:81], v[80:81], v[204:205]
	global_store_dwordx4 v155, v[208:211], s[18:19] offset:256
	v_pk_fma_f32 v[204:205], v[82:83], v[82:83], v[204:205]
	v_pk_fma_f32 v[204:205], v[84:85], v[84:85], v[204:205]
	v_pk_fma_f32 v[204:205], v[86:87], v[86:87], v[204:205]
	v_add_f32_e32 v157, v204, v205
	v_add_u32_e32 v155, 0x8000, v155
	v_mov_b32_e32 v158, v157
	s_nop 1
	v_permlane16_swap_b32_e32 v157, v158
	s_nop 0
	v_add_f32_e32 v157, v157, v158
	v_mov_b32_e32 v158, v157
	s_nop 1
	v_permlane32_swap_b32_e32 v157, v158
	s_nop 0
	v_add_f32_e32 v157, v157, v158
	s_and_saveexec_b64 s[38:39], s[4:5]
	global_store_dword v156, v157, s[20:21] offset:2048
	s_mov_b64 exec, s[38:39]
	global_load_dwordx4 v[200:203], v154, s[14:15]
	global_load_dwordx4 v[204:207], v154, s[14:15] offset:16
	global_load_dwordx4 v[208:211], v154, s[14:15] offset:512
	global_load_dwordx4 v[212:215], v154, s[14:15] offset:528
	v_add_u32_e32 v154, 0x10000, v154
	s_waitcnt vmcnt(21)
	v_pk_add_f32 v[72:73], v[72:73], v[216:217]
	v_pk_add_f32 v[74:75], v[74:75], v[218:219]
	v_pk_add_f32 v[76:77], v[76:77], v[220:221]
	v_pk_add_f32 v[78:79], v[78:79], v[222:223]
	v_cvt_pk_bf16_f32 v216, v72, v73
	v_cvt_pk_bf16_f32 v217, v74, v75
	v_cvt_pk_bf16_f32 v218, v76, v77
	v_cvt_pk_bf16_f32 v219, v78, v79
	v_pk_mul_f32 v[220:221], v[72:73], v[72:73]
	global_store_dwordx4 v155, v[216:219], s[18:19]
	v_pk_fma_f32 v[220:221], v[74:75], v[74:75], v[220:221]
	v_pk_fma_f32 v[220:221], v[76:77], v[76:77], v[220:221]
	v_pk_fma_f32 v[220:221], v[78:79], v[78:79], v[220:221]
	v_pk_add_f32 v[64:65], v[64:65], v[128:129]
	v_pk_add_f32 v[66:67], v[66:67], v[130:131]
	v_pk_add_f32 v[68:69], v[68:69], v[132:133]
	v_pk_add_f32 v[70:71], v[70:71], v[134:135]
	v_cvt_pk_bf16_f32 v128, v64, v65
	v_cvt_pk_bf16_f32 v129, v66, v67
	v_cvt_pk_bf16_f32 v130, v68, v69
	v_cvt_pk_bf16_f32 v131, v70, v71
	v_pk_fma_f32 v[220:221], v[64:65], v[64:65], v[220:221]
	global_store_dwordx4 v155, v[128:131], s[18:19] offset:256
	v_pk_fma_f32 v[220:221], v[66:67], v[66:67], v[220:221]
	v_pk_fma_f32 v[220:221], v[68:69], v[68:69], v[220:221]
	v_pk_fma_f32 v[220:221], v[70:71], v[70:71], v[220:221]
	v_add_f32_e32 v157, v220, v221
	v_add_u32_e32 v155, 0x28000, v155
	v_mov_b32_e32 v158, v157
	s_nop 1
	v_permlane16_swap_b32_e32 v157, v158
	s_nop 0
	v_add_f32_e32 v157, v157, v158
	v_mov_b32_e32 v158, v157
	s_nop 1
	v_permlane32_swap_b32_e32 v157, v158
	s_nop 0
	v_add_f32_e32 v157, v157, v158
	s_and_saveexec_b64 s[38:39], s[4:5]
	global_store_dword v156, v157, s[20:21] offset:3072
	s_mov_b64 exec, s[38:39]
	v_add_u32_e32 v156, 0x2000, v156
	global_load_dwordx4 v[216:219], v154, s[14:15]
	global_load_dwordx4 v[220:223], v154, s[14:15] offset:16
	global_load_dwordx4 v[128:131], v154, s[14:15] offset:512
	global_load_dwordx4 v[132:135], v154, s[14:15] offset:528
	s_waitcnt vmcnt(21)
	v_pk_add_f32 v[56:57], v[56:57], v[168:169]
	v_pk_add_f32 v[58:59], v[58:59], v[170:171]
	v_pk_add_f32 v[60:61], v[60:61], v[172:173]
	v_pk_add_f32 v[62:63], v[62:63], v[174:175]
	v_cvt_pk_bf16_f32 v168, v56, v57
	v_cvt_pk_bf16_f32 v169, v58, v59
	v_cvt_pk_bf16_f32 v170, v60, v61
	v_cvt_pk_bf16_f32 v171, v62, v63
	v_pk_mul_f32 v[172:173], v[56:57], v[56:57]
	global_store_dwordx4 v155, v[168:171], s[18:19]
	v_pk_fma_f32 v[172:173], v[58:59], v[58:59], v[172:173]
	v_pk_fma_f32 v[172:173], v[60:61], v[60:61], v[172:173]
	v_pk_fma_f32 v[172:173], v[62:63], v[62:63], v[172:173]
	v_pk_add_f32 v[48:49], v[48:49], v[176:177]
	v_pk_add_f32 v[50:51], v[50:51], v[178:179]
	v_pk_add_f32 v[52:53], v[52:53], v[180:181]
	v_pk_add_f32 v[54:55], v[54:55], v[182:183]
	v_cvt_pk_bf16_f32 v176, v48, v49
	v_cvt_pk_bf16_f32 v177, v50, v51
	v_cvt_pk_bf16_f32 v178, v52, v53
	v_cvt_pk_bf16_f32 v179, v54, v55
	v_pk_fma_f32 v[172:173], v[48:49], v[48:49], v[172:173]
	global_store_dwordx4 v155, v[176:179], s[18:19] offset:256
	v_pk_fma_f32 v[172:173], v[50:51], v[50:51], v[172:173]
	v_pk_fma_f32 v[172:173], v[52:53], v[52:53], v[172:173]
	v_pk_fma_f32 v[172:173], v[54:55], v[54:55], v[172:173]
	v_add_f32_e32 v157, v172, v173
	v_add_u32_e32 v155, 0x8000, v155
	v_mov_b32_e32 v158, v157
	s_nop 1
	v_permlane16_swap_b32_e32 v157, v158
	s_nop 0
	v_add_f32_e32 v157, v157, v158
	v_mov_b32_e32 v158, v157
	s_nop 1
	v_permlane32_swap_b32_e32 v157, v158
	s_nop 0
	v_add_f32_e32 v157, v157, v158
	s_and_saveexec_b64 s[38:39], s[4:5]
	global_store_dword v156, v157, s[20:21]
	s_mov_b64 exec, s[38:39]
	s_waitcnt vmcnt(17)
	v_pk_add_f32 v[40:41], v[40:41], v[184:185]
	v_pk_add_f32 v[42:43], v[42:43], v[186:187]
	v_pk_add_f32 v[44:45], v[44:45], v[188:189]
	v_pk_add_f32 v[46:47], v[46:47], v[190:191]
	v_cvt_pk_bf16_f32 v184, v40, v41
	v_cvt_pk_bf16_f32 v185, v42, v43
	v_cvt_pk_bf16_f32 v186, v44, v45
	v_cvt_pk_bf16_f32 v187, v46, v47
	v_pk_mul_f32 v[188:189], v[40:41], v[40:41]
	global_store_dwordx4 v155, v[184:187], s[18:19]
	v_pk_fma_f32 v[188:189], v[42:43], v[42:43], v[188:189]
	v_pk_fma_f32 v[188:189], v[44:45], v[44:45], v[188:189]
	v_pk_fma_f32 v[188:189], v[46:47], v[46:47], v[188:189]
	v_pk_add_f32 v[32:33], v[32:33], v[192:193]
	v_pk_add_f32 v[34:35], v[34:35], v[194:195]
	v_pk_add_f32 v[36:37], v[36:37], v[196:197]
	v_pk_add_f32 v[38:39], v[38:39], v[198:199]
	v_cvt_pk_bf16_f32 v192, v32, v33
	v_cvt_pk_bf16_f32 v193, v34, v35
	v_cvt_pk_bf16_f32 v194, v36, v37
	v_cvt_pk_bf16_f32 v195, v38, v39
	v_pk_fma_f32 v[188:189], v[32:33], v[32:33], v[188:189]
	global_store_dwordx4 v155, v[192:195], s[18:19] offset:256
	v_pk_fma_f32 v[188:189], v[34:35], v[34:35], v[188:189]
	v_pk_fma_f32 v[188:189], v[36:37], v[36:37], v[188:189]
	v_pk_fma_f32 v[188:189], v[38:39], v[38:39], v[188:189]
	v_add_f32_e32 v157, v188, v189
	v_add_u32_e32 v155, 0x8000, v155
	v_mov_b32_e32 v158, v157
	s_nop 1
	v_permlane16_swap_b32_e32 v157, v158
	s_nop 0
	v_add_f32_e32 v157, v157, v158
	v_mov_b32_e32 v158, v157
	s_nop 1
	v_permlane32_swap_b32_e32 v157, v158
	s_nop 0
	v_add_f32_e32 v157, v157, v158
	s_and_saveexec_b64 s[38:39], s[4:5]
	global_store_dword v156, v157, s[20:21] offset:1024
	s_mov_b64 exec, s[38:39]
	s_waitcnt vmcnt(13)
	v_pk_add_f32 v[24:25], v[24:25], v[200:201]
	v_pk_add_f32 v[26:27], v[26:27], v[202:203]
	v_pk_add_f32 v[28:29], v[28:29], v[204:205]
	v_pk_add_f32 v[30:31], v[30:31], v[206:207]
	v_cvt_pk_bf16_f32 v200, v24, v25
	v_cvt_pk_bf16_f32 v201, v26, v27
	v_cvt_pk_bf16_f32 v202, v28, v29
	v_cvt_pk_bf16_f32 v203, v30, v31
	v_pk_mul_f32 v[204:205], v[24:25], v[24:25]
	global_store_dwordx4 v155, v[200:203], s[18:19]
	v_pk_fma_f32 v[204:205], v[26:27], v[26:27], v[204:205]
	v_pk_fma_f32 v[204:205], v[28:29], v[28:29], v[204:205]
	v_pk_fma_f32 v[204:205], v[30:31], v[30:31], v[204:205]
	v_pk_add_f32 v[16:17], v[16:17], v[208:209]
	v_pk_add_f32 v[18:19], v[18:19], v[210:211]
	v_pk_add_f32 v[20:21], v[20:21], v[212:213]
	v_pk_add_f32 v[22:23], v[22:23], v[214:215]
	v_cvt_pk_bf16_f32 v208, v16, v17
	v_cvt_pk_bf16_f32 v209, v18, v19
	v_cvt_pk_bf16_f32 v210, v20, v21
	v_cvt_pk_bf16_f32 v211, v22, v23
	v_pk_fma_f32 v[204:205], v[16:17], v[16:17], v[204:205]
	global_store_dwordx4 v155, v[208:211], s[18:19] offset:256
	v_pk_fma_f32 v[204:205], v[18:19], v[18:19], v[204:205]
	v_pk_fma_f32 v[204:205], v[20:21], v[20:21], v[204:205]
	v_pk_fma_f32 v[204:205], v[22:23], v[22:23], v[204:205]
	v_add_f32_e32 v157, v204, v205
	v_add_u32_e32 v155, 0x8000, v155
	v_mov_b32_e32 v158, v157
	s_nop 1
	v_permlane16_swap_b32_e32 v157, v158
	s_nop 0
	v_add_f32_e32 v157, v157, v158
	v_mov_b32_e32 v158, v157
	s_nop 1
	v_permlane32_swap_b32_e32 v157, v158
	s_nop 0
	v_add_f32_e32 v157, v157, v158
	s_and_saveexec_b64 s[38:39], s[4:5]
	global_store_dword v156, v157, s[20:21] offset:2048
	s_mov_b64 exec, s[38:39]
	s_waitcnt vmcnt(9)
	v_pk_add_f32 v[8:9], v[8:9], v[216:217]
	v_pk_add_f32 v[10:11], v[10:11], v[218:219]
	v_pk_add_f32 v[12:13], v[12:13], v[220:221]
	v_pk_add_f32 v[14:15], v[14:15], v[222:223]
	v_cvt_pk_bf16_f32 v216, v8, v9
	v_cvt_pk_bf16_f32 v217, v10, v11
	v_cvt_pk_bf16_f32 v218, v12, v13
	v_cvt_pk_bf16_f32 v219, v14, v15
	v_pk_mul_f32 v[220:221], v[8:9], v[8:9]
	global_store_dwordx4 v155, v[216:219], s[18:19]
	v_pk_fma_f32 v[220:221], v[10:11], v[10:11], v[220:221]
	v_pk_fma_f32 v[220:221], v[12:13], v[12:13], v[220:221]
	v_pk_fma_f32 v[220:221], v[14:15], v[14:15], v[220:221]
	v_pk_add_f32 v[4:5], v[4:5], v[128:129]
	v_pk_add_f32 v[6:7], v[6:7], v[130:131]
	v_pk_add_f32 v[0:1], v[0:1], v[132:133]
	v_pk_add_f32 v[2:3], v[2:3], v[134:135]
	v_cvt_pk_bf16_f32 v128, v4, v5
	v_cvt_pk_bf16_f32 v129, v6, v7
	v_cvt_pk_bf16_f32 v130, v0, v1
	v_cvt_pk_bf16_f32 v131, v2, v3
	v_pk_fma_f32 v[220:221], v[4:5], v[4:5], v[220:221]
	global_store_dwordx4 v155, v[128:131], s[18:19] offset:256
	v_pk_fma_f32 v[220:221], v[6:7], v[6:7], v[220:221]
	v_pk_fma_f32 v[220:221], v[0:1], v[0:1], v[220:221]
	v_pk_fma_f32 v[220:221], v[2:3], v[2:3], v[220:221]
	v_add_f32_e32 v157, v220, v221
	v_add_u32_e32 v155, 0x8000, v155
	v_mov_b32_e32 v158, v157
	s_nop 1
	v_permlane16_swap_b32_e32 v157, v158
	s_nop 0
	v_add_f32_e32 v157, v157, v158
	v_mov_b32_e32 v158, v157
	s_nop 1
	v_permlane32_swap_b32_e32 v157, v158
	s_nop 0
	v_add_f32_e32 v157, v157, v158
	s_and_saveexec_b64 s[38:39], s[4:5]
	global_store_dword v156, v157, s[20:21] offset:3072
	s_mov_b64 exec, s[38:39]
	s_branch .LBB0_575

.LBB0_698:
	s_add_u32 s28, s26, 0xfffc0080
	s_addc_u32 s29, s27, -1
	s_add_i32 s68, 0, 0x10000
	v_add_u32_e32 v155, s68, v153
	ds_read_b128 v[138:141], v155
	ds_read_b128 v[142:145], v155 offset:1024
	ds_read_b128 v[146:149], v155 offset:2048
	ds_read_b128 v[156:159], v155 offset:3072
	s_cmp_eq_u32 s51, 12
	s_cselect_b32 s31, s21, s29
	s_cselect_b32 s30, s38, s28
	s_cselect_b32 s29, s7, s50
	s_cselect_b32 s28, s39, s46
	s_add_i32 m0, s58, 0xc000
	ds_read_b128 v[160:163], v154
	ds_read_b128 v[164:167], v154 offset:1024
	ds_read_b128 v[168:171], v154 offset:2048
	ds_read_b128 v[172:175], v154 offset:3072
	ds_read_b128 v[176:179], v154 offset:4096
	ds_read_b128 v[180:183], v154 offset:5120
	ds_read_b128 v[184:187], v154 offset:6144
	global_load_lds_dwordx4 v134, s[26:27]
	s_add_i32 m0, s58, 0xe000
	ds_read_b128 v[188:191], v154 offset:7168
	global_load_lds_dwordx4 v136, s[26:27]
	s_waitcnt lgkmcnt(8)
	s_barrier
	s_waitcnt lgkmcnt(0)
	v_mfma_f32_16x16x32_bf16 v[124:127], v[138:141], v[160:163], v[124:127]
	v_mfma_f32_16x16x32_bf16 v[120:123], v[146:149], v[160:163], v[120:123]
	v_mfma_f32_16x16x32_bf16 v[108:111], v[138:141], v[168:171], v[108:111]
	v_mfma_f32_16x16x32_bf16 v[104:107], v[146:149], v[168:171], v[104:107]
	v_mfma_f32_16x16x32_bf16 v[92:95], v[138:141], v[176:179], v[92:95]
	v_mfma_f32_16x16x32_bf16 v[88:91], v[146:149], v[176:179], v[88:91]
	v_mfma_f32_16x16x32_bf16 v[76:79], v[138:141], v[184:187], v[76:79]
	v_mfma_f32_16x16x32_bf16 v[72:75], v[146:149], v[184:187], v[72:75]
	v_mfma_f32_16x16x32_bf16 v[124:127], v[142:145], v[164:167], v[124:127]
	v_mfma_f32_16x16x32_bf16 v[120:123], v[156:159], v[164:167], v[120:123]
	v_mfma_f32_16x16x32_bf16 v[108:111], v[142:145], v[172:175], v[108:111]
	v_mfma_f32_16x16x32_bf16 v[104:107], v[156:159], v[172:175], v[104:107]
	v_mfma_f32_16x16x32_bf16 v[92:95], v[142:145], v[180:183], v[92:95]
	v_mfma_f32_16x16x32_bf16 v[88:91], v[156:159], v[180:183], v[88:91]
	v_mfma_f32_16x16x32_bf16 v[76:79], v[142:145], v[188:191], v[76:79]
	v_mfma_f32_16x16x32_bf16 v[72:75], v[156:159], v[188:191], v[72:75]
	s_barrier
	s_add_i32 s70, 0, 0x14000
	s_add_i32 s68, s68, s57
	v_add_u32_e32 v155, s70, v153
	s_add_u32 s98, s28, s40
	s_addc_u32 s99, s29, s41
	s_mov_b32 m0, s68
	ds_read_b128 v[192:195], v155
	ds_read_b128 v[196:199], v155 offset:1024
	ds_read_b128 v[200:203], v155 offset:2048
	global_load_lds_dwordx4 v208, s[28:29]
	s_add_i32 m0, s68, 0x2000
	ds_read_b128 v[204:207], v155 offset:3072
	global_load_lds_dwordx4 v128, s[28:29]
	s_barrier
	s_waitcnt lgkmcnt(0)
	v_mfma_f32_16x16x32_bf16 v[116:119], v[192:195], v[160:163], v[116:119]
	v_mfma_f32_16x16x32_bf16 v[112:115], v[200:203], v[160:163], v[112:115]
	v_mfma_f32_16x16x32_bf16 v[100:103], v[192:195], v[168:171], v[100:103]
	v_mfma_f32_16x16x32_bf16 v[96:99], v[200:203], v[168:171], v[96:99]
	v_mfma_f32_16x16x32_bf16 v[84:87], v[192:195], v[176:179], v[84:87]
	v_mfma_f32_16x16x32_bf16 v[80:83], v[200:203], v[176:179], v[80:83]
	v_mfma_f32_16x16x32_bf16 v[68:71], v[192:195], v[184:187], v[68:71]
	v_mfma_f32_16x16x32_bf16 v[64:67], v[200:203], v[184:187], v[64:67]
	v_mfma_f32_16x16x32_bf16 v[116:119], v[196:199], v[164:167], v[116:119]
	v_mfma_f32_16x16x32_bf16 v[112:115], v[204:207], v[164:167], v[112:115]
	v_mfma_f32_16x16x32_bf16 v[100:103], v[196:199], v[172:175], v[100:103]
	v_mfma_f32_16x16x32_bf16 v[96:99], v[204:207], v[172:175], v[96:99]
	v_mfma_f32_16x16x32_bf16 v[84:87], v[196:199], v[180:183], v[84:87]
	v_mfma_f32_16x16x32_bf16 v[80:83], v[204:207], v[180:183], v[80:83]
	v_mfma_f32_16x16x32_bf16 v[68:71], v[196:199], v[188:191], v[68:71]
	v_mfma_f32_16x16x32_bf16 v[64:67], v[204:207], v[188:191], v[64:67]
	s_mov_b32 m0, s58
	s_add_u32 s100, s30, s40
	s_addc_u32 s101, s31, s41
	s_barrier
	ds_read_b128 v[160:163], v154 offset:16384
	ds_read_b128 v[164:167], v154 offset:17408
	ds_read_b128 v[168:171], v154 offset:18432
	ds_read_b128 v[172:175], v154 offset:19456
	ds_read_b128 v[176:179], v154 offset:20480
	ds_read_b128 v[180:183], v154 offset:21504
	ds_read_b128 v[184:187], v154 offset:22528
	global_load_lds_dwordx4 v132, s[30:31]
	s_mov_b32 m0, s59
	ds_read_b128 v[188:191], v154 offset:23552
	global_load_lds_dwordx4 v130, s[30:31]
	s_barrier
	s_waitcnt lgkmcnt(0)
	v_mfma_f32_16x16x32_bf16 v[60:63], v[138:141], v[160:163], v[60:63]
	v_mfma_f32_16x16x32_bf16 v[56:59], v[146:149], v[160:163], v[56:59]
	v_mfma_f32_16x16x32_bf16 v[44:47], v[138:141], v[168:171], v[44:47]
	v_mfma_f32_16x16x32_bf16 v[40:43], v[146:149], v[168:171], v[40:43]
	v_mfma_f32_16x16x32_bf16 v[28:31], v[138:141], v[176:179], v[28:31]
	v_mfma_f32_16x16x32_bf16 v[24:27], v[146:149], v[176:179], v[24:27]
	v_mfma_f32_16x16x32_bf16 v[12:15], v[138:141], v[184:187], v[12:15]
	v_mfma_f32_16x16x32_bf16 v[8:11], v[146:149], v[184:187], v[8:11]
	v_mfma_f32_16x16x32_bf16 v[60:63], v[142:145], v[164:167], v[60:63]
	v_mfma_f32_16x16x32_bf16 v[56:59], v[156:159], v[164:167], v[56:59]
	v_mfma_f32_16x16x32_bf16 v[44:47], v[142:145], v[172:175], v[44:47]
	v_mfma_f32_16x16x32_bf16 v[40:43], v[156:159], v[172:175], v[40:43]
	v_mfma_f32_16x16x32_bf16 v[28:31], v[142:145], v[180:183], v[28:31]
	v_mfma_f32_16x16x32_bf16 v[24:27], v[156:159], v[180:183], v[24:27]
	v_mfma_f32_16x16x32_bf16 v[12:15], v[142:145], v[188:191], v[12:15]
	v_mfma_f32_16x16x32_bf16 v[8:11], v[156:159], v[188:191], v[8:11]
	s_barrier
	s_add_u32 s68, s28, 0x40000
	s_addc_u32 s69, s29, 0
	s_add_i32 s70, s70, s57
	s_mov_b32 m0, s70
	s_nop 0
	global_load_lds_dwordx4 v208, s[68:69]
	s_add_i32 m0, s70, 0x2000
	s_nop 0
	global_load_lds_dwordx4 v128, s[68:69]
	s_waitcnt vmcnt(6)
	s_barrier
	v_mfma_f32_16x16x32_bf16 v[52:55], v[192:195], v[160:163], v[52:55]
	v_mfma_f32_16x16x32_bf16 v[48:51], v[200:203], v[160:163], v[48:51]
	v_mfma_f32_16x16x32_bf16 v[36:39], v[192:195], v[168:171], v[36:39]
	v_mfma_f32_16x16x32_bf16 v[32:35], v[200:203], v[168:171], v[32:35]
	v_mfma_f32_16x16x32_bf16 v[20:23], v[192:195], v[176:179], v[20:23]
	v_mfma_f32_16x16x32_bf16 v[16:19], v[200:203], v[176:179], v[16:19]
	v_mfma_f32_16x16x32_bf16 v[4:7], v[192:195], v[184:187], v[4:7]
	v_mfma_f32_16x16x32_bf16 v[0:3], v[200:203], v[184:187], v[0:3]
	v_mfma_f32_16x16x32_bf16 v[52:55], v[196:199], v[164:167], v[52:55]
	v_mfma_f32_16x16x32_bf16 v[48:51], v[204:207], v[164:167], v[48:51]
	v_mfma_f32_16x16x32_bf16 v[36:39], v[196:199], v[172:175], v[36:39]
	v_mfma_f32_16x16x32_bf16 v[32:35], v[204:207], v[172:175], v[32:35]
	v_mfma_f32_16x16x32_bf16 v[20:23], v[196:199], v[180:183], v[20:23]
	v_mfma_f32_16x16x32_bf16 v[16:19], v[204:207], v[180:183], v[16:19]
	v_mfma_f32_16x16x32_bf16 v[4:7], v[196:199], v[188:191], v[4:7]
	v_mfma_f32_16x16x32_bf16 v[0:3], v[204:207], v[188:191], v[0:3]
	s_add_i32 s68, 0, 0x18000
	v_add_u32_e32 v155, s68, v153
	s_barrier
	ds_read_b128 v[138:141], v155
	ds_read_b128 v[142:145], v155 offset:1024
	ds_read_b128 v[146:149], v155 offset:2048
	ds_read_b128 v[156:159], v155 offset:3072
	s_add_u32 s30, s30, 0x40000
	s_addc_u32 s31, s31, 0
	s_mov_b32 m0, s60
	ds_read_b128 v[160:163], v154 offset:32768
	ds_read_b128 v[164:167], v154 offset:33792
	ds_read_b128 v[168:171], v154 offset:34816
	ds_read_b128 v[172:175], v154 offset:35840
	ds_read_b128 v[176:179], v154 offset:36864
	ds_read_b128 v[180:183], v154 offset:37888
	ds_read_b128 v[184:187], v154 offset:38912
	global_load_lds_dwordx4 v132, s[30:31]
	s_mov_b32 m0, s61
	ds_read_b128 v[188:191], v154 offset:39936
	global_load_lds_dwordx4 v130, s[30:31]
	s_waitcnt lgkmcnt(8)
	s_barrier
	s_waitcnt lgkmcnt(0)
	v_mfma_f32_16x16x32_bf16 v[124:127], v[138:141], v[160:163], v[124:127]
	v_mfma_f32_16x16x32_bf16 v[120:123], v[146:149], v[160:163], v[120:123]
	v_mfma_f32_16x16x32_bf16 v[108:111], v[138:141], v[168:171], v[108:111]
	v_mfma_f32_16x16x32_bf16 v[104:107], v[146:149], v[168:171], v[104:107]
	v_mfma_f32_16x16x32_bf16 v[92:95], v[138:141], v[176:179], v[92:95]
	v_mfma_f32_16x16x32_bf16 v[88:91], v[146:149], v[176:179], v[88:91]
	v_mfma_f32_16x16x32_bf16 v[76:79], v[138:141], v[184:187], v[76:79]
	v_mfma_f32_16x16x32_bf16 v[72:75], v[146:149], v[184:187], v[72:75]
	v_mfma_f32_16x16x32_bf16 v[124:127], v[142:145], v[164:167], v[124:127]
	v_mfma_f32_16x16x32_bf16 v[120:123], v[156:159], v[164:167], v[120:123]
	v_mfma_f32_16x16x32_bf16 v[108:111], v[142:145], v[172:175], v[108:111]
	v_mfma_f32_16x16x32_bf16 v[104:107], v[156:159], v[172:175], v[104:107]
	v_mfma_f32_16x16x32_bf16 v[92:95], v[142:145], v[180:183], v[92:95]
	v_mfma_f32_16x16x32_bf16 v[88:91], v[156:159], v[180:183], v[88:91]
	v_mfma_f32_16x16x32_bf16 v[76:79], v[142:145], v[188:191], v[76:79]
	v_mfma_f32_16x16x32_bf16 v[72:75], v[156:159], v[188:191], v[72:75]
	s_barrier
	s_add_i32 s30, 0, 0x1c000
	s_add_i32 s31, s68, s57
	v_add_u32_e32 v155, s30, v153
	s_mov_b32 m0, s31
	ds_read_b128 v[192:195], v155
	ds_read_b128 v[196:199], v155 offset:1024
	ds_read_b128 v[200:203], v155 offset:2048
	global_load_lds_dwordx4 v208, s[98:99]
	s_add_i32 m0, s31, 0x2000
	ds_read_b128 v[204:207], v155 offset:3072
	global_load_lds_dwordx4 v128, s[98:99]
	s_barrier
	s_waitcnt lgkmcnt(0)
	v_mfma_f32_16x16x32_bf16 v[116:119], v[192:195], v[160:163], v[116:119]
	v_mfma_f32_16x16x32_bf16 v[112:115], v[200:203], v[160:163], v[112:115]
	v_mfma_f32_16x16x32_bf16 v[100:103], v[192:195], v[168:171], v[100:103]
	v_mfma_f32_16x16x32_bf16 v[96:99], v[200:203], v[168:171], v[96:99]
	v_mfma_f32_16x16x32_bf16 v[84:87], v[192:195], v[176:179], v[84:87]
	v_mfma_f32_16x16x32_bf16 v[80:83], v[200:203], v[176:179], v[80:83]
	v_mfma_f32_16x16x32_bf16 v[68:71], v[192:195], v[184:187], v[68:71]
	v_mfma_f32_16x16x32_bf16 v[64:67], v[200:203], v[184:187], v[64:67]
	v_mfma_f32_16x16x32_bf16 v[116:119], v[196:199], v[164:167], v[116:119]
	v_mfma_f32_16x16x32_bf16 v[112:115], v[204:207], v[164:167], v[112:115]
	v_mfma_f32_16x16x32_bf16 v[100:103], v[196:199], v[172:175], v[100:103]
	v_mfma_f32_16x16x32_bf16 v[96:99], v[204:207], v[172:175], v[96:99]
	v_mfma_f32_16x16x32_bf16 v[84:87], v[196:199], v[180:183], v[84:87]
	v_mfma_f32_16x16x32_bf16 v[80:83], v[204:207], v[180:183], v[80:83]
	v_mfma_f32_16x16x32_bf16 v[68:71], v[196:199], v[188:191], v[68:71]
	v_mfma_f32_16x16x32_bf16 v[64:67], v[204:207], v[188:191], v[64:67]
	s_mov_b32 m0, s64
	s_barrier
	ds_read_b128 v[160:163], v154 offset:49152
	ds_read_b128 v[164:167], v154 offset:50176
	ds_read_b128 v[168:171], v154 offset:51200
	ds_read_b128 v[172:175], v154 offset:52224
	ds_read_b128 v[176:179], v154 offset:53248
	ds_read_b128 v[180:183], v154 offset:54272
	ds_read_b128 v[184:187], v154 offset:55296
	global_load_lds_dwordx4 v132, s[100:101]
	s_mov_b32 m0, s65
	ds_read_b128 v[188:191], v154 offset:56320
	global_load_lds_dwordx4 v130, s[100:101]
	s_barrier
	s_waitcnt lgkmcnt(0)
	v_mfma_f32_16x16x32_bf16 v[60:63], v[138:141], v[160:163], v[60:63]
	v_mfma_f32_16x16x32_bf16 v[56:59], v[146:149], v[160:163], v[56:59]
	v_mfma_f32_16x16x32_bf16 v[44:47], v[138:141], v[168:171], v[44:47]
	v_mfma_f32_16x16x32_bf16 v[40:43], v[146:149], v[168:171], v[40:43]
	v_mfma_f32_16x16x32_bf16 v[28:31], v[138:141], v[176:179], v[28:31]
	v_mfma_f32_16x16x32_bf16 v[24:27], v[146:149], v[176:179], v[24:27]
	v_mfma_f32_16x16x32_bf16 v[12:15], v[138:141], v[184:187], v[12:15]
	v_mfma_f32_16x16x32_bf16 v[8:11], v[146:149], v[184:187], v[8:11]
	v_mfma_f32_16x16x32_bf16 v[60:63], v[142:145], v[164:167], v[60:63]
	v_mfma_f32_16x16x32_bf16 v[56:59], v[156:159], v[164:167], v[56:59]
	v_mfma_f32_16x16x32_bf16 v[44:47], v[142:145], v[172:175], v[44:47]
	v_mfma_f32_16x16x32_bf16 v[40:43], v[156:159], v[172:175], v[40:43]
	v_mfma_f32_16x16x32_bf16 v[28:31], v[142:145], v[180:183], v[28:31]
	v_mfma_f32_16x16x32_bf16 v[24:27], v[156:159], v[180:183], v[24:27]
	v_mfma_f32_16x16x32_bf16 v[12:15], v[142:145], v[188:191], v[12:15]
	v_mfma_f32_16x16x32_bf16 v[8:11], v[156:159], v[188:191], v[8:11]
	s_barrier
	s_add_u32 s28, s28, 0x40080
	s_addc_u32 s29, s29, 0
	s_add_i32 s30, s30, s57
	s_mov_b32 m0, s30
	s_nop 0
	global_load_lds_dwordx4 v208, s[28:29]
	s_add_i32 m0, s30, 0x2000
	s_nop 0
	global_load_lds_dwordx4 v128, s[28:29]
	s_waitcnt vmcnt(6)
	s_barrier
	v_mfma_f32_16x16x32_bf16 v[52:55], v[192:195], v[160:163], v[52:55]
	v_mfma_f32_16x16x32_bf16 v[48:51], v[200:203], v[160:163], v[48:51]
	v_mfma_f32_16x16x32_bf16 v[36:39], v[192:195], v[168:171], v[36:39]
	v_mfma_f32_16x16x32_bf16 v[32:35], v[200:203], v[168:171], v[32:35]
	v_mfma_f32_16x16x32_bf16 v[20:23], v[192:195], v[176:179], v[20:23]
	v_mfma_f32_16x16x32_bf16 v[16:19], v[200:203], v[176:179], v[16:19]
	v_mfma_f32_16x16x32_bf16 v[4:7], v[192:195], v[184:187], v[4:7]
	v_mfma_f32_16x16x32_bf16 v[0:3], v[200:203], v[184:187], v[0:3]
	v_mfma_f32_16x16x32_bf16 v[52:55], v[196:199], v[164:167], v[52:55]
	v_mfma_f32_16x16x32_bf16 v[48:51], v[204:207], v[164:167], v[48:51]
	v_mfma_f32_16x16x32_bf16 v[36:39], v[196:199], v[172:175], v[36:39]
	v_mfma_f32_16x16x32_bf16 v[32:35], v[204:207], v[172:175], v[32:35]
	v_mfma_f32_16x16x32_bf16 v[20:23], v[196:199], v[180:183], v[20:23]
	v_mfma_f32_16x16x32_bf16 v[16:19], v[204:207], v[180:183], v[16:19]
	v_mfma_f32_16x16x32_bf16 v[4:7], v[196:199], v[188:191], v[4:7]
	v_mfma_f32_16x16x32_bf16 v[0:3], v[204:207], v[188:191], v[0:3]
	s_add_i32 s51, s51, 2
	s_add_u32 s26, s26, 0x100
	s_addc_u32 s27, s27, 0
	s_add_u32 s46, s46, 0x100
	s_addc_u32 s50, s50, 0
	s_cmp_gt_u32 s51, 13
	s_barrier
	s_cbranch_scc0 .LBB0_698
	s_cmp_lt_i32 s34, 4
	s_cselect_b64 vcc, -1, 0
	v_mov_b32_e32 v138, 0x3e38aa3b
	s_nop 0
	v_cndmask_b32_e32 v155, 1.0, v138, vcc
	s_and_b64 s[26:27], vcc, exec
	v_lshl_add_u32 v140, s35, 8, v152
	s_cselect_b32 s7, s9, s11
	s_cselect_b32 s21, s8, s10
	v_mov_b32_e32 v138, s21
	v_mov_b32_e32 v139, s7
	v_lshlrev_b32_e32 v142, 3, v151
	v_mov_b32_e32 v143, 0
	v_lshl_add_u64 v[138:139], v[142:143], 2, v[138:139]
	global_load_dwordx4 v[188:191], v[138:139], off
	global_load_dwordx4 v[192:195], v[138:139], off offset:16
	global_load_dwordx4 v[196:199], v[138:139], off offset:128
	global_load_dwordx4 v[200:203], v[138:139], off offset:144
	s_lshl_b32 s7, s34, 8
	s_or_b32 s26, s7, s66
	s_ashr_i32 s27, s26, 31
	s_lshl_b64 s[26:27], s[26:27], 1
	s_add_u32 s26, s62, s26
	s_addc_u32 s27, s63, s27
	s_mov_b32 s34, s6
	s_mov_b32 s35, s20
	s_mov_b64 s[28:29], s[24:25]
	v_mbcnt_lo_u32_b32 v210, -1, 0
	v_mbcnt_hi_u32_b32 v210, -1, v210
	v_and_b32_e32 v210, 48, v210
	v_lshl_add_u32 v210, v140, 6, v210
	v_lshlrev_b32_e32 v211, 12, v140
	v_lshl_add_u32 v211, v151, 4, v211
	global_load_dwordx4 v[156:159], v210, s[18:19]
	global_load_dwordx4 v[160:163], v210, s[18:19] offset:1024
	global_load_dwordx4 v[164:167], v210, s[18:19] offset:2048
	global_load_dwordx4 v[168:171], v210, s[18:19] offset:3072
	v_add_u32_e32 v210, 0x2000, v210
	global_load_dwordx4 v[172:175], v210, s[18:19]
	global_load_dwordx4 v[176:179], v210, s[18:19] offset:1024
	global_load_dwordx4 v[180:183], v210, s[18:19] offset:2048
	global_load_dwordx4 v[184:187], v210, s[18:19] offset:3072
	s_waitcnt vmcnt(7)
	v_pk_add_f32 v[156:157], v[156:157], v[158:159]
	s_nop 0
	v_add_f32_e32 v214, v156, v157
	v_mov_b32_e32 v215, v214
	s_nop 1
	v_permlane16_swap_b32_e32 v214, v215
	s_nop 0
	v_add_f32_e32 v214, v214, v215
	v_mov_b32_e32 v215, v214
	s_nop 1
	v_permlane32_swap_b32_e32 v214, v215
	s_nop 0
	v_add_f32_e32 v214, v214, v215
	v_fmamk_f32 v214, v214, 0x3a800000, v248
	v_rsq_f32_e32 v216, v214
	s_nop 0
	v_pk_mul_f32 v[124:125], v[124:125], v[216:217] op_sel_hi:[1,0]
	v_pk_mul_f32 v[126:127], v[126:127], v[216:217] op_sel_hi:[1,0]
	v_pk_mul_f32 v[120:121], v[120:121], v[216:217] op_sel_hi:[1,0]
	v_pk_mul_f32 v[122:123], v[122:123], v[216:217] op_sel_hi:[1,0]
	v_pk_mul_f32 v[116:117], v[116:117], v[216:217] op_sel_hi:[1,0]
	v_pk_mul_f32 v[118:119], v[118:119], v[216:217] op_sel_hi:[1,0]
	v_pk_mul_f32 v[112:113], v[112:113], v[216:217] op_sel_hi:[1,0]
	v_pk_mul_f32 v[114:115], v[114:115], v[216:217] op_sel_hi:[1,0]
	v_pk_mul_f32 v[148:149], v[124:125], v[124:125]
	v_pk_fma_f32 v[148:149], v[126:127], v[126:127], v[148:149]
	v_pk_fma_f32 v[148:149], v[120:121], v[120:121], v[148:149]
	v_pk_fma_f32 v[148:149], v[122:123], v[122:123], v[148:149]
	v_pk_fma_f32 v[148:149], v[116:117], v[116:117], v[148:149]
	v_pk_fma_f32 v[148:149], v[118:119], v[118:119], v[148:149]
	v_pk_fma_f32 v[148:149], v[112:113], v[112:113], v[148:149]
	v_pk_fma_f32 v[148:149], v[114:115], v[114:115], v[148:149]
	v_add_f32_e32 v214, v148, v149
	v_mov_b32_e32 v215, v214
	s_nop 1
	v_permlane16_swap_b32_e32 v214, v215
	s_nop 0
	v_add_f32_e32 v214, v214, v215
	v_mov_b32_e32 v215, v214
	s_nop 1
	v_permlane32_swap_b32_e32 v214, v215
	s_nop 0
	v_add_f32_e32 v214, v214, v215
	v_fmamk_f32 v214, v214, 0x3c800000, v248
	v_rsq_f32_e32 v214, v214
	s_nop 0
	v_mul_f32_e32 v218, v155, v214
	v_pk_mul_f32 v[156:157], v[188:189], v[218:219] op_sel_hi:[1,0]
	v_pk_mul_f32 v[124:125], v[124:125], v[156:157]
	v_pk_mul_f32 v[156:157], v[190:191], v[218:219] op_sel_hi:[1,0]
	v_pk_mul_f32 v[126:127], v[126:127], v[156:157]
	v_pk_mul_f32 v[156:157], v[192:193], v[218:219] op_sel_hi:[1,0]
	v_pk_mul_f32 v[120:121], v[120:121], v[156:157]
	v_pk_mul_f32 v[156:157], v[194:195], v[218:219] op_sel_hi:[1,0]
	v_pk_mul_f32 v[122:123], v[122:123], v[156:157]
	v_cvt_pk_bf16_f32 v204, v124, v125
	v_cvt_pk_bf16_f32 v205, v126, v127
	v_cvt_pk_bf16_f32 v206, v120, v121
	v_cvt_pk_bf16_f32 v207, v122, v123
	global_store_dwordx4 v211, v[204:207], s[26:27]
	v_pk_mul_f32 v[156:157], v[196:197], v[218:219] op_sel_hi:[1,0]
	v_pk_mul_f32 v[116:117], v[116:117], v[156:157]
	v_pk_mul_f32 v[156:157], v[198:199], v[218:219] op_sel_hi:[1,0]
	v_pk_mul_f32 v[118:119], v[118:119], v[156:157]
	v_pk_mul_f32 v[156:157], v[200:201], v[218:219] op_sel_hi:[1,0]
	v_pk_mul_f32 v[112:113], v[112:113], v[156:157]
	v_pk_mul_f32 v[156:157], v[202:203], v[218:219] op_sel_hi:[1,0]
	v_pk_mul_f32 v[114:115], v[114:115], v[156:157]
	v_cvt_pk_bf16_f32 v144, v116, v117
	v_cvt_pk_bf16_f32 v145, v118, v119
	v_cvt_pk_bf16_f32 v146, v112, v113
	v_cvt_pk_bf16_f32 v147, v114, v115
	global_store_dwordx4 v211, v[144:147], s[26:27] offset:64
	v_add_u32_e32 v211, 0x10000, v211
	s_waitcnt vmcnt(8)
	v_pk_add_f32 v[160:161], v[160:161], v[162:163]
	s_nop 0
	v_add_f32_e32 v214, v160, v161
	v_mov_b32_e32 v215, v214
	s_nop 1
	v_permlane16_swap_b32_e32 v214, v215
	s_nop 0
	v_add_f32_e32 v214, v214, v215
	v_mov_b32_e32 v215, v214
	s_nop 1
	v_permlane32_swap_b32_e32 v214, v215
	s_nop 0
	v_add_f32_e32 v214, v214, v215
	v_fmamk_f32 v214, v214, 0x3a800000, v248
	v_rsq_f32_e32 v216, v214
	s_nop 0
	v_pk_mul_f32 v[108:109], v[108:109], v[216:217] op_sel_hi:[1,0]
	v_pk_mul_f32 v[110:111], v[110:111], v[216:217] op_sel_hi:[1,0]
	v_pk_mul_f32 v[104:105], v[104:105], v[216:217] op_sel_hi:[1,0]
	v_pk_mul_f32 v[106:107], v[106:107], v[216:217] op_sel_hi:[1,0]
	v_pk_mul_f32 v[100:101], v[100:101], v[216:217] op_sel_hi:[1,0]
	v_pk_mul_f32 v[102:103], v[102:103], v[216:217] op_sel_hi:[1,0]
	v_pk_mul_f32 v[96:97], v[96:97], v[216:217] op_sel_hi:[1,0]
	v_pk_mul_f32 v[98:99], v[98:99], v[216:217] op_sel_hi:[1,0]
	v_pk_mul_f32 v[148:149], v[108:109], v[108:109]
	v_pk_fma_f32 v[148:149], v[110:111], v[110:111], v[148:149]
	v_pk_fma_f32 v[148:149], v[104:105], v[104:105], v[148:149]
	v_pk_fma_f32 v[148:149], v[106:107], v[106:107], v[148:149]
	v_pk_fma_f32 v[148:149], v[100:101], v[100:101], v[148:149]
	v_pk_fma_f32 v[148:149], v[102:103], v[102:103], v[148:149]
	v_pk_fma_f32 v[148:149], v[96:97], v[96:97], v[148:149]
	v_pk_fma_f32 v[148:149], v[98:99], v[98:99], v[148:149]
	v_add_f32_e32 v214, v148, v149
	v_mov_b32_e32 v215, v214
	s_nop 1
	v_permlane16_swap_b32_e32 v214, v215
	s_nop 0
	v_add_f32_e32 v214, v214, v215
	v_mov_b32_e32 v215, v214
	s_nop 1
	v_permlane32_swap_b32_e32 v214, v215
	s_nop 0
	v_add_f32_e32 v214, v214, v215
	v_fmamk_f32 v214, v214, 0x3c800000, v248
	v_rsq_f32_e32 v214, v214
	s_nop 0
	v_mul_f32_e32 v218, v155, v214
	v_pk_mul_f32 v[160:161], v[188:189], v[218:219] op_sel_hi:[1,0]
	v_pk_mul_f32 v[108:109], v[108:109], v[160:161]
	v_pk_mul_f32 v[160:161], v[190:191], v[218:219] op_sel_hi:[1,0]
	v_pk_mul_f32 v[110:111], v[110:111], v[160:161]
	v_pk_mul_f32 v[160:161], v[192:193], v[218:219] op_sel_hi:[1,0]
	v_pk_mul_f32 v[104:105], v[104:105], v[160:161]
	v_pk_mul_f32 v[160:161], v[194:195], v[218:219] op_sel_hi:[1,0]
	v_pk_mul_f32 v[106:107], v[106:107], v[160:161]
	v_cvt_pk_bf16_f32 v204, v108, v109
	v_cvt_pk_bf16_f32 v205, v110, v111
	v_cvt_pk_bf16_f32 v206, v104, v105
	v_cvt_pk_bf16_f32 v207, v106, v107
	global_store_dwordx4 v211, v[204:207], s[26:27]
	v_pk_mul_f32 v[160:161], v[196:197], v[218:219] op_sel_hi:[1,0]
	v_pk_mul_f32 v[100:101], v[100:101], v[160:161]
	v_pk_mul_f32 v[160:161], v[198:199], v[218:219] op_sel_hi:[1,0]
	v_pk_mul_f32 v[102:103], v[102:103], v[160:161]
	v_pk_mul_f32 v[160:161], v[200:201], v[218:219] op_sel_hi:[1,0]
	v_pk_mul_f32 v[96:97], v[96:97], v[160:161]
	v_pk_mul_f32 v[160:161], v[202:203], v[218:219] op_sel_hi:[1,0]
	v_pk_mul_f32 v[98:99], v[98:99], v[160:161]
	v_cvt_pk_bf16_f32 v144, v100, v101
	v_cvt_pk_bf16_f32 v145, v102, v103
	v_cvt_pk_bf16_f32 v146, v96, v97
	v_cvt_pk_bf16_f32 v147, v98, v99
	global_store_dwordx4 v211, v[144:147], s[26:27] offset:64
	v_add_u32_e32 v211, 0x10000, v211
	s_waitcnt vmcnt(9)
	v_pk_add_f32 v[164:165], v[164:165], v[166:167]
	s_nop 0
	v_add_f32_e32 v214, v164, v165
	v_mov_b32_e32 v215, v214
	s_nop 1
	v_permlane16_swap_b32_e32 v214, v215
	s_nop 0
	v_add_f32_e32 v214, v214, v215
	v_mov_b32_e32 v215, v214
	s_nop 1
	v_permlane32_swap_b32_e32 v214, v215
	s_nop 0
	v_add_f32_e32 v214, v214, v215
	v_fmamk_f32 v214, v214, 0x3a800000, v248
	v_rsq_f32_e32 v216, v214
	s_nop 0
	v_pk_mul_f32 v[92:93], v[92:93], v[216:217] op_sel_hi:[1,0]
	v_pk_mul_f32 v[94:95], v[94:95], v[216:217] op_sel_hi:[1,0]
	v_pk_mul_f32 v[88:89], v[88:89], v[216:217] op_sel_hi:[1,0]
	v_pk_mul_f32 v[90:91], v[90:91], v[216:217] op_sel_hi:[1,0]
	v_pk_mul_f32 v[84:85], v[84:85], v[216:217] op_sel_hi:[1,0]
	v_pk_mul_f32 v[86:87], v[86:87], v[216:217] op_sel_hi:[1,0]
	v_pk_mul_f32 v[80:81], v[80:81], v[216:217] op_sel_hi:[1,0]
	v_pk_mul_f32 v[82:83], v[82:83], v[216:217] op_sel_hi:[1,0]
	v_pk_mul_f32 v[148:149], v[92:93], v[92:93]
	v_pk_fma_f32 v[148:149], v[94:95], v[94:95], v[148:149]
	v_pk_fma_f32 v[148:149], v[88:89], v[88:89], v[148:149]
	v_pk_fma_f32 v[148:149], v[90:91], v[90:91], v[148:149]
	v_pk_fma_f32 v[148:149], v[84:85], v[84:85], v[148:149]
	v_pk_fma_f32 v[148:149], v[86:87], v[86:87], v[148:149]
	v_pk_fma_f32 v[148:149], v[80:81], v[80:81], v[148:149]
	v_pk_fma_f32 v[148:149], v[82:83], v[82:83], v[148:149]
	v_add_f32_e32 v214, v148, v149
	v_mov_b32_e32 v215, v214
	s_nop 1
	v_permlane16_swap_b32_e32 v214, v215
	s_nop 0
	v_add_f32_e32 v214, v214, v215
	v_mov_b32_e32 v215, v214
	s_nop 1
	v_permlane32_swap_b32_e32 v214, v215
	s_nop 0
	v_add_f32_e32 v214, v214, v215
	v_fmamk_f32 v214, v214, 0x3c800000, v248
	v_rsq_f32_e32 v214, v214
	s_nop 0
	v_mul_f32_e32 v218, v155, v214
	v_pk_mul_f32 v[164:165], v[188:189], v[218:219] op_sel_hi:[1,0]
	v_pk_mul_f32 v[92:93], v[92:93], v[164:165]
	v_pk_mul_f32 v[164:165], v[190:191], v[218:219] op_sel_hi:[1,0]
	v_pk_mul_f32 v[94:95], v[94:95], v[164:165]
	v_pk_mul_f32 v[164:165], v[192:193], v[218:219] op_sel_hi:[1,0]
	v_pk_mul_f32 v[88:89], v[88:89], v[164:165]
	v_pk_mul_f32 v[164:165], v[194:195], v[218:219] op_sel_hi:[1,0]
	v_pk_mul_f32 v[90:91], v[90:91], v[164:165]
	v_cvt_pk_bf16_f32 v204, v92, v93
	v_cvt_pk_bf16_f32 v205, v94, v95
	v_cvt_pk_bf16_f32 v206, v88, v89
	v_cvt_pk_bf16_f32 v207, v90, v91
	global_store_dwordx4 v211, v[204:207], s[26:27]
	v_pk_mul_f32 v[164:165], v[196:197], v[218:219] op_sel_hi:[1,0]
	v_pk_mul_f32 v[84:85], v[84:85], v[164:165]
	v_pk_mul_f32 v[164:165], v[198:199], v[218:219] op_sel_hi:[1,0]
	v_pk_mul_f32 v[86:87], v[86:87], v[164:165]
	v_pk_mul_f32 v[164:165], v[200:201], v[218:219] op_sel_hi:[1,0]
	v_pk_mul_f32 v[80:81], v[80:81], v[164:165]
	v_pk_mul_f32 v[164:165], v[202:203], v[218:219] op_sel_hi:[1,0]
	v_pk_mul_f32 v[82:83], v[82:83], v[164:165]
	v_cvt_pk_bf16_f32 v144, v84, v85
	v_cvt_pk_bf16_f32 v145, v86, v87
	v_cvt_pk_bf16_f32 v146, v80, v81
	v_cvt_pk_bf16_f32 v147, v82, v83
	global_store_dwordx4 v211, v[144:147], s[26:27] offset:64
	v_add_u32_e32 v211, 0x10000, v211
	s_waitcnt vmcnt(10)
	v_pk_add_f32 v[168:169], v[168:169], v[170:171]
	s_nop 0
	v_add_f32_e32 v214, v168, v169
	v_mov_b32_e32 v215, v214
	s_nop 1
	v_permlane16_swap_b32_e32 v214, v215
	s_nop 0
	v_add_f32_e32 v214, v214, v215
	v_mov_b32_e32 v215, v214
	s_nop 1
	v_permlane32_swap_b32_e32 v214, v215
	s_nop 0
	v_add_f32_e32 v214, v214, v215
	v_fmamk_f32 v214, v214, 0x3a800000, v248
	v_rsq_f32_e32 v216, v214
	s_nop 0
	v_pk_mul_f32 v[76:77], v[76:77], v[216:217] op_sel_hi:[1,0]
	v_pk_mul_f32 v[78:79], v[78:79], v[216:217] op_sel_hi:[1,0]
	v_pk_mul_f32 v[72:73], v[72:73], v[216:217] op_sel_hi:[1,0]
	v_pk_mul_f32 v[74:75], v[74:75], v[216:217] op_sel_hi:[1,0]
	v_pk_mul_f32 v[68:69], v[68:69], v[216:217] op_sel_hi:[1,0]
	v_pk_mul_f32 v[70:71], v[70:71], v[216:217] op_sel_hi:[1,0]
	v_pk_mul_f32 v[64:65], v[64:65], v[216:217] op_sel_hi:[1,0]
	v_pk_mul_f32 v[66:67], v[66:67], v[216:217] op_sel_hi:[1,0]
	v_pk_mul_f32 v[148:149], v[76:77], v[76:77]
	v_pk_fma_f32 v[148:149], v[78:79], v[78:79], v[148:149]
	v_pk_fma_f32 v[148:149], v[72:73], v[72:73], v[148:149]
	v_pk_fma_f32 v[148:149], v[74:75], v[74:75], v[148:149]
	v_pk_fma_f32 v[148:149], v[68:69], v[68:69], v[148:149]
	v_pk_fma_f32 v[148:149], v[70:71], v[70:71], v[148:149]
	v_pk_fma_f32 v[148:149], v[64:65], v[64:65], v[148:149]
	v_pk_fma_f32 v[148:149], v[66:67], v[66:67], v[148:149]
	v_add_f32_e32 v214, v148, v149
	v_mov_b32_e32 v215, v214
	s_nop 1
	v_permlane16_swap_b32_e32 v214, v215
	s_nop 0
	v_add_f32_e32 v214, v214, v215
	v_mov_b32_e32 v215, v214
	s_nop 1
	v_permlane32_swap_b32_e32 v214, v215
	s_nop 0
	v_add_f32_e32 v214, v214, v215
	v_fmamk_f32 v214, v214, 0x3c800000, v248
	v_rsq_f32_e32 v214, v214
	s_nop 0
	v_mul_f32_e32 v218, v155, v214
	v_pk_mul_f32 v[168:169], v[188:189], v[218:219] op_sel_hi:[1,0]
	v_pk_mul_f32 v[76:77], v[76:77], v[168:169]
	v_pk_mul_f32 v[168:169], v[190:191], v[218:219] op_sel_hi:[1,0]
	v_pk_mul_f32 v[78:79], v[78:79], v[168:169]
	v_pk_mul_f32 v[168:169], v[192:193], v[218:219] op_sel_hi:[1,0]
	v_pk_mul_f32 v[72:73], v[72:73], v[168:169]
	v_pk_mul_f32 v[168:169], v[194:195], v[218:219] op_sel_hi:[1,0]
	v_pk_mul_f32 v[74:75], v[74:75], v[168:169]
	v_cvt_pk_bf16_f32 v204, v76, v77
	v_cvt_pk_bf16_f32 v205, v78, v79
	v_cvt_pk_bf16_f32 v206, v72, v73
	v_cvt_pk_bf16_f32 v207, v74, v75
	global_store_dwordx4 v211, v[204:207], s[26:27]
	v_pk_mul_f32 v[168:169], v[196:197], v[218:219] op_sel_hi:[1,0]
	v_pk_mul_f32 v[68:69], v[68:69], v[168:169]
	v_pk_mul_f32 v[168:169], v[198:199], v[218:219] op_sel_hi:[1,0]
	v_pk_mul_f32 v[70:71], v[70:71], v[168:169]
	v_pk_mul_f32 v[168:169], v[200:201], v[218:219] op_sel_hi:[1,0]
	v_pk_mul_f32 v[64:65], v[64:65], v[168:169]
	v_pk_mul_f32 v[168:169], v[202:203], v[218:219] op_sel_hi:[1,0]
	v_pk_mul_f32 v[66:67], v[66:67], v[168:169]
	v_cvt_pk_bf16_f32 v144, v68, v69
	v_cvt_pk_bf16_f32 v145, v70, v71
	v_cvt_pk_bf16_f32 v146, v64, v65
	v_cvt_pk_bf16_f32 v147, v66, v67
	global_store_dwordx4 v211, v[144:147], s[26:27] offset:64
	v_add_u32_e32 v211, 0x50000, v211
	s_waitcnt vmcnt(11)
	v_pk_add_f32 v[172:173], v[172:173], v[174:175]
	s_nop 0
	v_add_f32_e32 v214, v172, v173
	v_mov_b32_e32 v215, v214
	s_nop 1
	v_permlane16_swap_b32_e32 v214, v215
	s_nop 0
	v_add_f32_e32 v214, v214, v215
	v_mov_b32_e32 v215, v214
	s_nop 1
	v_permlane32_swap_b32_e32 v214, v215
	s_nop 0
	v_add_f32_e32 v214, v214, v215
	v_fmamk_f32 v214, v214, 0x3a800000, v248
	v_rsq_f32_e32 v216, v214
	s_nop 0
	v_pk_mul_f32 v[60:61], v[60:61], v[216:217] op_sel_hi:[1,0]
	v_pk_mul_f32 v[62:63], v[62:63], v[216:217] op_sel_hi:[1,0]
	v_pk_mul_f32 v[56:57], v[56:57], v[216:217] op_sel_hi:[1,0]
	v_pk_mul_f32 v[58:59], v[58:59], v[216:217] op_sel_hi:[1,0]
	v_pk_mul_f32 v[52:53], v[52:53], v[216:217] op_sel_hi:[1,0]
	v_pk_mul_f32 v[54:55], v[54:55], v[216:217] op_sel_hi:[1,0]
	v_pk_mul_f32 v[48:49], v[48:49], v[216:217] op_sel_hi:[1,0]
	v_pk_mul_f32 v[50:51], v[50:51], v[216:217] op_sel_hi:[1,0]
	v_pk_mul_f32 v[148:149], v[60:61], v[60:61]
	v_pk_fma_f32 v[148:149], v[62:63], v[62:63], v[148:149]
	v_pk_fma_f32 v[148:149], v[56:57], v[56:57], v[148:149]
	v_pk_fma_f32 v[148:149], v[58:59], v[58:59], v[148:149]
	v_pk_fma_f32 v[148:149], v[52:53], v[52:53], v[148:149]
	v_pk_fma_f32 v[148:149], v[54:55], v[54:55], v[148:149]
	v_pk_fma_f32 v[148:149], v[48:49], v[48:49], v[148:149]
	v_pk_fma_f32 v[148:149], v[50:51], v[50:51], v[148:149]
	v_add_f32_e32 v214, v148, v149
	v_mov_b32_e32 v215, v214
	s_nop 1
	v_permlane16_swap_b32_e32 v214, v215
	s_nop 0
	v_add_f32_e32 v214, v214, v215
	v_mov_b32_e32 v215, v214
	s_nop 1
	v_permlane32_swap_b32_e32 v214, v215
	s_nop 0
	v_add_f32_e32 v214, v214, v215
	v_fmamk_f32 v214, v214, 0x3c800000, v248
	v_rsq_f32_e32 v214, v214
	s_nop 0
	v_mul_f32_e32 v218, v155, v214
	v_pk_mul_f32 v[172:173], v[188:189], v[218:219] op_sel_hi:[1,0]
	v_pk_mul_f32 v[60:61], v[60:61], v[172:173]
	v_pk_mul_f32 v[172:173], v[190:191], v[218:219] op_sel_hi:[1,0]
	v_pk_mul_f32 v[62:63], v[62:63], v[172:173]
	v_pk_mul_f32 v[172:173], v[192:193], v[218:219] op_sel_hi:[1,0]
	v_pk_mul_f32 v[56:57], v[56:57], v[172:173]
	v_pk_mul_f32 v[172:173], v[194:195], v[218:219] op_sel_hi:[1,0]
	v_pk_mul_f32 v[58:59], v[58:59], v[172:173]
	v_cvt_pk_bf16_f32 v204, v60, v61
	v_cvt_pk_bf16_f32 v205, v62, v63
	v_cvt_pk_bf16_f32 v206, v56, v57
	v_cvt_pk_bf16_f32 v207, v58, v59
	global_store_dwordx4 v211, v[204:207], s[26:27]
	v_pk_mul_f32 v[172:173], v[196:197], v[218:219] op_sel_hi:[1,0]
	v_pk_mul_f32 v[52:53], v[52:53], v[172:173]
	v_pk_mul_f32 v[172:173], v[198:199], v[218:219] op_sel_hi:[1,0]
	v_pk_mul_f32 v[54:55], v[54:55], v[172:173]
	v_pk_mul_f32 v[172:173], v[200:201], v[218:219] op_sel_hi:[1,0]
	v_pk_mul_f32 v[48:49], v[48:49], v[172:173]
	v_pk_mul_f32 v[172:173], v[202:203], v[218:219] op_sel_hi:[1,0]
	v_pk_mul_f32 v[50:51], v[50:51], v[172:173]
	v_cvt_pk_bf16_f32 v144, v52, v53
	v_cvt_pk_bf16_f32 v145, v54, v55
	v_cvt_pk_bf16_f32 v146, v48, v49
	v_cvt_pk_bf16_f32 v147, v50, v51
	global_store_dwordx4 v211, v[144:147], s[26:27] offset:64
	v_add_u32_e32 v211, 0x10000, v211
	s_waitcnt vmcnt(12)
	v_pk_add_f32 v[176:177], v[176:177], v[178:179]
	s_nop 0
	v_add_f32_e32 v214, v176, v177
	v_mov_b32_e32 v215, v214
	s_nop 1
	v_permlane16_swap_b32_e32 v214, v215
	s_nop 0
	v_add_f32_e32 v214, v214, v215
	v_mov_b32_e32 v215, v214
	s_nop 1
	v_permlane32_swap_b32_e32 v214, v215
	s_nop 0
	v_add_f32_e32 v214, v214, v215
	v_fmamk_f32 v214, v214, 0x3a800000, v248
	v_rsq_f32_e32 v216, v214
	s_nop 0
	v_pk_mul_f32 v[44:45], v[44:45], v[216:217] op_sel_hi:[1,0]
	v_pk_mul_f32 v[46:47], v[46:47], v[216:217] op_sel_hi:[1,0]
	v_pk_mul_f32 v[40:41], v[40:41], v[216:217] op_sel_hi:[1,0]
	v_pk_mul_f32 v[42:43], v[42:43], v[216:217] op_sel_hi:[1,0]
	v_pk_mul_f32 v[36:37], v[36:37], v[216:217] op_sel_hi:[1,0]
	v_pk_mul_f32 v[38:39], v[38:39], v[216:217] op_sel_hi:[1,0]
	v_pk_mul_f32 v[32:33], v[32:33], v[216:217] op_sel_hi:[1,0]
	v_pk_mul_f32 v[34:35], v[34:35], v[216:217] op_sel_hi:[1,0]
	v_pk_mul_f32 v[148:149], v[44:45], v[44:45]
	v_pk_fma_f32 v[148:149], v[46:47], v[46:47], v[148:149]
	v_pk_fma_f32 v[148:149], v[40:41], v[40:41], v[148:149]
	v_pk_fma_f32 v[148:149], v[42:43], v[42:43], v[148:149]
	v_pk_fma_f32 v[148:149], v[36:37], v[36:37], v[148:149]
	v_pk_fma_f32 v[148:149], v[38:39], v[38:39], v[148:149]
	v_pk_fma_f32 v[148:149], v[32:33], v[32:33], v[148:149]
	v_pk_fma_f32 v[148:149], v[34:35], v[34:35], v[148:149]
	v_add_f32_e32 v214, v148, v149
	v_mov_b32_e32 v215, v214
	s_nop 1
	v_permlane16_swap_b32_e32 v214, v215
	s_nop 0
	v_add_f32_e32 v214, v214, v215
	v_mov_b32_e32 v215, v214
	s_nop 1
	v_permlane32_swap_b32_e32 v214, v215
	s_nop 0
	v_add_f32_e32 v214, v214, v215
	v_fmamk_f32 v214, v214, 0x3c800000, v248
	v_rsq_f32_e32 v214, v214
	s_nop 0
	v_mul_f32_e32 v218, v155, v214
	v_pk_mul_f32 v[176:177], v[188:189], v[218:219] op_sel_hi:[1,0]
	v_pk_mul_f32 v[44:45], v[44:45], v[176:177]
	v_pk_mul_f32 v[176:177], v[190:191], v[218:219] op_sel_hi:[1,0]
	v_pk_mul_f32 v[46:47], v[46:47], v[176:177]
	v_pk_mul_f32 v[176:177], v[192:193], v[218:219] op_sel_hi:[1,0]
	v_pk_mul_f32 v[40:41], v[40:41], v[176:177]
	v_pk_mul_f32 v[176:177], v[194:195], v[218:219] op_sel_hi:[1,0]
	v_pk_mul_f32 v[42:43], v[42:43], v[176:177]
	v_cvt_pk_bf16_f32 v204, v44, v45
	v_cvt_pk_bf16_f32 v205, v46, v47
	v_cvt_pk_bf16_f32 v206, v40, v41
	v_cvt_pk_bf16_f32 v207, v42, v43
	global_store_dwordx4 v211, v[204:207], s[26:27]
	v_pk_mul_f32 v[176:177], v[196:197], v[218:219] op_sel_hi:[1,0]
	v_pk_mul_f32 v[36:37], v[36:37], v[176:177]
	v_pk_mul_f32 v[176:177], v[198:199], v[218:219] op_sel_hi:[1,0]
	v_pk_mul_f32 v[38:39], v[38:39], v[176:177]
	v_pk_mul_f32 v[176:177], v[200:201], v[218:219] op_sel_hi:[1,0]
	v_pk_mul_f32 v[32:33], v[32:33], v[176:177]
	v_pk_mul_f32 v[176:177], v[202:203], v[218:219] op_sel_hi:[1,0]
	v_pk_mul_f32 v[34:35], v[34:35], v[176:177]
	v_cvt_pk_bf16_f32 v144, v36, v37
	v_cvt_pk_bf16_f32 v145, v38, v39
	v_cvt_pk_bf16_f32 v146, v32, v33
	v_cvt_pk_bf16_f32 v147, v34, v35
	global_store_dwordx4 v211, v[144:147], s[26:27] offset:64
	v_add_u32_e32 v211, 0x10000, v211
	s_waitcnt vmcnt(13)
	v_pk_add_f32 v[180:181], v[180:181], v[182:183]
	s_nop 0
	v_add_f32_e32 v214, v180, v181
	v_mov_b32_e32 v215, v214
	s_nop 1
	v_permlane16_swap_b32_e32 v214, v215
	s_nop 0
	v_add_f32_e32 v214, v214, v215
	v_mov_b32_e32 v215, v214
	s_nop 1
	v_permlane32_swap_b32_e32 v214, v215
	s_nop 0
	v_add_f32_e32 v214, v214, v215
	v_fmamk_f32 v214, v214, 0x3a800000, v248
	v_rsq_f32_e32 v216, v214
	s_nop 0
	v_pk_mul_f32 v[28:29], v[28:29], v[216:217] op_sel_hi:[1,0]
	v_pk_mul_f32 v[30:31], v[30:31], v[216:217] op_sel_hi:[1,0]
	v_pk_mul_f32 v[24:25], v[24:25], v[216:217] op_sel_hi:[1,0]
	v_pk_mul_f32 v[26:27], v[26:27], v[216:217] op_sel_hi:[1,0]
	v_pk_mul_f32 v[20:21], v[20:21], v[216:217] op_sel_hi:[1,0]
	v_pk_mul_f32 v[22:23], v[22:23], v[216:217] op_sel_hi:[1,0]
	v_pk_mul_f32 v[16:17], v[16:17], v[216:217] op_sel_hi:[1,0]
	v_pk_mul_f32 v[18:19], v[18:19], v[216:217] op_sel_hi:[1,0]
	v_pk_mul_f32 v[148:149], v[28:29], v[28:29]
	v_pk_fma_f32 v[148:149], v[30:31], v[30:31], v[148:149]
	v_pk_fma_f32 v[148:149], v[24:25], v[24:25], v[148:149]
	v_pk_fma_f32 v[148:149], v[26:27], v[26:27], v[148:149]
	v_pk_fma_f32 v[148:149], v[20:21], v[20:21], v[148:149]
	v_pk_fma_f32 v[148:149], v[22:23], v[22:23], v[148:149]
	v_pk_fma_f32 v[148:149], v[16:17], v[16:17], v[148:149]
	v_pk_fma_f32 v[148:149], v[18:19], v[18:19], v[148:149]
	v_add_f32_e32 v214, v148, v149
	v_mov_b32_e32 v215, v214
	s_nop 1
	v_permlane16_swap_b32_e32 v214, v215
	s_nop 0
	v_add_f32_e32 v214, v214, v215
	v_mov_b32_e32 v215, v214
	s_nop 1
	v_permlane32_swap_b32_e32 v214, v215
	s_nop 0
	v_add_f32_e32 v214, v214, v215
	v_fmamk_f32 v214, v214, 0x3c800000, v248
	v_rsq_f32_e32 v214, v214
	s_nop 0
	v_mul_f32_e32 v218, v155, v214
	v_pk_mul_f32 v[180:181], v[188:189], v[218:219] op_sel_hi:[1,0]
	v_pk_mul_f32 v[28:29], v[28:29], v[180:181]
	v_pk_mul_f32 v[180:181], v[190:191], v[218:219] op_sel_hi:[1,0]
	v_pk_mul_f32 v[30:31], v[30:31], v[180:181]
	v_pk_mul_f32 v[180:181], v[192:193], v[218:219] op_sel_hi:[1,0]
	v_pk_mul_f32 v[24:25], v[24:25], v[180:181]
	v_pk_mul_f32 v[180:181], v[194:195], v[218:219] op_sel_hi:[1,0]
	v_pk_mul_f32 v[26:27], v[26:27], v[180:181]
	v_cvt_pk_bf16_f32 v204, v28, v29
	v_cvt_pk_bf16_f32 v205, v30, v31
	v_cvt_pk_bf16_f32 v206, v24, v25
	v_cvt_pk_bf16_f32 v207, v26, v27
	global_store_dwordx4 v211, v[204:207], s[26:27]
	v_pk_mul_f32 v[180:181], v[196:197], v[218:219] op_sel_hi:[1,0]
	v_pk_mul_f32 v[20:21], v[20:21], v[180:181]
	v_pk_mul_f32 v[180:181], v[198:199], v[218:219] op_sel_hi:[1,0]
	v_pk_mul_f32 v[22:23], v[22:23], v[180:181]
	v_pk_mul_f32 v[180:181], v[200:201], v[218:219] op_sel_hi:[1,0]
	v_pk_mul_f32 v[16:17], v[16:17], v[180:181]
	v_pk_mul_f32 v[180:181], v[202:203], v[218:219] op_sel_hi:[1,0]
	v_pk_mul_f32 v[18:19], v[18:19], v[180:181]
	v_cvt_pk_bf16_f32 v144, v20, v21
	v_cvt_pk_bf16_f32 v145, v22, v23
	v_cvt_pk_bf16_f32 v146, v16, v17
	v_cvt_pk_bf16_f32 v147, v18, v19
	global_store_dwordx4 v211, v[144:147], s[26:27] offset:64
	v_add_u32_e32 v211, 0x10000, v211
	s_waitcnt vmcnt(14)
	v_pk_add_f32 v[184:185], v[184:185], v[186:187]
	s_nop 0
	v_add_f32_e32 v214, v184, v185
	v_mov_b32_e32 v215, v214
	s_nop 1
	v_permlane16_swap_b32_e32 v214, v215
	s_nop 0
	v_add_f32_e32 v214, v214, v215
	v_mov_b32_e32 v215, v214
	s_nop 1
	v_permlane32_swap_b32_e32 v214, v215
	s_nop 0
	v_add_f32_e32 v214, v214, v215
	v_fmamk_f32 v214, v214, 0x3a800000, v248
	v_rsq_f32_e32 v216, v214
	s_nop 0
	v_pk_mul_f32 v[12:13], v[12:13], v[216:217] op_sel_hi:[1,0]
	v_pk_mul_f32 v[14:15], v[14:15], v[216:217] op_sel_hi:[1,0]
	v_pk_mul_f32 v[8:9], v[8:9], v[216:217] op_sel_hi:[1,0]
	v_pk_mul_f32 v[10:11], v[10:11], v[216:217] op_sel_hi:[1,0]
	v_pk_mul_f32 v[4:5], v[4:5], v[216:217] op_sel_hi:[1,0]
	v_pk_mul_f32 v[6:7], v[6:7], v[216:217] op_sel_hi:[1,0]
	v_pk_mul_f32 v[0:1], v[0:1], v[216:217] op_sel_hi:[1,0]
	v_pk_mul_f32 v[2:3], v[2:3], v[216:217] op_sel_hi:[1,0]
	v_pk_mul_f32 v[148:149], v[12:13], v[12:13]
	v_pk_fma_f32 v[148:149], v[14:15], v[14:15], v[148:149]
	v_pk_fma_f32 v[148:149], v[8:9], v[8:9], v[148:149]
	v_pk_fma_f32 v[148:149], v[10:11], v[10:11], v[148:149]
	v_pk_fma_f32 v[148:149], v[4:5], v[4:5], v[148:149]
	v_pk_fma_f32 v[148:149], v[6:7], v[6:7], v[148:149]
	v_pk_fma_f32 v[148:149], v[0:1], v[0:1], v[148:149]
	v_pk_fma_f32 v[148:149], v[2:3], v[2:3], v[148:149]
	v_add_f32_e32 v214, v148, v149
	v_mov_b32_e32 v215, v214
	s_nop 1
	v_permlane16_swap_b32_e32 v214, v215
	s_nop 0
	v_add_f32_e32 v214, v214, v215
	v_mov_b32_e32 v215, v214
	s_nop 1
	v_permlane32_swap_b32_e32 v214, v215
	s_nop 0
	v_add_f32_e32 v214, v214, v215
	v_fmamk_f32 v214, v214, 0x3c800000, v248
	v_rsq_f32_e32 v214, v214
	s_nop 0
	v_mul_f32_e32 v218, v155, v214
	v_pk_mul_f32 v[184:185], v[188:189], v[218:219] op_sel_hi:[1,0]
	v_pk_mul_f32 v[12:13], v[12:13], v[184:185]
	v_pk_mul_f32 v[184:185], v[190:191], v[218:219] op_sel_hi:[1,0]
	v_pk_mul_f32 v[14:15], v[14:15], v[184:185]
	v_pk_mul_f32 v[184:185], v[192:193], v[218:219] op_sel_hi:[1,0]
	v_pk_mul_f32 v[8:9], v[8:9], v[184:185]
	v_pk_mul_f32 v[184:185], v[194:195], v[218:219] op_sel_hi:[1,0]
	v_pk_mul_f32 v[10:11], v[10:11], v[184:185]
	v_cvt_pk_bf16_f32 v204, v12, v13
	v_cvt_pk_bf16_f32 v205, v14, v15
	v_cvt_pk_bf16_f32 v206, v8, v9
	v_cvt_pk_bf16_f32 v207, v10, v11
	global_store_dwordx4 v211, v[204:207], s[26:27]
	v_pk_mul_f32 v[184:185], v[196:197], v[218:219] op_sel_hi:[1,0]
	v_pk_mul_f32 v[4:5], v[4:5], v[184:185]
	v_pk_mul_f32 v[184:185], v[198:199], v[218:219] op_sel_hi:[1,0]
	v_pk_mul_f32 v[6:7], v[6:7], v[184:185]
	v_pk_mul_f32 v[184:185], v[200:201], v[218:219] op_sel_hi:[1,0]
	v_pk_mul_f32 v[0:1], v[0:1], v[184:185]
	v_pk_mul_f32 v[184:185], v[202:203], v[218:219] op_sel_hi:[1,0]
	v_pk_mul_f32 v[2:3], v[2:3], v[184:185]
	v_cvt_pk_bf16_f32 v144, v4, v5
	v_cvt_pk_bf16_f32 v145, v6, v7
	v_cvt_pk_bf16_f32 v146, v0, v1
	v_cvt_pk_bf16_f32 v147, v2, v3
	global_store_dwordx4 v211, v[144:147], s[26:27] offset:64
	s_and_b64 vcc, exec, s[4:5]
	s_mov_b64 s[26:27], s[22:23]
	s_cbranch_vccz .LBB0_691
	s_waitcnt vmcnt(0)
	s_cmpk_gt_u32 s54, 0xff
	s_cbranch_scc1 .LBB0_702
	s_barrier

.LBB0_714:
	s_add_u32 s26, s6, 0xfffc0080
	s_addc_u32 s27, s7, -1
	s_add_i32 s63, 0, 0x10000
	v_add_u32_e32 v140, s63, v165
	ds_read_b128 v[128:131], v140
	ds_read_b128 v[132:135], v140 offset:1024
	ds_read_b128 v[136:139], v140 offset:2048
	ds_read_b128 v[140:143], v140 offset:3072
	s_cmp_eq_u32 s51, 12
	s_cselect_b32 s29, s21, s27
	s_cselect_b32 s28, s38, s26
	s_cselect_b32 s27, s11, s50
	s_cselect_b32 s26, s39, s46
	s_add_i32 m0, s56, 0xc000
	ds_read_b128 v[154:157], v167
	ds_read_b128 v[158:161], v167 offset:1024
	ds_read_b128 v[168:171], v167 offset:2048
	ds_read_b128 v[172:175], v167 offset:3072
	ds_read_b128 v[176:179], v167 offset:4096
	ds_read_b128 v[180:183], v167 offset:5120
	ds_read_b128 v[184:187], v167 offset:6144
	global_load_lds_dwordx4 v150, s[6:7]
	s_add_i32 m0, s56, 0xe000
	ds_read_b128 v[188:191], v167 offset:7168
	global_load_lds_dwordx4 v152, s[6:7]
	s_waitcnt lgkmcnt(8)
	s_barrier
	s_waitcnt lgkmcnt(0)
	v_mfma_f32_16x16x32_bf16 v[124:127], v[128:131], v[154:157], v[124:127]
	v_mfma_f32_16x16x32_bf16 v[120:123], v[136:139], v[154:157], v[120:123]
	v_mfma_f32_16x16x32_bf16 v[116:119], v[128:131], v[168:171], v[116:119]
	v_mfma_f32_16x16x32_bf16 v[112:115], v[136:139], v[168:171], v[112:115]
	v_mfma_f32_16x16x32_bf16 v[108:111], v[128:131], v[176:179], v[108:111]
	v_mfma_f32_16x16x32_bf16 v[104:107], v[136:139], v[176:179], v[104:107]
	v_mfma_f32_16x16x32_bf16 v[100:103], v[128:131], v[184:187], v[100:103]
	v_mfma_f32_16x16x32_bf16 v[96:99], v[136:139], v[184:187], v[96:99]
	v_mfma_f32_16x16x32_bf16 v[124:127], v[132:135], v[158:161], v[124:127]
	v_mfma_f32_16x16x32_bf16 v[120:123], v[140:143], v[158:161], v[120:123]
	v_mfma_f32_16x16x32_bf16 v[116:119], v[132:135], v[172:175], v[116:119]
	v_mfma_f32_16x16x32_bf16 v[112:115], v[140:143], v[172:175], v[112:115]
	v_mfma_f32_16x16x32_bf16 v[108:111], v[132:135], v[180:183], v[108:111]
	v_mfma_f32_16x16x32_bf16 v[104:107], v[140:143], v[180:183], v[104:107]
	v_mfma_f32_16x16x32_bf16 v[100:103], v[132:135], v[188:191], v[100:103]
	v_mfma_f32_16x16x32_bf16 v[96:99], v[140:143], v[188:191], v[96:99]
	s_barrier
	s_add_i32 s66, 0, 0x14000
	v_add_u32_e32 v162, s66, v165
	s_add_i32 s63, s63, s55
	ds_read_b128 v[192:195], v162
	ds_read_b128 v[196:199], v162 offset:1024
	ds_read_b128 v[200:203], v162 offset:2048
	ds_read_b128 v[204:207], v162 offset:3072
	s_add_u32 s98, s26, s40
	s_addc_u32 s99, s27, s41
	s_mov_b32 m0, s63
	s_nop 0
	global_load_lds_dwordx4 v208, s[26:27]
	s_add_i32 m0, s63, 0x2000
	s_nop 0
	global_load_lds_dwordx4 v144, s[26:27]
	s_barrier
	s_waitcnt lgkmcnt(0)
	v_mfma_f32_16x16x32_bf16 v[60:63], v[192:195], v[154:157], v[60:63]
	v_mfma_f32_16x16x32_bf16 v[56:59], v[200:203], v[154:157], v[56:59]
	v_mfma_f32_16x16x32_bf16 v[52:55], v[192:195], v[168:171], v[52:55]
	v_mfma_f32_16x16x32_bf16 v[48:51], v[200:203], v[168:171], v[48:51]
	v_mfma_f32_16x16x32_bf16 v[44:47], v[192:195], v[176:179], v[44:47]
	v_mfma_f32_16x16x32_bf16 v[40:43], v[200:203], v[176:179], v[40:43]
	v_mfma_f32_16x16x32_bf16 v[36:39], v[192:195], v[184:187], v[36:39]
	v_mfma_f32_16x16x32_bf16 v[32:35], v[200:203], v[184:187], v[32:35]
	v_mfma_f32_16x16x32_bf16 v[60:63], v[196:199], v[158:161], v[60:63]
	v_mfma_f32_16x16x32_bf16 v[56:59], v[204:207], v[158:161], v[56:59]
	v_mfma_f32_16x16x32_bf16 v[52:55], v[196:199], v[172:175], v[52:55]
	v_mfma_f32_16x16x32_bf16 v[48:51], v[204:207], v[172:175], v[48:51]
	v_mfma_f32_16x16x32_bf16 v[44:47], v[196:199], v[180:183], v[44:47]
	v_mfma_f32_16x16x32_bf16 v[40:43], v[204:207], v[180:183], v[40:43]
	v_mfma_f32_16x16x32_bf16 v[36:39], v[196:199], v[188:191], v[36:39]
	v_mfma_f32_16x16x32_bf16 v[32:35], v[204:207], v[188:191], v[32:35]
	s_mov_b32 m0, s56
	s_add_u32 s100, s28, s40
	s_addc_u32 s101, s29, s41
	s_barrier
	ds_read_b128 v[154:157], v167 offset:16384
	ds_read_b128 v[158:161], v167 offset:17408
	ds_read_b128 v[168:171], v167 offset:18432
	ds_read_b128 v[172:175], v167 offset:19456
	ds_read_b128 v[176:179], v167 offset:20480
	ds_read_b128 v[180:183], v167 offset:21504
	ds_read_b128 v[184:187], v167 offset:22528
	global_load_lds_dwordx4 v148, s[28:29]
	s_mov_b32 m0, s57
	ds_read_b128 v[188:191], v167 offset:23552
	global_load_lds_dwordx4 v146, s[28:29]
	s_barrier
	s_waitcnt lgkmcnt(0)
	v_mfma_f32_16x16x32_bf16 v[92:95], v[128:131], v[154:157], v[92:95]
	v_mfma_f32_16x16x32_bf16 v[88:91], v[136:139], v[154:157], v[88:91]
	v_mfma_f32_16x16x32_bf16 v[84:87], v[128:131], v[168:171], v[84:87]
	v_mfma_f32_16x16x32_bf16 v[80:83], v[136:139], v[168:171], v[80:83]
	v_mfma_f32_16x16x32_bf16 v[76:79], v[128:131], v[176:179], v[76:79]
	v_mfma_f32_16x16x32_bf16 v[72:75], v[136:139], v[176:179], v[72:75]
	v_mfma_f32_16x16x32_bf16 v[68:71], v[128:131], v[184:187], v[68:71]
	v_mfma_f32_16x16x32_bf16 v[64:67], v[136:139], v[184:187], v[64:67]
	v_mfma_f32_16x16x32_bf16 v[92:95], v[132:135], v[158:161], v[92:95]
	v_mfma_f32_16x16x32_bf16 v[88:91], v[140:143], v[158:161], v[88:91]
	v_mfma_f32_16x16x32_bf16 v[84:87], v[132:135], v[172:175], v[84:87]
	v_mfma_f32_16x16x32_bf16 v[80:83], v[140:143], v[172:175], v[80:83]
	v_mfma_f32_16x16x32_bf16 v[76:79], v[132:135], v[180:183], v[76:79]
	v_mfma_f32_16x16x32_bf16 v[72:75], v[140:143], v[180:183], v[72:75]
	v_mfma_f32_16x16x32_bf16 v[68:71], v[132:135], v[188:191], v[68:71]
	v_mfma_f32_16x16x32_bf16 v[64:67], v[140:143], v[188:191], v[64:67]
	s_barrier
	s_add_u32 s64, s26, 0x40000
	s_addc_u32 s65, s27, 0
	s_add_i32 s63, s66, s55
	s_mov_b32 m0, s63
	s_nop 0
	global_load_lds_dwordx4 v208, s[64:65]
	s_add_i32 m0, s63, 0x2000
	s_nop 0
	global_load_lds_dwordx4 v144, s[64:65]
	s_waitcnt vmcnt(6)
	s_barrier
	v_mfma_f32_16x16x32_bf16 v[28:31], v[192:195], v[154:157], v[28:31]
	v_mfma_f32_16x16x32_bf16 v[24:27], v[200:203], v[154:157], v[24:27]
	v_mfma_f32_16x16x32_bf16 v[20:23], v[192:195], v[168:171], v[20:23]
	v_mfma_f32_16x16x32_bf16 v[16:19], v[200:203], v[168:171], v[16:19]
	v_mfma_f32_16x16x32_bf16 v[12:15], v[192:195], v[176:179], v[12:15]
	v_mfma_f32_16x16x32_bf16 v[8:11], v[200:203], v[176:179], v[8:11]
	v_mfma_f32_16x16x32_bf16 v[4:7], v[192:195], v[184:187], v[4:7]
	v_mfma_f32_16x16x32_bf16 v[0:3], v[200:203], v[184:187], v[0:3]
	v_mfma_f32_16x16x32_bf16 v[28:31], v[196:199], v[158:161], v[28:31]
	v_mfma_f32_16x16x32_bf16 v[24:27], v[204:207], v[158:161], v[24:27]
	v_mfma_f32_16x16x32_bf16 v[20:23], v[196:199], v[172:175], v[20:23]
	v_mfma_f32_16x16x32_bf16 v[16:19], v[204:207], v[172:175], v[16:19]
	v_mfma_f32_16x16x32_bf16 v[12:15], v[196:199], v[180:183], v[12:15]
	v_mfma_f32_16x16x32_bf16 v[8:11], v[204:207], v[180:183], v[8:11]
	v_mfma_f32_16x16x32_bf16 v[4:7], v[196:199], v[188:191], v[4:7]
	v_mfma_f32_16x16x32_bf16 v[0:3], v[204:207], v[188:191], v[0:3]
	s_add_i32 s63, 0, 0x18000
	v_add_u32_e32 v140, s63, v165
	s_barrier
	ds_read_b128 v[128:131], v140
	ds_read_b128 v[132:135], v140 offset:1024
	ds_read_b128 v[136:139], v140 offset:2048
	ds_read_b128 v[140:143], v140 offset:3072
	s_add_u32 s28, s28, 0x40000
	s_addc_u32 s29, s29, 0
	s_mov_b32 m0, s58
	ds_read_b128 v[154:157], v167 offset:32768
	ds_read_b128 v[158:161], v167 offset:33792
	ds_read_b128 v[168:171], v167 offset:34816
	ds_read_b128 v[172:175], v167 offset:35840
	ds_read_b128 v[176:179], v167 offset:36864
	ds_read_b128 v[180:183], v167 offset:37888
	ds_read_b128 v[184:187], v167 offset:38912
	global_load_lds_dwordx4 v148, s[28:29]
	s_mov_b32 m0, s59
	ds_read_b128 v[188:191], v167 offset:39936
	global_load_lds_dwordx4 v146, s[28:29]
	s_waitcnt lgkmcnt(8)
	s_barrier
	s_waitcnt lgkmcnt(0)
	v_mfma_f32_16x16x32_bf16 v[124:127], v[128:131], v[154:157], v[124:127]
	v_mfma_f32_16x16x32_bf16 v[120:123], v[136:139], v[154:157], v[120:123]
	v_mfma_f32_16x16x32_bf16 v[116:119], v[128:131], v[168:171], v[116:119]
	v_mfma_f32_16x16x32_bf16 v[112:115], v[136:139], v[168:171], v[112:115]
	v_mfma_f32_16x16x32_bf16 v[108:111], v[128:131], v[176:179], v[108:111]
	v_mfma_f32_16x16x32_bf16 v[104:107], v[136:139], v[176:179], v[104:107]
	v_mfma_f32_16x16x32_bf16 v[100:103], v[128:131], v[184:187], v[100:103]
	v_mfma_f32_16x16x32_bf16 v[96:99], v[136:139], v[184:187], v[96:99]
	v_mfma_f32_16x16x32_bf16 v[124:127], v[132:135], v[158:161], v[124:127]
	v_mfma_f32_16x16x32_bf16 v[120:123], v[140:143], v[158:161], v[120:123]
	v_mfma_f32_16x16x32_bf16 v[116:119], v[132:135], v[172:175], v[116:119]
	v_mfma_f32_16x16x32_bf16 v[112:115], v[140:143], v[172:175], v[112:115]
	v_mfma_f32_16x16x32_bf16 v[108:111], v[132:135], v[180:183], v[108:111]
	v_mfma_f32_16x16x32_bf16 v[104:107], v[140:143], v[180:183], v[104:107]
	v_mfma_f32_16x16x32_bf16 v[100:103], v[132:135], v[188:191], v[100:103]
	v_mfma_f32_16x16x32_bf16 v[96:99], v[140:143], v[188:191], v[96:99]
	s_barrier
	s_add_i32 s28, 0, 0x1c000
	s_add_i32 s29, s63, s55
	v_add_u32_e32 v204, s28, v165
	s_mov_b32 m0, s29
	ds_read_b128 v[192:195], v204
	ds_read_b128 v[196:199], v204 offset:1024
	ds_read_b128 v[200:203], v204 offset:2048
	global_load_lds_dwordx4 v208, s[98:99]
	s_add_i32 m0, s29, 0x2000
	ds_read_b128 v[204:207], v204 offset:3072
	global_load_lds_dwordx4 v144, s[98:99]
	s_barrier
	s_waitcnt lgkmcnt(0)
	v_mfma_f32_16x16x32_bf16 v[60:63], v[192:195], v[154:157], v[60:63]
	v_mfma_f32_16x16x32_bf16 v[56:59], v[200:203], v[154:157], v[56:59]
	v_mfma_f32_16x16x32_bf16 v[52:55], v[192:195], v[168:171], v[52:55]
	v_mfma_f32_16x16x32_bf16 v[48:51], v[200:203], v[168:171], v[48:51]
	v_mfma_f32_16x16x32_bf16 v[44:47], v[192:195], v[176:179], v[44:47]
	v_mfma_f32_16x16x32_bf16 v[40:43], v[200:203], v[176:179], v[40:43]
	v_mfma_f32_16x16x32_bf16 v[36:39], v[192:195], v[184:187], v[36:39]
	v_mfma_f32_16x16x32_bf16 v[32:35], v[200:203], v[184:187], v[32:35]
	v_mfma_f32_16x16x32_bf16 v[60:63], v[196:199], v[158:161], v[60:63]
	v_mfma_f32_16x16x32_bf16 v[56:59], v[204:207], v[158:161], v[56:59]
	v_mfma_f32_16x16x32_bf16 v[52:55], v[196:199], v[172:175], v[52:55]
	v_mfma_f32_16x16x32_bf16 v[48:51], v[204:207], v[172:175], v[48:51]
	v_mfma_f32_16x16x32_bf16 v[44:47], v[196:199], v[180:183], v[44:47]
	v_mfma_f32_16x16x32_bf16 v[40:43], v[204:207], v[180:183], v[40:43]
	v_mfma_f32_16x16x32_bf16 v[36:39], v[196:199], v[188:191], v[36:39]
	v_mfma_f32_16x16x32_bf16 v[32:35], v[204:207], v[188:191], v[32:35]
	s_mov_b32 m0, s60
	s_barrier
	ds_read_b128 v[154:157], v167 offset:49152
	ds_read_b128 v[158:161], v167 offset:50176
	ds_read_b128 v[168:171], v167 offset:51200
	ds_read_b128 v[172:175], v167 offset:52224
	ds_read_b128 v[176:179], v167 offset:53248
	ds_read_b128 v[180:183], v167 offset:54272
	ds_read_b128 v[184:187], v167 offset:55296
	global_load_lds_dwordx4 v148, s[100:101]
	s_mov_b32 m0, s61
	ds_read_b128 v[188:191], v167 offset:56320
	global_load_lds_dwordx4 v146, s[100:101]
	s_barrier
	s_waitcnt lgkmcnt(0)
	v_mfma_f32_16x16x32_bf16 v[92:95], v[128:131], v[154:157], v[92:95]
	v_mfma_f32_16x16x32_bf16 v[88:91], v[136:139], v[154:157], v[88:91]
	v_mfma_f32_16x16x32_bf16 v[84:87], v[128:131], v[168:171], v[84:87]
	v_mfma_f32_16x16x32_bf16 v[80:83], v[136:139], v[168:171], v[80:83]
	v_mfma_f32_16x16x32_bf16 v[76:79], v[128:131], v[176:179], v[76:79]
	v_mfma_f32_16x16x32_bf16 v[72:75], v[136:139], v[176:179], v[72:75]
	v_mfma_f32_16x16x32_bf16 v[68:71], v[128:131], v[184:187], v[68:71]
	v_mfma_f32_16x16x32_bf16 v[64:67], v[136:139], v[184:187], v[64:67]
	v_mfma_f32_16x16x32_bf16 v[92:95], v[132:135], v[158:161], v[92:95]
	v_mfma_f32_16x16x32_bf16 v[88:91], v[140:143], v[158:161], v[88:91]
	v_mfma_f32_16x16x32_bf16 v[84:87], v[132:135], v[172:175], v[84:87]
	v_mfma_f32_16x16x32_bf16 v[80:83], v[140:143], v[172:175], v[80:83]
	v_mfma_f32_16x16x32_bf16 v[76:79], v[132:135], v[180:183], v[76:79]
	v_mfma_f32_16x16x32_bf16 v[72:75], v[140:143], v[180:183], v[72:75]
	v_mfma_f32_16x16x32_bf16 v[68:71], v[132:135], v[188:191], v[68:71]
	v_mfma_f32_16x16x32_bf16 v[64:67], v[140:143], v[188:191], v[64:67]
	s_barrier
	s_add_u32 s26, s26, 0x40080
	s_addc_u32 s27, s27, 0
	s_add_i32 s28, s28, s55
	s_mov_b32 m0, s28
	s_nop 0
	global_load_lds_dwordx4 v208, s[26:27]
	s_add_i32 m0, s28, 0x2000
	s_nop 0
	global_load_lds_dwordx4 v144, s[26:27]
	s_waitcnt vmcnt(6)
	s_barrier
	v_mfma_f32_16x16x32_bf16 v[28:31], v[192:195], v[154:157], v[28:31]
	v_mfma_f32_16x16x32_bf16 v[24:27], v[200:203], v[154:157], v[24:27]
	v_mfma_f32_16x16x32_bf16 v[20:23], v[192:195], v[168:171], v[20:23]
	v_mfma_f32_16x16x32_bf16 v[16:19], v[200:203], v[168:171], v[16:19]
	v_mfma_f32_16x16x32_bf16 v[12:15], v[192:195], v[176:179], v[12:15]
	v_mfma_f32_16x16x32_bf16 v[8:11], v[200:203], v[176:179], v[8:11]
	v_mfma_f32_16x16x32_bf16 v[4:7], v[192:195], v[184:187], v[4:7]
	v_mfma_f32_16x16x32_bf16 v[0:3], v[200:203], v[184:187], v[0:3]
	v_mfma_f32_16x16x32_bf16 v[28:31], v[196:199], v[158:161], v[28:31]
	v_mfma_f32_16x16x32_bf16 v[24:27], v[204:207], v[158:161], v[24:27]
	v_mfma_f32_16x16x32_bf16 v[20:23], v[196:199], v[172:175], v[20:23]
	v_mfma_f32_16x16x32_bf16 v[16:19], v[204:207], v[172:175], v[16:19]
	v_mfma_f32_16x16x32_bf16 v[12:15], v[196:199], v[180:183], v[12:15]
	v_mfma_f32_16x16x32_bf16 v[8:11], v[204:207], v[180:183], v[8:11]
	v_mfma_f32_16x16x32_bf16 v[4:7], v[196:199], v[188:191], v[4:7]
	v_mfma_f32_16x16x32_bf16 v[0:3], v[204:207], v[188:191], v[0:3]
	s_add_i32 s51, s51, 2
	s_add_u32 s6, s6, 0x100
	s_addc_u32 s7, s7, 0
	s_add_u32 s46, s46, 0x100
	s_addc_u32 s50, s50, 0
	s_cmp_gt_u32 s51, 13
	s_barrier
	s_cbranch_scc0 .LBB0_714
	v_lshl_or_b32 v158, s34, 8, v166
	v_lshl_add_u32 v159, s35, 8, v164
	s_mov_b32 s34, s10
	s_mov_b32 s35, s20
	s_mov_b64 s[26:27], s[24:25]
	v_mbcnt_lo_u32_b32 v160, -1, 0
	v_mbcnt_hi_u32_b32 v160, -1, v160
	v_and_b32_e32 v157, 7, v160
	v_and_b32_e32 v160, 8, v160
	v_add_u32_e32 v157, v158, v157
	v_lshlrev_b32_e32 v157, 6, v157
	v_lshl_add_u32 v157, v160, 2, v157
	v_add_u32_e32 v161, 0x2000, v157
	global_load_dwordx4 v[128:131], v157, s[18:19]
	global_load_dwordx4 v[132:135], v157, s[18:19] offset:16
	global_load_dwordx4 v[136:139], v161, s[18:19]
	global_load_dwordx4 v[140:143], v161, s[18:19] offset:16
	v_mov_b32_e32 v155, 0x358637bd
	v_lshlrev_b32_e32 v156, 17, v159
	v_lshl_add_u32 v156, v158, 1, v156
	s_waitcnt vmcnt(0)
	v_pk_add_f32 v[128:129], v[128:129], v[130:131]
	v_pk_add_f32 v[132:133], v[132:133], v[134:135]
	v_pk_add_f32 v[128:129], v[128:129], v[132:133]
	s_nop 0
	v_add_f32_e32 v154, v128, v129
	s_nop 1
	v_add_f32_dpp v154, v154, v154 row_ror:8 row_mask:0xf bank_mask:0xf
	s_nop 0
	v_fmamk_f32 v154, v154, 0x3a800000, v155
	v_rsq_f32_e32 v154, v154
	s_nop 1
	v_mov_b32_dpp v168, v154 row_newbcast:0 row_mask:0xf bank_mask:0xf
	v_mov_b32_dpp v169, v154 row_newbcast:1 row_mask:0xf bank_mask:0xf
	v_mov_b32_dpp v170, v154 row_newbcast:2 row_mask:0xf bank_mask:0xf
	v_mov_b32_dpp v171, v154 row_newbcast:3 row_mask:0xf bank_mask:0xf
	v_mov_b32_dpp v172, v154 row_newbcast:4 row_mask:0xf bank_mask:0xf
	v_mov_b32_dpp v173, v154 row_newbcast:5 row_mask:0xf bank_mask:0xf
	v_mov_b32_dpp v174, v154 row_newbcast:6 row_mask:0xf bank_mask:0xf
	v_mov_b32_dpp v175, v154 row_newbcast:7 row_mask:0xf bank_mask:0xf
	v_pk_add_f32 v[136:137], v[136:137], v[138:139]
	v_pk_add_f32 v[140:141], v[140:141], v[142:143]
	v_pk_add_f32 v[136:137], v[136:137], v[140:141]
	s_nop 0
	v_add_f32_e32 v154, v136, v137
	s_nop 1
	v_add_f32_dpp v154, v154, v154 row_ror:8 row_mask:0xf bank_mask:0xf
	s_nop 0
	v_fmamk_f32 v154, v154, 0x3a800000, v155
	v_rsq_f32_e32 v154, v154
	s_nop 1
	v_mov_b32_dpp v176, v154 row_newbcast:0 row_mask:0xf bank_mask:0xf
	v_mov_b32_dpp v177, v154 row_newbcast:1 row_mask:0xf bank_mask:0xf
	v_mov_b32_dpp v178, v154 row_newbcast:2 row_mask:0xf bank_mask:0xf
	v_mov_b32_dpp v179, v154 row_newbcast:3 row_mask:0xf bank_mask:0xf
	v_mov_b32_dpp v180, v154 row_newbcast:4 row_mask:0xf bank_mask:0xf
	v_mov_b32_dpp v181, v154 row_newbcast:5 row_mask:0xf bank_mask:0xf
	v_mov_b32_dpp v182, v154 row_newbcast:6 row_mask:0xf bank_mask:0xf
	v_mov_b32_dpp v183, v154 row_newbcast:7 row_mask:0xf bank_mask:0xf
	v_pk_mul_f32 v[124:125], v[124:125], v[168:169]
	v_pk_mul_f32 v[126:127], v[126:127], v[170:171]
	v_pk_mul_f32 v[120:121], v[120:121], v[172:173]
	v_pk_mul_f32 v[122:123], v[122:123], v[174:175]
	v_cvt_pk_bf16_f32 v184, v124, v125
	v_cvt_pk_bf16_f32 v185, v126, v127
	v_cvt_pk_bf16_f32 v186, v120, v121
	v_cvt_pk_bf16_f32 v187, v122, v123
	global_store_dwordx4 v156, v[184:187], s[8:9]
	v_pk_mul_f32 v[60:61], v[60:61], v[176:177]
	v_pk_mul_f32 v[62:63], v[62:63], v[178:179]
	v_pk_mul_f32 v[56:57], v[56:57], v[180:181]
	v_pk_mul_f32 v[58:59], v[58:59], v[182:183]
	v_cvt_pk_bf16_f32 v188, v60, v61
	v_cvt_pk_bf16_f32 v189, v62, v63
	v_cvt_pk_bf16_f32 v190, v56, v57
	v_cvt_pk_bf16_f32 v191, v58, v59
	global_store_dwordx4 v156, v[188:191], s[8:9] offset:256
	v_add_u32_e32 v156, 0x200000, v156
	v_pk_mul_f32 v[116:117], v[116:117], v[168:169]
	v_pk_mul_f32 v[118:119], v[118:119], v[170:171]
	v_pk_mul_f32 v[112:113], v[112:113], v[172:173]
	v_pk_mul_f32 v[114:115], v[114:115], v[174:175]
	v_cvt_pk_bf16_f32 v184, v116, v117
	v_cvt_pk_bf16_f32 v185, v118, v119
	v_cvt_pk_bf16_f32 v186, v112, v113
	v_cvt_pk_bf16_f32 v187, v114, v115
	global_store_dwordx4 v156, v[184:187], s[8:9]
	v_pk_mul_f32 v[52:53], v[52:53], v[176:177]
	v_pk_mul_f32 v[54:55], v[54:55], v[178:179]
	v_pk_mul_f32 v[48:49], v[48:49], v[180:181]
	v_pk_mul_f32 v[50:51], v[50:51], v[182:183]
	v_cvt_pk_bf16_f32 v188, v52, v53
	v_cvt_pk_bf16_f32 v189, v54, v55
	v_cvt_pk_bf16_f32 v190, v48, v49
	v_cvt_pk_bf16_f32 v191, v50, v51
	global_store_dwordx4 v156, v[188:191], s[8:9] offset:256
	v_add_u32_e32 v156, 0x200000, v156
	v_pk_mul_f32 v[108:109], v[108:109], v[168:169]
	v_pk_mul_f32 v[110:111], v[110:111], v[170:171]
	v_pk_mul_f32 v[104:105], v[104:105], v[172:173]
	v_pk_mul_f32 v[106:107], v[106:107], v[174:175]
	v_cvt_pk_bf16_f32 v184, v108, v109
	v_cvt_pk_bf16_f32 v185, v110, v111
	v_cvt_pk_bf16_f32 v186, v104, v105
	v_cvt_pk_bf16_f32 v187, v106, v107
	global_store_dwordx4 v156, v[184:187], s[8:9]
	v_pk_mul_f32 v[44:45], v[44:45], v[176:177]
	v_pk_mul_f32 v[46:47], v[46:47], v[178:179]
	v_pk_mul_f32 v[40:41], v[40:41], v[180:181]
	v_pk_mul_f32 v[42:43], v[42:43], v[182:183]
	v_cvt_pk_bf16_f32 v188, v44, v45
	v_cvt_pk_bf16_f32 v189, v46, v47
	v_cvt_pk_bf16_f32 v190, v40, v41
	v_cvt_pk_bf16_f32 v191, v42, v43
	global_store_dwordx4 v156, v[188:191], s[8:9] offset:256
	v_add_u32_e32 v156, 0x200000, v156
	v_pk_mul_f32 v[100:101], v[100:101], v[168:169]
	v_pk_mul_f32 v[102:103], v[102:103], v[170:171]
	v_pk_mul_f32 v[96:97], v[96:97], v[172:173]
	v_pk_mul_f32 v[98:99], v[98:99], v[174:175]
	v_cvt_pk_bf16_f32 v184, v100, v101
	v_cvt_pk_bf16_f32 v185, v102, v103
	v_cvt_pk_bf16_f32 v186, v96, v97
	v_cvt_pk_bf16_f32 v187, v98, v99
	global_store_dwordx4 v156, v[184:187], s[8:9]
	v_pk_mul_f32 v[36:37], v[36:37], v[176:177]
	v_pk_mul_f32 v[38:39], v[38:39], v[178:179]
	v_pk_mul_f32 v[32:33], v[32:33], v[180:181]
	v_pk_mul_f32 v[34:35], v[34:35], v[182:183]
	v_cvt_pk_bf16_f32 v188, v36, v37
	v_cvt_pk_bf16_f32 v189, v38, v39
	v_cvt_pk_bf16_f32 v190, v32, v33
	v_cvt_pk_bf16_f32 v191, v34, v35
	global_store_dwordx4 v156, v[188:191], s[8:9] offset:256
	v_add_u32_e32 v156, 0xa00000, v156
	v_pk_mul_f32 v[92:93], v[92:93], v[168:169]
	v_pk_mul_f32 v[94:95], v[94:95], v[170:171]
	v_pk_mul_f32 v[88:89], v[88:89], v[172:173]
	v_pk_mul_f32 v[90:91], v[90:91], v[174:175]
	v_cvt_pk_bf16_f32 v184, v92, v93
	v_cvt_pk_bf16_f32 v185, v94, v95
	v_cvt_pk_bf16_f32 v186, v88, v89
	v_cvt_pk_bf16_f32 v187, v90, v91
	global_store_dwordx4 v156, v[184:187], s[8:9]
	v_pk_mul_f32 v[28:29], v[28:29], v[176:177]
	v_pk_mul_f32 v[30:31], v[30:31], v[178:179]
	v_pk_mul_f32 v[24:25], v[24:25], v[180:181]
	v_pk_mul_f32 v[26:27], v[26:27], v[182:183]
	v_cvt_pk_bf16_f32 v188, v28, v29
	v_cvt_pk_bf16_f32 v189, v30, v31
	v_cvt_pk_bf16_f32 v190, v24, v25
	v_cvt_pk_bf16_f32 v191, v26, v27
	global_store_dwordx4 v156, v[188:191], s[8:9] offset:256
	v_add_u32_e32 v156, 0x200000, v156
	v_pk_mul_f32 v[84:85], v[84:85], v[168:169]
	v_pk_mul_f32 v[86:87], v[86:87], v[170:171]
	v_pk_mul_f32 v[80:81], v[80:81], v[172:173]
	v_pk_mul_f32 v[82:83], v[82:83], v[174:175]
	v_cvt_pk_bf16_f32 v184, v84, v85
	v_cvt_pk_bf16_f32 v185, v86, v87
	v_cvt_pk_bf16_f32 v186, v80, v81
	v_cvt_pk_bf16_f32 v187, v82, v83
	global_store_dwordx4 v156, v[184:187], s[8:9]
	v_pk_mul_f32 v[20:21], v[20:21], v[176:177]
	v_pk_mul_f32 v[22:23], v[22:23], v[178:179]
	v_pk_mul_f32 v[16:17], v[16:17], v[180:181]
	v_pk_mul_f32 v[18:19], v[18:19], v[182:183]
	v_cvt_pk_bf16_f32 v188, v20, v21
	v_cvt_pk_bf16_f32 v189, v22, v23
	v_cvt_pk_bf16_f32 v190, v16, v17
	v_cvt_pk_bf16_f32 v191, v18, v19
	global_store_dwordx4 v156, v[188:191], s[8:9] offset:256
	v_add_u32_e32 v156, 0x200000, v156
	v_pk_mul_f32 v[76:77], v[76:77], v[168:169]
	v_pk_mul_f32 v[78:79], v[78:79], v[170:171]
	v_pk_mul_f32 v[72:73], v[72:73], v[172:173]
	v_pk_mul_f32 v[74:75], v[74:75], v[174:175]
	v_cvt_pk_bf16_f32 v184, v76, v77
	v_cvt_pk_bf16_f32 v185, v78, v79
	v_cvt_pk_bf16_f32 v186, v72, v73
	v_cvt_pk_bf16_f32 v187, v74, v75
	global_store_dwordx4 v156, v[184:187], s[8:9]
	v_pk_mul_f32 v[12:13], v[12:13], v[176:177]
	v_pk_mul_f32 v[14:15], v[14:15], v[178:179]
	v_pk_mul_f32 v[8:9], v[8:9], v[180:181]
	v_pk_mul_f32 v[10:11], v[10:11], v[182:183]
	v_cvt_pk_bf16_f32 v188, v12, v13
	v_cvt_pk_bf16_f32 v189, v14, v15
	v_cvt_pk_bf16_f32 v190, v8, v9
	v_cvt_pk_bf16_f32 v191, v10, v11
	global_store_dwordx4 v156, v[188:191], s[8:9] offset:256
	v_add_u32_e32 v156, 0x200000, v156
	v_pk_mul_f32 v[68:69], v[68:69], v[168:169]
	v_pk_mul_f32 v[70:71], v[70:71], v[170:171]
	v_pk_mul_f32 v[64:65], v[64:65], v[172:173]
	v_pk_mul_f32 v[66:67], v[66:67], v[174:175]
	v_cvt_pk_bf16_f32 v184, v68, v69
	v_cvt_pk_bf16_f32 v185, v70, v71
	v_cvt_pk_bf16_f32 v186, v64, v65
	v_cvt_pk_bf16_f32 v187, v66, v67
	global_store_dwordx4 v156, v[184:187], s[8:9]
	v_pk_mul_f32 v[4:5], v[4:5], v[176:177]
	v_pk_mul_f32 v[6:7], v[6:7], v[178:179]
	v_pk_mul_f32 v[0:1], v[0:1], v[180:181]
	v_pk_mul_f32 v[2:3], v[2:3], v[182:183]
	v_cvt_pk_bf16_f32 v188, v4, v5
	v_cvt_pk_bf16_f32 v189, v6, v7
	v_cvt_pk_bf16_f32 v190, v0, v1
	v_cvt_pk_bf16_f32 v191, v2, v3
	global_store_dwordx4 v156, v[188:191], s[8:9] offset:256
	s_mov_b64 s[6:7], s[22:23]
	s_and_b64 vcc, exec, s[4:5]
	s_cbranch_vccz .LBB0_707
	s_waitcnt vmcnt(0)
	s_cmpk_gt_u32 s30, 0xff
	s_cbranch_scc1 .LBB0_718
	s_barrier

.LBB0_776:
	s_add_u32 s28, s26, 0xfffc0080
	s_addc_u32 s29, s27, -1
	s_add_i32 s66, 0, 0x10000
	v_add_u32_e32 v154, s66, v143
	ds_read_b128 v[138:141], v154
	ds_read_b128 v[146:149], v154 offset:1024
	ds_read_b128 v[150:153], v154 offset:2048
	ds_read_b128 v[154:157], v154 offset:3072
	s_cmp_eq_u32 s65, 12
	s_cselect_b32 s31, s21, s29
	s_cselect_b32 s30, s39, s28
	s_cselect_b32 s29, s19, s64
	s_cselect_b32 s28, s62, s63
	s_add_i32 m0, s54, 0xc000
	ds_read_b128 v[158:161], v145
	ds_read_b128 v[162:165], v145 offset:1024
	ds_read_b128 v[166:169], v145 offset:2048
	ds_read_b128 v[170:173], v145 offset:3072
	ds_read_b128 v[174:177], v145 offset:4096
	ds_read_b128 v[178:181], v145 offset:5120
	ds_read_b128 v[182:185], v145 offset:6144
	global_load_lds_dwordx4 v134, s[26:27]
	s_add_i32 m0, s54, 0xe000
	ds_read_b128 v[186:189], v145 offset:7168
	global_load_lds_dwordx4 v136, s[26:27]
	s_waitcnt lgkmcnt(8)
	s_barrier
	s_waitcnt lgkmcnt(0)
	v_mfma_f32_16x16x32_bf16 v[124:127], v[138:141], v[158:161], v[124:127]
	v_mfma_f32_16x16x32_bf16 v[120:123], v[150:153], v[158:161], v[120:123]
	v_mfma_f32_16x16x32_bf16 v[108:111], v[138:141], v[166:169], v[108:111]
	v_mfma_f32_16x16x32_bf16 v[104:107], v[150:153], v[166:169], v[104:107]
	v_mfma_f32_16x16x32_bf16 v[92:95], v[138:141], v[174:177], v[92:95]
	v_mfma_f32_16x16x32_bf16 v[88:91], v[150:153], v[174:177], v[88:91]
	v_mfma_f32_16x16x32_bf16 v[76:79], v[138:141], v[182:185], v[76:79]
	v_mfma_f32_16x16x32_bf16 v[72:75], v[150:153], v[182:185], v[72:75]
	v_mfma_f32_16x16x32_bf16 v[124:127], v[146:149], v[162:165], v[124:127]
	v_mfma_f32_16x16x32_bf16 v[120:123], v[154:157], v[162:165], v[120:123]
	v_mfma_f32_16x16x32_bf16 v[108:111], v[146:149], v[170:173], v[108:111]
	v_mfma_f32_16x16x32_bf16 v[104:107], v[154:157], v[170:173], v[104:107]
	v_mfma_f32_16x16x32_bf16 v[92:95], v[146:149], v[178:181], v[92:95]
	v_mfma_f32_16x16x32_bf16 v[88:91], v[154:157], v[178:181], v[88:91]
	v_mfma_f32_16x16x32_bf16 v[76:79], v[146:149], v[186:189], v[76:79]
	v_mfma_f32_16x16x32_bf16 v[72:75], v[154:157], v[186:189], v[72:75]
	s_barrier
	s_add_i32 s68, 0, 0x14000
	s_add_i32 s66, s66, s53
	v_add_u32_e32 v202, s68, v143
	s_add_u32 s98, s28, s40
	s_addc_u32 s99, s29, s41
	s_mov_b32 m0, s66
	ds_read_b128 v[190:193], v202
	ds_read_b128 v[194:197], v202 offset:1024
	ds_read_b128 v[198:201], v202 offset:2048
	global_load_lds_dwordx4 v208, s[28:29]
	s_add_i32 m0, s66, 0x2000
	ds_read_b128 v[202:205], v202 offset:3072
	global_load_lds_dwordx4 v128, s[28:29]
	s_barrier
	s_waitcnt lgkmcnt(0)
	v_mfma_f32_16x16x32_bf16 v[116:119], v[190:193], v[158:161], v[116:119]
	v_mfma_f32_16x16x32_bf16 v[112:115], v[198:201], v[158:161], v[112:115]
	v_mfma_f32_16x16x32_bf16 v[100:103], v[190:193], v[166:169], v[100:103]
	v_mfma_f32_16x16x32_bf16 v[96:99], v[198:201], v[166:169], v[96:99]
	v_mfma_f32_16x16x32_bf16 v[84:87], v[190:193], v[174:177], v[84:87]
	v_mfma_f32_16x16x32_bf16 v[80:83], v[198:201], v[174:177], v[80:83]
	v_mfma_f32_16x16x32_bf16 v[68:71], v[190:193], v[182:185], v[68:71]
	v_mfma_f32_16x16x32_bf16 v[64:67], v[198:201], v[182:185], v[64:67]
	v_mfma_f32_16x16x32_bf16 v[116:119], v[194:197], v[162:165], v[116:119]
	v_mfma_f32_16x16x32_bf16 v[112:115], v[202:205], v[162:165], v[112:115]
	v_mfma_f32_16x16x32_bf16 v[100:103], v[194:197], v[170:173], v[100:103]
	v_mfma_f32_16x16x32_bf16 v[96:99], v[202:205], v[170:173], v[96:99]
	v_mfma_f32_16x16x32_bf16 v[84:87], v[194:197], v[178:181], v[84:87]
	v_mfma_f32_16x16x32_bf16 v[80:83], v[202:205], v[178:181], v[80:83]
	v_mfma_f32_16x16x32_bf16 v[68:71], v[194:197], v[186:189], v[68:71]
	v_mfma_f32_16x16x32_bf16 v[64:67], v[202:205], v[186:189], v[64:67]
	s_mov_b32 m0, s54
	s_add_u32 s100, s30, s40
	s_addc_u32 s101, s31, s41
	s_barrier
	ds_read_b128 v[158:161], v145 offset:16384
	ds_read_b128 v[162:165], v145 offset:17408
	ds_read_b128 v[166:169], v145 offset:18432
	ds_read_b128 v[170:173], v145 offset:19456
	ds_read_b128 v[174:177], v145 offset:20480
	ds_read_b128 v[178:181], v145 offset:21504
	ds_read_b128 v[182:185], v145 offset:22528
	global_load_lds_dwordx4 v132, s[30:31]
	s_mov_b32 m0, s55
	ds_read_b128 v[186:189], v145 offset:23552
	global_load_lds_dwordx4 v130, s[30:31]
	s_barrier
	s_waitcnt lgkmcnt(0)
	v_mfma_f32_16x16x32_bf16 v[60:63], v[138:141], v[158:161], v[60:63]
	v_mfma_f32_16x16x32_bf16 v[56:59], v[150:153], v[158:161], v[56:59]
	v_mfma_f32_16x16x32_bf16 v[44:47], v[138:141], v[166:169], v[44:47]
	v_mfma_f32_16x16x32_bf16 v[40:43], v[150:153], v[166:169], v[40:43]
	v_mfma_f32_16x16x32_bf16 v[28:31], v[138:141], v[174:177], v[28:31]
	v_mfma_f32_16x16x32_bf16 v[24:27], v[150:153], v[174:177], v[24:27]
	v_mfma_f32_16x16x32_bf16 v[12:15], v[138:141], v[182:185], v[12:15]
	v_mfma_f32_16x16x32_bf16 v[8:11], v[150:153], v[182:185], v[8:11]
	v_mfma_f32_16x16x32_bf16 v[60:63], v[146:149], v[162:165], v[60:63]
	v_mfma_f32_16x16x32_bf16 v[56:59], v[154:157], v[162:165], v[56:59]
	v_mfma_f32_16x16x32_bf16 v[44:47], v[146:149], v[170:173], v[44:47]
	v_mfma_f32_16x16x32_bf16 v[40:43], v[154:157], v[170:173], v[40:43]
	v_mfma_f32_16x16x32_bf16 v[28:31], v[146:149], v[178:181], v[28:31]
	v_mfma_f32_16x16x32_bf16 v[24:27], v[154:157], v[178:181], v[24:27]
	v_mfma_f32_16x16x32_bf16 v[12:15], v[146:149], v[186:189], v[12:15]
	v_mfma_f32_16x16x32_bf16 v[8:11], v[154:157], v[186:189], v[8:11]
	s_barrier
	s_add_u32 s66, s28, 0x40000
	s_addc_u32 s67, s29, 0
	s_add_i32 s68, s68, s53
	s_mov_b32 m0, s68
	s_nop 0
	global_load_lds_dwordx4 v208, s[66:67]
	s_add_i32 m0, s68, 0x2000
	s_nop 0
	global_load_lds_dwordx4 v128, s[66:67]
	s_waitcnt vmcnt(6)
	s_barrier
	v_mfma_f32_16x16x32_bf16 v[52:55], v[190:193], v[158:161], v[52:55]
	v_mfma_f32_16x16x32_bf16 v[48:51], v[198:201], v[158:161], v[48:51]
	v_mfma_f32_16x16x32_bf16 v[36:39], v[190:193], v[166:169], v[36:39]
	v_mfma_f32_16x16x32_bf16 v[32:35], v[198:201], v[166:169], v[32:35]
	v_mfma_f32_16x16x32_bf16 v[20:23], v[190:193], v[174:177], v[20:23]
	v_mfma_f32_16x16x32_bf16 v[16:19], v[198:201], v[174:177], v[16:19]
	v_mfma_f32_16x16x32_bf16 v[4:7], v[190:193], v[182:185], v[4:7]
	v_mfma_f32_16x16x32_bf16 v[0:3], v[198:201], v[182:185], v[0:3]
	v_mfma_f32_16x16x32_bf16 v[52:55], v[194:197], v[162:165], v[52:55]
	v_mfma_f32_16x16x32_bf16 v[48:51], v[202:205], v[162:165], v[48:51]
	v_mfma_f32_16x16x32_bf16 v[36:39], v[194:197], v[170:173], v[36:39]
	v_mfma_f32_16x16x32_bf16 v[32:35], v[202:205], v[170:173], v[32:35]
	v_mfma_f32_16x16x32_bf16 v[20:23], v[194:197], v[178:181], v[20:23]
	v_mfma_f32_16x16x32_bf16 v[16:19], v[202:205], v[178:181], v[16:19]
	v_mfma_f32_16x16x32_bf16 v[4:7], v[194:197], v[186:189], v[4:7]
	v_mfma_f32_16x16x32_bf16 v[0:3], v[202:205], v[186:189], v[0:3]
	s_add_i32 s66, 0, 0x18000
	v_add_u32_e32 v154, s66, v143
	s_barrier
	ds_read_b128 v[138:141], v154
	ds_read_b128 v[146:149], v154 offset:1024
	ds_read_b128 v[150:153], v154 offset:2048
	ds_read_b128 v[154:157], v154 offset:3072
	s_add_u32 s30, s30, 0x40000
	s_addc_u32 s31, s31, 0
	s_mov_b32 m0, s56
	ds_read_b128 v[158:161], v145 offset:32768
	ds_read_b128 v[162:165], v145 offset:33792
	ds_read_b128 v[166:169], v145 offset:34816
	ds_read_b128 v[170:173], v145 offset:35840
	ds_read_b128 v[174:177], v145 offset:36864
	ds_read_b128 v[178:181], v145 offset:37888
	ds_read_b128 v[182:185], v145 offset:38912
	global_load_lds_dwordx4 v132, s[30:31]
	s_mov_b32 m0, s57
	ds_read_b128 v[186:189], v145 offset:39936
	global_load_lds_dwordx4 v130, s[30:31]
	s_waitcnt lgkmcnt(8)
	s_barrier
	s_waitcnt lgkmcnt(0)
	v_mfma_f32_16x16x32_bf16 v[124:127], v[138:141], v[158:161], v[124:127]
	v_mfma_f32_16x16x32_bf16 v[120:123], v[150:153], v[158:161], v[120:123]
	v_mfma_f32_16x16x32_bf16 v[108:111], v[138:141], v[166:169], v[108:111]
	v_mfma_f32_16x16x32_bf16 v[104:107], v[150:153], v[166:169], v[104:107]
	v_mfma_f32_16x16x32_bf16 v[92:95], v[138:141], v[174:177], v[92:95]
	v_mfma_f32_16x16x32_bf16 v[88:91], v[150:153], v[174:177], v[88:91]
	v_mfma_f32_16x16x32_bf16 v[76:79], v[138:141], v[182:185], v[76:79]
	v_mfma_f32_16x16x32_bf16 v[72:75], v[150:153], v[182:185], v[72:75]
	v_mfma_f32_16x16x32_bf16 v[124:127], v[146:149], v[162:165], v[124:127]
	v_mfma_f32_16x16x32_bf16 v[120:123], v[154:157], v[162:165], v[120:123]
	v_mfma_f32_16x16x32_bf16 v[108:111], v[146:149], v[170:173], v[108:111]
	v_mfma_f32_16x16x32_bf16 v[104:107], v[154:157], v[170:173], v[104:107]
	v_mfma_f32_16x16x32_bf16 v[92:95], v[146:149], v[178:181], v[92:95]
	v_mfma_f32_16x16x32_bf16 v[88:91], v[154:157], v[178:181], v[88:91]
	v_mfma_f32_16x16x32_bf16 v[76:79], v[146:149], v[186:189], v[76:79]
	v_mfma_f32_16x16x32_bf16 v[72:75], v[154:157], v[186:189], v[72:75]
	s_barrier
	s_add_i32 s30, 0, 0x1c000
	s_add_i32 s31, s66, s53
	v_add_u32_e32 v202, s30, v143
	s_mov_b32 m0, s31
	ds_read_b128 v[190:193], v202
	ds_read_b128 v[194:197], v202 offset:1024
	ds_read_b128 v[198:201], v202 offset:2048
	global_load_lds_dwordx4 v208, s[98:99]
	s_add_i32 m0, s31, 0x2000
	ds_read_b128 v[202:205], v202 offset:3072
	global_load_lds_dwordx4 v128, s[98:99]
	s_barrier
	s_waitcnt lgkmcnt(0)
	v_mfma_f32_16x16x32_bf16 v[116:119], v[190:193], v[158:161], v[116:119]
	v_mfma_f32_16x16x32_bf16 v[112:115], v[198:201], v[158:161], v[112:115]
	v_mfma_f32_16x16x32_bf16 v[100:103], v[190:193], v[166:169], v[100:103]
	v_mfma_f32_16x16x32_bf16 v[96:99], v[198:201], v[166:169], v[96:99]
	v_mfma_f32_16x16x32_bf16 v[84:87], v[190:193], v[174:177], v[84:87]
	v_mfma_f32_16x16x32_bf16 v[80:83], v[198:201], v[174:177], v[80:83]
	v_mfma_f32_16x16x32_bf16 v[68:71], v[190:193], v[182:185], v[68:71]
	v_mfma_f32_16x16x32_bf16 v[64:67], v[198:201], v[182:185], v[64:67]
	v_mfma_f32_16x16x32_bf16 v[116:119], v[194:197], v[162:165], v[116:119]
	v_mfma_f32_16x16x32_bf16 v[112:115], v[202:205], v[162:165], v[112:115]
	v_mfma_f32_16x16x32_bf16 v[100:103], v[194:197], v[170:173], v[100:103]
	v_mfma_f32_16x16x32_bf16 v[96:99], v[202:205], v[170:173], v[96:99]
	v_mfma_f32_16x16x32_bf16 v[84:87], v[194:197], v[178:181], v[84:87]
	v_mfma_f32_16x16x32_bf16 v[80:83], v[202:205], v[178:181], v[80:83]
	v_mfma_f32_16x16x32_bf16 v[68:71], v[194:197], v[186:189], v[68:71]
	v_mfma_f32_16x16x32_bf16 v[64:67], v[202:205], v[186:189], v[64:67]
	s_mov_b32 m0, s59
	s_barrier
	ds_read_b128 v[158:161], v145 offset:49152
	ds_read_b128 v[162:165], v145 offset:50176
	ds_read_b128 v[166:169], v145 offset:51200
	ds_read_b128 v[170:173], v145 offset:52224
	ds_read_b128 v[174:177], v145 offset:53248
	ds_read_b128 v[178:181], v145 offset:54272
	ds_read_b128 v[182:185], v145 offset:55296
	global_load_lds_dwordx4 v132, s[100:101]
	s_mov_b32 m0, s60
	ds_read_b128 v[186:189], v145 offset:56320
	global_load_lds_dwordx4 v130, s[100:101]
	s_barrier
	s_waitcnt lgkmcnt(0)
	v_mfma_f32_16x16x32_bf16 v[60:63], v[138:141], v[158:161], v[60:63]
	v_mfma_f32_16x16x32_bf16 v[56:59], v[150:153], v[158:161], v[56:59]
	v_mfma_f32_16x16x32_bf16 v[44:47], v[138:141], v[166:169], v[44:47]
	v_mfma_f32_16x16x32_bf16 v[40:43], v[150:153], v[166:169], v[40:43]
	v_mfma_f32_16x16x32_bf16 v[28:31], v[138:141], v[174:177], v[28:31]
	v_mfma_f32_16x16x32_bf16 v[24:27], v[150:153], v[174:177], v[24:27]
	v_mfma_f32_16x16x32_bf16 v[12:15], v[138:141], v[182:185], v[12:15]
	v_mfma_f32_16x16x32_bf16 v[8:11], v[150:153], v[182:185], v[8:11]
	v_mfma_f32_16x16x32_bf16 v[60:63], v[146:149], v[162:165], v[60:63]
	v_mfma_f32_16x16x32_bf16 v[56:59], v[154:157], v[162:165], v[56:59]
	v_mfma_f32_16x16x32_bf16 v[44:47], v[146:149], v[170:173], v[44:47]
	v_mfma_f32_16x16x32_bf16 v[40:43], v[154:157], v[170:173], v[40:43]
	v_mfma_f32_16x16x32_bf16 v[28:31], v[146:149], v[178:181], v[28:31]
	v_mfma_f32_16x16x32_bf16 v[24:27], v[154:157], v[178:181], v[24:27]
	v_mfma_f32_16x16x32_bf16 v[12:15], v[146:149], v[186:189], v[12:15]
	v_mfma_f32_16x16x32_bf16 v[8:11], v[154:157], v[186:189], v[8:11]
	s_barrier
	s_add_u32 s28, s28, 0x40080
	s_addc_u32 s29, s29, 0
	s_add_i32 s30, s30, s53
	s_mov_b32 m0, s30
	s_nop 0
	global_load_lds_dwordx4 v208, s[28:29]
	s_add_i32 m0, s30, 0x2000
	s_nop 0
	global_load_lds_dwordx4 v128, s[28:29]
	s_waitcnt vmcnt(6)
	s_barrier
	v_mfma_f32_16x16x32_bf16 v[52:55], v[190:193], v[158:161], v[52:55]
	v_mfma_f32_16x16x32_bf16 v[48:51], v[198:201], v[158:161], v[48:51]
	v_mfma_f32_16x16x32_bf16 v[36:39], v[190:193], v[166:169], v[36:39]
	v_mfma_f32_16x16x32_bf16 v[32:35], v[198:201], v[166:169], v[32:35]
	v_mfma_f32_16x16x32_bf16 v[20:23], v[190:193], v[174:177], v[20:23]
	v_mfma_f32_16x16x32_bf16 v[16:19], v[198:201], v[174:177], v[16:19]
	v_mfma_f32_16x16x32_bf16 v[4:7], v[190:193], v[182:185], v[4:7]
	v_mfma_f32_16x16x32_bf16 v[0:3], v[198:201], v[182:185], v[0:3]
	v_mfma_f32_16x16x32_bf16 v[52:55], v[194:197], v[162:165], v[52:55]
	v_mfma_f32_16x16x32_bf16 v[48:51], v[202:205], v[162:165], v[48:51]
	v_mfma_f32_16x16x32_bf16 v[36:39], v[194:197], v[170:173], v[36:39]
	v_mfma_f32_16x16x32_bf16 v[32:35], v[202:205], v[170:173], v[32:35]
	v_mfma_f32_16x16x32_bf16 v[20:23], v[194:197], v[178:181], v[20:23]
	v_mfma_f32_16x16x32_bf16 v[16:19], v[202:205], v[178:181], v[16:19]
	v_mfma_f32_16x16x32_bf16 v[4:7], v[194:197], v[186:189], v[4:7]
	v_mfma_f32_16x16x32_bf16 v[0:3], v[202:205], v[186:189], v[0:3]
	s_add_i32 s65, s65, 2
	s_add_u32 s26, s26, 0x100
	s_addc_u32 s27, s27, 0
	s_add_u32 s63, s63, 0x100
	s_addc_u32 s64, s64, 0
	s_cmp_gt_u32 s65, 13
	s_barrier
	s_cbranch_scc0 .LBB0_776
	v_lshl_add_u32 v140, s38, 8, v142
	v_lshl_or_b32 v141, s36, 8, v144
	s_lshl_b32 s26, s36, 2
	s_ashr_i32 s27, s26, 31
	s_lshl_b32 s36, s58, 2
	v_lshlrev_b32_e32 v206, 11, v140
	v_lshl_add_u32 v206, v141, 1, v206
	v_lshl_add_u32 v210, v140, 6, s36
	v_lshl_add_u32 v210, s26, 2, v210
	v_mov_b32_e32 v207, v206
	global_load_dwordx4 v[146:149], v206, s[10:11]
	global_load_dwordx4 v[150:153], v206, s[10:11] offset:256
	v_add_u32_e32 v206, 0x8000, v206
	global_load_dwordx4 v[154:157], v206, s[10:11]
	global_load_dwordx4 v[158:161], v206, s[10:11] offset:256
	v_add_u32_e32 v206, 0x8000, v206
	global_load_dwordx4 v[162:165], v206, s[10:11]
	global_load_dwordx4 v[166:169], v206, s[10:11] offset:256
	v_add_u32_e32 v206, 0x8000, v206
	global_load_dwordx4 v[170:173], v206, s[10:11]
	global_load_dwordx4 v[174:177], v206, s[10:11] offset:256
	v_add_u32_e32 v206, 0x28000, v206
	global_load_dwordx4 v[178:181], v206, s[10:11]
	global_load_dwordx4 v[182:185], v206, s[10:11] offset:256
	v_add_u32_e32 v206, 0x8000, v206
	global_load_dwordx4 v[186:189], v206, s[10:11]
	global_load_dwordx4 v[190:193], v206, s[10:11] offset:256
	v_add_u32_e32 v206, 0x8000, v206
	global_load_dwordx4 v[194:197], v206, s[10:11]
	global_load_dwordx4 v[198:201], v206, s[10:11] offset:256
	v_add_u32_e32 v206, 0x8000, v206
	s_waitcnt vmcnt(12)
	v_lshlrev_b32_e32 v202, 16, v146
	v_and_b32_e32 v203, 0xffff0000, v146
	v_lshlrev_b32_e32 v204, 16, v147
	v_and_b32_e32 v205, 0xffff0000, v147
	v_pk_add_f32 v[124:125], v[124:125], v[202:203]
	v_pk_add_f32 v[126:127], v[126:127], v[204:205]
	v_lshlrev_b32_e32 v202, 16, v148
	v_and_b32_e32 v203, 0xffff0000, v148
	v_lshlrev_b32_e32 v204, 16, v149
	v_and_b32_e32 v205, 0xffff0000, v149
	v_pk_add_f32 v[120:121], v[120:121], v[202:203]
	v_pk_add_f32 v[122:123], v[122:123], v[204:205]
	v_cvt_pk_bf16_f32 v146, v124, v125
	v_cvt_pk_bf16_f32 v147, v126, v127
	v_cvt_pk_bf16_f32 v148, v120, v121
	v_cvt_pk_bf16_f32 v149, v122, v123
	v_pk_mul_f32 v[138:139], v[124:125], v[124:125]
	global_store_dwordx4 v207, v[146:149], s[10:11]
	v_pk_fma_f32 v[138:139], v[126:127], v[126:127], v[138:139]
	v_pk_fma_f32 v[138:139], v[120:121], v[120:121], v[138:139]
	v_pk_fma_f32 v[138:139], v[122:123], v[122:123], v[138:139]
	v_lshlrev_b32_e32 v202, 16, v150
	v_and_b32_e32 v203, 0xffff0000, v150
	v_lshlrev_b32_e32 v204, 16, v151
	v_and_b32_e32 v205, 0xffff0000, v151
	v_pk_add_f32 v[116:117], v[116:117], v[202:203]
	v_pk_add_f32 v[118:119], v[118:119], v[204:205]
	v_lshlrev_b32_e32 v202, 16, v152
	v_and_b32_e32 v203, 0xffff0000, v152
	v_lshlrev_b32_e32 v204, 16, v153
	v_and_b32_e32 v205, 0xffff0000, v153
	v_pk_add_f32 v[112:113], v[112:113], v[202:203]
	v_pk_add_f32 v[114:115], v[114:115], v[204:205]
	v_cvt_pk_bf16_f32 v150, v116, v117
	v_cvt_pk_bf16_f32 v151, v118, v119
	v_cvt_pk_bf16_f32 v152, v112, v113
	v_cvt_pk_bf16_f32 v153, v114, v115
	v_pk_fma_f32 v[138:139], v[116:117], v[116:117], v[138:139]
	global_store_dwordx4 v207, v[150:153], s[10:11] offset:256
	v_pk_fma_f32 v[138:139], v[118:119], v[118:119], v[138:139]
	v_pk_fma_f32 v[138:139], v[112:113], v[112:113], v[138:139]
	v_pk_fma_f32 v[138:139], v[114:115], v[114:115], v[138:139]
	v_add_f32_e32 v214, v138, v139
	v_add_u32_e32 v207, 0x8000, v207
	v_mov_b32_e32 v215, v214
	s_nop 1
	v_permlane16_swap_b32_e32 v214, v215
	s_nop 0
	v_add_f32_e32 v214, v214, v215
	v_mov_b32_e32 v215, v214
	s_nop 1
	v_permlane32_swap_b32_e32 v214, v215
	s_nop 0
	v_add_f32_e32 v214, v214, v215
	s_and_saveexec_b64 s[28:29], s[4:5]
	global_store_dword v210, v214, s[16:17]
	s_mov_b64 exec, s[28:29]
	global_load_dwordx4 v[146:149], v206, s[10:11]
	global_load_dwordx4 v[150:153], v206, s[10:11] offset:256
	s_waitcnt vmcnt(15)
	v_lshlrev_b32_e32 v202, 16, v154
	v_and_b32_e32 v203, 0xffff0000, v154
	v_lshlrev_b32_e32 v204, 16, v155
	v_and_b32_e32 v205, 0xffff0000, v155
	v_pk_add_f32 v[108:109], v[108:109], v[202:203]
	v_pk_add_f32 v[110:111], v[110:111], v[204:205]
	v_lshlrev_b32_e32 v202, 16, v156
	v_and_b32_e32 v203, 0xffff0000, v156
	v_lshlrev_b32_e32 v204, 16, v157
	v_and_b32_e32 v205, 0xffff0000, v157
	v_pk_add_f32 v[104:105], v[104:105], v[202:203]
	v_pk_add_f32 v[106:107], v[106:107], v[204:205]
	v_cvt_pk_bf16_f32 v154, v108, v109
	v_cvt_pk_bf16_f32 v155, v110, v111
	v_cvt_pk_bf16_f32 v156, v104, v105
	v_cvt_pk_bf16_f32 v157, v106, v107
	v_pk_mul_f32 v[138:139], v[108:109], v[108:109]
	global_store_dwordx4 v207, v[154:157], s[10:11]
	v_pk_fma_f32 v[138:139], v[110:111], v[110:111], v[138:139]
	v_pk_fma_f32 v[138:139], v[104:105], v[104:105], v[138:139]
	v_pk_fma_f32 v[138:139], v[106:107], v[106:107], v[138:139]
	v_lshlrev_b32_e32 v202, 16, v158
	v_and_b32_e32 v203, 0xffff0000, v158
	v_lshlrev_b32_e32 v204, 16, v159
	v_and_b32_e32 v205, 0xffff0000, v159
	v_pk_add_f32 v[100:101], v[100:101], v[202:203]
	v_pk_add_f32 v[102:103], v[102:103], v[204:205]
	v_lshlrev_b32_e32 v202, 16, v160
	v_and_b32_e32 v203, 0xffff0000, v160
	v_lshlrev_b32_e32 v204, 16, v161
	v_and_b32_e32 v205, 0xffff0000, v161
	v_pk_add_f32 v[96:97], v[96:97], v[202:203]
	v_pk_add_f32 v[98:99], v[98:99], v[204:205]
	v_cvt_pk_bf16_f32 v158, v100, v101
	v_cvt_pk_bf16_f32 v159, v102, v103
	v_cvt_pk_bf16_f32 v160, v96, v97
	v_cvt_pk_bf16_f32 v161, v98, v99
	v_pk_fma_f32 v[138:139], v[100:101], v[100:101], v[138:139]
	global_store_dwordx4 v207, v[158:161], s[10:11] offset:256
	v_pk_fma_f32 v[138:139], v[102:103], v[102:103], v[138:139]
	v_pk_fma_f32 v[138:139], v[96:97], v[96:97], v[138:139]
	v_pk_fma_f32 v[138:139], v[98:99], v[98:99], v[138:139]
	v_add_f32_e32 v214, v138, v139
	v_add_u32_e32 v207, 0x8000, v207
	v_mov_b32_e32 v215, v214
	s_nop 1
	v_permlane16_swap_b32_e32 v214, v215
	s_nop 0
	v_add_f32_e32 v214, v214, v215
	v_mov_b32_e32 v215, v214
	s_nop 1
	v_permlane32_swap_b32_e32 v214, v215
	s_nop 0
	v_add_f32_e32 v214, v214, v215
	s_and_saveexec_b64 s[28:29], s[4:5]
	global_store_dword v210, v214, s[16:17] offset:1024
	s_mov_b64 exec, s[28:29]
	s_waitcnt vmcnt(16)
	v_lshlrev_b32_e32 v202, 16, v162
	v_and_b32_e32 v203, 0xffff0000, v162
	v_lshlrev_b32_e32 v204, 16, v163
	v_and_b32_e32 v205, 0xffff0000, v163
	v_pk_add_f32 v[92:93], v[92:93], v[202:203]
	v_pk_add_f32 v[94:95], v[94:95], v[204:205]
	v_lshlrev_b32_e32 v202, 16, v164
	v_and_b32_e32 v203, 0xffff0000, v164
	v_lshlrev_b32_e32 v204, 16, v165
	v_and_b32_e32 v205, 0xffff0000, v165
	v_pk_add_f32 v[88:89], v[88:89], v[202:203]
	v_pk_add_f32 v[90:91], v[90:91], v[204:205]
	v_cvt_pk_bf16_f32 v162, v92, v93
	v_cvt_pk_bf16_f32 v163, v94, v95
	v_cvt_pk_bf16_f32 v164, v88, v89
	v_cvt_pk_bf16_f32 v165, v90, v91
	v_pk_mul_f32 v[138:139], v[92:93], v[92:93]
	global_store_dwordx4 v207, v[162:165], s[10:11]
	v_pk_fma_f32 v[138:139], v[94:95], v[94:95], v[138:139]
	v_pk_fma_f32 v[138:139], v[88:89], v[88:89], v[138:139]
	v_pk_fma_f32 v[138:139], v[90:91], v[90:91], v[138:139]
	v_lshlrev_b32_e32 v202, 16, v166
	v_and_b32_e32 v203, 0xffff0000, v166
	v_lshlrev_b32_e32 v204, 16, v167
	v_and_b32_e32 v205, 0xffff0000, v167
	v_pk_add_f32 v[84:85], v[84:85], v[202:203]
	v_pk_add_f32 v[86:87], v[86:87], v[204:205]
	v_lshlrev_b32_e32 v202, 16, v168
	v_and_b32_e32 v203, 0xffff0000, v168
	v_lshlrev_b32_e32 v204, 16, v169
	v_and_b32_e32 v205, 0xffff0000, v169
	v_pk_add_f32 v[80:81], v[80:81], v[202:203]
	v_pk_add_f32 v[82:83], v[82:83], v[204:205]
	v_cvt_pk_bf16_f32 v166, v84, v85
	v_cvt_pk_bf16_f32 v167, v86, v87
	v_cvt_pk_bf16_f32 v168, v80, v81
	v_cvt_pk_bf16_f32 v169, v82, v83
	v_pk_fma_f32 v[138:139], v[84:85], v[84:85], v[138:139]
	global_store_dwordx4 v207, v[166:169], s[10:11] offset:256
	v_pk_fma_f32 v[138:139], v[86:87], v[86:87], v[138:139]
	v_pk_fma_f32 v[138:139], v[80:81], v[80:81], v[138:139]
	v_pk_fma_f32 v[138:139], v[82:83], v[82:83], v[138:139]
	v_add_f32_e32 v214, v138, v139
	v_add_u32_e32 v207, 0x8000, v207
	v_mov_b32_e32 v215, v214
	s_nop 1
	v_permlane16_swap_b32_e32 v214, v215
	s_nop 0
	v_add_f32_e32 v214, v214, v215
	v_mov_b32_e32 v215, v214
	s_nop 1
	v_permlane32_swap_b32_e32 v214, v215
	s_nop 0
	v_add_f32_e32 v214, v214, v215
	s_and_saveexec_b64 s[28:29], s[4:5]
	global_store_dword v210, v214, s[16:17] offset:2048
	s_mov_b64 exec, s[28:29]
	s_waitcnt vmcnt(17)
	v_lshlrev_b32_e32 v202, 16, v170
	v_and_b32_e32 v203, 0xffff0000, v170
	v_lshlrev_b32_e32 v204, 16, v171
	v_and_b32_e32 v205, 0xffff0000, v171
	v_pk_add_f32 v[76:77], v[76:77], v[202:203]
	v_pk_add_f32 v[78:79], v[78:79], v[204:205]
	v_lshlrev_b32_e32 v202, 16, v172
	v_and_b32_e32 v203, 0xffff0000, v172
	v_lshlrev_b32_e32 v204, 16, v173
	v_and_b32_e32 v205, 0xffff0000, v173
	v_pk_add_f32 v[72:73], v[72:73], v[202:203]
	v_pk_add_f32 v[74:75], v[74:75], v[204:205]
	v_cvt_pk_bf16_f32 v170, v76, v77
	v_cvt_pk_bf16_f32 v171, v78, v79
	v_cvt_pk_bf16_f32 v172, v72, v73
	v_cvt_pk_bf16_f32 v173, v74, v75
	v_pk_mul_f32 v[138:139], v[76:77], v[76:77]
	global_store_dwordx4 v207, v[170:173], s[10:11]
	v_pk_fma_f32 v[138:139], v[78:79], v[78:79], v[138:139]
	v_pk_fma_f32 v[138:139], v[72:73], v[72:73], v[138:139]
	v_pk_fma_f32 v[138:139], v[74:75], v[74:75], v[138:139]
	v_lshlrev_b32_e32 v202, 16, v174
	v_and_b32_e32 v203, 0xffff0000, v174
	v_lshlrev_b32_e32 v204, 16, v175
	v_and_b32_e32 v205, 0xffff0000, v175
	v_pk_add_f32 v[68:69], v[68:69], v[202:203]
	v_pk_add_f32 v[70:71], v[70:71], v[204:205]
	v_lshlrev_b32_e32 v202, 16, v176
	v_and_b32_e32 v203, 0xffff0000, v176
	v_lshlrev_b32_e32 v204, 16, v177
	v_and_b32_e32 v205, 0xffff0000, v177
	v_pk_add_f32 v[64:65], v[64:65], v[202:203]
	v_pk_add_f32 v[66:67], v[66:67], v[204:205]
	v_cvt_pk_bf16_f32 v174, v68, v69
	v_cvt_pk_bf16_f32 v175, v70, v71
	v_cvt_pk_bf16_f32 v176, v64, v65
	v_cvt_pk_bf16_f32 v177, v66, v67
	v_pk_fma_f32 v[138:139], v[68:69], v[68:69], v[138:139]
	global_store_dwordx4 v207, v[174:177], s[10:11] offset:256
	v_pk_fma_f32 v[138:139], v[70:71], v[70:71], v[138:139]
	v_pk_fma_f32 v[138:139], v[64:65], v[64:65], v[138:139]
	v_pk_fma_f32 v[138:139], v[66:67], v[66:67], v[138:139]
	v_add_f32_e32 v214, v138, v139
	v_add_u32_e32 v207, 0x28000, v207
	v_mov_b32_e32 v215, v214
	s_nop 1
	v_permlane16_swap_b32_e32 v214, v215
	s_nop 0
	v_add_f32_e32 v214, v214, v215
	v_mov_b32_e32 v215, v214
	s_nop 1
	v_permlane32_swap_b32_e32 v214, v215
	s_nop 0
	v_add_f32_e32 v214, v214, v215
	s_and_saveexec_b64 s[28:29], s[4:5]
	global_store_dword v210, v214, s[16:17] offset:3072
	s_mov_b64 exec, s[28:29]
	v_add_u32_e32 v210, 0x2000, v210
	s_waitcnt vmcnt(18)
	v_lshlrev_b32_e32 v202, 16, v178
	v_and_b32_e32 v203, 0xffff0000, v178
	v_lshlrev_b32_e32 v204, 16, v179
	v_and_b32_e32 v205, 0xffff0000, v179
	v_pk_add_f32 v[60:61], v[60:61], v[202:203]
	v_pk_add_f32 v[62:63], v[62:63], v[204:205]
	v_lshlrev_b32_e32 v202, 16, v180
	v_and_b32_e32 v203, 0xffff0000, v180
	v_lshlrev_b32_e32 v204, 16, v181
	v_and_b32_e32 v205, 0xffff0000, v181
	v_pk_add_f32 v[56:57], v[56:57], v[202:203]
	v_pk_add_f32 v[58:59], v[58:59], v[204:205]
	v_cvt_pk_bf16_f32 v178, v60, v61
	v_cvt_pk_bf16_f32 v179, v62, v63
	v_cvt_pk_bf16_f32 v180, v56, v57
	v_cvt_pk_bf16_f32 v181, v58, v59
	v_pk_mul_f32 v[138:139], v[60:61], v[60:61]
	global_store_dwordx4 v207, v[178:181], s[10:11]
	v_pk_fma_f32 v[138:139], v[62:63], v[62:63], v[138:139]
	v_pk_fma_f32 v[138:139], v[56:57], v[56:57], v[138:139]
	v_pk_fma_f32 v[138:139], v[58:59], v[58:59], v[138:139]
	v_lshlrev_b32_e32 v202, 16, v182
	v_and_b32_e32 v203, 0xffff0000, v182
	v_lshlrev_b32_e32 v204, 16, v183
	v_and_b32_e32 v205, 0xffff0000, v183
	v_pk_add_f32 v[52:53], v[52:53], v[202:203]
	v_pk_add_f32 v[54:55], v[54:55], v[204:205]
	v_lshlrev_b32_e32 v202, 16, v184
	v_and_b32_e32 v203, 0xffff0000, v184
	v_lshlrev_b32_e32 v204, 16, v185
	v_and_b32_e32 v205, 0xffff0000, v185
	v_pk_add_f32 v[48:49], v[48:49], v[202:203]
	v_pk_add_f32 v[50:51], v[50:51], v[204:205]
	v_cvt_pk_bf16_f32 v182, v52, v53
	v_cvt_pk_bf16_f32 v183, v54, v55
	v_cvt_pk_bf16_f32 v184, v48, v49
	v_cvt_pk_bf16_f32 v185, v50, v51
	v_pk_fma_f32 v[138:139], v[52:53], v[52:53], v[138:139]
	global_store_dwordx4 v207, v[182:185], s[10:11] offset:256
	v_pk_fma_f32 v[138:139], v[54:55], v[54:55], v[138:139]
	v_pk_fma_f32 v[138:139], v[48:49], v[48:49], v[138:139]
	v_pk_fma_f32 v[138:139], v[50:51], v[50:51], v[138:139]
	v_add_f32_e32 v214, v138, v139
	v_add_u32_e32 v207, 0x8000, v207
	v_mov_b32_e32 v215, v214
	s_nop 1
	v_permlane16_swap_b32_e32 v214, v215
	s_nop 0
	v_add_f32_e32 v214, v214, v215
	v_mov_b32_e32 v215, v214
	s_nop 1
	v_permlane32_swap_b32_e32 v214, v215
	s_nop 0
	v_add_f32_e32 v214, v214, v215
	s_and_saveexec_b64 s[28:29], s[4:5]
	global_store_dword v210, v214, s[16:17]
	s_mov_b64 exec, s[28:29]
	s_waitcnt vmcnt(19)
	v_lshlrev_b32_e32 v202, 16, v186
	v_and_b32_e32 v203, 0xffff0000, v186
	v_lshlrev_b32_e32 v204, 16, v187
	v_and_b32_e32 v205, 0xffff0000, v187
	v_pk_add_f32 v[44:45], v[44:45], v[202:203]
	v_pk_add_f32 v[46:47], v[46:47], v[204:205]
	v_lshlrev_b32_e32 v202, 16, v188
	v_and_b32_e32 v203, 0xffff0000, v188
	v_lshlrev_b32_e32 v204, 16, v189
	v_and_b32_e32 v205, 0xffff0000, v189
	v_pk_add_f32 v[40:41], v[40:41], v[202:203]
	v_pk_add_f32 v[42:43], v[42:43], v[204:205]
	v_cvt_pk_bf16_f32 v186, v44, v45
	v_cvt_pk_bf16_f32 v187, v46, v47
	v_cvt_pk_bf16_f32 v188, v40, v41
	v_cvt_pk_bf16_f32 v189, v42, v43
	v_pk_mul_f32 v[138:139], v[44:45], v[44:45]
	global_store_dwordx4 v207, v[186:189], s[10:11]
	v_pk_fma_f32 v[138:139], v[46:47], v[46:47], v[138:139]
	v_pk_fma_f32 v[138:139], v[40:41], v[40:41], v[138:139]
	v_pk_fma_f32 v[138:139], v[42:43], v[42:43], v[138:139]
	v_lshlrev_b32_e32 v202, 16, v190
	v_and_b32_e32 v203, 0xffff0000, v190
	v_lshlrev_b32_e32 v204, 16, v191
	v_and_b32_e32 v205, 0xffff0000, v191
	v_pk_add_f32 v[36:37], v[36:37], v[202:203]
	v_pk_add_f32 v[38:39], v[38:39], v[204:205]
	v_lshlrev_b32_e32 v202, 16, v192
	v_and_b32_e32 v203, 0xffff0000, v192
	v_lshlrev_b32_e32 v204, 16, v193
	v_and_b32_e32 v205, 0xffff0000, v193
	v_pk_add_f32 v[32:33], v[32:33], v[202:203]
	v_pk_add_f32 v[34:35], v[34:35], v[204:205]
	v_cvt_pk_bf16_f32 v190, v36, v37
	v_cvt_pk_bf16_f32 v191, v38, v39
	v_cvt_pk_bf16_f32 v192, v32, v33
	v_cvt_pk_bf16_f32 v193, v34, v35
	v_pk_fma_f32 v[138:139], v[36:37], v[36:37], v[138:139]
	global_store_dwordx4 v207, v[190:193], s[10:11] offset:256
	v_pk_fma_f32 v[138:139], v[38:39], v[38:39], v[138:139]
	v_pk_fma_f32 v[138:139], v[32:33], v[32:33], v[138:139]
	v_pk_fma_f32 v[138:139], v[34:35], v[34:35], v[138:139]
	v_add_f32_e32 v214, v138, v139
	v_add_u32_e32 v207, 0x8000, v207
	v_mov_b32_e32 v215, v214
	s_nop 1
	v_permlane16_swap_b32_e32 v214, v215
	s_nop 0
	v_add_f32_e32 v214, v214, v215
	v_mov_b32_e32 v215, v214
	s_nop 1
	v_permlane32_swap_b32_e32 v214, v215
	s_nop 0
	v_add_f32_e32 v214, v214, v215
	s_and_saveexec_b64 s[28:29], s[4:5]
	global_store_dword v210, v214, s[16:17] offset:1024
	s_mov_b64 exec, s[28:29]
	s_waitcnt vmcnt(20)
	v_lshlrev_b32_e32 v202, 16, v194
	v_and_b32_e32 v203, 0xffff0000, v194
	v_lshlrev_b32_e32 v204, 16, v195
	v_and_b32_e32 v205, 0xffff0000, v195
	v_pk_add_f32 v[28:29], v[28:29], v[202:203]
	v_pk_add_f32 v[30:31], v[30:31], v[204:205]
	v_lshlrev_b32_e32 v202, 16, v196
	v_and_b32_e32 v203, 0xffff0000, v196
	v_lshlrev_b32_e32 v204, 16, v197
	v_and_b32_e32 v205, 0xffff0000, v197
	v_pk_add_f32 v[24:25], v[24:25], v[202:203]
	v_pk_add_f32 v[26:27], v[26:27], v[204:205]
	v_cvt_pk_bf16_f32 v194, v28, v29
	v_cvt_pk_bf16_f32 v195, v30, v31
	v_cvt_pk_bf16_f32 v196, v24, v25
	v_cvt_pk_bf16_f32 v197, v26, v27
	v_pk_mul_f32 v[138:139], v[28:29], v[28:29]
	global_store_dwordx4 v207, v[194:197], s[10:11]
	v_pk_fma_f32 v[138:139], v[30:31], v[30:31], v[138:139]
	v_pk_fma_f32 v[138:139], v[24:25], v[24:25], v[138:139]
	v_pk_fma_f32 v[138:139], v[26:27], v[26:27], v[138:139]
	v_lshlrev_b32_e32 v202, 16, v198
	v_and_b32_e32 v203, 0xffff0000, v198
	v_lshlrev_b32_e32 v204, 16, v199
	v_and_b32_e32 v205, 0xffff0000, v199
	v_pk_add_f32 v[20:21], v[20:21], v[202:203]
	v_pk_add_f32 v[22:23], v[22:23], v[204:205]
	v_lshlrev_b32_e32 v202, 16, v200
	v_and_b32_e32 v203, 0xffff0000, v200
	v_lshlrev_b32_e32 v204, 16, v201
	v_and_b32_e32 v205, 0xffff0000, v201
	v_pk_add_f32 v[16:17], v[16:17], v[202:203]
	v_pk_add_f32 v[18:19], v[18:19], v[204:205]
	v_cvt_pk_bf16_f32 v198, v20, v21
	v_cvt_pk_bf16_f32 v199, v22, v23
	v_cvt_pk_bf16_f32 v200, v16, v17
	v_cvt_pk_bf16_f32 v201, v18, v19
	v_pk_fma_f32 v[138:139], v[20:21], v[20:21], v[138:139]
	global_store_dwordx4 v207, v[198:201], s[10:11] offset:256
	v_pk_fma_f32 v[138:139], v[22:23], v[22:23], v[138:139]
	v_pk_fma_f32 v[138:139], v[16:17], v[16:17], v[138:139]
	v_pk_fma_f32 v[138:139], v[18:19], v[18:19], v[138:139]
	v_add_f32_e32 v214, v138, v139
	v_add_u32_e32 v207, 0x8000, v207
	v_mov_b32_e32 v215, v214
	s_nop 1
	v_permlane16_swap_b32_e32 v214, v215
	s_nop 0
	v_add_f32_e32 v214, v214, v215
	v_mov_b32_e32 v215, v214
	s_nop 1
	v_permlane32_swap_b32_e32 v214, v215
	s_nop 0
	v_add_f32_e32 v214, v214, v215
	s_and_saveexec_b64 s[28:29], s[4:5]
	global_store_dword v210, v214, s[16:17] offset:2048
	s_mov_b64 exec, s[28:29]
	s_waitcnt vmcnt(18)
	v_lshlrev_b32_e32 v202, 16, v146
	v_and_b32_e32 v203, 0xffff0000, v146
	v_lshlrev_b32_e32 v204, 16, v147
	v_and_b32_e32 v205, 0xffff0000, v147
	v_pk_add_f32 v[12:13], v[12:13], v[202:203]
	v_pk_add_f32 v[14:15], v[14:15], v[204:205]
	v_lshlrev_b32_e32 v202, 16, v148
	v_and_b32_e32 v203, 0xffff0000, v148
	v_lshlrev_b32_e32 v204, 16, v149
	v_and_b32_e32 v205, 0xffff0000, v149
	v_pk_add_f32 v[8:9], v[8:9], v[202:203]
	v_pk_add_f32 v[10:11], v[10:11], v[204:205]
	v_cvt_pk_bf16_f32 v146, v12, v13
	v_cvt_pk_bf16_f32 v147, v14, v15
	v_cvt_pk_bf16_f32 v148, v8, v9
	v_cvt_pk_bf16_f32 v149, v10, v11
	v_pk_mul_f32 v[138:139], v[12:13], v[12:13]
	global_store_dwordx4 v207, v[146:149], s[10:11]
	v_pk_fma_f32 v[138:139], v[14:15], v[14:15], v[138:139]
	v_pk_fma_f32 v[138:139], v[8:9], v[8:9], v[138:139]
	v_pk_fma_f32 v[138:139], v[10:11], v[10:11], v[138:139]
	v_lshlrev_b32_e32 v202, 16, v150
	v_and_b32_e32 v203, 0xffff0000, v150
	v_lshlrev_b32_e32 v204, 16, v151
	v_and_b32_e32 v205, 0xffff0000, v151
	v_pk_add_f32 v[4:5], v[4:5], v[202:203]
	v_pk_add_f32 v[6:7], v[6:7], v[204:205]
	v_lshlrev_b32_e32 v202, 16, v152
	v_and_b32_e32 v203, 0xffff0000, v152
	v_lshlrev_b32_e32 v204, 16, v153
	v_and_b32_e32 v205, 0xffff0000, v153
	v_pk_add_f32 v[0:1], v[0:1], v[202:203]
	v_pk_add_f32 v[2:3], v[2:3], v[204:205]
	v_cvt_pk_bf16_f32 v150, v4, v5
	v_cvt_pk_bf16_f32 v151, v6, v7
	v_cvt_pk_bf16_f32 v152, v0, v1
	v_cvt_pk_bf16_f32 v153, v2, v3
	v_pk_fma_f32 v[138:139], v[4:5], v[4:5], v[138:139]
	global_store_dwordx4 v207, v[150:153], s[10:11] offset:256
	v_pk_fma_f32 v[138:139], v[6:7], v[6:7], v[138:139]
	v_pk_fma_f32 v[138:139], v[0:1], v[0:1], v[138:139]
	v_pk_fma_f32 v[138:139], v[2:3], v[2:3], v[138:139]
	v_add_f32_e32 v214, v138, v139
	v_add_u32_e32 v207, 0x8000, v207
	v_mov_b32_e32 v215, v214
	s_nop 1
	v_permlane16_swap_b32_e32 v214, v215
	s_nop 0
	v_add_f32_e32 v214, v214, v215
	v_mov_b32_e32 v215, v214
	s_nop 1
	v_permlane32_swap_b32_e32 v214, v215
	s_nop 0
	v_add_f32_e32 v214, v214, v215
	s_and_saveexec_b64 s[28:29], s[4:5]
	global_store_dword v210, v214, s[16:17] offset:3072
	s_mov_b64 exec, s[28:29]
	s_branch .LBB0_768

.LBB0_823:
	s_add_u32 s26, s24, 0xfffc0080
	s_addc_u32 s27, s25, -1
	s_add_i32 s65, 0, 0x10000
	v_add_u32_e32 v154, s65, v143
	ds_read_b128 v[138:141], v154
	ds_read_b128 v[146:149], v154 offset:1024
	ds_read_b128 v[150:153], v154 offset:2048
	ds_read_b128 v[154:157], v154 offset:3072
	s_cmp_eq_u32 s51, 12
	s_cselect_b32 s29, s19, s27
	s_cselect_b32 s28, s38, s26
	s_cselect_b32 s27, s17, s50
	s_cselect_b32 s26, s39, s46
	s_add_i32 m0, s58, 0xc000
	ds_read_b128 v[158:161], v145
	ds_read_b128 v[162:165], v145 offset:1024
	ds_read_b128 v[166:169], v145 offset:2048
	ds_read_b128 v[170:173], v145 offset:3072
	ds_read_b128 v[174:177], v145 offset:4096
	ds_read_b128 v[178:181], v145 offset:5120
	ds_read_b128 v[182:185], v145 offset:6144
	global_load_lds_dwordx4 v134, s[24:25]
	s_add_i32 m0, s58, 0xe000
	ds_read_b128 v[186:189], v145 offset:7168
	global_load_lds_dwordx4 v136, s[24:25]
	s_waitcnt lgkmcnt(8)
	s_barrier
	s_waitcnt lgkmcnt(0)
	v_mfma_f32_16x16x32_bf16 v[124:127], v[138:141], v[158:161], v[124:127]
	v_mfma_f32_16x16x32_bf16 v[120:123], v[150:153], v[158:161], v[120:123]
	v_mfma_f32_16x16x32_bf16 v[108:111], v[138:141], v[166:169], v[108:111]
	v_mfma_f32_16x16x32_bf16 v[104:107], v[150:153], v[166:169], v[104:107]
	v_mfma_f32_16x16x32_bf16 v[92:95], v[138:141], v[174:177], v[92:95]
	v_mfma_f32_16x16x32_bf16 v[88:91], v[150:153], v[174:177], v[88:91]
	v_mfma_f32_16x16x32_bf16 v[76:79], v[138:141], v[182:185], v[76:79]
	v_mfma_f32_16x16x32_bf16 v[72:75], v[150:153], v[182:185], v[72:75]
	v_mfma_f32_16x16x32_bf16 v[124:127], v[146:149], v[162:165], v[124:127]
	v_mfma_f32_16x16x32_bf16 v[120:123], v[154:157], v[162:165], v[120:123]
	v_mfma_f32_16x16x32_bf16 v[108:111], v[146:149], v[170:173], v[108:111]
	v_mfma_f32_16x16x32_bf16 v[104:107], v[154:157], v[170:173], v[104:107]
	v_mfma_f32_16x16x32_bf16 v[92:95], v[146:149], v[178:181], v[92:95]
	v_mfma_f32_16x16x32_bf16 v[88:91], v[154:157], v[178:181], v[88:91]
	v_mfma_f32_16x16x32_bf16 v[76:79], v[146:149], v[186:189], v[76:79]
	v_mfma_f32_16x16x32_bf16 v[72:75], v[154:157], v[186:189], v[72:75]
	s_barrier
	s_add_i32 s68, 0, 0x14000
	s_add_i32 s65, s65, s57
	v_add_u32_e32 v202, s68, v143
	s_add_u32 s98, s26, s40
	s_addc_u32 s99, s27, s41
	s_mov_b32 m0, s65
	ds_read_b128 v[190:193], v202
	ds_read_b128 v[194:197], v202 offset:1024
	ds_read_b128 v[198:201], v202 offset:2048
	global_load_lds_dwordx4 v208, s[26:27]
	s_add_i32 m0, s65, 0x2000
	ds_read_b128 v[202:205], v202 offset:3072
	global_load_lds_dwordx4 v128, s[26:27]
	s_barrier
	s_waitcnt lgkmcnt(0)
	v_mfma_f32_16x16x32_bf16 v[116:119], v[190:193], v[158:161], v[116:119]
	v_mfma_f32_16x16x32_bf16 v[112:115], v[198:201], v[158:161], v[112:115]
	v_mfma_f32_16x16x32_bf16 v[100:103], v[190:193], v[166:169], v[100:103]
	v_mfma_f32_16x16x32_bf16 v[96:99], v[198:201], v[166:169], v[96:99]
	v_mfma_f32_16x16x32_bf16 v[84:87], v[190:193], v[174:177], v[84:87]
	v_mfma_f32_16x16x32_bf16 v[80:83], v[198:201], v[174:177], v[80:83]
	v_mfma_f32_16x16x32_bf16 v[68:71], v[190:193], v[182:185], v[68:71]
	v_mfma_f32_16x16x32_bf16 v[64:67], v[198:201], v[182:185], v[64:67]
	v_mfma_f32_16x16x32_bf16 v[116:119], v[194:197], v[162:165], v[116:119]
	v_mfma_f32_16x16x32_bf16 v[112:115], v[202:205], v[162:165], v[112:115]
	v_mfma_f32_16x16x32_bf16 v[100:103], v[194:197], v[170:173], v[100:103]
	v_mfma_f32_16x16x32_bf16 v[96:99], v[202:205], v[170:173], v[96:99]
	v_mfma_f32_16x16x32_bf16 v[84:87], v[194:197], v[178:181], v[84:87]
	v_mfma_f32_16x16x32_bf16 v[80:83], v[202:205], v[178:181], v[80:83]
	v_mfma_f32_16x16x32_bf16 v[68:71], v[194:197], v[186:189], v[68:71]
	v_mfma_f32_16x16x32_bf16 v[64:67], v[202:205], v[186:189], v[64:67]
	s_mov_b32 m0, s58
	s_add_u32 s100, s28, s40
	s_addc_u32 s101, s29, s41
	s_barrier
	ds_read_b128 v[158:161], v145 offset:16384
	ds_read_b128 v[162:165], v145 offset:17408
	ds_read_b128 v[166:169], v145 offset:18432
	ds_read_b128 v[170:173], v145 offset:19456
	ds_read_b128 v[174:177], v145 offset:20480
	ds_read_b128 v[178:181], v145 offset:21504
	ds_read_b128 v[182:185], v145 offset:22528
	global_load_lds_dwordx4 v132, s[28:29]
	s_mov_b32 m0, s59
	ds_read_b128 v[186:189], v145 offset:23552
	global_load_lds_dwordx4 v130, s[28:29]
	s_barrier
	s_waitcnt lgkmcnt(0)
	v_mfma_f32_16x16x32_bf16 v[60:63], v[138:141], v[158:161], v[60:63]
	v_mfma_f32_16x16x32_bf16 v[56:59], v[150:153], v[158:161], v[56:59]
	v_mfma_f32_16x16x32_bf16 v[44:47], v[138:141], v[166:169], v[44:47]
	v_mfma_f32_16x16x32_bf16 v[40:43], v[150:153], v[166:169], v[40:43]
	v_mfma_f32_16x16x32_bf16 v[28:31], v[138:141], v[174:177], v[28:31]
	v_mfma_f32_16x16x32_bf16 v[24:27], v[150:153], v[174:177], v[24:27]
	v_mfma_f32_16x16x32_bf16 v[12:15], v[138:141], v[182:185], v[12:15]
	v_mfma_f32_16x16x32_bf16 v[8:11], v[150:153], v[182:185], v[8:11]
	v_mfma_f32_16x16x32_bf16 v[60:63], v[146:149], v[162:165], v[60:63]
	v_mfma_f32_16x16x32_bf16 v[56:59], v[154:157], v[162:165], v[56:59]
	v_mfma_f32_16x16x32_bf16 v[44:47], v[146:149], v[170:173], v[44:47]
	v_mfma_f32_16x16x32_bf16 v[40:43], v[154:157], v[170:173], v[40:43]
	v_mfma_f32_16x16x32_bf16 v[28:31], v[146:149], v[178:181], v[28:31]
	v_mfma_f32_16x16x32_bf16 v[24:27], v[154:157], v[178:181], v[24:27]
	v_mfma_f32_16x16x32_bf16 v[12:15], v[146:149], v[186:189], v[12:15]
	v_mfma_f32_16x16x32_bf16 v[8:11], v[154:157], v[186:189], v[8:11]
	s_barrier
	s_add_u32 s66, s26, 0x40000
	s_addc_u32 s67, s27, 0
	s_add_i32 s65, s68, s57
	s_mov_b32 m0, s65
	s_nop 0
	global_load_lds_dwordx4 v208, s[66:67]
	s_add_i32 m0, s65, 0x2000
	s_nop 0
	global_load_lds_dwordx4 v128, s[66:67]
	s_waitcnt vmcnt(6)
	s_barrier
	v_mfma_f32_16x16x32_bf16 v[52:55], v[190:193], v[158:161], v[52:55]
	v_mfma_f32_16x16x32_bf16 v[48:51], v[198:201], v[158:161], v[48:51]
	v_mfma_f32_16x16x32_bf16 v[36:39], v[190:193], v[166:169], v[36:39]
	v_mfma_f32_16x16x32_bf16 v[32:35], v[198:201], v[166:169], v[32:35]
	v_mfma_f32_16x16x32_bf16 v[20:23], v[190:193], v[174:177], v[20:23]
	v_mfma_f32_16x16x32_bf16 v[16:19], v[198:201], v[174:177], v[16:19]
	v_mfma_f32_16x16x32_bf16 v[4:7], v[190:193], v[182:185], v[4:7]
	v_mfma_f32_16x16x32_bf16 v[0:3], v[198:201], v[182:185], v[0:3]
	v_mfma_f32_16x16x32_bf16 v[52:55], v[194:197], v[162:165], v[52:55]
	v_mfma_f32_16x16x32_bf16 v[48:51], v[202:205], v[162:165], v[48:51]
	v_mfma_f32_16x16x32_bf16 v[36:39], v[194:197], v[170:173], v[36:39]
	v_mfma_f32_16x16x32_bf16 v[32:35], v[202:205], v[170:173], v[32:35]
	v_mfma_f32_16x16x32_bf16 v[20:23], v[194:197], v[178:181], v[20:23]
	v_mfma_f32_16x16x32_bf16 v[16:19], v[202:205], v[178:181], v[16:19]
	v_mfma_f32_16x16x32_bf16 v[4:7], v[194:197], v[186:189], v[4:7]
	v_mfma_f32_16x16x32_bf16 v[0:3], v[202:205], v[186:189], v[0:3]
	s_add_i32 s65, 0, 0x18000
	v_add_u32_e32 v154, s65, v143
	s_barrier
	ds_read_b128 v[138:141], v154
	ds_read_b128 v[146:149], v154 offset:1024
	ds_read_b128 v[150:153], v154 offset:2048
	ds_read_b128 v[154:157], v154 offset:3072
	s_add_u32 s28, s28, 0x40000
	s_addc_u32 s29, s29, 0
	s_mov_b32 m0, s60
	ds_read_b128 v[158:161], v145 offset:32768
	ds_read_b128 v[162:165], v145 offset:33792
	ds_read_b128 v[166:169], v145 offset:34816
	ds_read_b128 v[170:173], v145 offset:35840
	ds_read_b128 v[174:177], v145 offset:36864
	ds_read_b128 v[178:181], v145 offset:37888
	ds_read_b128 v[182:185], v145 offset:38912
	global_load_lds_dwordx4 v132, s[28:29]
	s_mov_b32 m0, s61
	ds_read_b128 v[186:189], v145 offset:39936
	global_load_lds_dwordx4 v130, s[28:29]
	s_waitcnt lgkmcnt(8)
	s_barrier
	s_waitcnt lgkmcnt(0)
	v_mfma_f32_16x16x32_bf16 v[124:127], v[138:141], v[158:161], v[124:127]
	v_mfma_f32_16x16x32_bf16 v[120:123], v[150:153], v[158:161], v[120:123]
	v_mfma_f32_16x16x32_bf16 v[108:111], v[138:141], v[166:169], v[108:111]
	v_mfma_f32_16x16x32_bf16 v[104:107], v[150:153], v[166:169], v[104:107]
	v_mfma_f32_16x16x32_bf16 v[92:95], v[138:141], v[174:177], v[92:95]
	v_mfma_f32_16x16x32_bf16 v[88:91], v[150:153], v[174:177], v[88:91]
	v_mfma_f32_16x16x32_bf16 v[76:79], v[138:141], v[182:185], v[76:79]
	v_mfma_f32_16x16x32_bf16 v[72:75], v[150:153], v[182:185], v[72:75]
	v_mfma_f32_16x16x32_bf16 v[124:127], v[146:149], v[162:165], v[124:127]
	v_mfma_f32_16x16x32_bf16 v[120:123], v[154:157], v[162:165], v[120:123]
	v_mfma_f32_16x16x32_bf16 v[108:111], v[146:149], v[170:173], v[108:111]
	v_mfma_f32_16x16x32_bf16 v[104:107], v[154:157], v[170:173], v[104:107]
	v_mfma_f32_16x16x32_bf16 v[92:95], v[146:149], v[178:181], v[92:95]
	v_mfma_f32_16x16x32_bf16 v[88:91], v[154:157], v[178:181], v[88:91]
	v_mfma_f32_16x16x32_bf16 v[76:79], v[146:149], v[186:189], v[76:79]
	v_mfma_f32_16x16x32_bf16 v[72:75], v[154:157], v[186:189], v[72:75]
	s_barrier
	s_add_i32 s28, 0, 0x1c000
	s_add_i32 s29, s65, s57
	v_add_u32_e32 v202, s28, v143
	s_mov_b32 m0, s29
	ds_read_b128 v[190:193], v202
	ds_read_b128 v[194:197], v202 offset:1024
	ds_read_b128 v[198:201], v202 offset:2048
	global_load_lds_dwordx4 v208, s[98:99]
	s_add_i32 m0, s29, 0x2000
	ds_read_b128 v[202:205], v202 offset:3072
	global_load_lds_dwordx4 v128, s[98:99]
	s_barrier
	s_waitcnt lgkmcnt(0)
	v_mfma_f32_16x16x32_bf16 v[116:119], v[190:193], v[158:161], v[116:119]
	v_mfma_f32_16x16x32_bf16 v[112:115], v[198:201], v[158:161], v[112:115]
	v_mfma_f32_16x16x32_bf16 v[100:103], v[190:193], v[166:169], v[100:103]
	v_mfma_f32_16x16x32_bf16 v[96:99], v[198:201], v[166:169], v[96:99]
	v_mfma_f32_16x16x32_bf16 v[84:87], v[190:193], v[174:177], v[84:87]
	v_mfma_f32_16x16x32_bf16 v[80:83], v[198:201], v[174:177], v[80:83]
	v_mfma_f32_16x16x32_bf16 v[68:71], v[190:193], v[182:185], v[68:71]
	v_mfma_f32_16x16x32_bf16 v[64:67], v[198:201], v[182:185], v[64:67]
	v_mfma_f32_16x16x32_bf16 v[116:119], v[194:197], v[162:165], v[116:119]
	v_mfma_f32_16x16x32_bf16 v[112:115], v[202:205], v[162:165], v[112:115]
	v_mfma_f32_16x16x32_bf16 v[100:103], v[194:197], v[170:173], v[100:103]
	v_mfma_f32_16x16x32_bf16 v[96:99], v[202:205], v[170:173], v[96:99]
	v_mfma_f32_16x16x32_bf16 v[84:87], v[194:197], v[178:181], v[84:87]
	v_mfma_f32_16x16x32_bf16 v[80:83], v[202:205], v[178:181], v[80:83]
	v_mfma_f32_16x16x32_bf16 v[68:71], v[194:197], v[186:189], v[68:71]
	v_mfma_f32_16x16x32_bf16 v[64:67], v[202:205], v[186:189], v[64:67]
	s_mov_b32 m0, s62
	s_barrier
	ds_read_b128 v[158:161], v145 offset:49152
	ds_read_b128 v[162:165], v145 offset:50176
	ds_read_b128 v[166:169], v145 offset:51200
	ds_read_b128 v[170:173], v145 offset:52224
	ds_read_b128 v[174:177], v145 offset:53248
	ds_read_b128 v[178:181], v145 offset:54272
	ds_read_b128 v[182:185], v145 offset:55296
	global_load_lds_dwordx4 v132, s[100:101]
	s_mov_b32 m0, s63
	ds_read_b128 v[186:189], v145 offset:56320
	global_load_lds_dwordx4 v130, s[100:101]
	s_barrier
	s_waitcnt lgkmcnt(0)
	v_mfma_f32_16x16x32_bf16 v[60:63], v[138:141], v[158:161], v[60:63]
	v_mfma_f32_16x16x32_bf16 v[56:59], v[150:153], v[158:161], v[56:59]
	v_mfma_f32_16x16x32_bf16 v[44:47], v[138:141], v[166:169], v[44:47]
	v_mfma_f32_16x16x32_bf16 v[40:43], v[150:153], v[166:169], v[40:43]
	v_mfma_f32_16x16x32_bf16 v[28:31], v[138:141], v[174:177], v[28:31]
	v_mfma_f32_16x16x32_bf16 v[24:27], v[150:153], v[174:177], v[24:27]
	v_mfma_f32_16x16x32_bf16 v[12:15], v[138:141], v[182:185], v[12:15]
	v_mfma_f32_16x16x32_bf16 v[8:11], v[150:153], v[182:185], v[8:11]
	v_mfma_f32_16x16x32_bf16 v[60:63], v[146:149], v[162:165], v[60:63]
	v_mfma_f32_16x16x32_bf16 v[56:59], v[154:157], v[162:165], v[56:59]
	v_mfma_f32_16x16x32_bf16 v[44:47], v[146:149], v[170:173], v[44:47]
	v_mfma_f32_16x16x32_bf16 v[40:43], v[154:157], v[170:173], v[40:43]
	v_mfma_f32_16x16x32_bf16 v[28:31], v[146:149], v[178:181], v[28:31]
	v_mfma_f32_16x16x32_bf16 v[24:27], v[154:157], v[178:181], v[24:27]
	v_mfma_f32_16x16x32_bf16 v[12:15], v[146:149], v[186:189], v[12:15]
	v_mfma_f32_16x16x32_bf16 v[8:11], v[154:157], v[186:189], v[8:11]
	s_barrier
	s_add_u32 s26, s26, 0x40080
	s_addc_u32 s27, s27, 0
	s_add_i32 s28, s28, s57
	s_mov_b32 m0, s28
	s_nop 0
	global_load_lds_dwordx4 v208, s[26:27]
	s_add_i32 m0, s28, 0x2000
	s_nop 0
	global_load_lds_dwordx4 v128, s[26:27]
	s_waitcnt vmcnt(6)
	s_barrier
	v_mfma_f32_16x16x32_bf16 v[52:55], v[190:193], v[158:161], v[52:55]
	v_mfma_f32_16x16x32_bf16 v[48:51], v[198:201], v[158:161], v[48:51]
	v_mfma_f32_16x16x32_bf16 v[36:39], v[190:193], v[166:169], v[36:39]
	v_mfma_f32_16x16x32_bf16 v[32:35], v[198:201], v[166:169], v[32:35]
	v_mfma_f32_16x16x32_bf16 v[20:23], v[190:193], v[174:177], v[20:23]
	v_mfma_f32_16x16x32_bf16 v[16:19], v[198:201], v[174:177], v[16:19]
	v_mfma_f32_16x16x32_bf16 v[4:7], v[190:193], v[182:185], v[4:7]
	v_mfma_f32_16x16x32_bf16 v[0:3], v[198:201], v[182:185], v[0:3]
	v_mfma_f32_16x16x32_bf16 v[52:55], v[194:197], v[162:165], v[52:55]
	v_mfma_f32_16x16x32_bf16 v[48:51], v[202:205], v[162:165], v[48:51]
	v_mfma_f32_16x16x32_bf16 v[36:39], v[194:197], v[170:173], v[36:39]
	v_mfma_f32_16x16x32_bf16 v[32:35], v[202:205], v[170:173], v[32:35]
	v_mfma_f32_16x16x32_bf16 v[20:23], v[194:197], v[178:181], v[20:23]
	v_mfma_f32_16x16x32_bf16 v[16:19], v[202:205], v[178:181], v[16:19]
	v_mfma_f32_16x16x32_bf16 v[4:7], v[194:197], v[186:189], v[4:7]
	v_mfma_f32_16x16x32_bf16 v[0:3], v[202:205], v[186:189], v[0:3]
	s_add_i32 s51, s51, 2
	s_add_u32 s24, s24, 0x100
	s_addc_u32 s25, s25, 0
	s_add_u32 s46, s46, 0x100
	s_addc_u32 s50, s50, 0
	s_cmp_gt_u32 s51, 13
	s_barrier
	s_cbranch_scc0 .LBB0_823
	v_lshl_add_u32 v140, s35, 8, v142
	v_lshl_or_b32 v141, s34, 8, v144
	s_mov_b32 s34, s16
	s_mov_b32 s35, s18
	s_mov_b64 s[26:27], s[22:23]
	s_mov_b64 s[24:25], s[20:21]
	v_mbcnt_lo_u32_b32 v206, -1, 0
	v_mbcnt_hi_u32_b32 v206, -1, v206
	v_and_b32_e32 v206, 48, v206
	v_lshl_add_u32 v206, v140, 6, v206
	v_lshlrev_b32_e32 v207, 11, v140
	v_lshl_add_u32 v207, v141, 1, v207
	global_load_dwordx4 v[146:149], v206, s[14:15]
	global_load_dwordx4 v[150:153], v206, s[14:15] offset:1024
	global_load_dwordx4 v[154:157], v206, s[14:15] offset:2048
	global_load_dwordx4 v[158:161], v206, s[14:15] offset:3072
	v_add_u32_e32 v206, 0x2000, v206
	global_load_dwordx4 v[162:165], v206, s[14:15]
	global_load_dwordx4 v[166:169], v206, s[14:15] offset:1024
	global_load_dwordx4 v[170:173], v206, s[14:15] offset:2048
	global_load_dwordx4 v[174:177], v206, s[14:15] offset:3072
	s_waitcnt vmcnt(7)
	v_pk_add_f32 v[146:147], v[146:147], v[148:149]
	s_nop 0
	v_add_f32_e32 v214, v146, v147
	v_mov_b32_e32 v215, v214
	s_nop 1
	v_permlane16_swap_b32_e32 v214, v215
	s_nop 0
	v_add_f32_e32 v214, v214, v215
	v_mov_b32_e32 v215, v214
	s_nop 1
	v_permlane32_swap_b32_e32 v214, v215
	s_nop 0
	v_add_f32_e32 v214, v214, v215
	v_fmamk_f32 v214, v214, 0x3a800000, v248
	v_rsq_f32_e32 v178, v214
	s_nop 0
	v_pk_mul_f32 v[124:125], v[124:125], v[178:179] op_sel_hi:[1,0]
	v_pk_mul_f32 v[126:127], v[126:127], v[178:179] op_sel_hi:[1,0]
	v_pk_mul_f32 v[120:121], v[120:121], v[178:179] op_sel_hi:[1,0]
	v_pk_mul_f32 v[122:123], v[122:123], v[178:179] op_sel_hi:[1,0]
	v_cvt_pk_bf16_f32 v198, v124, v125
	v_cvt_pk_bf16_f32 v199, v126, v127
	v_cvt_pk_bf16_f32 v200, v120, v121
	v_cvt_pk_bf16_f32 v201, v122, v123
	global_store_dwordx4 v207, v[198:201], s[10:11]
	v_pk_mul_f32 v[116:117], v[116:117], v[178:179] op_sel_hi:[1,0]
	v_pk_mul_f32 v[118:119], v[118:119], v[178:179] op_sel_hi:[1,0]
	v_pk_mul_f32 v[112:113], v[112:113], v[178:179] op_sel_hi:[1,0]
	v_pk_mul_f32 v[114:115], v[114:115], v[178:179] op_sel_hi:[1,0]
	v_cvt_pk_bf16_f32 v202, v116, v117
	v_cvt_pk_bf16_f32 v203, v118, v119
	v_cvt_pk_bf16_f32 v204, v112, v113
	v_cvt_pk_bf16_f32 v205, v114, v115
	global_store_dwordx4 v207, v[202:205], s[10:11] offset:256
	v_add_u32_e32 v207, 0x8000, v207
	s_waitcnt vmcnt(8)
	v_pk_add_f32 v[150:151], v[150:151], v[152:153]
	s_nop 0
	v_add_f32_e32 v214, v150, v151
	v_mov_b32_e32 v215, v214
	s_nop 1
	v_permlane16_swap_b32_e32 v214, v215
	s_nop 0
	v_add_f32_e32 v214, v214, v215
	v_mov_b32_e32 v215, v214
	s_nop 1
	v_permlane32_swap_b32_e32 v214, v215
	s_nop 0
	v_add_f32_e32 v214, v214, v215
	v_fmamk_f32 v214, v214, 0x3a800000, v248
	v_rsq_f32_e32 v180, v214
	s_nop 0
	v_pk_mul_f32 v[108:109], v[108:109], v[180:181] op_sel_hi:[1,0]
	v_pk_mul_f32 v[110:111], v[110:111], v[180:181] op_sel_hi:[1,0]
	v_pk_mul_f32 v[104:105], v[104:105], v[180:181] op_sel_hi:[1,0]
	v_pk_mul_f32 v[106:107], v[106:107], v[180:181] op_sel_hi:[1,0]
	v_cvt_pk_bf16_f32 v198, v108, v109
	v_cvt_pk_bf16_f32 v199, v110, v111
	v_cvt_pk_bf16_f32 v200, v104, v105
	v_cvt_pk_bf16_f32 v201, v106, v107
	global_store_dwordx4 v207, v[198:201], s[10:11]
	v_pk_mul_f32 v[100:101], v[100:101], v[180:181] op_sel_hi:[1,0]
	v_pk_mul_f32 v[102:103], v[102:103], v[180:181] op_sel_hi:[1,0]
	v_pk_mul_f32 v[96:97], v[96:97], v[180:181] op_sel_hi:[1,0]
	v_pk_mul_f32 v[98:99], v[98:99], v[180:181] op_sel_hi:[1,0]
	v_cvt_pk_bf16_f32 v202, v100, v101
	v_cvt_pk_bf16_f32 v203, v102, v103
	v_cvt_pk_bf16_f32 v204, v96, v97
	v_cvt_pk_bf16_f32 v205, v98, v99
	global_store_dwordx4 v207, v[202:205], s[10:11] offset:256
	v_add_u32_e32 v207, 0x8000, v207
	s_waitcnt vmcnt(9)
	v_pk_add_f32 v[154:155], v[154:155], v[156:157]
	s_nop 0
	v_add_f32_e32 v214, v154, v155
	v_mov_b32_e32 v215, v214
	s_nop 1
	v_permlane16_swap_b32_e32 v214, v215
	s_nop 0
	v_add_f32_e32 v214, v214, v215
	v_mov_b32_e32 v215, v214
	s_nop 1
	v_permlane32_swap_b32_e32 v214, v215
	s_nop 0
	v_add_f32_e32 v214, v214, v215
	v_fmamk_f32 v214, v214, 0x3a800000, v248
	v_rsq_f32_e32 v182, v214
	s_nop 0
	v_pk_mul_f32 v[92:93], v[92:93], v[182:183] op_sel_hi:[1,0]
	v_pk_mul_f32 v[94:95], v[94:95], v[182:183] op_sel_hi:[1,0]
	v_pk_mul_f32 v[88:89], v[88:89], v[182:183] op_sel_hi:[1,0]
	v_pk_mul_f32 v[90:91], v[90:91], v[182:183] op_sel_hi:[1,0]
	v_cvt_pk_bf16_f32 v198, v92, v93
	v_cvt_pk_bf16_f32 v199, v94, v95
	v_cvt_pk_bf16_f32 v200, v88, v89
	v_cvt_pk_bf16_f32 v201, v90, v91
	global_store_dwordx4 v207, v[198:201], s[10:11]
	v_pk_mul_f32 v[84:85], v[84:85], v[182:183] op_sel_hi:[1,0]
	v_pk_mul_f32 v[86:87], v[86:87], v[182:183] op_sel_hi:[1,0]
	v_pk_mul_f32 v[80:81], v[80:81], v[182:183] op_sel_hi:[1,0]
	v_pk_mul_f32 v[82:83], v[82:83], v[182:183] op_sel_hi:[1,0]
	v_cvt_pk_bf16_f32 v202, v84, v85
	v_cvt_pk_bf16_f32 v203, v86, v87
	v_cvt_pk_bf16_f32 v204, v80, v81
	v_cvt_pk_bf16_f32 v205, v82, v83
	global_store_dwordx4 v207, v[202:205], s[10:11] offset:256
	v_add_u32_e32 v207, 0x8000, v207
	s_waitcnt vmcnt(10)
	v_pk_add_f32 v[158:159], v[158:159], v[160:161]
	s_nop 0
	v_add_f32_e32 v214, v158, v159
	v_mov_b32_e32 v215, v214
	s_nop 1
	v_permlane16_swap_b32_e32 v214, v215
	s_nop 0
	v_add_f32_e32 v214, v214, v215
	v_mov_b32_e32 v215, v214
	s_nop 1
	v_permlane32_swap_b32_e32 v214, v215
	s_nop 0
	v_add_f32_e32 v214, v214, v215
	v_fmamk_f32 v214, v214, 0x3a800000, v248
	v_rsq_f32_e32 v184, v214
	s_nop 0
	v_pk_mul_f32 v[76:77], v[76:77], v[184:185] op_sel_hi:[1,0]
	v_pk_mul_f32 v[78:79], v[78:79], v[184:185] op_sel_hi:[1,0]
	v_pk_mul_f32 v[72:73], v[72:73], v[184:185] op_sel_hi:[1,0]
	v_pk_mul_f32 v[74:75], v[74:75], v[184:185] op_sel_hi:[1,0]
	v_cvt_pk_bf16_f32 v198, v76, v77
	v_cvt_pk_bf16_f32 v199, v78, v79
	v_cvt_pk_bf16_f32 v200, v72, v73
	v_cvt_pk_bf16_f32 v201, v74, v75
	global_store_dwordx4 v207, v[198:201], s[10:11]
	v_pk_mul_f32 v[68:69], v[68:69], v[184:185] op_sel_hi:[1,0]
	v_pk_mul_f32 v[70:71], v[70:71], v[184:185] op_sel_hi:[1,0]
	v_pk_mul_f32 v[64:65], v[64:65], v[184:185] op_sel_hi:[1,0]
	v_pk_mul_f32 v[66:67], v[66:67], v[184:185] op_sel_hi:[1,0]
	v_cvt_pk_bf16_f32 v202, v68, v69
	v_cvt_pk_bf16_f32 v203, v70, v71
	v_cvt_pk_bf16_f32 v204, v64, v65
	v_cvt_pk_bf16_f32 v205, v66, v67
	global_store_dwordx4 v207, v[202:205], s[10:11] offset:256
	v_add_u32_e32 v207, 0x28000, v207
	s_waitcnt vmcnt(11)
	v_pk_add_f32 v[162:163], v[162:163], v[164:165]
	s_nop 0
	v_add_f32_e32 v214, v162, v163
	v_mov_b32_e32 v215, v214
	s_nop 1
	v_permlane16_swap_b32_e32 v214, v215
	s_nop 0
	v_add_f32_e32 v214, v214, v215
	v_mov_b32_e32 v215, v214
	s_nop 1
	v_permlane32_swap_b32_e32 v214, v215
	s_nop 0
	v_add_f32_e32 v214, v214, v215
	v_fmamk_f32 v214, v214, 0x3a800000, v248
	v_rsq_f32_e32 v186, v214
	s_nop 0
	v_pk_mul_f32 v[60:61], v[60:61], v[186:187] op_sel_hi:[1,0]
	v_pk_mul_f32 v[62:63], v[62:63], v[186:187] op_sel_hi:[1,0]
	v_pk_mul_f32 v[56:57], v[56:57], v[186:187] op_sel_hi:[1,0]
	v_pk_mul_f32 v[58:59], v[58:59], v[186:187] op_sel_hi:[1,0]
	v_cvt_pk_bf16_f32 v198, v60, v61
	v_cvt_pk_bf16_f32 v199, v62, v63
	v_cvt_pk_bf16_f32 v200, v56, v57
	v_cvt_pk_bf16_f32 v201, v58, v59
	global_store_dwordx4 v207, v[198:201], s[10:11]
	v_pk_mul_f32 v[52:53], v[52:53], v[186:187] op_sel_hi:[1,0]
	v_pk_mul_f32 v[54:55], v[54:55], v[186:187] op_sel_hi:[1,0]
	v_pk_mul_f32 v[48:49], v[48:49], v[186:187] op_sel_hi:[1,0]
	v_pk_mul_f32 v[50:51], v[50:51], v[186:187] op_sel_hi:[1,0]
	v_cvt_pk_bf16_f32 v202, v52, v53
	v_cvt_pk_bf16_f32 v203, v54, v55
	v_cvt_pk_bf16_f32 v204, v48, v49
	v_cvt_pk_bf16_f32 v205, v50, v51
	global_store_dwordx4 v207, v[202:205], s[10:11] offset:256
	v_add_u32_e32 v207, 0x8000, v207
	s_waitcnt vmcnt(12)
	v_pk_add_f32 v[166:167], v[166:167], v[168:169]
	s_nop 0
	v_add_f32_e32 v214, v166, v167
	v_mov_b32_e32 v215, v214
	s_nop 1
	v_permlane16_swap_b32_e32 v214, v215
	s_nop 0
	v_add_f32_e32 v214, v214, v215
	v_mov_b32_e32 v215, v214
	s_nop 1
	v_permlane32_swap_b32_e32 v214, v215
	s_nop 0
	v_add_f32_e32 v214, v214, v215
	v_fmamk_f32 v214, v214, 0x3a800000, v248
	v_rsq_f32_e32 v188, v214
	s_nop 0
	v_pk_mul_f32 v[44:45], v[44:45], v[188:189] op_sel_hi:[1,0]
	v_pk_mul_f32 v[46:47], v[46:47], v[188:189] op_sel_hi:[1,0]
	v_pk_mul_f32 v[40:41], v[40:41], v[188:189] op_sel_hi:[1,0]
	v_pk_mul_f32 v[42:43], v[42:43], v[188:189] op_sel_hi:[1,0]
	v_cvt_pk_bf16_f32 v198, v44, v45
	v_cvt_pk_bf16_f32 v199, v46, v47
	v_cvt_pk_bf16_f32 v200, v40, v41
	v_cvt_pk_bf16_f32 v201, v42, v43
	global_store_dwordx4 v207, v[198:201], s[10:11]
	v_pk_mul_f32 v[36:37], v[36:37], v[188:189] op_sel_hi:[1,0]
	v_pk_mul_f32 v[38:39], v[38:39], v[188:189] op_sel_hi:[1,0]
	v_pk_mul_f32 v[32:33], v[32:33], v[188:189] op_sel_hi:[1,0]
	v_pk_mul_f32 v[34:35], v[34:35], v[188:189] op_sel_hi:[1,0]
	v_cvt_pk_bf16_f32 v202, v36, v37
	v_cvt_pk_bf16_f32 v203, v38, v39
	v_cvt_pk_bf16_f32 v204, v32, v33
	v_cvt_pk_bf16_f32 v205, v34, v35
	global_store_dwordx4 v207, v[202:205], s[10:11] offset:256
	v_add_u32_e32 v207, 0x8000, v207
	s_waitcnt vmcnt(13)
	v_pk_add_f32 v[170:171], v[170:171], v[172:173]
	s_nop 0
	v_add_f32_e32 v214, v170, v171
	v_mov_b32_e32 v215, v214
	s_nop 1
	v_permlane16_swap_b32_e32 v214, v215
	s_nop 0
	v_add_f32_e32 v214, v214, v215
	v_mov_b32_e32 v215, v214
	s_nop 1
	v_permlane32_swap_b32_e32 v214, v215
	s_nop 0
	v_add_f32_e32 v214, v214, v215
	v_fmamk_f32 v214, v214, 0x3a800000, v248
	v_rsq_f32_e32 v190, v214
	s_nop 0
	v_pk_mul_f32 v[28:29], v[28:29], v[190:191] op_sel_hi:[1,0]
	v_pk_mul_f32 v[30:31], v[30:31], v[190:191] op_sel_hi:[1,0]
	v_pk_mul_f32 v[24:25], v[24:25], v[190:191] op_sel_hi:[1,0]
	v_pk_mul_f32 v[26:27], v[26:27], v[190:191] op_sel_hi:[1,0]
	v_cvt_pk_bf16_f32 v198, v28, v29
	v_cvt_pk_bf16_f32 v199, v30, v31
	v_cvt_pk_bf16_f32 v200, v24, v25
	v_cvt_pk_bf16_f32 v201, v26, v27
	global_store_dwordx4 v207, v[198:201], s[10:11]
	v_pk_mul_f32 v[20:21], v[20:21], v[190:191] op_sel_hi:[1,0]
	v_pk_mul_f32 v[22:23], v[22:23], v[190:191] op_sel_hi:[1,0]
	v_pk_mul_f32 v[16:17], v[16:17], v[190:191] op_sel_hi:[1,0]
	v_pk_mul_f32 v[18:19], v[18:19], v[190:191] op_sel_hi:[1,0]
	v_cvt_pk_bf16_f32 v202, v20, v21
	v_cvt_pk_bf16_f32 v203, v22, v23
	v_cvt_pk_bf16_f32 v204, v16, v17
	v_cvt_pk_bf16_f32 v205, v18, v19
	global_store_dwordx4 v207, v[202:205], s[10:11] offset:256
	v_add_u32_e32 v207, 0x8000, v207
	s_waitcnt vmcnt(14)
	v_pk_add_f32 v[174:175], v[174:175], v[176:177]
	s_nop 0
	v_add_f32_e32 v214, v174, v175
	v_mov_b32_e32 v215, v214
	s_nop 1
	v_permlane16_swap_b32_e32 v214, v215
	s_nop 0
	v_add_f32_e32 v214, v214, v215
	v_mov_b32_e32 v215, v214
	s_nop 1
	v_permlane32_swap_b32_e32 v214, v215
	s_nop 0
	v_add_f32_e32 v214, v214, v215
	v_fmamk_f32 v214, v214, 0x3a800000, v248
	v_rsq_f32_e32 v192, v214
	s_nop 0
	v_pk_mul_f32 v[12:13], v[12:13], v[192:193] op_sel_hi:[1,0]
	v_pk_mul_f32 v[14:15], v[14:15], v[192:193] op_sel_hi:[1,0]
	v_pk_mul_f32 v[8:9], v[8:9], v[192:193] op_sel_hi:[1,0]
	v_pk_mul_f32 v[10:11], v[10:11], v[192:193] op_sel_hi:[1,0]
	v_cvt_pk_bf16_f32 v198, v12, v13
	v_cvt_pk_bf16_f32 v199, v14, v15
	v_cvt_pk_bf16_f32 v200, v8, v9
	v_cvt_pk_bf16_f32 v201, v10, v11
	global_store_dwordx4 v207, v[198:201], s[10:11]
	v_pk_mul_f32 v[4:5], v[4:5], v[192:193] op_sel_hi:[1,0]
	v_pk_mul_f32 v[6:7], v[6:7], v[192:193] op_sel_hi:[1,0]
	v_pk_mul_f32 v[0:1], v[0:1], v[192:193] op_sel_hi:[1,0]
	v_pk_mul_f32 v[2:3], v[2:3], v[192:193] op_sel_hi:[1,0]
	v_cvt_pk_bf16_f32 v202, v4, v5
	v_cvt_pk_bf16_f32 v203, v6, v7
	v_cvt_pk_bf16_f32 v204, v0, v1
	v_cvt_pk_bf16_f32 v205, v2, v3
	global_store_dwordx4 v207, v[202:205], s[10:11] offset:256
	s_and_b64 vcc, exec, s[4:5]
	s_cbranch_vccz .LBB0_816
	s_waitcnt vmcnt(0)
	s_cmpk_gt_u32 s30, 0xff
	s_cbranch_scc1 .LBB0_827
	s_barrier

.LBB0_878:
	s_add_u32 s26, s24, 0xfffc0080
	s_addc_u32 s27, s25, -1
	s_add_i32 s65, 0, 0x10000
	v_add_u32_e32 v154, s65, v143
	ds_read_b128 v[138:141], v154
	ds_read_b128 v[146:149], v154 offset:1024
	ds_read_b128 v[150:153], v154 offset:2048
	ds_read_b128 v[154:157], v154 offset:3072
	s_cmp_eq_u32 s64, 12
	s_cselect_b32 s29, s19, s27
	s_cselect_b32 s28, s39, s26
	s_cselect_b32 s27, s17, s63
	s_cselect_b32 s26, s61, s62
	s_add_i32 m0, s50, 0xc000
	ds_read_b128 v[158:161], v145
	ds_read_b128 v[162:165], v145 offset:1024
	ds_read_b128 v[166:169], v145 offset:2048
	ds_read_b128 v[170:173], v145 offset:3072
	ds_read_b128 v[174:177], v145 offset:4096
	ds_read_b128 v[178:181], v145 offset:5120
	ds_read_b128 v[182:185], v145 offset:6144
	global_load_lds_dwordx4 v134, s[24:25]
	s_add_i32 m0, s50, 0xe000
	ds_read_b128 v[186:189], v145 offset:7168
	global_load_lds_dwordx4 v136, s[24:25]
	s_waitcnt lgkmcnt(8)
	s_barrier
	s_waitcnt lgkmcnt(0)
	v_mfma_f32_16x16x32_bf16 v[124:127], v[138:141], v[158:161], v[124:127]
	v_mfma_f32_16x16x32_bf16 v[120:123], v[150:153], v[158:161], v[120:123]
	v_mfma_f32_16x16x32_bf16 v[108:111], v[138:141], v[166:169], v[108:111]
	v_mfma_f32_16x16x32_bf16 v[104:107], v[150:153], v[166:169], v[104:107]
	v_mfma_f32_16x16x32_bf16 v[92:95], v[138:141], v[174:177], v[92:95]
	v_mfma_f32_16x16x32_bf16 v[88:91], v[150:153], v[174:177], v[88:91]
	v_mfma_f32_16x16x32_bf16 v[76:79], v[138:141], v[182:185], v[76:79]
	v_mfma_f32_16x16x32_bf16 v[72:75], v[150:153], v[182:185], v[72:75]
	v_mfma_f32_16x16x32_bf16 v[124:127], v[146:149], v[162:165], v[124:127]
	v_mfma_f32_16x16x32_bf16 v[120:123], v[154:157], v[162:165], v[120:123]
	v_mfma_f32_16x16x32_bf16 v[108:111], v[146:149], v[170:173], v[108:111]
	v_mfma_f32_16x16x32_bf16 v[104:107], v[154:157], v[170:173], v[104:107]
	v_mfma_f32_16x16x32_bf16 v[92:95], v[146:149], v[178:181], v[92:95]
	v_mfma_f32_16x16x32_bf16 v[88:91], v[154:157], v[178:181], v[88:91]
	v_mfma_f32_16x16x32_bf16 v[76:79], v[146:149], v[186:189], v[76:79]
	v_mfma_f32_16x16x32_bf16 v[72:75], v[154:157], v[186:189], v[72:75]
	s_barrier
	s_add_i32 s68, 0, 0x14000
	s_add_i32 s65, s65, s47
	v_add_u32_e32 v202, s68, v143
	s_add_u32 s98, s26, s40
	s_addc_u32 s99, s27, s41
	s_mov_b32 m0, s65
	ds_read_b128 v[190:193], v202
	ds_read_b128 v[194:197], v202 offset:1024
	ds_read_b128 v[198:201], v202 offset:2048
	global_load_lds_dwordx4 v208, s[26:27]
	s_add_i32 m0, s65, 0x2000
	ds_read_b128 v[202:205], v202 offset:3072
	global_load_lds_dwordx4 v128, s[26:27]
	s_barrier
	s_waitcnt lgkmcnt(0)
	v_mfma_f32_16x16x32_bf16 v[116:119], v[190:193], v[158:161], v[116:119]
	v_mfma_f32_16x16x32_bf16 v[112:115], v[198:201], v[158:161], v[112:115]
	v_mfma_f32_16x16x32_bf16 v[100:103], v[190:193], v[166:169], v[100:103]
	v_mfma_f32_16x16x32_bf16 v[96:99], v[198:201], v[166:169], v[96:99]
	v_mfma_f32_16x16x32_bf16 v[84:87], v[190:193], v[174:177], v[84:87]
	v_mfma_f32_16x16x32_bf16 v[80:83], v[198:201], v[174:177], v[80:83]
	v_mfma_f32_16x16x32_bf16 v[68:71], v[190:193], v[182:185], v[68:71]
	v_mfma_f32_16x16x32_bf16 v[64:67], v[198:201], v[182:185], v[64:67]
	v_mfma_f32_16x16x32_bf16 v[116:119], v[194:197], v[162:165], v[116:119]
	v_mfma_f32_16x16x32_bf16 v[112:115], v[202:205], v[162:165], v[112:115]
	v_mfma_f32_16x16x32_bf16 v[100:103], v[194:197], v[170:173], v[100:103]
	v_mfma_f32_16x16x32_bf16 v[96:99], v[202:205], v[170:173], v[96:99]
	v_mfma_f32_16x16x32_bf16 v[84:87], v[194:197], v[178:181], v[84:87]
	v_mfma_f32_16x16x32_bf16 v[80:83], v[202:205], v[178:181], v[80:83]
	v_mfma_f32_16x16x32_bf16 v[68:71], v[194:197], v[186:189], v[68:71]
	v_mfma_f32_16x16x32_bf16 v[64:67], v[202:205], v[186:189], v[64:67]
	s_mov_b32 m0, s50
	s_add_u32 s100, s28, s40
	s_addc_u32 s101, s29, s41
	s_barrier
	ds_read_b128 v[158:161], v145 offset:16384
	ds_read_b128 v[162:165], v145 offset:17408
	ds_read_b128 v[166:169], v145 offset:18432
	ds_read_b128 v[170:173], v145 offset:19456
	ds_read_b128 v[174:177], v145 offset:20480
	ds_read_b128 v[178:181], v145 offset:21504
	ds_read_b128 v[182:185], v145 offset:22528
	global_load_lds_dwordx4 v132, s[28:29]
	s_mov_b32 m0, s51
	ds_read_b128 v[186:189], v145 offset:23552
	global_load_lds_dwordx4 v130, s[28:29]
	s_barrier
	s_waitcnt lgkmcnt(0)
	v_mfma_f32_16x16x32_bf16 v[60:63], v[138:141], v[158:161], v[60:63]
	v_mfma_f32_16x16x32_bf16 v[56:59], v[150:153], v[158:161], v[56:59]
	v_mfma_f32_16x16x32_bf16 v[44:47], v[138:141], v[166:169], v[44:47]
	v_mfma_f32_16x16x32_bf16 v[40:43], v[150:153], v[166:169], v[40:43]
	v_mfma_f32_16x16x32_bf16 v[28:31], v[138:141], v[174:177], v[28:31]
	v_mfma_f32_16x16x32_bf16 v[24:27], v[150:153], v[174:177], v[24:27]
	v_mfma_f32_16x16x32_bf16 v[12:15], v[138:141], v[182:185], v[12:15]
	v_mfma_f32_16x16x32_bf16 v[8:11], v[150:153], v[182:185], v[8:11]
	v_mfma_f32_16x16x32_bf16 v[60:63], v[146:149], v[162:165], v[60:63]
	v_mfma_f32_16x16x32_bf16 v[56:59], v[154:157], v[162:165], v[56:59]
	v_mfma_f32_16x16x32_bf16 v[44:47], v[146:149], v[170:173], v[44:47]
	v_mfma_f32_16x16x32_bf16 v[40:43], v[154:157], v[170:173], v[40:43]
	v_mfma_f32_16x16x32_bf16 v[28:31], v[146:149], v[178:181], v[28:31]
	v_mfma_f32_16x16x32_bf16 v[24:27], v[154:157], v[178:181], v[24:27]
	v_mfma_f32_16x16x32_bf16 v[12:15], v[146:149], v[186:189], v[12:15]
	v_mfma_f32_16x16x32_bf16 v[8:11], v[154:157], v[186:189], v[8:11]
	s_barrier
	s_add_u32 s66, s26, 0x40000
	s_addc_u32 s67, s27, 0
	s_add_i32 s65, s68, s47
	s_mov_b32 m0, s65
	s_nop 0
	global_load_lds_dwordx4 v208, s[66:67]
	s_add_i32 m0, s65, 0x2000
	s_nop 0
	global_load_lds_dwordx4 v128, s[66:67]
	s_waitcnt vmcnt(6)
	s_barrier
	v_mfma_f32_16x16x32_bf16 v[52:55], v[190:193], v[158:161], v[52:55]
	v_mfma_f32_16x16x32_bf16 v[48:51], v[198:201], v[158:161], v[48:51]
	v_mfma_f32_16x16x32_bf16 v[36:39], v[190:193], v[166:169], v[36:39]
	v_mfma_f32_16x16x32_bf16 v[32:35], v[198:201], v[166:169], v[32:35]
	v_mfma_f32_16x16x32_bf16 v[20:23], v[190:193], v[174:177], v[20:23]
	v_mfma_f32_16x16x32_bf16 v[16:19], v[198:201], v[174:177], v[16:19]
	v_mfma_f32_16x16x32_bf16 v[4:7], v[190:193], v[182:185], v[4:7]
	v_mfma_f32_16x16x32_bf16 v[0:3], v[198:201], v[182:185], v[0:3]
	v_mfma_f32_16x16x32_bf16 v[52:55], v[194:197], v[162:165], v[52:55]
	v_mfma_f32_16x16x32_bf16 v[48:51], v[202:205], v[162:165], v[48:51]
	v_mfma_f32_16x16x32_bf16 v[36:39], v[194:197], v[170:173], v[36:39]
	v_mfma_f32_16x16x32_bf16 v[32:35], v[202:205], v[170:173], v[32:35]
	v_mfma_f32_16x16x32_bf16 v[20:23], v[194:197], v[178:181], v[20:23]
	v_mfma_f32_16x16x32_bf16 v[16:19], v[202:205], v[178:181], v[16:19]
	v_mfma_f32_16x16x32_bf16 v[4:7], v[194:197], v[186:189], v[4:7]
	v_mfma_f32_16x16x32_bf16 v[0:3], v[202:205], v[186:189], v[0:3]
	s_add_i32 s65, 0, 0x18000
	v_add_u32_e32 v154, s65, v143
	s_barrier
	ds_read_b128 v[138:141], v154
	ds_read_b128 v[146:149], v154 offset:1024
	ds_read_b128 v[150:153], v154 offset:2048
	ds_read_b128 v[154:157], v154 offset:3072
	s_add_u32 s28, s28, 0x40000
	s_addc_u32 s29, s29, 0
	s_mov_b32 m0, s53
	ds_read_b128 v[158:161], v145 offset:32768
	ds_read_b128 v[162:165], v145 offset:33792
	ds_read_b128 v[166:169], v145 offset:34816
	ds_read_b128 v[170:173], v145 offset:35840
	ds_read_b128 v[174:177], v145 offset:36864
	ds_read_b128 v[178:181], v145 offset:37888
	ds_read_b128 v[182:185], v145 offset:38912
	global_load_lds_dwordx4 v132, s[28:29]
	s_mov_b32 m0, s56
	ds_read_b128 v[186:189], v145 offset:39936
	global_load_lds_dwordx4 v130, s[28:29]
	s_waitcnt lgkmcnt(8)
	s_barrier
	s_waitcnt lgkmcnt(0)
	v_mfma_f32_16x16x32_bf16 v[124:127], v[138:141], v[158:161], v[124:127]
	v_mfma_f32_16x16x32_bf16 v[120:123], v[150:153], v[158:161], v[120:123]
	v_mfma_f32_16x16x32_bf16 v[108:111], v[138:141], v[166:169], v[108:111]
	v_mfma_f32_16x16x32_bf16 v[104:107], v[150:153], v[166:169], v[104:107]
	v_mfma_f32_16x16x32_bf16 v[92:95], v[138:141], v[174:177], v[92:95]
	v_mfma_f32_16x16x32_bf16 v[88:91], v[150:153], v[174:177], v[88:91]
	v_mfma_f32_16x16x32_bf16 v[76:79], v[138:141], v[182:185], v[76:79]
	v_mfma_f32_16x16x32_bf16 v[72:75], v[150:153], v[182:185], v[72:75]
	v_mfma_f32_16x16x32_bf16 v[124:127], v[146:149], v[162:165], v[124:127]
	v_mfma_f32_16x16x32_bf16 v[120:123], v[154:157], v[162:165], v[120:123]
	v_mfma_f32_16x16x32_bf16 v[108:111], v[146:149], v[170:173], v[108:111]
	v_mfma_f32_16x16x32_bf16 v[104:107], v[154:157], v[170:173], v[104:107]
	v_mfma_f32_16x16x32_bf16 v[92:95], v[146:149], v[178:181], v[92:95]
	v_mfma_f32_16x16x32_bf16 v[88:91], v[154:157], v[178:181], v[88:91]
	v_mfma_f32_16x16x32_bf16 v[76:79], v[146:149], v[186:189], v[76:79]
	v_mfma_f32_16x16x32_bf16 v[72:75], v[154:157], v[186:189], v[72:75]
	s_barrier
	s_add_i32 s28, 0, 0x1c000
	s_add_i32 s29, s65, s47
	v_add_u32_e32 v202, s28, v143
	s_mov_b32 m0, s29
	ds_read_b128 v[190:193], v202
	ds_read_b128 v[194:197], v202 offset:1024
	ds_read_b128 v[198:201], v202 offset:2048
	global_load_lds_dwordx4 v208, s[98:99]
	s_add_i32 m0, s29, 0x2000
	ds_read_b128 v[202:205], v202 offset:3072
	global_load_lds_dwordx4 v128, s[98:99]
	s_barrier
	s_waitcnt lgkmcnt(0)
	v_mfma_f32_16x16x32_bf16 v[116:119], v[190:193], v[158:161], v[116:119]
	v_mfma_f32_16x16x32_bf16 v[112:115], v[198:201], v[158:161], v[112:115]
	v_mfma_f32_16x16x32_bf16 v[100:103], v[190:193], v[166:169], v[100:103]
	v_mfma_f32_16x16x32_bf16 v[96:99], v[198:201], v[166:169], v[96:99]
	v_mfma_f32_16x16x32_bf16 v[84:87], v[190:193], v[174:177], v[84:87]
	v_mfma_f32_16x16x32_bf16 v[80:83], v[198:201], v[174:177], v[80:83]
	v_mfma_f32_16x16x32_bf16 v[68:71], v[190:193], v[182:185], v[68:71]
	v_mfma_f32_16x16x32_bf16 v[64:67], v[198:201], v[182:185], v[64:67]
	v_mfma_f32_16x16x32_bf16 v[116:119], v[194:197], v[162:165], v[116:119]
	v_mfma_f32_16x16x32_bf16 v[112:115], v[202:205], v[162:165], v[112:115]
	v_mfma_f32_16x16x32_bf16 v[100:103], v[194:197], v[170:173], v[100:103]
	v_mfma_f32_16x16x32_bf16 v[96:99], v[202:205], v[170:173], v[96:99]
	v_mfma_f32_16x16x32_bf16 v[84:87], v[194:197], v[178:181], v[84:87]
	v_mfma_f32_16x16x32_bf16 v[80:83], v[202:205], v[178:181], v[80:83]
	v_mfma_f32_16x16x32_bf16 v[68:71], v[194:197], v[186:189], v[68:71]
	v_mfma_f32_16x16x32_bf16 v[64:67], v[202:205], v[186:189], v[64:67]
	s_mov_b32 m0, s58
	s_barrier
	ds_read_b128 v[158:161], v145 offset:49152
	ds_read_b128 v[162:165], v145 offset:50176
	ds_read_b128 v[166:169], v145 offset:51200
	ds_read_b128 v[170:173], v145 offset:52224
	ds_read_b128 v[174:177], v145 offset:53248
	ds_read_b128 v[178:181], v145 offset:54272
	ds_read_b128 v[182:185], v145 offset:55296
	global_load_lds_dwordx4 v132, s[100:101]
	s_mov_b32 m0, s59
	ds_read_b128 v[186:189], v145 offset:56320
	global_load_lds_dwordx4 v130, s[100:101]
	s_barrier
	s_waitcnt lgkmcnt(0)
	v_mfma_f32_16x16x32_bf16 v[60:63], v[138:141], v[158:161], v[60:63]
	v_mfma_f32_16x16x32_bf16 v[56:59], v[150:153], v[158:161], v[56:59]
	v_mfma_f32_16x16x32_bf16 v[44:47], v[138:141], v[166:169], v[44:47]
	v_mfma_f32_16x16x32_bf16 v[40:43], v[150:153], v[166:169], v[40:43]
	v_mfma_f32_16x16x32_bf16 v[28:31], v[138:141], v[174:177], v[28:31]
	v_mfma_f32_16x16x32_bf16 v[24:27], v[150:153], v[174:177], v[24:27]
	v_mfma_f32_16x16x32_bf16 v[12:15], v[138:141], v[182:185], v[12:15]
	v_mfma_f32_16x16x32_bf16 v[8:11], v[150:153], v[182:185], v[8:11]
	v_mfma_f32_16x16x32_bf16 v[60:63], v[146:149], v[162:165], v[60:63]
	v_mfma_f32_16x16x32_bf16 v[56:59], v[154:157], v[162:165], v[56:59]
	v_mfma_f32_16x16x32_bf16 v[44:47], v[146:149], v[170:173], v[44:47]
	v_mfma_f32_16x16x32_bf16 v[40:43], v[154:157], v[170:173], v[40:43]
	v_mfma_f32_16x16x32_bf16 v[28:31], v[146:149], v[178:181], v[28:31]
	v_mfma_f32_16x16x32_bf16 v[24:27], v[154:157], v[178:181], v[24:27]
	v_mfma_f32_16x16x32_bf16 v[12:15], v[146:149], v[186:189], v[12:15]
	v_mfma_f32_16x16x32_bf16 v[8:11], v[154:157], v[186:189], v[8:11]
	s_barrier
	s_add_u32 s26, s26, 0x40080
	s_addc_u32 s27, s27, 0
	s_add_i32 s28, s28, s47
	s_mov_b32 m0, s28
	s_nop 0
	global_load_lds_dwordx4 v208, s[26:27]
	s_add_i32 m0, s28, 0x2000
	s_nop 0
	global_load_lds_dwordx4 v128, s[26:27]
	s_waitcnt vmcnt(6)
	s_barrier
	v_mfma_f32_16x16x32_bf16 v[52:55], v[190:193], v[158:161], v[52:55]
	v_mfma_f32_16x16x32_bf16 v[48:51], v[198:201], v[158:161], v[48:51]
	v_mfma_f32_16x16x32_bf16 v[36:39], v[190:193], v[166:169], v[36:39]
	v_mfma_f32_16x16x32_bf16 v[32:35], v[198:201], v[166:169], v[32:35]
	v_mfma_f32_16x16x32_bf16 v[20:23], v[190:193], v[174:177], v[20:23]
	v_mfma_f32_16x16x32_bf16 v[16:19], v[198:201], v[174:177], v[16:19]
	v_mfma_f32_16x16x32_bf16 v[4:7], v[190:193], v[182:185], v[4:7]
	v_mfma_f32_16x16x32_bf16 v[0:3], v[198:201], v[182:185], v[0:3]
	v_mfma_f32_16x16x32_bf16 v[52:55], v[194:197], v[162:165], v[52:55]
	v_mfma_f32_16x16x32_bf16 v[48:51], v[202:205], v[162:165], v[48:51]
	v_mfma_f32_16x16x32_bf16 v[36:39], v[194:197], v[170:173], v[36:39]
	v_mfma_f32_16x16x32_bf16 v[32:35], v[202:205], v[170:173], v[32:35]
	v_mfma_f32_16x16x32_bf16 v[20:23], v[194:197], v[178:181], v[20:23]
	v_mfma_f32_16x16x32_bf16 v[16:19], v[202:205], v[178:181], v[16:19]
	v_mfma_f32_16x16x32_bf16 v[4:7], v[194:197], v[186:189], v[4:7]
	v_mfma_f32_16x16x32_bf16 v[0:3], v[202:205], v[186:189], v[0:3]
	s_add_i32 s64, s64, 2
	s_add_u32 s24, s24, 0x100
	s_addc_u32 s25, s25, 0
	s_add_u32 s62, s62, 0x100
	s_addc_u32 s63, s63, 0
	s_cmp_gt_u32 s64, 13
	s_barrier
	s_cbranch_scc0 .LBB0_878
	v_lshl_add_u32 v140, s38, 8, v142
	v_lshl_or_b32 v141, s36, 8, v144
	s_lshl_b32 s24, s36, 2
	s_ashr_i32 s25, s24, 31
	s_lshl_b32 s36, s57, 2
	v_lshlrev_b32_e32 v206, 11, v140
	v_lshl_add_u32 v206, v141, 1, v206
	v_lshl_add_u32 v210, v140, 6, s36
	v_lshl_add_u32 v210, s24, 2, v210
	v_mov_b32_e32 v207, v206
	global_load_dwordx4 v[146:149], v206, s[8:9]
	global_load_dwordx4 v[150:153], v206, s[8:9] offset:256
	v_add_u32_e32 v206, 0x8000, v206
	global_load_dwordx4 v[154:157], v206, s[8:9]
	global_load_dwordx4 v[158:161], v206, s[8:9] offset:256
	v_add_u32_e32 v206, 0x8000, v206
	global_load_dwordx4 v[162:165], v206, s[8:9]
	global_load_dwordx4 v[166:169], v206, s[8:9] offset:256
	v_add_u32_e32 v206, 0x8000, v206
	global_load_dwordx4 v[170:173], v206, s[8:9]
	global_load_dwordx4 v[174:177], v206, s[8:9] offset:256
	v_add_u32_e32 v206, 0x28000, v206
	global_load_dwordx4 v[178:181], v206, s[8:9]
	global_load_dwordx4 v[182:185], v206, s[8:9] offset:256
	v_add_u32_e32 v206, 0x8000, v206
	global_load_dwordx4 v[186:189], v206, s[8:9]
	global_load_dwordx4 v[190:193], v206, s[8:9] offset:256
	v_add_u32_e32 v206, 0x8000, v206
	global_load_dwordx4 v[194:197], v206, s[8:9]
	global_load_dwordx4 v[198:201], v206, s[8:9] offset:256
	v_add_u32_e32 v206, 0x8000, v206
	s_waitcnt vmcnt(12)
	v_lshlrev_b32_e32 v202, 16, v146
	v_and_b32_e32 v203, 0xffff0000, v146
	v_lshlrev_b32_e32 v204, 16, v147
	v_and_b32_e32 v205, 0xffff0000, v147
	v_pk_add_f32 v[124:125], v[124:125], v[202:203]
	v_pk_add_f32 v[126:127], v[126:127], v[204:205]
	v_lshlrev_b32_e32 v202, 16, v148
	v_and_b32_e32 v203, 0xffff0000, v148
	v_lshlrev_b32_e32 v204, 16, v149
	v_and_b32_e32 v205, 0xffff0000, v149
	v_pk_add_f32 v[120:121], v[120:121], v[202:203]
	v_pk_add_f32 v[122:123], v[122:123], v[204:205]
	v_cvt_pk_bf16_f32 v146, v124, v125
	v_cvt_pk_bf16_f32 v147, v126, v127
	v_cvt_pk_bf16_f32 v148, v120, v121
	v_cvt_pk_bf16_f32 v149, v122, v123
	v_pk_mul_f32 v[138:139], v[124:125], v[124:125]
	global_store_dwordx4 v207, v[146:149], s[8:9]
	v_pk_fma_f32 v[138:139], v[126:127], v[126:127], v[138:139]
	v_pk_fma_f32 v[138:139], v[120:121], v[120:121], v[138:139]
	v_pk_fma_f32 v[138:139], v[122:123], v[122:123], v[138:139]
	v_lshlrev_b32_e32 v202, 16, v150
	v_and_b32_e32 v203, 0xffff0000, v150
	v_lshlrev_b32_e32 v204, 16, v151
	v_and_b32_e32 v205, 0xffff0000, v151
	v_pk_add_f32 v[116:117], v[116:117], v[202:203]
	v_pk_add_f32 v[118:119], v[118:119], v[204:205]
	v_lshlrev_b32_e32 v202, 16, v152
	v_and_b32_e32 v203, 0xffff0000, v152
	v_lshlrev_b32_e32 v204, 16, v153
	v_and_b32_e32 v205, 0xffff0000, v153
	v_pk_add_f32 v[112:113], v[112:113], v[202:203]
	v_pk_add_f32 v[114:115], v[114:115], v[204:205]
	v_cvt_pk_bf16_f32 v150, v116, v117
	v_cvt_pk_bf16_f32 v151, v118, v119
	v_cvt_pk_bf16_f32 v152, v112, v113
	v_cvt_pk_bf16_f32 v153, v114, v115
	v_pk_fma_f32 v[138:139], v[116:117], v[116:117], v[138:139]
	global_store_dwordx4 v207, v[150:153], s[8:9] offset:256
	v_pk_fma_f32 v[138:139], v[118:119], v[118:119], v[138:139]
	v_pk_fma_f32 v[138:139], v[112:113], v[112:113], v[138:139]
	v_pk_fma_f32 v[138:139], v[114:115], v[114:115], v[138:139]
	v_add_f32_e32 v214, v138, v139
	v_add_u32_e32 v207, 0x8000, v207
	v_mov_b32_e32 v215, v214
	s_nop 1
	v_permlane16_swap_b32_e32 v214, v215
	s_nop 0
	v_add_f32_e32 v214, v214, v215
	v_mov_b32_e32 v215, v214
	s_nop 1
	v_permlane32_swap_b32_e32 v214, v215
	s_nop 0
	v_add_f32_e32 v214, v214, v215
	s_and_saveexec_b64 s[26:27], s[4:5]
	global_store_dword v210, v214, s[14:15]
	s_mov_b64 exec, s[26:27]
	global_load_dwordx4 v[146:149], v206, s[8:9]
	global_load_dwordx4 v[150:153], v206, s[8:9] offset:256
	s_waitcnt vmcnt(15)
	v_lshlrev_b32_e32 v202, 16, v154
	v_and_b32_e32 v203, 0xffff0000, v154
	v_lshlrev_b32_e32 v204, 16, v155
	v_and_b32_e32 v205, 0xffff0000, v155
	v_pk_add_f32 v[108:109], v[108:109], v[202:203]
	v_pk_add_f32 v[110:111], v[110:111], v[204:205]
	v_lshlrev_b32_e32 v202, 16, v156
	v_and_b32_e32 v203, 0xffff0000, v156
	v_lshlrev_b32_e32 v204, 16, v157
	v_and_b32_e32 v205, 0xffff0000, v157
	v_pk_add_f32 v[104:105], v[104:105], v[202:203]
	v_pk_add_f32 v[106:107], v[106:107], v[204:205]
	v_cvt_pk_bf16_f32 v154, v108, v109
	v_cvt_pk_bf16_f32 v155, v110, v111
	v_cvt_pk_bf16_f32 v156, v104, v105
	v_cvt_pk_bf16_f32 v157, v106, v107
	v_pk_mul_f32 v[138:139], v[108:109], v[108:109]
	global_store_dwordx4 v207, v[154:157], s[8:9]
	v_pk_fma_f32 v[138:139], v[110:111], v[110:111], v[138:139]
	v_pk_fma_f32 v[138:139], v[104:105], v[104:105], v[138:139]
	v_pk_fma_f32 v[138:139], v[106:107], v[106:107], v[138:139]
	v_lshlrev_b32_e32 v202, 16, v158
	v_and_b32_e32 v203, 0xffff0000, v158
	v_lshlrev_b32_e32 v204, 16, v159
	v_and_b32_e32 v205, 0xffff0000, v159
	v_pk_add_f32 v[100:101], v[100:101], v[202:203]
	v_pk_add_f32 v[102:103], v[102:103], v[204:205]
	v_lshlrev_b32_e32 v202, 16, v160
	v_and_b32_e32 v203, 0xffff0000, v160
	v_lshlrev_b32_e32 v204, 16, v161
	v_and_b32_e32 v205, 0xffff0000, v161
	v_pk_add_f32 v[96:97], v[96:97], v[202:203]
	v_pk_add_f32 v[98:99], v[98:99], v[204:205]
	v_cvt_pk_bf16_f32 v158, v100, v101
	v_cvt_pk_bf16_f32 v159, v102, v103
	v_cvt_pk_bf16_f32 v160, v96, v97
	v_cvt_pk_bf16_f32 v161, v98, v99
	v_pk_fma_f32 v[138:139], v[100:101], v[100:101], v[138:139]
	global_store_dwordx4 v207, v[158:161], s[8:9] offset:256
	v_pk_fma_f32 v[138:139], v[102:103], v[102:103], v[138:139]
	v_pk_fma_f32 v[138:139], v[96:97], v[96:97], v[138:139]
	v_pk_fma_f32 v[138:139], v[98:99], v[98:99], v[138:139]
	v_add_f32_e32 v214, v138, v139
	v_add_u32_e32 v207, 0x8000, v207
	v_mov_b32_e32 v215, v214
	s_nop 1
	v_permlane16_swap_b32_e32 v214, v215
	s_nop 0
	v_add_f32_e32 v214, v214, v215
	v_mov_b32_e32 v215, v214
	s_nop 1
	v_permlane32_swap_b32_e32 v214, v215
	s_nop 0
	v_add_f32_e32 v214, v214, v215
	s_and_saveexec_b64 s[26:27], s[4:5]
	global_store_dword v210, v214, s[14:15] offset:1024
	s_mov_b64 exec, s[26:27]
	s_waitcnt vmcnt(16)
	v_lshlrev_b32_e32 v202, 16, v162
	v_and_b32_e32 v203, 0xffff0000, v162
	v_lshlrev_b32_e32 v204, 16, v163
	v_and_b32_e32 v205, 0xffff0000, v163
	v_pk_add_f32 v[92:93], v[92:93], v[202:203]
	v_pk_add_f32 v[94:95], v[94:95], v[204:205]
	v_lshlrev_b32_e32 v202, 16, v164
	v_and_b32_e32 v203, 0xffff0000, v164
	v_lshlrev_b32_e32 v204, 16, v165
	v_and_b32_e32 v205, 0xffff0000, v165
	v_pk_add_f32 v[88:89], v[88:89], v[202:203]
	v_pk_add_f32 v[90:91], v[90:91], v[204:205]
	v_cvt_pk_bf16_f32 v162, v92, v93
	v_cvt_pk_bf16_f32 v163, v94, v95
	v_cvt_pk_bf16_f32 v164, v88, v89
	v_cvt_pk_bf16_f32 v165, v90, v91
	v_pk_mul_f32 v[138:139], v[92:93], v[92:93]
	global_store_dwordx4 v207, v[162:165], s[8:9]
	v_pk_fma_f32 v[138:139], v[94:95], v[94:95], v[138:139]
	v_pk_fma_f32 v[138:139], v[88:89], v[88:89], v[138:139]
	v_pk_fma_f32 v[138:139], v[90:91], v[90:91], v[138:139]
	v_lshlrev_b32_e32 v202, 16, v166
	v_and_b32_e32 v203, 0xffff0000, v166
	v_lshlrev_b32_e32 v204, 16, v167
	v_and_b32_e32 v205, 0xffff0000, v167
	v_pk_add_f32 v[84:85], v[84:85], v[202:203]
	v_pk_add_f32 v[86:87], v[86:87], v[204:205]
	v_lshlrev_b32_e32 v202, 16, v168
	v_and_b32_e32 v203, 0xffff0000, v168
	v_lshlrev_b32_e32 v204, 16, v169
	v_and_b32_e32 v205, 0xffff0000, v169
	v_pk_add_f32 v[80:81], v[80:81], v[202:203]
	v_pk_add_f32 v[82:83], v[82:83], v[204:205]
	v_cvt_pk_bf16_f32 v166, v84, v85
	v_cvt_pk_bf16_f32 v167, v86, v87
	v_cvt_pk_bf16_f32 v168, v80, v81
	v_cvt_pk_bf16_f32 v169, v82, v83
	v_pk_fma_f32 v[138:139], v[84:85], v[84:85], v[138:139]
	global_store_dwordx4 v207, v[166:169], s[8:9] offset:256
	v_pk_fma_f32 v[138:139], v[86:87], v[86:87], v[138:139]
	v_pk_fma_f32 v[138:139], v[80:81], v[80:81], v[138:139]
	v_pk_fma_f32 v[138:139], v[82:83], v[82:83], v[138:139]
	v_add_f32_e32 v214, v138, v139
	v_add_u32_e32 v207, 0x8000, v207
	v_mov_b32_e32 v215, v214
	s_nop 1
	v_permlane16_swap_b32_e32 v214, v215
	s_nop 0
	v_add_f32_e32 v214, v214, v215
	v_mov_b32_e32 v215, v214
	s_nop 1
	v_permlane32_swap_b32_e32 v214, v215
	s_nop 0
	v_add_f32_e32 v214, v214, v215
	s_and_saveexec_b64 s[26:27], s[4:5]
	global_store_dword v210, v214, s[14:15] offset:2048
	s_mov_b64 exec, s[26:27]
	s_waitcnt vmcnt(17)
	v_lshlrev_b32_e32 v202, 16, v170
	v_and_b32_e32 v203, 0xffff0000, v170
	v_lshlrev_b32_e32 v204, 16, v171
	v_and_b32_e32 v205, 0xffff0000, v171
	v_pk_add_f32 v[76:77], v[76:77], v[202:203]
	v_pk_add_f32 v[78:79], v[78:79], v[204:205]
	v_lshlrev_b32_e32 v202, 16, v172
	v_and_b32_e32 v203, 0xffff0000, v172
	v_lshlrev_b32_e32 v204, 16, v173
	v_and_b32_e32 v205, 0xffff0000, v173
	v_pk_add_f32 v[72:73], v[72:73], v[202:203]
	v_pk_add_f32 v[74:75], v[74:75], v[204:205]
	v_cvt_pk_bf16_f32 v170, v76, v77
	v_cvt_pk_bf16_f32 v171, v78, v79
	v_cvt_pk_bf16_f32 v172, v72, v73
	v_cvt_pk_bf16_f32 v173, v74, v75
	v_pk_mul_f32 v[138:139], v[76:77], v[76:77]
	global_store_dwordx4 v207, v[170:173], s[8:9]
	v_pk_fma_f32 v[138:139], v[78:79], v[78:79], v[138:139]
	v_pk_fma_f32 v[138:139], v[72:73], v[72:73], v[138:139]
	v_pk_fma_f32 v[138:139], v[74:75], v[74:75], v[138:139]
	v_lshlrev_b32_e32 v202, 16, v174
	v_and_b32_e32 v203, 0xffff0000, v174
	v_lshlrev_b32_e32 v204, 16, v175
	v_and_b32_e32 v205, 0xffff0000, v175
	v_pk_add_f32 v[68:69], v[68:69], v[202:203]
	v_pk_add_f32 v[70:71], v[70:71], v[204:205]
	v_lshlrev_b32_e32 v202, 16, v176
	v_and_b32_e32 v203, 0xffff0000, v176
	v_lshlrev_b32_e32 v204, 16, v177
	v_and_b32_e32 v205, 0xffff0000, v177
	v_pk_add_f32 v[64:65], v[64:65], v[202:203]
	v_pk_add_f32 v[66:67], v[66:67], v[204:205]
	v_cvt_pk_bf16_f32 v174, v68, v69
	v_cvt_pk_bf16_f32 v175, v70, v71
	v_cvt_pk_bf16_f32 v176, v64, v65
	v_cvt_pk_bf16_f32 v177, v66, v67
	v_pk_fma_f32 v[138:139], v[68:69], v[68:69], v[138:139]
	global_store_dwordx4 v207, v[174:177], s[8:9] offset:256
	v_pk_fma_f32 v[138:139], v[70:71], v[70:71], v[138:139]
	v_pk_fma_f32 v[138:139], v[64:65], v[64:65], v[138:139]
	v_pk_fma_f32 v[138:139], v[66:67], v[66:67], v[138:139]
	v_add_f32_e32 v214, v138, v139
	v_add_u32_e32 v207, 0x28000, v207
	v_mov_b32_e32 v215, v214
	s_nop 1
	v_permlane16_swap_b32_e32 v214, v215
	s_nop 0
	v_add_f32_e32 v214, v214, v215
	v_mov_b32_e32 v215, v214
	s_nop 1
	v_permlane32_swap_b32_e32 v214, v215
	s_nop 0
	v_add_f32_e32 v214, v214, v215
	s_and_saveexec_b64 s[26:27], s[4:5]
	global_store_dword v210, v214, s[14:15] offset:3072
	s_mov_b64 exec, s[26:27]
	v_add_u32_e32 v210, 0x2000, v210
	s_waitcnt vmcnt(18)
	v_lshlrev_b32_e32 v202, 16, v178
	v_and_b32_e32 v203, 0xffff0000, v178
	v_lshlrev_b32_e32 v204, 16, v179
	v_and_b32_e32 v205, 0xffff0000, v179
	v_pk_add_f32 v[60:61], v[60:61], v[202:203]
	v_pk_add_f32 v[62:63], v[62:63], v[204:205]
	v_lshlrev_b32_e32 v202, 16, v180
	v_and_b32_e32 v203, 0xffff0000, v180
	v_lshlrev_b32_e32 v204, 16, v181
	v_and_b32_e32 v205, 0xffff0000, v181
	v_pk_add_f32 v[56:57], v[56:57], v[202:203]
	v_pk_add_f32 v[58:59], v[58:59], v[204:205]
	v_cvt_pk_bf16_f32 v178, v60, v61
	v_cvt_pk_bf16_f32 v179, v62, v63
	v_cvt_pk_bf16_f32 v180, v56, v57
	v_cvt_pk_bf16_f32 v181, v58, v59
	v_pk_mul_f32 v[138:139], v[60:61], v[60:61]
	global_store_dwordx4 v207, v[178:181], s[8:9]
	v_pk_fma_f32 v[138:139], v[62:63], v[62:63], v[138:139]
	v_pk_fma_f32 v[138:139], v[56:57], v[56:57], v[138:139]
	v_pk_fma_f32 v[138:139], v[58:59], v[58:59], v[138:139]
	v_lshlrev_b32_e32 v202, 16, v182
	v_and_b32_e32 v203, 0xffff0000, v182
	v_lshlrev_b32_e32 v204, 16, v183
	v_and_b32_e32 v205, 0xffff0000, v183
	v_pk_add_f32 v[52:53], v[52:53], v[202:203]
	v_pk_add_f32 v[54:55], v[54:55], v[204:205]
	v_lshlrev_b32_e32 v202, 16, v184
	v_and_b32_e32 v203, 0xffff0000, v184
	v_lshlrev_b32_e32 v204, 16, v185
	v_and_b32_e32 v205, 0xffff0000, v185
	v_pk_add_f32 v[48:49], v[48:49], v[202:203]
	v_pk_add_f32 v[50:51], v[50:51], v[204:205]
	v_cvt_pk_bf16_f32 v182, v52, v53
	v_cvt_pk_bf16_f32 v183, v54, v55
	v_cvt_pk_bf16_f32 v184, v48, v49
	v_cvt_pk_bf16_f32 v185, v50, v51
	v_pk_fma_f32 v[138:139], v[52:53], v[52:53], v[138:139]
	global_store_dwordx4 v207, v[182:185], s[8:9] offset:256
	v_pk_fma_f32 v[138:139], v[54:55], v[54:55], v[138:139]
	v_pk_fma_f32 v[138:139], v[48:49], v[48:49], v[138:139]
	v_pk_fma_f32 v[138:139], v[50:51], v[50:51], v[138:139]
	v_add_f32_e32 v214, v138, v139
	v_add_u32_e32 v207, 0x8000, v207
	v_mov_b32_e32 v215, v214
	s_nop 1
	v_permlane16_swap_b32_e32 v214, v215
	s_nop 0
	v_add_f32_e32 v214, v214, v215
	v_mov_b32_e32 v215, v214
	s_nop 1
	v_permlane32_swap_b32_e32 v214, v215
	s_nop 0
	v_add_f32_e32 v214, v214, v215
	s_and_saveexec_b64 s[26:27], s[4:5]
	global_store_dword v210, v214, s[14:15]
	s_mov_b64 exec, s[26:27]
	s_waitcnt vmcnt(19)
	v_lshlrev_b32_e32 v202, 16, v186
	v_and_b32_e32 v203, 0xffff0000, v186
	v_lshlrev_b32_e32 v204, 16, v187
	v_and_b32_e32 v205, 0xffff0000, v187
	v_pk_add_f32 v[44:45], v[44:45], v[202:203]
	v_pk_add_f32 v[46:47], v[46:47], v[204:205]
	v_lshlrev_b32_e32 v202, 16, v188
	v_and_b32_e32 v203, 0xffff0000, v188
	v_lshlrev_b32_e32 v204, 16, v189
	v_and_b32_e32 v205, 0xffff0000, v189
	v_pk_add_f32 v[40:41], v[40:41], v[202:203]
	v_pk_add_f32 v[42:43], v[42:43], v[204:205]
	v_cvt_pk_bf16_f32 v186, v44, v45
	v_cvt_pk_bf16_f32 v187, v46, v47
	v_cvt_pk_bf16_f32 v188, v40, v41
	v_cvt_pk_bf16_f32 v189, v42, v43
	v_pk_mul_f32 v[138:139], v[44:45], v[44:45]
	global_store_dwordx4 v207, v[186:189], s[8:9]
	v_pk_fma_f32 v[138:139], v[46:47], v[46:47], v[138:139]
	v_pk_fma_f32 v[138:139], v[40:41], v[40:41], v[138:139]
	v_pk_fma_f32 v[138:139], v[42:43], v[42:43], v[138:139]
	v_lshlrev_b32_e32 v202, 16, v190
	v_and_b32_e32 v203, 0xffff0000, v190
	v_lshlrev_b32_e32 v204, 16, v191
	v_and_b32_e32 v205, 0xffff0000, v191
	v_pk_add_f32 v[36:37], v[36:37], v[202:203]
	v_pk_add_f32 v[38:39], v[38:39], v[204:205]
	v_lshlrev_b32_e32 v202, 16, v192
	v_and_b32_e32 v203, 0xffff0000, v192
	v_lshlrev_b32_e32 v204, 16, v193
	v_and_b32_e32 v205, 0xffff0000, v193
	v_pk_add_f32 v[32:33], v[32:33], v[202:203]
	v_pk_add_f32 v[34:35], v[34:35], v[204:205]
	v_cvt_pk_bf16_f32 v190, v36, v37
	v_cvt_pk_bf16_f32 v191, v38, v39
	v_cvt_pk_bf16_f32 v192, v32, v33
	v_cvt_pk_bf16_f32 v193, v34, v35
	v_pk_fma_f32 v[138:139], v[36:37], v[36:37], v[138:139]
	global_store_dwordx4 v207, v[190:193], s[8:9] offset:256
	v_pk_fma_f32 v[138:139], v[38:39], v[38:39], v[138:139]
	v_pk_fma_f32 v[138:139], v[32:33], v[32:33], v[138:139]
	v_pk_fma_f32 v[138:139], v[34:35], v[34:35], v[138:139]
	v_add_f32_e32 v214, v138, v139
	v_add_u32_e32 v207, 0x8000, v207
	v_mov_b32_e32 v215, v214
	s_nop 1
	v_permlane16_swap_b32_e32 v214, v215
	s_nop 0
	v_add_f32_e32 v214, v214, v215
	v_mov_b32_e32 v215, v214
	s_nop 1
	v_permlane32_swap_b32_e32 v214, v215
	s_nop 0
	v_add_f32_e32 v214, v214, v215
	s_and_saveexec_b64 s[26:27], s[4:5]
	global_store_dword v210, v214, s[14:15] offset:1024
	s_mov_b64 exec, s[26:27]
	s_waitcnt vmcnt(20)
	v_lshlrev_b32_e32 v202, 16, v194
	v_and_b32_e32 v203, 0xffff0000, v194
	v_lshlrev_b32_e32 v204, 16, v195
	v_and_b32_e32 v205, 0xffff0000, v195
	v_pk_add_f32 v[28:29], v[28:29], v[202:203]
	v_pk_add_f32 v[30:31], v[30:31], v[204:205]
	v_lshlrev_b32_e32 v202, 16, v196
	v_and_b32_e32 v203, 0xffff0000, v196
	v_lshlrev_b32_e32 v204, 16, v197
	v_and_b32_e32 v205, 0xffff0000, v197
	v_pk_add_f32 v[24:25], v[24:25], v[202:203]
	v_pk_add_f32 v[26:27], v[26:27], v[204:205]
	v_cvt_pk_bf16_f32 v194, v28, v29
	v_cvt_pk_bf16_f32 v195, v30, v31
	v_cvt_pk_bf16_f32 v196, v24, v25
	v_cvt_pk_bf16_f32 v197, v26, v27
	v_pk_mul_f32 v[138:139], v[28:29], v[28:29]
	global_store_dwordx4 v207, v[194:197], s[8:9]
	v_pk_fma_f32 v[138:139], v[30:31], v[30:31], v[138:139]
	v_pk_fma_f32 v[138:139], v[24:25], v[24:25], v[138:139]
	v_pk_fma_f32 v[138:139], v[26:27], v[26:27], v[138:139]
	v_lshlrev_b32_e32 v202, 16, v198
	v_and_b32_e32 v203, 0xffff0000, v198
	v_lshlrev_b32_e32 v204, 16, v199
	v_and_b32_e32 v205, 0xffff0000, v199
	v_pk_add_f32 v[20:21], v[20:21], v[202:203]
	v_pk_add_f32 v[22:23], v[22:23], v[204:205]
	v_lshlrev_b32_e32 v202, 16, v200
	v_and_b32_e32 v203, 0xffff0000, v200
	v_lshlrev_b32_e32 v204, 16, v201
	v_and_b32_e32 v205, 0xffff0000, v201
	v_pk_add_f32 v[16:17], v[16:17], v[202:203]
	v_pk_add_f32 v[18:19], v[18:19], v[204:205]
	v_cvt_pk_bf16_f32 v198, v20, v21
	v_cvt_pk_bf16_f32 v199, v22, v23
	v_cvt_pk_bf16_f32 v200, v16, v17
	v_cvt_pk_bf16_f32 v201, v18, v19
	v_pk_fma_f32 v[138:139], v[20:21], v[20:21], v[138:139]
	global_store_dwordx4 v207, v[198:201], s[8:9] offset:256
	v_pk_fma_f32 v[138:139], v[22:23], v[22:23], v[138:139]
	v_pk_fma_f32 v[138:139], v[16:17], v[16:17], v[138:139]
	v_pk_fma_f32 v[138:139], v[18:19], v[18:19], v[138:139]
	v_add_f32_e32 v214, v138, v139
	v_add_u32_e32 v207, 0x8000, v207
	v_mov_b32_e32 v215, v214
	s_nop 1
	v_permlane16_swap_b32_e32 v214, v215
	s_nop 0
	v_add_f32_e32 v214, v214, v215
	v_mov_b32_e32 v215, v214
	s_nop 1
	v_permlane32_swap_b32_e32 v214, v215
	s_nop 0
	v_add_f32_e32 v214, v214, v215
	s_and_saveexec_b64 s[26:27], s[4:5]
	global_store_dword v210, v214, s[14:15] offset:2048
	s_mov_b64 exec, s[26:27]
	s_waitcnt vmcnt(18)
	v_lshlrev_b32_e32 v202, 16, v146
	v_and_b32_e32 v203, 0xffff0000, v146
	v_lshlrev_b32_e32 v204, 16, v147
	v_and_b32_e32 v205, 0xffff0000, v147
	v_pk_add_f32 v[12:13], v[12:13], v[202:203]
	v_pk_add_f32 v[14:15], v[14:15], v[204:205]
	v_lshlrev_b32_e32 v202, 16, v148
	v_and_b32_e32 v203, 0xffff0000, v148
	v_lshlrev_b32_e32 v204, 16, v149
	v_and_b32_e32 v205, 0xffff0000, v149
	v_pk_add_f32 v[8:9], v[8:9], v[202:203]
	v_pk_add_f32 v[10:11], v[10:11], v[204:205]
	v_cvt_pk_bf16_f32 v146, v12, v13
	v_cvt_pk_bf16_f32 v147, v14, v15
	v_cvt_pk_bf16_f32 v148, v8, v9
	v_cvt_pk_bf16_f32 v149, v10, v11
	v_pk_mul_f32 v[138:139], v[12:13], v[12:13]
	global_store_dwordx4 v207, v[146:149], s[8:9]
	v_pk_fma_f32 v[138:139], v[14:15], v[14:15], v[138:139]
	v_pk_fma_f32 v[138:139], v[8:9], v[8:9], v[138:139]
	v_pk_fma_f32 v[138:139], v[10:11], v[10:11], v[138:139]
	v_lshlrev_b32_e32 v202, 16, v150
	v_and_b32_e32 v203, 0xffff0000, v150
	v_lshlrev_b32_e32 v204, 16, v151
	v_and_b32_e32 v205, 0xffff0000, v151
	v_pk_add_f32 v[4:5], v[4:5], v[202:203]
	v_pk_add_f32 v[6:7], v[6:7], v[204:205]
	v_lshlrev_b32_e32 v202, 16, v152
	v_and_b32_e32 v203, 0xffff0000, v152
	v_lshlrev_b32_e32 v204, 16, v153
	v_and_b32_e32 v205, 0xffff0000, v153
	v_pk_add_f32 v[0:1], v[0:1], v[202:203]
	v_pk_add_f32 v[2:3], v[2:3], v[204:205]
	v_cvt_pk_bf16_f32 v150, v4, v5
	v_cvt_pk_bf16_f32 v151, v6, v7
	v_cvt_pk_bf16_f32 v152, v0, v1
	v_cvt_pk_bf16_f32 v153, v2, v3
	v_pk_fma_f32 v[138:139], v[4:5], v[4:5], v[138:139]
	global_store_dwordx4 v207, v[150:153], s[8:9] offset:256
	v_pk_fma_f32 v[138:139], v[6:7], v[6:7], v[138:139]
	v_pk_fma_f32 v[138:139], v[0:1], v[0:1], v[138:139]
	v_pk_fma_f32 v[138:139], v[2:3], v[2:3], v[138:139]
	v_add_f32_e32 v214, v138, v139
	v_add_u32_e32 v207, 0x8000, v207
	v_mov_b32_e32 v215, v214
	s_nop 1
	v_permlane16_swap_b32_e32 v214, v215
	s_nop 0
	v_add_f32_e32 v214, v214, v215
	v_mov_b32_e32 v215, v214
	s_nop 1
	v_permlane32_swap_b32_e32 v214, v215
	s_nop 0
	v_add_f32_e32 v214, v214, v215
	s_and_saveexec_b64 s[26:27], s[4:5]
	global_store_dword v210, v214, s[14:15] offset:3072
	s_mov_b64 exec, s[26:27]
	s_branch .LBB0_870

.LBB0_921:
	s_add_u32 s8, s6, 0xfffe0080
	s_addc_u32 s9, s7, -1
	s_add_i32 s84, 0, 0x10000
	v_add_u32_e32 v140, s84, v253
	ds_read_b128 v[128:131], v140
	ds_read_b128 v[132:135], v140 offset:1024
	ds_read_b128 v[136:139], v140 offset:2048
	ds_read_b128 v[140:143], v140 offset:3072
	s_cmp_eq_u32 s73, 12
	s_cselect_b32 s11, s15, s9
	s_cselect_b32 s10, s39, s8
	s_cselect_b32 s9, s65, vcc_hi
	s_cselect_b32 s8, s67, vcc_lo
	s_add_i32 m0, s46, 0xc000
	ds_read_b128 v[144:147], v251
	ds_read_b128 v[148:151], v251 offset:1024
	ds_read_b128 v[152:155], v251 offset:2048
	ds_read_b128 v[156:159], v251 offset:3072
	ds_read_b128 v[160:163], v251 offset:4096
	ds_read_b128 v[164:167], v251 offset:5120
	ds_read_b128 v[168:171], v251 offset:6144
	global_load_lds_dwordx4 v220, s[6:7]
	s_add_i32 m0, s46, 0xe000
	ds_read_b128 v[172:175], v251 offset:7168
	global_load_lds_dwordx4 v222, s[6:7]
	s_waitcnt lgkmcnt(8)
	s_barrier
	s_waitcnt lgkmcnt(0)
	v_mfma_f32_16x16x32_bf16 v[124:127], v[128:131], v[144:147], v[124:127]
	v_mfma_f32_16x16x32_bf16 v[120:123], v[136:139], v[144:147], v[120:123]
	v_mfma_f32_16x16x32_bf16 v[92:95], v[128:131], v[152:155], v[92:95]
	v_mfma_f32_16x16x32_bf16 v[44:47], v[136:139], v[152:155], v[44:47]
	v_mfma_f32_16x16x32_bf16 v[84:87], v[128:131], v[160:163], v[84:87]
	v_mfma_f32_16x16x32_bf16 v[40:43], v[136:139], v[160:163], v[40:43]
	v_mfma_f32_16x16x32_bf16 v[76:79], v[128:131], v[168:171], v[76:79]
	v_mfma_f32_16x16x32_bf16 v[36:39], v[136:139], v[168:171], v[36:39]
	v_mfma_f32_16x16x32_bf16 v[124:127], v[132:135], v[148:151], v[124:127]
	v_mfma_f32_16x16x32_bf16 v[120:123], v[140:143], v[148:151], v[120:123]
	v_mfma_f32_16x16x32_bf16 v[92:95], v[132:135], v[156:159], v[92:95]
	v_mfma_f32_16x16x32_bf16 v[44:47], v[140:143], v[156:159], v[44:47]
	v_mfma_f32_16x16x32_bf16 v[84:87], v[132:135], v[164:167], v[84:87]
	v_mfma_f32_16x16x32_bf16 v[40:43], v[140:143], v[164:167], v[40:43]
	v_mfma_f32_16x16x32_bf16 v[76:79], v[132:135], v[172:175], v[76:79]
	v_mfma_f32_16x16x32_bf16 v[36:39], v[140:143], v[172:175], v[36:39]
	s_barrier
	s_add_i32 s86, 0, 0x14000
	s_add_i32 s84, s84, s88
	v_add_u32_e32 v188, s86, v253
	s_add_u32 s98, s8, s40
	s_addc_u32 s99, s9, s41
	s_mov_b32 m0, s84
	ds_read_b128 v[176:179], v188
	ds_read_b128 v[180:183], v188 offset:1024
	ds_read_b128 v[184:187], v188 offset:2048
	global_load_lds_dwordx4 v208, s[8:9]
	s_add_i32 m0, s84, 0x2000
	ds_read_b128 v[188:191], v188 offset:3072
	global_load_lds_dwordx4 v214, s[8:9]
	s_barrier
	s_waitcnt lgkmcnt(0)
	v_mfma_f32_16x16x32_bf16 v[116:119], v[176:179], v[144:147], v[116:119]
	v_mfma_f32_16x16x32_bf16 v[112:115], v[184:187], v[144:147], v[112:115]
	v_mfma_f32_16x16x32_bf16 v[88:91], v[176:179], v[152:155], v[88:91]
	v_mfma_f32_16x16x32_bf16 v[32:35], v[184:187], v[152:155], v[32:35]
	v_mfma_f32_16x16x32_bf16 v[80:83], v[176:179], v[160:163], v[80:83]
	v_mfma_f32_16x16x32_bf16 v[28:31], v[184:187], v[160:163], v[28:31]
	v_mfma_f32_16x16x32_bf16 v[72:75], v[176:179], v[168:171], v[72:75]
	v_mfma_f32_16x16x32_bf16 v[24:27], v[184:187], v[168:171], v[24:27]
	v_mfma_f32_16x16x32_bf16 v[116:119], v[180:183], v[148:151], v[116:119]
	v_mfma_f32_16x16x32_bf16 v[112:115], v[188:191], v[148:151], v[112:115]
	v_mfma_f32_16x16x32_bf16 v[88:91], v[180:183], v[156:159], v[88:91]
	v_mfma_f32_16x16x32_bf16 v[32:35], v[188:191], v[156:159], v[32:35]
	v_mfma_f32_16x16x32_bf16 v[80:83], v[180:183], v[164:167], v[80:83]
	v_mfma_f32_16x16x32_bf16 v[28:31], v[188:191], v[164:167], v[28:31]
	v_mfma_f32_16x16x32_bf16 v[72:75], v[180:183], v[172:175], v[72:75]
	v_mfma_f32_16x16x32_bf16 v[24:27], v[188:191], v[172:175], v[24:27]
	s_mov_b32 m0, s46
	s_add_u32 s100, s10, s40
	s_addc_u32 s101, s11, s41
	s_barrier
	ds_read_b128 v[144:147], v251 offset:16384
	ds_read_b128 v[148:151], v251 offset:17408
	ds_read_b128 v[152:155], v251 offset:18432
	ds_read_b128 v[156:159], v251 offset:19456
	ds_read_b128 v[160:163], v251 offset:20480
	ds_read_b128 v[164:167], v251 offset:21504
	ds_read_b128 v[168:171], v251 offset:22528
	global_load_lds_dwordx4 v218, s[10:11]
	s_mov_b32 m0, s50
	ds_read_b128 v[172:175], v251 offset:23552
	global_load_lds_dwordx4 v216, s[10:11]
	s_barrier
	s_waitcnt lgkmcnt(0)
	v_mfma_f32_16x16x32_bf16 v[68:71], v[128:131], v[144:147], v[68:71]
	v_mfma_f32_16x16x32_bf16 v[20:23], v[136:139], v[144:147], v[20:23]
	v_mfma_f32_16x16x32_bf16 v[64:67], v[128:131], v[152:155], v[64:67]
	v_mfma_f32_16x16x32_bf16 v[16:19], v[136:139], v[152:155], v[16:19]
	v_mfma_f32_16x16x32_bf16 v[60:63], v[128:131], v[160:163], v[60:63]
	v_mfma_f32_16x16x32_bf16 v[12:15], v[136:139], v[160:163], v[12:15]
	v_mfma_f32_16x16x32_bf16 v[108:111], v[128:131], v[168:171], v[108:111]
	v_mfma_f32_16x16x32_bf16 v[104:107], v[136:139], v[168:171], v[104:107]
	v_mfma_f32_16x16x32_bf16 v[68:71], v[132:135], v[148:151], v[68:71]
	v_mfma_f32_16x16x32_bf16 v[20:23], v[140:143], v[148:151], v[20:23]
	v_mfma_f32_16x16x32_bf16 v[64:67], v[132:135], v[156:159], v[64:67]
	v_mfma_f32_16x16x32_bf16 v[16:19], v[140:143], v[156:159], v[16:19]
	v_mfma_f32_16x16x32_bf16 v[60:63], v[132:135], v[164:167], v[60:63]
	v_mfma_f32_16x16x32_bf16 v[12:15], v[140:143], v[164:167], v[12:15]
	v_mfma_f32_16x16x32_bf16 v[108:111], v[132:135], v[172:175], v[108:111]
	v_mfma_f32_16x16x32_bf16 v[104:107], v[140:143], v[172:175], v[104:107]
	s_barrier
	s_add_u32 s84, s8, 0x40000
	s_addc_u32 s85, s9, 0
	s_add_i32 s86, s86, s88
	s_mov_b32 m0, s86
	s_nop 0
	global_load_lds_dwordx4 v208, s[84:85]
	s_add_i32 m0, s86, 0x2000
	s_nop 0
	global_load_lds_dwordx4 v214, s[84:85]
	s_waitcnt vmcnt(6)
	s_barrier
	v_mfma_f32_16x16x32_bf16 v[56:59], v[176:179], v[144:147], v[56:59]
	v_mfma_f32_16x16x32_bf16 v[8:11], v[184:187], v[144:147], v[8:11]
	v_mfma_f32_16x16x32_bf16 v[52:55], v[176:179], v[152:155], v[52:55]
	v_mfma_f32_16x16x32_bf16 v[4:7], v[184:187], v[152:155], v[4:7]
	v_mfma_f32_16x16x32_bf16 v[48:51], v[176:179], v[160:163], v[48:51]
	v_mfma_f32_16x16x32_bf16 v[0:3], v[184:187], v[160:163], v[0:3]
	v_mfma_f32_16x16x32_bf16 v[100:103], v[176:179], v[168:171], v[100:103]
	v_mfma_f32_16x16x32_bf16 v[96:99], v[184:187], v[168:171], v[96:99]
	v_mfma_f32_16x16x32_bf16 v[56:59], v[180:183], v[148:151], v[56:59]
	v_mfma_f32_16x16x32_bf16 v[8:11], v[188:191], v[148:151], v[8:11]
	v_mfma_f32_16x16x32_bf16 v[52:55], v[180:183], v[156:159], v[52:55]
	v_mfma_f32_16x16x32_bf16 v[4:7], v[188:191], v[156:159], v[4:7]
	v_mfma_f32_16x16x32_bf16 v[48:51], v[180:183], v[164:167], v[48:51]
	v_mfma_f32_16x16x32_bf16 v[0:3], v[188:191], v[164:167], v[0:3]
	v_mfma_f32_16x16x32_bf16 v[100:103], v[180:183], v[172:175], v[100:103]
	v_mfma_f32_16x16x32_bf16 v[96:99], v[188:191], v[172:175], v[96:99]
	s_add_i32 s84, 0, 0x18000
	v_add_u32_e32 v140, s84, v253
	s_barrier
	ds_read_b128 v[128:131], v140
	ds_read_b128 v[132:135], v140 offset:1024
	ds_read_b128 v[136:139], v140 offset:2048
	ds_read_b128 v[140:143], v140 offset:3072
	s_add_u32 s10, s10, 0x20000
	s_addc_u32 s11, s11, 0
	s_mov_b32 m0, s51
	ds_read_b128 v[144:147], v251 offset:32768
	ds_read_b128 v[148:151], v251 offset:33792
	ds_read_b128 v[152:155], v251 offset:34816
	ds_read_b128 v[156:159], v251 offset:35840
	ds_read_b128 v[160:163], v251 offset:36864
	ds_read_b128 v[164:167], v251 offset:37888
	ds_read_b128 v[168:171], v251 offset:38912
	global_load_lds_dwordx4 v218, s[10:11]
	s_mov_b32 m0, s34
	ds_read_b128 v[172:175], v251 offset:39936
	global_load_lds_dwordx4 v216, s[10:11]
	s_waitcnt lgkmcnt(8)
	s_barrier
	s_waitcnt lgkmcnt(0)
	v_mfma_f32_16x16x32_bf16 v[124:127], v[128:131], v[144:147], v[124:127]
	v_mfma_f32_16x16x32_bf16 v[120:123], v[136:139], v[144:147], v[120:123]
	v_mfma_f32_16x16x32_bf16 v[92:95], v[128:131], v[152:155], v[92:95]
	v_mfma_f32_16x16x32_bf16 v[44:47], v[136:139], v[152:155], v[44:47]
	v_mfma_f32_16x16x32_bf16 v[84:87], v[128:131], v[160:163], v[84:87]
	v_mfma_f32_16x16x32_bf16 v[40:43], v[136:139], v[160:163], v[40:43]
	v_mfma_f32_16x16x32_bf16 v[76:79], v[128:131], v[168:171], v[76:79]
	v_mfma_f32_16x16x32_bf16 v[36:39], v[136:139], v[168:171], v[36:39]
	v_mfma_f32_16x16x32_bf16 v[124:127], v[132:135], v[148:151], v[124:127]
	v_mfma_f32_16x16x32_bf16 v[120:123], v[140:143], v[148:151], v[120:123]
	v_mfma_f32_16x16x32_bf16 v[92:95], v[132:135], v[156:159], v[92:95]
	v_mfma_f32_16x16x32_bf16 v[44:47], v[140:143], v[156:159], v[44:47]
	v_mfma_f32_16x16x32_bf16 v[84:87], v[132:135], v[164:167], v[84:87]
	v_mfma_f32_16x16x32_bf16 v[40:43], v[140:143], v[164:167], v[40:43]
	v_mfma_f32_16x16x32_bf16 v[76:79], v[132:135], v[172:175], v[76:79]
	v_mfma_f32_16x16x32_bf16 v[36:39], v[140:143], v[172:175], v[36:39]
	s_barrier
	s_add_i32 s10, 0, 0x1c000
	s_add_i32 s11, s84, s88
	v_add_u32_e32 v188, s10, v253
	s_mov_b32 m0, s11
	ds_read_b128 v[176:179], v188
	ds_read_b128 v[180:183], v188 offset:1024
	ds_read_b128 v[184:187], v188 offset:2048
	global_load_lds_dwordx4 v208, s[98:99]
	s_add_i32 m0, s11, 0x2000
	ds_read_b128 v[188:191], v188 offset:3072
	global_load_lds_dwordx4 v214, s[98:99]
	s_barrier
	s_waitcnt lgkmcnt(0)
	v_mfma_f32_16x16x32_bf16 v[116:119], v[176:179], v[144:147], v[116:119]
	v_mfma_f32_16x16x32_bf16 v[112:115], v[184:187], v[144:147], v[112:115]
	v_mfma_f32_16x16x32_bf16 v[88:91], v[176:179], v[152:155], v[88:91]
	v_mfma_f32_16x16x32_bf16 v[32:35], v[184:187], v[152:155], v[32:35]
	v_mfma_f32_16x16x32_bf16 v[80:83], v[176:179], v[160:163], v[80:83]
	v_mfma_f32_16x16x32_bf16 v[28:31], v[184:187], v[160:163], v[28:31]
	v_mfma_f32_16x16x32_bf16 v[72:75], v[176:179], v[168:171], v[72:75]
	v_mfma_f32_16x16x32_bf16 v[24:27], v[184:187], v[168:171], v[24:27]
	v_mfma_f32_16x16x32_bf16 v[116:119], v[180:183], v[148:151], v[116:119]
	v_mfma_f32_16x16x32_bf16 v[112:115], v[188:191], v[148:151], v[112:115]
	v_mfma_f32_16x16x32_bf16 v[88:91], v[180:183], v[156:159], v[88:91]
	v_mfma_f32_16x16x32_bf16 v[32:35], v[188:191], v[156:159], v[32:35]
	v_mfma_f32_16x16x32_bf16 v[80:83], v[180:183], v[164:167], v[80:83]
	v_mfma_f32_16x16x32_bf16 v[28:31], v[188:191], v[164:167], v[28:31]
	v_mfma_f32_16x16x32_bf16 v[72:75], v[180:183], v[172:175], v[72:75]
	v_mfma_f32_16x16x32_bf16 v[24:27], v[188:191], v[172:175], v[24:27]
	s_mov_b32 m0, s92
	s_barrier
	ds_read_b128 v[144:147], v251 offset:49152
	ds_read_b128 v[148:151], v251 offset:50176
	ds_read_b128 v[152:155], v251 offset:51200
	ds_read_b128 v[156:159], v251 offset:52224
	ds_read_b128 v[160:163], v251 offset:53248
	ds_read_b128 v[164:167], v251 offset:54272
	ds_read_b128 v[168:171], v251 offset:55296
	global_load_lds_dwordx4 v218, s[100:101]
	s_mov_b32 m0, s93
	ds_read_b128 v[172:175], v251 offset:56320
	global_load_lds_dwordx4 v216, s[100:101]
	s_barrier
	s_waitcnt lgkmcnt(0)
	v_mfma_f32_16x16x32_bf16 v[68:71], v[128:131], v[144:147], v[68:71]
	v_mfma_f32_16x16x32_bf16 v[20:23], v[136:139], v[144:147], v[20:23]
	v_mfma_f32_16x16x32_bf16 v[64:67], v[128:131], v[152:155], v[64:67]
	v_mfma_f32_16x16x32_bf16 v[16:19], v[136:139], v[152:155], v[16:19]
	v_mfma_f32_16x16x32_bf16 v[60:63], v[128:131], v[160:163], v[60:63]
	v_mfma_f32_16x16x32_bf16 v[12:15], v[136:139], v[160:163], v[12:15]
	v_mfma_f32_16x16x32_bf16 v[108:111], v[128:131], v[168:171], v[108:111]
	v_mfma_f32_16x16x32_bf16 v[104:107], v[136:139], v[168:171], v[104:107]
	v_mfma_f32_16x16x32_bf16 v[68:71], v[132:135], v[148:151], v[68:71]
	v_mfma_f32_16x16x32_bf16 v[20:23], v[140:143], v[148:151], v[20:23]
	v_mfma_f32_16x16x32_bf16 v[64:67], v[132:135], v[156:159], v[64:67]
	v_mfma_f32_16x16x32_bf16 v[16:19], v[140:143], v[156:159], v[16:19]
	v_mfma_f32_16x16x32_bf16 v[60:63], v[132:135], v[164:167], v[60:63]
	v_mfma_f32_16x16x32_bf16 v[12:15], v[140:143], v[164:167], v[12:15]
	v_mfma_f32_16x16x32_bf16 v[108:111], v[132:135], v[172:175], v[108:111]
	v_mfma_f32_16x16x32_bf16 v[104:107], v[140:143], v[172:175], v[104:107]
	s_barrier
	s_add_u32 s8, s8, 0x40080
	s_addc_u32 s9, s9, 0
	s_add_i32 s10, s10, s88
	s_mov_b32 m0, s10
	s_nop 0
	global_load_lds_dwordx4 v208, s[8:9]
	s_add_i32 m0, s10, 0x2000
	s_nop 0
	global_load_lds_dwordx4 v214, s[8:9]
	s_waitcnt vmcnt(6)
	s_barrier
	v_mfma_f32_16x16x32_bf16 v[56:59], v[176:179], v[144:147], v[56:59]
	v_mfma_f32_16x16x32_bf16 v[8:11], v[184:187], v[144:147], v[8:11]
	v_mfma_f32_16x16x32_bf16 v[52:55], v[176:179], v[152:155], v[52:55]
	v_mfma_f32_16x16x32_bf16 v[4:7], v[184:187], v[152:155], v[4:7]
	v_mfma_f32_16x16x32_bf16 v[48:51], v[176:179], v[160:163], v[48:51]
	v_mfma_f32_16x16x32_bf16 v[0:3], v[184:187], v[160:163], v[0:3]
	v_mfma_f32_16x16x32_bf16 v[100:103], v[176:179], v[168:171], v[100:103]
	v_mfma_f32_16x16x32_bf16 v[96:99], v[184:187], v[168:171], v[96:99]
	v_mfma_f32_16x16x32_bf16 v[56:59], v[180:183], v[148:151], v[56:59]
	v_mfma_f32_16x16x32_bf16 v[8:11], v[188:191], v[148:151], v[8:11]
	v_mfma_f32_16x16x32_bf16 v[52:55], v[180:183], v[156:159], v[52:55]
	v_mfma_f32_16x16x32_bf16 v[4:7], v[188:191], v[156:159], v[4:7]
	v_mfma_f32_16x16x32_bf16 v[48:51], v[180:183], v[164:167], v[48:51]
	v_mfma_f32_16x16x32_bf16 v[0:3], v[188:191], v[164:167], v[0:3]
	v_mfma_f32_16x16x32_bf16 v[100:103], v[180:183], v[172:175], v[100:103]
	v_mfma_f32_16x16x32_bf16 v[96:99], v[188:191], v[172:175], v[96:99]
	s_add_i32 s73, s73, 2
	s_add_u32 s6, s6, 0x100
	s_addc_u32 s7, s7, 0
	s_add_u32 vcc_lo, vcc_lo, 0x100
	s_addc_u32 vcc_hi, vcc_hi, 0
	s_cmp_gt_u32 s73, 13
	s_barrier
	s_cbranch_scc0 .LBB0_921
	s_lshl_b32 s6, s38, 8
	v_mov_b32_e32 v250, v210
	v_mov_b32_e32 v254, v249
	s_add_i32 s6, s6, s90
	v_mov_b64_e32 v[242:243], s[44:45]
	v_add_u32_e32 v234, s6, v254
	v_ashrrev_i32_e32 v235, 31, v234
	v_mbcnt_lo_u32_b32 v212, -1, 0
	v_mbcnt_hi_u32_b32 v212, -1, v212
	v_lshlrev_b32_e32 v244, 6, v234
	v_and_b32_e32 v212, 48, v212
	v_add_u32_e32 v212, v244, v212
	v_add_u32_e32 v213, 0x1000, v212
	v_add_u32_e32 v245, 0x1000, v244
	global_load_dwordx4 v[192:195], v212, s[20:21]
	global_load_dwordx4 v[196:199], v212, s[20:21] offset:1024
	global_load_dwordx4 v[200:203], v213, s[20:21] offset:2048
	global_load_dwordx4 v[204:207], v213, s[20:21] offset:3072
	global_load_dwordx4 v[160:163], v244, s[20:21] offset:2096
	global_load_dwordx4 v[164:167], v244, s[20:21] offset:2080
	global_load_dwordx4 v[176:179], v244, s[20:21] offset:2064
	global_load_dwordx4 v[180:183], v244, s[20:21] offset:2048
	global_load_dwordx4 v[168:171], v244, s[20:21] offset:3120
	global_load_dwordx4 v[172:175], v244, s[20:21] offset:3104
	global_load_dwordx4 v[184:187], v244, s[20:21] offset:3088
	global_load_dwordx4 v[188:191], v244, s[20:21] offset:3072
	global_load_dwordx4 v[144:147], v245, s[20:21] offset:48
	global_load_dwordx4 v[148:151], v245, s[20:21] offset:32
	global_load_dwordx4 v[152:155], v245, s[20:21] offset:16
	global_load_dwordx4 v[156:159], v245, s[20:21]
	global_load_dwordx4 v[128:131], v245, s[20:21] offset:1072
	global_load_dwordx4 v[132:135], v245, s[20:21] offset:1056
	global_load_dwordx4 v[136:139], v245, s[20:21] offset:1040
	global_load_dwordx4 v[140:143], v245, s[20:21] offset:1024
	v_add_u32_e32 v236, 16, v234
	v_ashrrev_i32_e32 v237, 31, v236
	v_add_u32_e32 v238, 32, v234
	v_ashrrev_i32_e32 v239, 31, v238
	v_add_u32_e32 v232, 48, v234
	v_ashrrev_i32_e32 v233, 31, v232
	v_add_u32_e32 v230, 64, v234
	v_ashrrev_i32_e32 v231, 31, v230
	v_add_u32_e32 v228, 0x50, v234
	v_ashrrev_i32_e32 v229, 31, v228
	v_add_u32_e32 v224, 0x60, v234
	v_ashrrev_i32_e32 v225, 31, v224
	v_add_u32_e32 v226, 0x70, v234
	v_ashrrev_i32_e32 v227, 31, v226
	s_lshl_b32 s14, s14, 7
	s_or_b32 s14, s14, s35
	s_waitcnt vmcnt(16)
	v_pk_add_f32 v[192:193], v[192:193], v[194:195]
	s_nop 0
	v_add_f32_e32 v246, v192, v193
	v_mov_b32_e32 v247, v246
	s_nop 1
	v_permlane16_swap_b32_e32 v246, v247
	s_nop 0
	v_add_f32_e32 v246, v246, v247
	v_mov_b32_e32 v247, v246
	s_nop 1
	v_permlane32_swap_b32_e32 v246, v247
	s_nop 0
	v_add_f32_e32 v193, v246, v247
	v_pk_add_f32 v[196:197], v[196:197], v[198:199]
	s_nop 0
	v_add_f32_e32 v246, v196, v197
	v_mov_b32_e32 v247, v246
	s_nop 1
	v_permlane16_swap_b32_e32 v246, v247
	s_nop 0
	v_add_f32_e32 v246, v246, v247
	v_mov_b32_e32 v247, v246
	s_nop 1
	v_permlane32_swap_b32_e32 v246, v247
	s_nop 0
	v_add_f32_e32 v192, v246, v247
	v_pk_add_f32 v[200:201], v[200:201], v[202:203]
	s_nop 0
	v_add_f32_e32 v246, v200, v201
	v_mov_b32_e32 v247, v246
	s_nop 1
	v_permlane16_swap_b32_e32 v246, v247
	s_nop 0
	v_add_f32_e32 v246, v246, v247
	v_mov_b32_e32 v247, v246
	s_nop 1
	v_permlane32_swap_b32_e32 v246, v247
	s_nop 0
	v_add_f32_e32 v197, v246, v247
	v_pk_add_f32 v[204:205], v[204:205], v[206:207]
	s_nop 0
	v_add_f32_e32 v246, v204, v205
	v_mov_b32_e32 v247, v246
	s_nop 1
	v_permlane16_swap_b32_e32 v246, v247
	s_nop 0
	v_add_f32_e32 v246, v246, v247
	v_mov_b32_e32 v247, v246
	s_nop 1
	v_permlane32_swap_b32_e32 v246, v247
	s_nop 0
	v_add_f32_e32 v196, v246, v247
	s_nop 0
	v_pk_fma_f32 v[240:241], v[192:193], s[42:43], v[242:243] op_sel_hi:[1,0,0]
	v_pk_fma_f32 v[202:203], v[196:197], s[42:43], v[242:243] op_sel_hi:[1,0,0]
	v_cmp_gt_f32_e64 s[6:7], s97, v240
	v_cmp_gt_f32_e32 vcc, s97, v241
	s_waitcnt vmcnt(0)
	v_lshl_add_u32 v192, v250, 3, s14
	v_add_u32_e32 v193, -14, v254
	v_cmp_gt_f32_e64 s[8:9], s97, v203
	v_cmp_gt_f32_e64 s[10:11], s97, v202
	v_cmp_lt_u32_e64 s[14:15], -13, v193
	v_ashrrev_i32_e32 v193, 31, v192
	s_and_saveexec_b64 s[86:87], s[14:15]
	s_xor_b64 s[14:15], exec, s[86:87]
	s_or_saveexec_b64 s[14:15], s[14:15]
	v_mul_f32_e32 v194, 0x4b800000, v241
	v_cndmask_b32_e32 v194, v241, v194, vcc
	v_rsq_f32_e32 v194, v194
	s_nop 0
	v_mul_f32_e32 v195, 0x45800000, v194
	v_cndmask_b32_e32 v204, v194, v195, vcc
	v_pk_mul_f32 v[196:197], v[118:119], v[204:205] op_sel_hi:[1,0]
	v_mul_f32_e32 v118, 0x4b800000, v202
	v_cndmask_b32_e64 v118, v202, v118, s[10:11]
	v_rsq_f32_e32 v118, v118
	v_pk_mul_f32 v[200:201], v[116:117], v[204:205] op_sel_hi:[1,0]
	v_pk_mul_f32 v[194:195], v[126:127], v[204:205] op_sel_hi:[1,0]
	v_pk_mul_f32 v[198:199], v[124:125], v[204:205] op_sel_hi:[1,0]
	v_mul_f32_e32 v116, 0x45800000, v118
	v_cndmask_b32_e64 v116, v118, v116, s[10:11]
	v_pk_mul_f32 v[122:123], v[122:123], v[204:205] op_sel_hi:[1,0]
	v_pk_mul_f32 v[120:121], v[120:121], v[204:205] op_sel_hi:[1,0]
	v_pk_mul_f32 v[114:115], v[114:115], v[204:205] op_sel_hi:[1,0]
	v_pk_mul_f32 v[112:113], v[112:113], v[204:205] op_sel_hi:[1,0]
	v_pk_mul_f32 v[110:111], v[110:111], v[116:117] op_sel_hi:[1,0]
	v_pk_mul_f32 v[108:109], v[108:109], v[116:117] op_sel_hi:[1,0]
	v_pk_mul_f32 v[106:107], v[106:107], v[116:117] op_sel_hi:[1,0]
	v_pk_mul_f32 v[104:105], v[104:105], v[116:117] op_sel_hi:[1,0]
	v_pk_mul_f32 v[102:103], v[102:103], v[116:117] op_sel_hi:[1,0]
	v_pk_mul_f32 v[100:101], v[100:101], v[116:117] op_sel_hi:[1,0]
	v_pk_mul_f32 v[98:99], v[98:99], v[116:117] op_sel_hi:[1,0]
	v_pk_mul_f32 v[96:97], v[96:97], v[116:117] op_sel_hi:[1,0]
	s_xor_b64 exec, exec, s[14:15]
	s_cbranch_execz .LBB0_917
	v_add_u32_e32 v116, -12, v254
	v_cmp_gt_i32_e64 s[10:11], 2, v254
	s_lshl_b32 s38, s38, 3
	s_add_i32 s38, s38, s91
	v_cndmask_b32_e64 v116, v116, v254, s[10:11]
	v_add_u32_e32 v126, s38, v116
	v_mov_b64_e32 v[124:125], s[22:23]
	s_movk_i32 s38, 0x5800
	v_mad_i64_i32 v[124:125], s[38:39], v126, s38, v[124:125]
	v_cndmask_b32_e64 v119, v111, v195, s[10:11]
	v_cndmask_b32_e64 v118, v110, v194, s[10:11]
	v_cndmask_b32_e64 v117, v109, v199, s[10:11]
	v_cndmask_b32_e64 v116, v108, v198, s[10:11]
	v_lshl_add_u64 v[124:125], v[192:193], 2, v[124:125]
	s_mov_b64 s[38:39], 0x2c00
	global_store_dwordx4 v[124:125], v[116:119], off
	v_lshl_add_u64 v[126:127], v[124:125], 0, s[38:39]
	s_movk_i32 s38, 0x2000
	v_cndmask_b32_e64 v119, v107, v123, s[10:11]
	v_cndmask_b32_e64 v118, v106, v122, s[10:11]
	v_cndmask_b32_e64 v117, v105, v121, s[10:11]
	v_cndmask_b32_e64 v116, v104, v120, s[10:11]
	global_store_dwordx4 v[124:125], v[116:119], off offset:16
	v_add_co_u32_e32 v124, vcc, s38, v124
	s_nop 0
	v_cndmask_b32_e64 v119, v103, v197, s[10:11]
	v_cndmask_b32_e64 v118, v102, v196, s[10:11]
	v_cndmask_b32_e64 v117, v101, v201, s[10:11]
	v_cndmask_b32_e64 v116, v100, v200, s[10:11]
	v_addc_co_u32_e32 v125, vcc, 0, v125, vcc
	global_store_dwordx4 v[124:125], v[116:119], off offset:3072
	s_nop 1
	v_cndmask_b32_e64 v119, v99, v115, s[10:11]
	v_cndmask_b32_e64 v118, v98, v114, s[10:11]
	v_cndmask_b32_e64 v117, v97, v113, s[10:11]
	v_cndmask_b32_e64 v116, v96, v112, s[10:11]
	global_store_dwordx4 v[126:127], v[116:119], off offset:16
	s_branch .LBB0_917

.LBB0_998:
	s_add_u32 s20, s10, 0x100
	s_addc_u32 s21, s11, 0
	s_add_i32 s60, 0, 0x10000
	v_add_u32_e32 v142, s60, v145
	ds_read_b128 v[138:141], v142
	ds_read_b128 v[148:151], v142 offset:1024
	ds_read_b128 v[152:155], v142 offset:2048
	ds_read_b128 v[156:159], v142 offset:3072
	s_cmp_eq_u32 s59, 40
	s_cselect_b32 s25, s7, s21
	s_cselect_b32 s24, s6, s20
	s_cselect_b32 s23, s9, s58
	s_cselect_b32 s22, s8, s57
	s_add_i32 m0, s34, 0xc000
	ds_read_b128 v[160:163], v147
	ds_read_b128 v[164:167], v147 offset:1024
	ds_read_b128 v[168:171], v147 offset:2048
	ds_read_b128 v[172:175], v147 offset:3072
	ds_read_b128 v[176:179], v147 offset:4096
	ds_read_b128 v[180:183], v147 offset:5120
	ds_read_b128 v[184:187], v147 offset:6144
	global_load_lds_dwordx4 v134, s[10:11]
	s_add_i32 m0, s34, 0xe000
	ds_read_b128 v[188:191], v147 offset:7168
	global_load_lds_dwordx4 v136, s[10:11]
	s_waitcnt lgkmcnt(8)
	s_barrier
	s_waitcnt lgkmcnt(0)
	v_mfma_f32_16x16x32_bf16 v[124:127], v[138:141], v[160:163], v[124:127]
	v_mfma_f32_16x16x32_bf16 v[120:123], v[152:155], v[160:163], v[120:123]
	v_mfma_f32_16x16x32_bf16 v[108:111], v[138:141], v[168:171], v[108:111]
	v_mfma_f32_16x16x32_bf16 v[104:107], v[152:155], v[168:171], v[104:107]
	v_mfma_f32_16x16x32_bf16 v[92:95], v[138:141], v[176:179], v[92:95]
	v_mfma_f32_16x16x32_bf16 v[88:91], v[152:155], v[176:179], v[88:91]
	v_mfma_f32_16x16x32_bf16 v[76:79], v[138:141], v[184:187], v[76:79]
	v_mfma_f32_16x16x32_bf16 v[72:75], v[152:155], v[184:187], v[72:75]
	v_mfma_f32_16x16x32_bf16 v[124:127], v[148:151], v[164:167], v[124:127]
	v_mfma_f32_16x16x32_bf16 v[120:123], v[156:159], v[164:167], v[120:123]
	v_mfma_f32_16x16x32_bf16 v[108:111], v[148:151], v[172:175], v[108:111]
	v_mfma_f32_16x16x32_bf16 v[104:107], v[156:159], v[172:175], v[104:107]
	v_mfma_f32_16x16x32_bf16 v[92:95], v[148:151], v[180:183], v[92:95]
	v_mfma_f32_16x16x32_bf16 v[88:91], v[156:159], v[180:183], v[88:91]
	v_mfma_f32_16x16x32_bf16 v[76:79], v[148:151], v[188:191], v[76:79]
	v_mfma_f32_16x16x32_bf16 v[72:75], v[156:159], v[188:191], v[72:75]
	s_barrier
	s_add_i32 s61, 0, 0x14000
	v_add_u32_e32 v142, s61, v145
	s_add_i32 s10, s60, s27
	ds_read_b128 v[192:195], v142
	ds_read_b128 v[196:199], v142 offset:1024
	ds_read_b128 v[200:203], v142 offset:2048
	ds_read_b128 v[204:207], v142 offset:3072
	s_add_u32 s98, s22, s40
	s_addc_u32 s99, s23, s41
	s_mov_b32 m0, s10
	s_nop 0
	global_load_lds_dwordx4 v208, s[22:23]
	s_add_i32 m0, s10, 0x2000
	s_nop 0
	global_load_lds_dwordx4 v128, s[22:23]
	s_barrier
	s_waitcnt lgkmcnt(0)
	v_mfma_f32_16x16x32_bf16 v[116:119], v[192:195], v[160:163], v[116:119]
	v_mfma_f32_16x16x32_bf16 v[112:115], v[200:203], v[160:163], v[112:115]
	v_mfma_f32_16x16x32_bf16 v[100:103], v[192:195], v[168:171], v[100:103]
	v_mfma_f32_16x16x32_bf16 v[96:99], v[200:203], v[168:171], v[96:99]
	v_mfma_f32_16x16x32_bf16 v[84:87], v[192:195], v[176:179], v[84:87]
	v_mfma_f32_16x16x32_bf16 v[80:83], v[200:203], v[176:179], v[80:83]
	v_mfma_f32_16x16x32_bf16 v[68:71], v[192:195], v[184:187], v[68:71]
	v_mfma_f32_16x16x32_bf16 v[64:67], v[200:203], v[184:187], v[64:67]
	v_mfma_f32_16x16x32_bf16 v[116:119], v[196:199], v[164:167], v[116:119]
	v_mfma_f32_16x16x32_bf16 v[112:115], v[204:207], v[164:167], v[112:115]
	v_mfma_f32_16x16x32_bf16 v[100:103], v[196:199], v[172:175], v[100:103]
	v_mfma_f32_16x16x32_bf16 v[96:99], v[204:207], v[172:175], v[96:99]
	v_mfma_f32_16x16x32_bf16 v[84:87], v[196:199], v[180:183], v[84:87]
	v_mfma_f32_16x16x32_bf16 v[80:83], v[204:207], v[180:183], v[80:83]
	v_mfma_f32_16x16x32_bf16 v[68:71], v[196:199], v[188:191], v[68:71]
	v_mfma_f32_16x16x32_bf16 v[64:67], v[204:207], v[188:191], v[64:67]
	s_mov_b32 m0, s34
	s_add_u32 s100, s24, s40
	s_addc_u32 s101, s25, s41
	s_barrier
	ds_read_b128 v[160:163], v147 offset:16384
	ds_read_b128 v[164:167], v147 offset:17408
	ds_read_b128 v[168:171], v147 offset:18432
	ds_read_b128 v[172:175], v147 offset:19456
	ds_read_b128 v[176:179], v147 offset:20480
	ds_read_b128 v[180:183], v147 offset:21504
	ds_read_b128 v[184:187], v147 offset:22528
	global_load_lds_dwordx4 v132, s[24:25]
	s_mov_b32 m0, s35
	ds_read_b128 v[188:191], v147 offset:23552
	global_load_lds_dwordx4 v130, s[24:25]
	s_barrier
	s_waitcnt lgkmcnt(0)
	v_mfma_f32_16x16x32_bf16 v[60:63], v[138:141], v[160:163], v[60:63]
	v_mfma_f32_16x16x32_bf16 v[56:59], v[152:155], v[160:163], v[56:59]
	v_mfma_f32_16x16x32_bf16 v[44:47], v[138:141], v[168:171], v[44:47]
	v_mfma_f32_16x16x32_bf16 v[40:43], v[152:155], v[168:171], v[40:43]
	v_mfma_f32_16x16x32_bf16 v[28:31], v[138:141], v[176:179], v[28:31]
	v_mfma_f32_16x16x32_bf16 v[24:27], v[152:155], v[176:179], v[24:27]
	v_mfma_f32_16x16x32_bf16 v[12:15], v[138:141], v[184:187], v[12:15]
	v_mfma_f32_16x16x32_bf16 v[8:11], v[152:155], v[184:187], v[8:11]
	v_mfma_f32_16x16x32_bf16 v[60:63], v[148:151], v[164:167], v[60:63]
	v_mfma_f32_16x16x32_bf16 v[56:59], v[156:159], v[164:167], v[56:59]
	v_mfma_f32_16x16x32_bf16 v[44:47], v[148:151], v[172:175], v[44:47]
	v_mfma_f32_16x16x32_bf16 v[40:43], v[156:159], v[172:175], v[40:43]
	v_mfma_f32_16x16x32_bf16 v[28:31], v[148:151], v[180:183], v[28:31]
	v_mfma_f32_16x16x32_bf16 v[24:27], v[156:159], v[180:183], v[24:27]
	v_mfma_f32_16x16x32_bf16 v[12:15], v[148:151], v[188:191], v[12:15]
	v_mfma_f32_16x16x32_bf16 v[8:11], v[156:159], v[188:191], v[8:11]
	s_barrier
	s_add_u32 s10, s22, 0xb0000
	s_addc_u32 s11, s23, 0
	s_add_i32 s60, s61, s27
	s_mov_b32 m0, s60
	s_nop 0
	global_load_lds_dwordx4 v208, s[10:11]
	s_add_i32 m0, s60, 0x2000
	s_nop 0
	global_load_lds_dwordx4 v128, s[10:11]
	s_waitcnt vmcnt(6)
	s_barrier
	v_mfma_f32_16x16x32_bf16 v[52:55], v[192:195], v[160:163], v[52:55]
	v_mfma_f32_16x16x32_bf16 v[48:51], v[200:203], v[160:163], v[48:51]
	v_mfma_f32_16x16x32_bf16 v[36:39], v[192:195], v[168:171], v[36:39]
	v_mfma_f32_16x16x32_bf16 v[32:35], v[200:203], v[168:171], v[32:35]
	v_mfma_f32_16x16x32_bf16 v[20:23], v[192:195], v[176:179], v[20:23]
	v_mfma_f32_16x16x32_bf16 v[16:19], v[200:203], v[176:179], v[16:19]
	v_mfma_f32_16x16x32_bf16 v[4:7], v[192:195], v[184:187], v[4:7]
	v_mfma_f32_16x16x32_bf16 v[0:3], v[200:203], v[184:187], v[0:3]
	v_mfma_f32_16x16x32_bf16 v[52:55], v[196:199], v[164:167], v[52:55]
	v_mfma_f32_16x16x32_bf16 v[48:51], v[204:207], v[164:167], v[48:51]
	v_mfma_f32_16x16x32_bf16 v[36:39], v[196:199], v[172:175], v[36:39]
	v_mfma_f32_16x16x32_bf16 v[32:35], v[204:207], v[172:175], v[32:35]
	v_mfma_f32_16x16x32_bf16 v[20:23], v[196:199], v[180:183], v[20:23]
	v_mfma_f32_16x16x32_bf16 v[16:19], v[204:207], v[180:183], v[16:19]
	v_mfma_f32_16x16x32_bf16 v[4:7], v[196:199], v[188:191], v[4:7]
	v_mfma_f32_16x16x32_bf16 v[0:3], v[204:207], v[188:191], v[0:3]
	s_add_i32 s60, 0, 0x18000
	v_add_u32_e32 v156, s60, v145
	s_barrier
	ds_read_b128 v[138:141], v156
	ds_read_b128 v[148:151], v156 offset:1024
	ds_read_b128 v[152:155], v156 offset:2048
	ds_read_b128 v[156:159], v156 offset:3072
	s_add_u32 s10, s24, 0xb0000
	s_addc_u32 s11, s25, 0
	s_mov_b32 m0, s36
	ds_read_b128 v[160:163], v147 offset:32768
	ds_read_b128 v[164:167], v147 offset:33792
	ds_read_b128 v[168:171], v147 offset:34816
	ds_read_b128 v[172:175], v147 offset:35840
	ds_read_b128 v[176:179], v147 offset:36864
	ds_read_b128 v[180:183], v147 offset:37888
	ds_read_b128 v[184:187], v147 offset:38912
	global_load_lds_dwordx4 v132, s[10:11]
	s_mov_b32 m0, s46
	ds_read_b128 v[188:191], v147 offset:39936
	global_load_lds_dwordx4 v130, s[10:11]
	s_waitcnt lgkmcnt(8)
	s_barrier
	s_waitcnt lgkmcnt(0)
	v_mfma_f32_16x16x32_bf16 v[124:127], v[138:141], v[160:163], v[124:127]
	v_mfma_f32_16x16x32_bf16 v[120:123], v[152:155], v[160:163], v[120:123]
	v_mfma_f32_16x16x32_bf16 v[108:111], v[138:141], v[168:171], v[108:111]
	v_mfma_f32_16x16x32_bf16 v[104:107], v[152:155], v[168:171], v[104:107]
	v_mfma_f32_16x16x32_bf16 v[92:95], v[138:141], v[176:179], v[92:95]
	v_mfma_f32_16x16x32_bf16 v[88:91], v[152:155], v[176:179], v[88:91]
	v_mfma_f32_16x16x32_bf16 v[76:79], v[138:141], v[184:187], v[76:79]
	v_mfma_f32_16x16x32_bf16 v[72:75], v[152:155], v[184:187], v[72:75]
	v_mfma_f32_16x16x32_bf16 v[124:127], v[148:151], v[164:167], v[124:127]
	v_mfma_f32_16x16x32_bf16 v[120:123], v[156:159], v[164:167], v[120:123]
	v_mfma_f32_16x16x32_bf16 v[108:111], v[148:151], v[172:175], v[108:111]
	v_mfma_f32_16x16x32_bf16 v[104:107], v[156:159], v[172:175], v[104:107]
	v_mfma_f32_16x16x32_bf16 v[92:95], v[148:151], v[180:183], v[92:95]
	v_mfma_f32_16x16x32_bf16 v[88:91], v[156:159], v[180:183], v[88:91]
	v_mfma_f32_16x16x32_bf16 v[76:79], v[148:151], v[188:191], v[76:79]
	v_mfma_f32_16x16x32_bf16 v[72:75], v[156:159], v[188:191], v[72:75]
	s_barrier
	s_add_i32 s24, 0, 0x1c000
	s_add_i32 s10, s60, s27
	v_add_u32_e32 v204, s24, v145
	s_mov_b32 m0, s10
	ds_read_b128 v[192:195], v204
	ds_read_b128 v[196:199], v204 offset:1024
	ds_read_b128 v[200:203], v204 offset:2048
	global_load_lds_dwordx4 v208, s[98:99]
	s_add_i32 m0, s10, 0x2000
	ds_read_b128 v[204:207], v204 offset:3072
	global_load_lds_dwordx4 v128, s[98:99]
	s_barrier
	s_waitcnt lgkmcnt(0)
	v_mfma_f32_16x16x32_bf16 v[116:119], v[192:195], v[160:163], v[116:119]
	v_mfma_f32_16x16x32_bf16 v[112:115], v[200:203], v[160:163], v[112:115]
	v_mfma_f32_16x16x32_bf16 v[100:103], v[192:195], v[168:171], v[100:103]
	v_mfma_f32_16x16x32_bf16 v[96:99], v[200:203], v[168:171], v[96:99]
	v_mfma_f32_16x16x32_bf16 v[84:87], v[192:195], v[176:179], v[84:87]
	v_mfma_f32_16x16x32_bf16 v[80:83], v[200:203], v[176:179], v[80:83]
	v_mfma_f32_16x16x32_bf16 v[68:71], v[192:195], v[184:187], v[68:71]
	v_mfma_f32_16x16x32_bf16 v[64:67], v[200:203], v[184:187], v[64:67]
	v_mfma_f32_16x16x32_bf16 v[116:119], v[196:199], v[164:167], v[116:119]
	v_mfma_f32_16x16x32_bf16 v[112:115], v[204:207], v[164:167], v[112:115]
	v_mfma_f32_16x16x32_bf16 v[100:103], v[196:199], v[172:175], v[100:103]
	v_mfma_f32_16x16x32_bf16 v[96:99], v[204:207], v[172:175], v[96:99]
	v_mfma_f32_16x16x32_bf16 v[84:87], v[196:199], v[180:183], v[84:87]
	v_mfma_f32_16x16x32_bf16 v[80:83], v[204:207], v[180:183], v[80:83]
	v_mfma_f32_16x16x32_bf16 v[68:71], v[196:199], v[188:191], v[68:71]
	v_mfma_f32_16x16x32_bf16 v[64:67], v[204:207], v[188:191], v[64:67]
	s_mov_b32 m0, s50
	s_barrier
	ds_read_b128 v[160:163], v147 offset:49152
	ds_read_b128 v[164:167], v147 offset:50176
	ds_read_b128 v[168:171], v147 offset:51200
	ds_read_b128 v[172:175], v147 offset:52224
	ds_read_b128 v[176:179], v147 offset:53248
	ds_read_b128 v[180:183], v147 offset:54272
	ds_read_b128 v[184:187], v147 offset:55296
	global_load_lds_dwordx4 v132, s[100:101]
	s_mov_b32 m0, s51
	ds_read_b128 v[188:191], v147 offset:56320
	global_load_lds_dwordx4 v130, s[100:101]
	s_barrier
	s_waitcnt lgkmcnt(0)
	v_mfma_f32_16x16x32_bf16 v[60:63], v[138:141], v[160:163], v[60:63]
	v_mfma_f32_16x16x32_bf16 v[56:59], v[152:155], v[160:163], v[56:59]
	v_mfma_f32_16x16x32_bf16 v[44:47], v[138:141], v[168:171], v[44:47]
	v_mfma_f32_16x16x32_bf16 v[40:43], v[152:155], v[168:171], v[40:43]
	v_mfma_f32_16x16x32_bf16 v[28:31], v[138:141], v[176:179], v[28:31]
	v_mfma_f32_16x16x32_bf16 v[24:27], v[152:155], v[176:179], v[24:27]
	v_mfma_f32_16x16x32_bf16 v[12:15], v[138:141], v[184:187], v[12:15]
	v_mfma_f32_16x16x32_bf16 v[8:11], v[152:155], v[184:187], v[8:11]
	v_mfma_f32_16x16x32_bf16 v[60:63], v[148:151], v[164:167], v[60:63]
	v_mfma_f32_16x16x32_bf16 v[56:59], v[156:159], v[164:167], v[56:59]
	v_mfma_f32_16x16x32_bf16 v[44:47], v[148:151], v[172:175], v[44:47]
	v_mfma_f32_16x16x32_bf16 v[40:43], v[156:159], v[172:175], v[40:43]
	v_mfma_f32_16x16x32_bf16 v[28:31], v[148:151], v[180:183], v[28:31]
	v_mfma_f32_16x16x32_bf16 v[24:27], v[156:159], v[180:183], v[24:27]
	v_mfma_f32_16x16x32_bf16 v[12:15], v[148:151], v[188:191], v[12:15]
	v_mfma_f32_16x16x32_bf16 v[8:11], v[156:159], v[188:191], v[8:11]
	s_barrier
	s_add_u32 s10, s22, 0xb0080
	s_addc_u32 s11, s23, 0
	s_add_i32 s22, s24, s27
	s_mov_b32 m0, s22
	s_nop 0
	global_load_lds_dwordx4 v208, s[10:11]
	s_add_i32 m0, s22, 0x2000
	s_nop 0
	global_load_lds_dwordx4 v128, s[10:11]
	s_waitcnt vmcnt(6)
	s_barrier
	v_mfma_f32_16x16x32_bf16 v[52:55], v[192:195], v[160:163], v[52:55]
	v_mfma_f32_16x16x32_bf16 v[48:51], v[200:203], v[160:163], v[48:51]
	v_mfma_f32_16x16x32_bf16 v[36:39], v[192:195], v[168:171], v[36:39]
	v_mfma_f32_16x16x32_bf16 v[32:35], v[200:203], v[168:171], v[32:35]
	v_mfma_f32_16x16x32_bf16 v[20:23], v[192:195], v[176:179], v[20:23]
	v_mfma_f32_16x16x32_bf16 v[16:19], v[200:203], v[176:179], v[16:19]
	v_mfma_f32_16x16x32_bf16 v[4:7], v[192:195], v[184:187], v[4:7]
	v_mfma_f32_16x16x32_bf16 v[0:3], v[200:203], v[184:187], v[0:3]
	v_mfma_f32_16x16x32_bf16 v[52:55], v[196:199], v[164:167], v[52:55]
	v_mfma_f32_16x16x32_bf16 v[48:51], v[204:207], v[164:167], v[48:51]
	v_mfma_f32_16x16x32_bf16 v[36:39], v[196:199], v[172:175], v[36:39]
	v_mfma_f32_16x16x32_bf16 v[32:35], v[204:207], v[172:175], v[32:35]
	v_mfma_f32_16x16x32_bf16 v[20:23], v[196:199], v[180:183], v[20:23]
	v_mfma_f32_16x16x32_bf16 v[16:19], v[204:207], v[180:183], v[16:19]
	v_mfma_f32_16x16x32_bf16 v[4:7], v[196:199], v[188:191], v[4:7]
	v_mfma_f32_16x16x32_bf16 v[0:3], v[204:207], v[188:191], v[0:3]
	s_add_i32 s59, s59, 2
	s_add_u32 s57, s57, 0x100
	s_addc_u32 s58, s58, 0
	s_cmp_gt_u32 s59, 41
	s_mov_b64 s[10:11], s[20:21]
	s_barrier
	s_cbranch_scc0 .LBB0_998
	v_lshl_add_u32 v142, s39, 8, v144
	v_lshl_or_b32 v143, s38, 8, v146
	s_and_b64 vcc, exec, s[4:5]
	s_mov_b32 s38, s53
	s_mov_b32 s39, s56
	s_mov_b64 s[20:21], s[8:9]
	s_mov_b64 s[10:11], s[6:7]
	v_lshl_add_u32 v210, v142, 10, v143
	v_lshlrev_b32_e32 v211, 2, v210
	v_lshlrev_b32_e32 v210, 1, v210
	global_load_dwordx4 v[148:151], v210, s[14:15]
	global_load_dwordx4 v[152:155], v210, s[14:15] offset:256
	v_add_u32_e32 v210, 0x8000, v210
	global_load_dwordx4 v[156:159], v210, s[14:15]
	global_load_dwordx4 v[160:163], v210, s[14:15] offset:256
	v_add_u32_e32 v210, 0x8000, v210
	global_load_dwordx4 v[164:167], v210, s[14:15]
	global_load_dwordx4 v[168:171], v210, s[14:15] offset:256
	v_add_u32_e32 v210, 0x8000, v210
	global_load_dwordx4 v[172:175], v210, s[14:15]
	global_load_dwordx4 v[176:179], v210, s[14:15] offset:256
	v_add_u32_e32 v210, 0x28000, v210
	global_load_dwordx4 v[180:183], v210, s[14:15]
	global_load_dwordx4 v[184:187], v210, s[14:15] offset:256
	v_add_u32_e32 v210, 0x8000, v210
	global_load_dwordx4 v[188:191], v210, s[14:15]
	global_load_dwordx4 v[192:195], v210, s[14:15] offset:256
	v_add_u32_e32 v210, 0x8000, v210
	global_load_dwordx4 v[196:199], v210, s[14:15]
	global_load_dwordx4 v[200:203], v210, s[14:15] offset:256
	v_add_u32_e32 v210, 0x8000, v210
	s_waitcnt vmcnt(12)
	v_lshlrev_b32_e32 v204, 16, v148
	v_and_b32_e32 v205, 0xffff0000, v148
	v_lshlrev_b32_e32 v206, 16, v149
	v_and_b32_e32 v207, 0xffff0000, v149
	v_pk_add_f32 v[124:125], v[124:125], v[204:205]
	v_pk_add_f32 v[126:127], v[126:127], v[206:207]
	v_lshlrev_b32_e32 v204, 16, v150
	v_and_b32_e32 v205, 0xffff0000, v150
	v_lshlrev_b32_e32 v206, 16, v151
	v_and_b32_e32 v207, 0xffff0000, v151
	v_pk_add_f32 v[120:121], v[120:121], v[204:205]
	v_pk_add_f32 v[122:123], v[122:123], v[206:207]
	global_store_dwordx4 v211, v[124:127], s[16:17]
	global_store_dwordx4 v211, v[120:123], s[16:17] offset:16
	v_lshlrev_b32_e32 v204, 16, v152
	v_and_b32_e32 v205, 0xffff0000, v152
	v_lshlrev_b32_e32 v206, 16, v153
	v_and_b32_e32 v207, 0xffff0000, v153
	v_pk_add_f32 v[116:117], v[116:117], v[204:205]
	v_pk_add_f32 v[118:119], v[118:119], v[206:207]
	v_lshlrev_b32_e32 v204, 16, v154
	v_and_b32_e32 v205, 0xffff0000, v154
	v_lshlrev_b32_e32 v206, 16, v155
	v_and_b32_e32 v207, 0xffff0000, v155
	v_pk_add_f32 v[112:113], v[112:113], v[204:205]
	v_pk_add_f32 v[114:115], v[114:115], v[206:207]
	global_store_dwordx4 v211, v[116:119], s[16:17] offset:512
	global_store_dwordx4 v211, v[112:115], s[16:17] offset:528
	v_add_u32_e32 v211, 0x10000, v211
	global_load_dwordx4 v[148:151], v210, s[14:15]
	global_load_dwordx4 v[152:155], v210, s[14:15] offset:256
	s_waitcnt vmcnt(16)
	v_lshlrev_b32_e32 v204, 16, v156
	v_and_b32_e32 v205, 0xffff0000, v156
	v_lshlrev_b32_e32 v206, 16, v157
	v_and_b32_e32 v207, 0xffff0000, v157
	v_pk_add_f32 v[108:109], v[108:109], v[204:205]
	v_pk_add_f32 v[110:111], v[110:111], v[206:207]
	v_lshlrev_b32_e32 v204, 16, v158
	v_and_b32_e32 v205, 0xffff0000, v158
	v_lshlrev_b32_e32 v206, 16, v159
	v_and_b32_e32 v207, 0xffff0000, v159
	v_pk_add_f32 v[104:105], v[104:105], v[204:205]
	v_pk_add_f32 v[106:107], v[106:107], v[206:207]
	global_store_dwordx4 v211, v[108:111], s[16:17]
	global_store_dwordx4 v211, v[104:107], s[16:17] offset:16
	v_lshlrev_b32_e32 v204, 16, v160
	v_and_b32_e32 v205, 0xffff0000, v160
	v_lshlrev_b32_e32 v206, 16, v161
	v_and_b32_e32 v207, 0xffff0000, v161
	v_pk_add_f32 v[100:101], v[100:101], v[204:205]
	v_pk_add_f32 v[102:103], v[102:103], v[206:207]
	v_lshlrev_b32_e32 v204, 16, v162
	v_and_b32_e32 v205, 0xffff0000, v162
	v_lshlrev_b32_e32 v206, 16, v163
	v_and_b32_e32 v207, 0xffff0000, v163
	v_pk_add_f32 v[96:97], v[96:97], v[204:205]
	v_pk_add_f32 v[98:99], v[98:99], v[206:207]
	global_store_dwordx4 v211, v[100:103], s[16:17] offset:512
	global_store_dwordx4 v211, v[96:99], s[16:17] offset:528
	v_add_u32_e32 v211, 0x10000, v211
	s_waitcnt vmcnt(18)
	v_lshlrev_b32_e32 v204, 16, v164
	v_and_b32_e32 v205, 0xffff0000, v164
	v_lshlrev_b32_e32 v206, 16, v165
	v_and_b32_e32 v207, 0xffff0000, v165
	v_pk_add_f32 v[92:93], v[92:93], v[204:205]
	v_pk_add_f32 v[94:95], v[94:95], v[206:207]
	v_lshlrev_b32_e32 v204, 16, v166
	v_and_b32_e32 v205, 0xffff0000, v166
	v_lshlrev_b32_e32 v206, 16, v167
	v_and_b32_e32 v207, 0xffff0000, v167
	v_pk_add_f32 v[88:89], v[88:89], v[204:205]
	v_pk_add_f32 v[90:91], v[90:91], v[206:207]
	global_store_dwordx4 v211, v[92:95], s[16:17]
	global_store_dwordx4 v211, v[88:91], s[16:17] offset:16
	v_lshlrev_b32_e32 v204, 16, v168
	v_and_b32_e32 v205, 0xffff0000, v168
	v_lshlrev_b32_e32 v206, 16, v169
	v_and_b32_e32 v207, 0xffff0000, v169
	v_pk_add_f32 v[84:85], v[84:85], v[204:205]
	v_pk_add_f32 v[86:87], v[86:87], v[206:207]
	v_lshlrev_b32_e32 v204, 16, v170
	v_and_b32_e32 v205, 0xffff0000, v170
	v_lshlrev_b32_e32 v206, 16, v171
	v_and_b32_e32 v207, 0xffff0000, v171
	v_pk_add_f32 v[80:81], v[80:81], v[204:205]
	v_pk_add_f32 v[82:83], v[82:83], v[206:207]
	global_store_dwordx4 v211, v[84:87], s[16:17] offset:512
	global_store_dwordx4 v211, v[80:83], s[16:17] offset:528
	v_add_u32_e32 v211, 0x10000, v211
	s_waitcnt vmcnt(20)
	v_lshlrev_b32_e32 v204, 16, v172
	v_and_b32_e32 v205, 0xffff0000, v172
	v_lshlrev_b32_e32 v206, 16, v173
	v_and_b32_e32 v207, 0xffff0000, v173
	v_pk_add_f32 v[76:77], v[76:77], v[204:205]
	v_pk_add_f32 v[78:79], v[78:79], v[206:207]
	v_lshlrev_b32_e32 v204, 16, v174
	v_and_b32_e32 v205, 0xffff0000, v174
	v_lshlrev_b32_e32 v206, 16, v175
	v_and_b32_e32 v207, 0xffff0000, v175
	v_pk_add_f32 v[72:73], v[72:73], v[204:205]
	v_pk_add_f32 v[74:75], v[74:75], v[206:207]
	global_store_dwordx4 v211, v[76:79], s[16:17]
	global_store_dwordx4 v211, v[72:75], s[16:17] offset:16
	v_lshlrev_b32_e32 v204, 16, v176
	v_and_b32_e32 v205, 0xffff0000, v176
	v_lshlrev_b32_e32 v206, 16, v177
	v_and_b32_e32 v207, 0xffff0000, v177
	v_pk_add_f32 v[68:69], v[68:69], v[204:205]
	v_pk_add_f32 v[70:71], v[70:71], v[206:207]
	v_lshlrev_b32_e32 v204, 16, v178
	v_and_b32_e32 v205, 0xffff0000, v178
	v_lshlrev_b32_e32 v206, 16, v179
	v_and_b32_e32 v207, 0xffff0000, v179
	v_pk_add_f32 v[64:65], v[64:65], v[204:205]
	v_pk_add_f32 v[66:67], v[66:67], v[206:207]
	global_store_dwordx4 v211, v[68:71], s[16:17] offset:512
	global_store_dwordx4 v211, v[64:67], s[16:17] offset:528
	v_add_u32_e32 v211, 0x50000, v211
	s_waitcnt vmcnt(22)
	v_lshlrev_b32_e32 v204, 16, v180
	v_and_b32_e32 v205, 0xffff0000, v180
	v_lshlrev_b32_e32 v206, 16, v181
	v_and_b32_e32 v207, 0xffff0000, v181
	v_pk_add_f32 v[60:61], v[60:61], v[204:205]
	v_pk_add_f32 v[62:63], v[62:63], v[206:207]
	v_lshlrev_b32_e32 v204, 16, v182
	v_and_b32_e32 v205, 0xffff0000, v182
	v_lshlrev_b32_e32 v206, 16, v183
	v_and_b32_e32 v207, 0xffff0000, v183
	v_pk_add_f32 v[56:57], v[56:57], v[204:205]
	v_pk_add_f32 v[58:59], v[58:59], v[206:207]
	global_store_dwordx4 v211, v[60:63], s[16:17]
	global_store_dwordx4 v211, v[56:59], s[16:17] offset:16
	v_lshlrev_b32_e32 v204, 16, v184
	v_and_b32_e32 v205, 0xffff0000, v184
	v_lshlrev_b32_e32 v206, 16, v185
	v_and_b32_e32 v207, 0xffff0000, v185
	v_pk_add_f32 v[52:53], v[52:53], v[204:205]
	v_pk_add_f32 v[54:55], v[54:55], v[206:207]
	v_lshlrev_b32_e32 v204, 16, v186
	v_and_b32_e32 v205, 0xffff0000, v186
	v_lshlrev_b32_e32 v206, 16, v187
	v_and_b32_e32 v207, 0xffff0000, v187
	v_pk_add_f32 v[48:49], v[48:49], v[204:205]
	v_pk_add_f32 v[50:51], v[50:51], v[206:207]
	global_store_dwordx4 v211, v[52:55], s[16:17] offset:512
	global_store_dwordx4 v211, v[48:51], s[16:17] offset:528
	v_add_u32_e32 v211, 0x10000, v211
	s_waitcnt vmcnt(24)
	v_lshlrev_b32_e32 v204, 16, v188
	v_and_b32_e32 v205, 0xffff0000, v188
	v_lshlrev_b32_e32 v206, 16, v189
	v_and_b32_e32 v207, 0xffff0000, v189
	v_pk_add_f32 v[44:45], v[44:45], v[204:205]
	v_pk_add_f32 v[46:47], v[46:47], v[206:207]
	v_lshlrev_b32_e32 v204, 16, v190
	v_and_b32_e32 v205, 0xffff0000, v190
	v_lshlrev_b32_e32 v206, 16, v191
	v_and_b32_e32 v207, 0xffff0000, v191
	v_pk_add_f32 v[40:41], v[40:41], v[204:205]
	v_pk_add_f32 v[42:43], v[42:43], v[206:207]
	global_store_dwordx4 v211, v[44:47], s[16:17]
	global_store_dwordx4 v211, v[40:43], s[16:17] offset:16
	v_lshlrev_b32_e32 v204, 16, v192
	v_and_b32_e32 v205, 0xffff0000, v192
	v_lshlrev_b32_e32 v206, 16, v193
	v_and_b32_e32 v207, 0xffff0000, v193
	v_pk_add_f32 v[36:37], v[36:37], v[204:205]
	v_pk_add_f32 v[38:39], v[38:39], v[206:207]
	v_lshlrev_b32_e32 v204, 16, v194
	v_and_b32_e32 v205, 0xffff0000, v194
	v_lshlrev_b32_e32 v206, 16, v195
	v_and_b32_e32 v207, 0xffff0000, v195
	v_pk_add_f32 v[32:33], v[32:33], v[204:205]
	v_pk_add_f32 v[34:35], v[34:35], v[206:207]
	global_store_dwordx4 v211, v[36:39], s[16:17] offset:512
	global_store_dwordx4 v211, v[32:35], s[16:17] offset:528
	v_add_u32_e32 v211, 0x10000, v211
	s_waitcnt vmcnt(26)
	v_lshlrev_b32_e32 v204, 16, v196
	v_and_b32_e32 v205, 0xffff0000, v196
	v_lshlrev_b32_e32 v206, 16, v197
	v_and_b32_e32 v207, 0xffff0000, v197
	v_pk_add_f32 v[28:29], v[28:29], v[204:205]
	v_pk_add_f32 v[30:31], v[30:31], v[206:207]
	v_lshlrev_b32_e32 v204, 16, v198
	v_and_b32_e32 v205, 0xffff0000, v198
	v_lshlrev_b32_e32 v206, 16, v199
	v_and_b32_e32 v207, 0xffff0000, v199
	v_pk_add_f32 v[24:25], v[24:25], v[204:205]
	v_pk_add_f32 v[26:27], v[26:27], v[206:207]
	global_store_dwordx4 v211, v[28:31], s[16:17]
	global_store_dwordx4 v211, v[24:27], s[16:17] offset:16
	v_lshlrev_b32_e32 v204, 16, v200
	v_and_b32_e32 v205, 0xffff0000, v200
	v_lshlrev_b32_e32 v206, 16, v201
	v_and_b32_e32 v207, 0xffff0000, v201
	v_pk_add_f32 v[20:21], v[20:21], v[204:205]
	v_pk_add_f32 v[22:23], v[22:23], v[206:207]
	v_lshlrev_b32_e32 v204, 16, v202
	v_and_b32_e32 v205, 0xffff0000, v202
	v_lshlrev_b32_e32 v206, 16, v203
	v_and_b32_e32 v207, 0xffff0000, v203
	v_pk_add_f32 v[16:17], v[16:17], v[204:205]
	v_pk_add_f32 v[18:19], v[18:19], v[206:207]
	global_store_dwordx4 v211, v[20:23], s[16:17] offset:512
	global_store_dwordx4 v211, v[16:19], s[16:17] offset:528
	v_add_u32_e32 v211, 0x10000, v211
	s_waitcnt vmcnt(24)
	v_lshlrev_b32_e32 v204, 16, v148
	v_and_b32_e32 v205, 0xffff0000, v148
	v_lshlrev_b32_e32 v206, 16, v149
	v_and_b32_e32 v207, 0xffff0000, v149
	v_pk_add_f32 v[12:13], v[12:13], v[204:205]
	v_pk_add_f32 v[14:15], v[14:15], v[206:207]
	v_lshlrev_b32_e32 v204, 16, v150
	v_and_b32_e32 v205, 0xffff0000, v150
	v_lshlrev_b32_e32 v206, 16, v151
	v_and_b32_e32 v207, 0xffff0000, v151
	v_pk_add_f32 v[8:9], v[8:9], v[204:205]
	v_pk_add_f32 v[10:11], v[10:11], v[206:207]
	global_store_dwordx4 v211, v[12:15], s[16:17]
	global_store_dwordx4 v211, v[8:11], s[16:17] offset:16
	v_lshlrev_b32_e32 v204, 16, v152
	v_and_b32_e32 v205, 0xffff0000, v152
	v_lshlrev_b32_e32 v206, 16, v153
	v_and_b32_e32 v207, 0xffff0000, v153
	v_pk_add_f32 v[4:5], v[4:5], v[204:205]
	v_pk_add_f32 v[6:7], v[6:7], v[206:207]
	v_lshlrev_b32_e32 v204, 16, v154
	v_and_b32_e32 v205, 0xffff0000, v154
	v_lshlrev_b32_e32 v206, 16, v155
	v_and_b32_e32 v207, 0xffff0000, v155
	v_pk_add_f32 v[0:1], v[0:1], v[204:205]
	v_pk_add_f32 v[2:3], v[2:3], v[206:207]
	global_store_dwordx4 v211, v[4:7], s[16:17] offset:512
	global_store_dwordx4 v211, v[0:3], s[16:17] offset:528
	v_add_u32_e32 v211, 0x10000, v211
	s_cbranch_vccz .LBB0_987
	s_waitcnt vmcnt(0)
	s_cmpk_gt_u32 s26, 0xff
	s_cbranch_scc1 .LBB0_1002
	s_barrier

.LBB0_1021:
	s_add_u32 s22, s20, 0x100
	s_addc_u32 s23, s21, 0
	s_add_i32 s62, 0, 0x10000
	v_add_u32_e32 v154, s62, v143
	ds_read_b128 v[138:141], v154
	ds_read_b128 v[146:149], v154 offset:1024
	ds_read_b128 v[150:153], v154 offset:2048
	ds_read_b128 v[154:157], v154 offset:3072
	s_cmp_eq_u32 s61, 40
	s_cselect_b32 s27, s9, s23
	s_cselect_b32 s26, s8, s22
	s_cselect_b32 s25, s11, s60
	s_cselect_b32 s24, s10, s39
	s_add_i32 m0, s46, 0xc000
	ds_read_b128 v[158:161], v145
	ds_read_b128 v[162:165], v145 offset:1024
	ds_read_b128 v[166:169], v145 offset:2048
	ds_read_b128 v[170:173], v145 offset:3072
	ds_read_b128 v[174:177], v145 offset:4096
	ds_read_b128 v[178:181], v145 offset:5120
	ds_read_b128 v[182:185], v145 offset:6144
	global_load_lds_dwordx4 v134, s[20:21]
	s_add_i32 m0, s46, 0xe000
	ds_read_b128 v[186:189], v145 offset:7168
	global_load_lds_dwordx4 v136, s[20:21]
	s_waitcnt lgkmcnt(8)
	s_barrier
	s_waitcnt lgkmcnt(0)
	v_mfma_f32_16x16x32_bf16 v[124:127], v[138:141], v[158:161], v[124:127]
	v_mfma_f32_16x16x32_bf16 v[120:123], v[150:153], v[158:161], v[120:123]
	v_mfma_f32_16x16x32_bf16 v[108:111], v[138:141], v[166:169], v[108:111]
	v_mfma_f32_16x16x32_bf16 v[104:107], v[150:153], v[166:169], v[104:107]
	v_mfma_f32_16x16x32_bf16 v[92:95], v[138:141], v[174:177], v[92:95]
	v_mfma_f32_16x16x32_bf16 v[88:91], v[150:153], v[174:177], v[88:91]
	v_mfma_f32_16x16x32_bf16 v[76:79], v[138:141], v[182:185], v[76:79]
	v_mfma_f32_16x16x32_bf16 v[72:75], v[150:153], v[182:185], v[72:75]
	v_mfma_f32_16x16x32_bf16 v[124:127], v[146:149], v[162:165], v[124:127]
	v_mfma_f32_16x16x32_bf16 v[120:123], v[154:157], v[162:165], v[120:123]
	v_mfma_f32_16x16x32_bf16 v[108:111], v[146:149], v[170:173], v[108:111]
	v_mfma_f32_16x16x32_bf16 v[104:107], v[154:157], v[170:173], v[104:107]
	v_mfma_f32_16x16x32_bf16 v[92:95], v[146:149], v[178:181], v[92:95]
	v_mfma_f32_16x16x32_bf16 v[88:91], v[154:157], v[178:181], v[88:91]
	v_mfma_f32_16x16x32_bf16 v[76:79], v[146:149], v[186:189], v[76:79]
	v_mfma_f32_16x16x32_bf16 v[72:75], v[154:157], v[186:189], v[72:75]
	s_barrier
	s_add_i32 s63, 0, 0x14000
	s_add_i32 s20, s62, s35
	v_add_u32_e32 v202, s63, v143
	s_add_u32 s98, s24, s40
	s_addc_u32 s99, s25, s41
	s_mov_b32 m0, s20
	ds_read_b128 v[190:193], v202
	ds_read_b128 v[194:197], v202 offset:1024
	ds_read_b128 v[198:201], v202 offset:2048
	global_load_lds_dwordx4 v208, s[24:25]
	s_add_i32 m0, s20, 0x2000
	ds_read_b128 v[202:205], v202 offset:3072
	global_load_lds_dwordx4 v128, s[24:25]
	s_barrier
	s_waitcnt lgkmcnt(0)
	v_mfma_f32_16x16x32_bf16 v[116:119], v[190:193], v[158:161], v[116:119]
	v_mfma_f32_16x16x32_bf16 v[112:115], v[198:201], v[158:161], v[112:115]
	v_mfma_f32_16x16x32_bf16 v[100:103], v[190:193], v[166:169], v[100:103]
	v_mfma_f32_16x16x32_bf16 v[96:99], v[198:201], v[166:169], v[96:99]
	v_mfma_f32_16x16x32_bf16 v[84:87], v[190:193], v[174:177], v[84:87]
	v_mfma_f32_16x16x32_bf16 v[80:83], v[198:201], v[174:177], v[80:83]
	v_mfma_f32_16x16x32_bf16 v[68:71], v[190:193], v[182:185], v[68:71]
	v_mfma_f32_16x16x32_bf16 v[64:67], v[198:201], v[182:185], v[64:67]
	v_mfma_f32_16x16x32_bf16 v[116:119], v[194:197], v[162:165], v[116:119]
	v_mfma_f32_16x16x32_bf16 v[112:115], v[202:205], v[162:165], v[112:115]
	v_mfma_f32_16x16x32_bf16 v[100:103], v[194:197], v[170:173], v[100:103]
	v_mfma_f32_16x16x32_bf16 v[96:99], v[202:205], v[170:173], v[96:99]
	v_mfma_f32_16x16x32_bf16 v[84:87], v[194:197], v[178:181], v[84:87]
	v_mfma_f32_16x16x32_bf16 v[80:83], v[202:205], v[178:181], v[80:83]
	v_mfma_f32_16x16x32_bf16 v[68:71], v[194:197], v[186:189], v[68:71]
	v_mfma_f32_16x16x32_bf16 v[64:67], v[202:205], v[186:189], v[64:67]
	s_mov_b32 m0, s46
	s_add_u32 s100, s26, s40
	s_addc_u32 s101, s27, s41
	s_barrier
	ds_read_b128 v[158:161], v145 offset:16384
	ds_read_b128 v[162:165], v145 offset:17408
	ds_read_b128 v[166:169], v145 offset:18432
	ds_read_b128 v[170:173], v145 offset:19456
	ds_read_b128 v[174:177], v145 offset:20480
	ds_read_b128 v[178:181], v145 offset:21504
	ds_read_b128 v[182:185], v145 offset:22528
	global_load_lds_dwordx4 v132, s[26:27]
	s_mov_b32 m0, s47
	ds_read_b128 v[186:189], v145 offset:23552
	global_load_lds_dwordx4 v130, s[26:27]
	s_barrier
	s_waitcnt lgkmcnt(0)
	v_mfma_f32_16x16x32_bf16 v[60:63], v[138:141], v[158:161], v[60:63]
	v_mfma_f32_16x16x32_bf16 v[56:59], v[150:153], v[158:161], v[56:59]
	v_mfma_f32_16x16x32_bf16 v[44:47], v[138:141], v[166:169], v[44:47]
	v_mfma_f32_16x16x32_bf16 v[40:43], v[150:153], v[166:169], v[40:43]
	v_mfma_f32_16x16x32_bf16 v[28:31], v[138:141], v[174:177], v[28:31]
	v_mfma_f32_16x16x32_bf16 v[24:27], v[150:153], v[174:177], v[24:27]
	v_mfma_f32_16x16x32_bf16 v[12:15], v[138:141], v[182:185], v[12:15]
	v_mfma_f32_16x16x32_bf16 v[8:11], v[150:153], v[182:185], v[8:11]
	v_mfma_f32_16x16x32_bf16 v[60:63], v[146:149], v[162:165], v[60:63]
	v_mfma_f32_16x16x32_bf16 v[56:59], v[154:157], v[162:165], v[56:59]
	v_mfma_f32_16x16x32_bf16 v[44:47], v[146:149], v[170:173], v[44:47]
	v_mfma_f32_16x16x32_bf16 v[40:43], v[154:157], v[170:173], v[40:43]
	v_mfma_f32_16x16x32_bf16 v[28:31], v[146:149], v[178:181], v[28:31]
	v_mfma_f32_16x16x32_bf16 v[24:27], v[154:157], v[178:181], v[24:27]
	v_mfma_f32_16x16x32_bf16 v[12:15], v[146:149], v[186:189], v[12:15]
	v_mfma_f32_16x16x32_bf16 v[8:11], v[154:157], v[186:189], v[8:11]
	s_barrier
	s_add_u32 s20, s24, 0xb0000
	s_addc_u32 s21, s25, 0
	s_add_i32 s62, s63, s35
	s_mov_b32 m0, s62
	s_nop 0
	global_load_lds_dwordx4 v208, s[20:21]
	s_add_i32 m0, s62, 0x2000
	s_nop 0
	global_load_lds_dwordx4 v128, s[20:21]
	s_waitcnt vmcnt(6)
	s_barrier
	v_mfma_f32_16x16x32_bf16 v[52:55], v[190:193], v[158:161], v[52:55]
	v_mfma_f32_16x16x32_bf16 v[48:51], v[198:201], v[158:161], v[48:51]
	v_mfma_f32_16x16x32_bf16 v[36:39], v[190:193], v[166:169], v[36:39]
	v_mfma_f32_16x16x32_bf16 v[32:35], v[198:201], v[166:169], v[32:35]
	v_mfma_f32_16x16x32_bf16 v[20:23], v[190:193], v[174:177], v[20:23]
	v_mfma_f32_16x16x32_bf16 v[16:19], v[198:201], v[174:177], v[16:19]
	v_mfma_f32_16x16x32_bf16 v[4:7], v[190:193], v[182:185], v[4:7]
	v_mfma_f32_16x16x32_bf16 v[0:3], v[198:201], v[182:185], v[0:3]
	v_mfma_f32_16x16x32_bf16 v[52:55], v[194:197], v[162:165], v[52:55]
	v_mfma_f32_16x16x32_bf16 v[48:51], v[202:205], v[162:165], v[48:51]
	v_mfma_f32_16x16x32_bf16 v[36:39], v[194:197], v[170:173], v[36:39]
	v_mfma_f32_16x16x32_bf16 v[32:35], v[202:205], v[170:173], v[32:35]
	v_mfma_f32_16x16x32_bf16 v[20:23], v[194:197], v[178:181], v[20:23]
	v_mfma_f32_16x16x32_bf16 v[16:19], v[202:205], v[178:181], v[16:19]
	v_mfma_f32_16x16x32_bf16 v[4:7], v[194:197], v[186:189], v[4:7]
	v_mfma_f32_16x16x32_bf16 v[0:3], v[202:205], v[186:189], v[0:3]
	s_add_i32 s62, 0, 0x18000
	v_add_u32_e32 v154, s62, v143
	s_barrier
	ds_read_b128 v[138:141], v154
	ds_read_b128 v[146:149], v154 offset:1024
	ds_read_b128 v[150:153], v154 offset:2048
	ds_read_b128 v[154:157], v154 offset:3072
	s_add_u32 s20, s26, 0xb0000
	s_addc_u32 s21, s27, 0
	s_mov_b32 m0, s50
	ds_read_b128 v[158:161], v145 offset:32768
	ds_read_b128 v[162:165], v145 offset:33792
	ds_read_b128 v[166:169], v145 offset:34816
	ds_read_b128 v[170:173], v145 offset:35840
	ds_read_b128 v[174:177], v145 offset:36864
	ds_read_b128 v[178:181], v145 offset:37888
	ds_read_b128 v[182:185], v145 offset:38912
	global_load_lds_dwordx4 v132, s[20:21]
	s_mov_b32 m0, s51
	ds_read_b128 v[186:189], v145 offset:39936
	global_load_lds_dwordx4 v130, s[20:21]
	s_waitcnt lgkmcnt(8)
	s_barrier
	s_waitcnt lgkmcnt(0)
	v_mfma_f32_16x16x32_bf16 v[124:127], v[138:141], v[158:161], v[124:127]
	v_mfma_f32_16x16x32_bf16 v[120:123], v[150:153], v[158:161], v[120:123]
	v_mfma_f32_16x16x32_bf16 v[108:111], v[138:141], v[166:169], v[108:111]
	v_mfma_f32_16x16x32_bf16 v[104:107], v[150:153], v[166:169], v[104:107]
	v_mfma_f32_16x16x32_bf16 v[92:95], v[138:141], v[174:177], v[92:95]
	v_mfma_f32_16x16x32_bf16 v[88:91], v[150:153], v[174:177], v[88:91]
	v_mfma_f32_16x16x32_bf16 v[76:79], v[138:141], v[182:185], v[76:79]
	v_mfma_f32_16x16x32_bf16 v[72:75], v[150:153], v[182:185], v[72:75]
	v_mfma_f32_16x16x32_bf16 v[124:127], v[146:149], v[162:165], v[124:127]
	v_mfma_f32_16x16x32_bf16 v[120:123], v[154:157], v[162:165], v[120:123]
	v_mfma_f32_16x16x32_bf16 v[108:111], v[146:149], v[170:173], v[108:111]
	v_mfma_f32_16x16x32_bf16 v[104:107], v[154:157], v[170:173], v[104:107]
	v_mfma_f32_16x16x32_bf16 v[92:95], v[146:149], v[178:181], v[92:95]
	v_mfma_f32_16x16x32_bf16 v[88:91], v[154:157], v[178:181], v[88:91]
	v_mfma_f32_16x16x32_bf16 v[76:79], v[146:149], v[186:189], v[76:79]
	v_mfma_f32_16x16x32_bf16 v[72:75], v[154:157], v[186:189], v[72:75]
	s_barrier
	s_add_i32 s26, 0, 0x1c000
	s_add_i32 s20, s62, s35
	v_add_u32_e32 v202, s26, v143
	s_mov_b32 m0, s20
	ds_read_b128 v[190:193], v202
	ds_read_b128 v[194:197], v202 offset:1024
	ds_read_b128 v[198:201], v202 offset:2048
	global_load_lds_dwordx4 v208, s[98:99]
	s_add_i32 m0, s20, 0x2000
	ds_read_b128 v[202:205], v202 offset:3072
	global_load_lds_dwordx4 v128, s[98:99]
	s_barrier
	s_waitcnt lgkmcnt(0)
	v_mfma_f32_16x16x32_bf16 v[116:119], v[190:193], v[158:161], v[116:119]
	v_mfma_f32_16x16x32_bf16 v[112:115], v[198:201], v[158:161], v[112:115]
	v_mfma_f32_16x16x32_bf16 v[100:103], v[190:193], v[166:169], v[100:103]
	v_mfma_f32_16x16x32_bf16 v[96:99], v[198:201], v[166:169], v[96:99]
	v_mfma_f32_16x16x32_bf16 v[84:87], v[190:193], v[174:177], v[84:87]
	v_mfma_f32_16x16x32_bf16 v[80:83], v[198:201], v[174:177], v[80:83]
	v_mfma_f32_16x16x32_bf16 v[68:71], v[190:193], v[182:185], v[68:71]
	v_mfma_f32_16x16x32_bf16 v[64:67], v[198:201], v[182:185], v[64:67]
	v_mfma_f32_16x16x32_bf16 v[116:119], v[194:197], v[162:165], v[116:119]
	v_mfma_f32_16x16x32_bf16 v[112:115], v[202:205], v[162:165], v[112:115]
	v_mfma_f32_16x16x32_bf16 v[100:103], v[194:197], v[170:173], v[100:103]
	v_mfma_f32_16x16x32_bf16 v[96:99], v[202:205], v[170:173], v[96:99]
	v_mfma_f32_16x16x32_bf16 v[84:87], v[194:197], v[178:181], v[84:87]
	v_mfma_f32_16x16x32_bf16 v[80:83], v[202:205], v[178:181], v[80:83]
	v_mfma_f32_16x16x32_bf16 v[68:71], v[194:197], v[186:189], v[68:71]
	v_mfma_f32_16x16x32_bf16 v[64:67], v[202:205], v[186:189], v[64:67]
	s_mov_b32 m0, s53
	s_barrier
	ds_read_b128 v[158:161], v145 offset:49152
	ds_read_b128 v[162:165], v145 offset:50176
	ds_read_b128 v[166:169], v145 offset:51200
	ds_read_b128 v[170:173], v145 offset:52224
	ds_read_b128 v[174:177], v145 offset:53248
	ds_read_b128 v[178:181], v145 offset:54272
	ds_read_b128 v[182:185], v145 offset:55296
	global_load_lds_dwordx4 v132, s[100:101]
	s_mov_b32 m0, s56
	ds_read_b128 v[186:189], v145 offset:56320
	global_load_lds_dwordx4 v130, s[100:101]
	s_barrier
	s_waitcnt lgkmcnt(0)
	v_mfma_f32_16x16x32_bf16 v[60:63], v[138:141], v[158:161], v[60:63]
	v_mfma_f32_16x16x32_bf16 v[56:59], v[150:153], v[158:161], v[56:59]
	v_mfma_f32_16x16x32_bf16 v[44:47], v[138:141], v[166:169], v[44:47]
	v_mfma_f32_16x16x32_bf16 v[40:43], v[150:153], v[166:169], v[40:43]
	v_mfma_f32_16x16x32_bf16 v[28:31], v[138:141], v[174:177], v[28:31]
	v_mfma_f32_16x16x32_bf16 v[24:27], v[150:153], v[174:177], v[24:27]
	v_mfma_f32_16x16x32_bf16 v[12:15], v[138:141], v[182:185], v[12:15]
	v_mfma_f32_16x16x32_bf16 v[8:11], v[150:153], v[182:185], v[8:11]
	v_mfma_f32_16x16x32_bf16 v[60:63], v[146:149], v[162:165], v[60:63]
	v_mfma_f32_16x16x32_bf16 v[56:59], v[154:157], v[162:165], v[56:59]
	v_mfma_f32_16x16x32_bf16 v[44:47], v[146:149], v[170:173], v[44:47]
	v_mfma_f32_16x16x32_bf16 v[40:43], v[154:157], v[170:173], v[40:43]
	v_mfma_f32_16x16x32_bf16 v[28:31], v[146:149], v[178:181], v[28:31]
	v_mfma_f32_16x16x32_bf16 v[24:27], v[154:157], v[178:181], v[24:27]
	v_mfma_f32_16x16x32_bf16 v[12:15], v[146:149], v[186:189], v[12:15]
	v_mfma_f32_16x16x32_bf16 v[8:11], v[154:157], v[186:189], v[8:11]
	s_barrier
	s_add_u32 s20, s24, 0xb0080
	s_addc_u32 s21, s25, 0
	s_add_i32 s24, s26, s35
	s_mov_b32 m0, s24
	s_nop 0
	global_load_lds_dwordx4 v208, s[20:21]
	s_add_i32 m0, s24, 0x2000
	s_nop 0
	global_load_lds_dwordx4 v128, s[20:21]
	s_waitcnt vmcnt(6)
	s_barrier
	v_mfma_f32_16x16x32_bf16 v[52:55], v[190:193], v[158:161], v[52:55]
	v_mfma_f32_16x16x32_bf16 v[48:51], v[198:201], v[158:161], v[48:51]
	v_mfma_f32_16x16x32_bf16 v[36:39], v[190:193], v[166:169], v[36:39]
	v_mfma_f32_16x16x32_bf16 v[32:35], v[198:201], v[166:169], v[32:35]
	v_mfma_f32_16x16x32_bf16 v[20:23], v[190:193], v[174:177], v[20:23]
	v_mfma_f32_16x16x32_bf16 v[16:19], v[198:201], v[174:177], v[16:19]
	v_mfma_f32_16x16x32_bf16 v[4:7], v[190:193], v[182:185], v[4:7]
	v_mfma_f32_16x16x32_bf16 v[0:3], v[198:201], v[182:185], v[0:3]
	v_mfma_f32_16x16x32_bf16 v[52:55], v[194:197], v[162:165], v[52:55]
	v_mfma_f32_16x16x32_bf16 v[48:51], v[202:205], v[162:165], v[48:51]
	v_mfma_f32_16x16x32_bf16 v[36:39], v[194:197], v[170:173], v[36:39]
	v_mfma_f32_16x16x32_bf16 v[32:35], v[202:205], v[170:173], v[32:35]
	v_mfma_f32_16x16x32_bf16 v[20:23], v[194:197], v[178:181], v[20:23]
	v_mfma_f32_16x16x32_bf16 v[16:19], v[202:205], v[178:181], v[16:19]
	v_mfma_f32_16x16x32_bf16 v[4:7], v[194:197], v[186:189], v[4:7]
	v_mfma_f32_16x16x32_bf16 v[0:3], v[202:205], v[186:189], v[0:3]
	s_add_i32 s61, s61, 2
	s_add_u32 s39, s39, 0x100
	s_addc_u32 s60, s60, 0
	s_cmp_gt_u32 s61, 41
	s_mov_b64 s[20:21], s[22:23]
	s_barrier
	s_cbranch_scc0 .LBB0_1021
	v_lshl_add_u32 v140, s38, 8, v142
	v_lshl_or_b32 v141, s36, 8, v144
	s_lshl_b32 s20, s36, 2
	s_ashr_i32 s21, s20, 31
	s_lshl_b32 s36, s52, 2
	v_lshlrev_b32_e32 v206, 11, v140
	v_lshl_add_u32 v206, v141, 1, v206
	v_lshl_add_u32 v210, v140, 6, s36
	v_lshl_add_u32 v210, s20, 2, v210
	v_mov_b32_e32 v207, v206
	global_load_dwordx4 v[146:149], v206, s[14:15]
	global_load_dwordx4 v[150:153], v206, s[14:15] offset:256
	v_add_u32_e32 v206, 0x8000, v206
	global_load_dwordx4 v[154:157], v206, s[14:15]
	global_load_dwordx4 v[158:161], v206, s[14:15] offset:256
	v_add_u32_e32 v206, 0x8000, v206
	global_load_dwordx4 v[162:165], v206, s[14:15]
	global_load_dwordx4 v[166:169], v206, s[14:15] offset:256
	v_add_u32_e32 v206, 0x8000, v206
	global_load_dwordx4 v[170:173], v206, s[14:15]
	global_load_dwordx4 v[174:177], v206, s[14:15] offset:256
	v_add_u32_e32 v206, 0x28000, v206
	global_load_dwordx4 v[178:181], v206, s[14:15]
	global_load_dwordx4 v[182:185], v206, s[14:15] offset:256
	v_add_u32_e32 v206, 0x8000, v206
	global_load_dwordx4 v[186:189], v206, s[14:15]
	global_load_dwordx4 v[190:193], v206, s[14:15] offset:256
	v_add_u32_e32 v206, 0x8000, v206
	global_load_dwordx4 v[194:197], v206, s[14:15]
	global_load_dwordx4 v[198:201], v206, s[14:15] offset:256
	v_add_u32_e32 v206, 0x8000, v206
	s_waitcnt vmcnt(12)
	v_lshlrev_b32_e32 v202, 16, v146
	v_and_b32_e32 v203, 0xffff0000, v146
	v_lshlrev_b32_e32 v204, 16, v147
	v_and_b32_e32 v205, 0xffff0000, v147
	v_pk_add_f32 v[124:125], v[124:125], v[202:203]
	v_pk_add_f32 v[126:127], v[126:127], v[204:205]
	v_lshlrev_b32_e32 v202, 16, v148
	v_and_b32_e32 v203, 0xffff0000, v148
	v_lshlrev_b32_e32 v204, 16, v149
	v_and_b32_e32 v205, 0xffff0000, v149
	v_pk_add_f32 v[120:121], v[120:121], v[202:203]
	v_pk_add_f32 v[122:123], v[122:123], v[204:205]
	v_cvt_pk_bf16_f32 v146, v124, v125
	v_cvt_pk_bf16_f32 v147, v126, v127
	v_cvt_pk_bf16_f32 v148, v120, v121
	v_cvt_pk_bf16_f32 v149, v122, v123
	v_pk_mul_f32 v[138:139], v[124:125], v[124:125]
	global_store_dwordx4 v207, v[146:149], s[14:15]
	v_pk_fma_f32 v[138:139], v[126:127], v[126:127], v[138:139]
	v_pk_fma_f32 v[138:139], v[120:121], v[120:121], v[138:139]
	v_pk_fma_f32 v[138:139], v[122:123], v[122:123], v[138:139]
	v_lshlrev_b32_e32 v202, 16, v150
	v_and_b32_e32 v203, 0xffff0000, v150
	v_lshlrev_b32_e32 v204, 16, v151
	v_and_b32_e32 v205, 0xffff0000, v151
	v_pk_add_f32 v[116:117], v[116:117], v[202:203]
	v_pk_add_f32 v[118:119], v[118:119], v[204:205]
	v_lshlrev_b32_e32 v202, 16, v152
	v_and_b32_e32 v203, 0xffff0000, v152
	v_lshlrev_b32_e32 v204, 16, v153
	v_and_b32_e32 v205, 0xffff0000, v153
	v_pk_add_f32 v[112:113], v[112:113], v[202:203]
	v_pk_add_f32 v[114:115], v[114:115], v[204:205]
	v_cvt_pk_bf16_f32 v150, v116, v117
	v_cvt_pk_bf16_f32 v151, v118, v119
	v_cvt_pk_bf16_f32 v152, v112, v113
	v_cvt_pk_bf16_f32 v153, v114, v115
	v_pk_fma_f32 v[138:139], v[116:117], v[116:117], v[138:139]
	global_store_dwordx4 v207, v[150:153], s[14:15] offset:256
	v_pk_fma_f32 v[138:139], v[118:119], v[118:119], v[138:139]
	v_pk_fma_f32 v[138:139], v[112:113], v[112:113], v[138:139]
	v_pk_fma_f32 v[138:139], v[114:115], v[114:115], v[138:139]
	v_add_f32_e32 v214, v138, v139
	v_add_u32_e32 v207, 0x8000, v207
	v_mov_b32_e32 v215, v214
	s_nop 1
	v_permlane16_swap_b32_e32 v214, v215
	s_nop 0
	v_add_f32_e32 v214, v214, v215
	v_mov_b32_e32 v215, v214
	s_nop 1
	v_permlane32_swap_b32_e32 v214, v215
	s_nop 0
	v_add_f32_e32 v214, v214, v215
	s_and_saveexec_b64 s[22:23], s[4:5]
	global_store_dword v210, v214, s[16:17]
	s_mov_b64 exec, s[22:23]
	global_load_dwordx4 v[146:149], v206, s[14:15]
	global_load_dwordx4 v[150:153], v206, s[14:15] offset:256
	s_waitcnt vmcnt(15)
	v_lshlrev_b32_e32 v202, 16, v154
	v_and_b32_e32 v203, 0xffff0000, v154
	v_lshlrev_b32_e32 v204, 16, v155
	v_and_b32_e32 v205, 0xffff0000, v155
	v_pk_add_f32 v[108:109], v[108:109], v[202:203]
	v_pk_add_f32 v[110:111], v[110:111], v[204:205]
	v_lshlrev_b32_e32 v202, 16, v156
	v_and_b32_e32 v203, 0xffff0000, v156
	v_lshlrev_b32_e32 v204, 16, v157
	v_and_b32_e32 v205, 0xffff0000, v157
	v_pk_add_f32 v[104:105], v[104:105], v[202:203]
	v_pk_add_f32 v[106:107], v[106:107], v[204:205]
	v_cvt_pk_bf16_f32 v154, v108, v109
	v_cvt_pk_bf16_f32 v155, v110, v111
	v_cvt_pk_bf16_f32 v156, v104, v105
	v_cvt_pk_bf16_f32 v157, v106, v107
	v_pk_mul_f32 v[138:139], v[108:109], v[108:109]
	global_store_dwordx4 v207, v[154:157], s[14:15]
	v_pk_fma_f32 v[138:139], v[110:111], v[110:111], v[138:139]
	v_pk_fma_f32 v[138:139], v[104:105], v[104:105], v[138:139]
	v_pk_fma_f32 v[138:139], v[106:107], v[106:107], v[138:139]
	v_lshlrev_b32_e32 v202, 16, v158
	v_and_b32_e32 v203, 0xffff0000, v158
	v_lshlrev_b32_e32 v204, 16, v159
	v_and_b32_e32 v205, 0xffff0000, v159
	v_pk_add_f32 v[100:101], v[100:101], v[202:203]
	v_pk_add_f32 v[102:103], v[102:103], v[204:205]
	v_lshlrev_b32_e32 v202, 16, v160
	v_and_b32_e32 v203, 0xffff0000, v160
	v_lshlrev_b32_e32 v204, 16, v161
	v_and_b32_e32 v205, 0xffff0000, v161
	v_pk_add_f32 v[96:97], v[96:97], v[202:203]
	v_pk_add_f32 v[98:99], v[98:99], v[204:205]
	v_cvt_pk_bf16_f32 v158, v100, v101
	v_cvt_pk_bf16_f32 v159, v102, v103
	v_cvt_pk_bf16_f32 v160, v96, v97
	v_cvt_pk_bf16_f32 v161, v98, v99
	v_pk_fma_f32 v[138:139], v[100:101], v[100:101], v[138:139]
	global_store_dwordx4 v207, v[158:161], s[14:15] offset:256
	v_pk_fma_f32 v[138:139], v[102:103], v[102:103], v[138:139]
	v_pk_fma_f32 v[138:139], v[96:97], v[96:97], v[138:139]
	v_pk_fma_f32 v[138:139], v[98:99], v[98:99], v[138:139]
	v_add_f32_e32 v214, v138, v139
	v_add_u32_e32 v207, 0x8000, v207
	v_mov_b32_e32 v215, v214
	s_nop 1
	v_permlane16_swap_b32_e32 v214, v215
	s_nop 0
	v_add_f32_e32 v214, v214, v215
	v_mov_b32_e32 v215, v214
	s_nop 1
	v_permlane32_swap_b32_e32 v214, v215
	s_nop 0
	v_add_f32_e32 v214, v214, v215
	s_and_saveexec_b64 s[22:23], s[4:5]
	global_store_dword v210, v214, s[16:17] offset:1024
	s_mov_b64 exec, s[22:23]
	s_waitcnt vmcnt(16)
	v_lshlrev_b32_e32 v202, 16, v162
	v_and_b32_e32 v203, 0xffff0000, v162
	v_lshlrev_b32_e32 v204, 16, v163
	v_and_b32_e32 v205, 0xffff0000, v163
	v_pk_add_f32 v[92:93], v[92:93], v[202:203]
	v_pk_add_f32 v[94:95], v[94:95], v[204:205]
	v_lshlrev_b32_e32 v202, 16, v164
	v_and_b32_e32 v203, 0xffff0000, v164
	v_lshlrev_b32_e32 v204, 16, v165
	v_and_b32_e32 v205, 0xffff0000, v165
	v_pk_add_f32 v[88:89], v[88:89], v[202:203]
	v_pk_add_f32 v[90:91], v[90:91], v[204:205]
	v_cvt_pk_bf16_f32 v162, v92, v93
	v_cvt_pk_bf16_f32 v163, v94, v95
	v_cvt_pk_bf16_f32 v164, v88, v89
	v_cvt_pk_bf16_f32 v165, v90, v91
	v_pk_mul_f32 v[138:139], v[92:93], v[92:93]
	global_store_dwordx4 v207, v[162:165], s[14:15]
	v_pk_fma_f32 v[138:139], v[94:95], v[94:95], v[138:139]
	v_pk_fma_f32 v[138:139], v[88:89], v[88:89], v[138:139]
	v_pk_fma_f32 v[138:139], v[90:91], v[90:91], v[138:139]
	v_lshlrev_b32_e32 v202, 16, v166
	v_and_b32_e32 v203, 0xffff0000, v166
	v_lshlrev_b32_e32 v204, 16, v167
	v_and_b32_e32 v205, 0xffff0000, v167
	v_pk_add_f32 v[84:85], v[84:85], v[202:203]
	v_pk_add_f32 v[86:87], v[86:87], v[204:205]
	v_lshlrev_b32_e32 v202, 16, v168
	v_and_b32_e32 v203, 0xffff0000, v168
	v_lshlrev_b32_e32 v204, 16, v169
	v_and_b32_e32 v205, 0xffff0000, v169
	v_pk_add_f32 v[80:81], v[80:81], v[202:203]
	v_pk_add_f32 v[82:83], v[82:83], v[204:205]
	v_cvt_pk_bf16_f32 v166, v84, v85
	v_cvt_pk_bf16_f32 v167, v86, v87
	v_cvt_pk_bf16_f32 v168, v80, v81
	v_cvt_pk_bf16_f32 v169, v82, v83
	v_pk_fma_f32 v[138:139], v[84:85], v[84:85], v[138:139]
	global_store_dwordx4 v207, v[166:169], s[14:15] offset:256
	v_pk_fma_f32 v[138:139], v[86:87], v[86:87], v[138:139]
	v_pk_fma_f32 v[138:139], v[80:81], v[80:81], v[138:139]
	v_pk_fma_f32 v[138:139], v[82:83], v[82:83], v[138:139]
	v_add_f32_e32 v214, v138, v139
	v_add_u32_e32 v207, 0x8000, v207
	v_mov_b32_e32 v215, v214
	s_nop 1
	v_permlane16_swap_b32_e32 v214, v215
	s_nop 0
	v_add_f32_e32 v214, v214, v215
	v_mov_b32_e32 v215, v214
	s_nop 1
	v_permlane32_swap_b32_e32 v214, v215
	s_nop 0
	v_add_f32_e32 v214, v214, v215
	s_and_saveexec_b64 s[22:23], s[4:5]
	global_store_dword v210, v214, s[16:17] offset:2048
	s_mov_b64 exec, s[22:23]
	s_waitcnt vmcnt(17)
	v_lshlrev_b32_e32 v202, 16, v170
	v_and_b32_e32 v203, 0xffff0000, v170
	v_lshlrev_b32_e32 v204, 16, v171
	v_and_b32_e32 v205, 0xffff0000, v171
	v_pk_add_f32 v[76:77], v[76:77], v[202:203]
	v_pk_add_f32 v[78:79], v[78:79], v[204:205]
	v_lshlrev_b32_e32 v202, 16, v172
	v_and_b32_e32 v203, 0xffff0000, v172
	v_lshlrev_b32_e32 v204, 16, v173
	v_and_b32_e32 v205, 0xffff0000, v173
	v_pk_add_f32 v[72:73], v[72:73], v[202:203]
	v_pk_add_f32 v[74:75], v[74:75], v[204:205]
	v_cvt_pk_bf16_f32 v170, v76, v77
	v_cvt_pk_bf16_f32 v171, v78, v79
	v_cvt_pk_bf16_f32 v172, v72, v73
	v_cvt_pk_bf16_f32 v173, v74, v75
	v_pk_mul_f32 v[138:139], v[76:77], v[76:77]
	global_store_dwordx4 v207, v[170:173], s[14:15]
	v_pk_fma_f32 v[138:139], v[78:79], v[78:79], v[138:139]
	v_pk_fma_f32 v[138:139], v[72:73], v[72:73], v[138:139]
	v_pk_fma_f32 v[138:139], v[74:75], v[74:75], v[138:139]
	v_lshlrev_b32_e32 v202, 16, v174
	v_and_b32_e32 v203, 0xffff0000, v174
	v_lshlrev_b32_e32 v204, 16, v175
	v_and_b32_e32 v205, 0xffff0000, v175
	v_pk_add_f32 v[68:69], v[68:69], v[202:203]
	v_pk_add_f32 v[70:71], v[70:71], v[204:205]
	v_lshlrev_b32_e32 v202, 16, v176
	v_and_b32_e32 v203, 0xffff0000, v176
	v_lshlrev_b32_e32 v204, 16, v177
	v_and_b32_e32 v205, 0xffff0000, v177
	v_pk_add_f32 v[64:65], v[64:65], v[202:203]
	v_pk_add_f32 v[66:67], v[66:67], v[204:205]
	v_cvt_pk_bf16_f32 v174, v68, v69
	v_cvt_pk_bf16_f32 v175, v70, v71
	v_cvt_pk_bf16_f32 v176, v64, v65
	v_cvt_pk_bf16_f32 v177, v66, v67
	v_pk_fma_f32 v[138:139], v[68:69], v[68:69], v[138:139]
	global_store_dwordx4 v207, v[174:177], s[14:15] offset:256
	v_pk_fma_f32 v[138:139], v[70:71], v[70:71], v[138:139]
	v_pk_fma_f32 v[138:139], v[64:65], v[64:65], v[138:139]
	v_pk_fma_f32 v[138:139], v[66:67], v[66:67], v[138:139]
	v_add_f32_e32 v214, v138, v139
	v_add_u32_e32 v207, 0x28000, v207
	v_mov_b32_e32 v215, v214
	s_nop 1
	v_permlane16_swap_b32_e32 v214, v215
	s_nop 0
	v_add_f32_e32 v214, v214, v215
	v_mov_b32_e32 v215, v214
	s_nop 1
	v_permlane32_swap_b32_e32 v214, v215
	s_nop 0
	v_add_f32_e32 v214, v214, v215
	s_and_saveexec_b64 s[22:23], s[4:5]
	global_store_dword v210, v214, s[16:17] offset:3072
	s_mov_b64 exec, s[22:23]
	v_add_u32_e32 v210, 0x2000, v210
	s_waitcnt vmcnt(18)
	v_lshlrev_b32_e32 v202, 16, v178
	v_and_b32_e32 v203, 0xffff0000, v178
	v_lshlrev_b32_e32 v204, 16, v179
	v_and_b32_e32 v205, 0xffff0000, v179
	v_pk_add_f32 v[60:61], v[60:61], v[202:203]
	v_pk_add_f32 v[62:63], v[62:63], v[204:205]
	v_lshlrev_b32_e32 v202, 16, v180
	v_and_b32_e32 v203, 0xffff0000, v180
	v_lshlrev_b32_e32 v204, 16, v181
	v_and_b32_e32 v205, 0xffff0000, v181
	v_pk_add_f32 v[56:57], v[56:57], v[202:203]
	v_pk_add_f32 v[58:59], v[58:59], v[204:205]
	v_cvt_pk_bf16_f32 v178, v60, v61
	v_cvt_pk_bf16_f32 v179, v62, v63
	v_cvt_pk_bf16_f32 v180, v56, v57
	v_cvt_pk_bf16_f32 v181, v58, v59
	v_pk_mul_f32 v[138:139], v[60:61], v[60:61]
	global_store_dwordx4 v207, v[178:181], s[14:15]
	v_pk_fma_f32 v[138:139], v[62:63], v[62:63], v[138:139]
	v_pk_fma_f32 v[138:139], v[56:57], v[56:57], v[138:139]
	v_pk_fma_f32 v[138:139], v[58:59], v[58:59], v[138:139]
	v_lshlrev_b32_e32 v202, 16, v182
	v_and_b32_e32 v203, 0xffff0000, v182
	v_lshlrev_b32_e32 v204, 16, v183
	v_and_b32_e32 v205, 0xffff0000, v183
	v_pk_add_f32 v[52:53], v[52:53], v[202:203]
	v_pk_add_f32 v[54:55], v[54:55], v[204:205]
	v_lshlrev_b32_e32 v202, 16, v184
	v_and_b32_e32 v203, 0xffff0000, v184
	v_lshlrev_b32_e32 v204, 16, v185
	v_and_b32_e32 v205, 0xffff0000, v185
	v_pk_add_f32 v[48:49], v[48:49], v[202:203]
	v_pk_add_f32 v[50:51], v[50:51], v[204:205]
	v_cvt_pk_bf16_f32 v182, v52, v53
	v_cvt_pk_bf16_f32 v183, v54, v55
	v_cvt_pk_bf16_f32 v184, v48, v49
	v_cvt_pk_bf16_f32 v185, v50, v51
	v_pk_fma_f32 v[138:139], v[52:53], v[52:53], v[138:139]
	global_store_dwordx4 v207, v[182:185], s[14:15] offset:256
	v_pk_fma_f32 v[138:139], v[54:55], v[54:55], v[138:139]
	v_pk_fma_f32 v[138:139], v[48:49], v[48:49], v[138:139]
	v_pk_fma_f32 v[138:139], v[50:51], v[50:51], v[138:139]
	v_add_f32_e32 v214, v138, v139
	v_add_u32_e32 v207, 0x8000, v207
	v_mov_b32_e32 v215, v214
	s_nop 1
	v_permlane16_swap_b32_e32 v214, v215
	s_nop 0
	v_add_f32_e32 v214, v214, v215
	v_mov_b32_e32 v215, v214
	s_nop 1
	v_permlane32_swap_b32_e32 v214, v215
	s_nop 0
	v_add_f32_e32 v214, v214, v215
	s_and_saveexec_b64 s[22:23], s[4:5]
	global_store_dword v210, v214, s[16:17]
	s_mov_b64 exec, s[22:23]
	s_waitcnt vmcnt(19)
	v_lshlrev_b32_e32 v202, 16, v186
	v_and_b32_e32 v203, 0xffff0000, v186
	v_lshlrev_b32_e32 v204, 16, v187
	v_and_b32_e32 v205, 0xffff0000, v187
	v_pk_add_f32 v[44:45], v[44:45], v[202:203]
	v_pk_add_f32 v[46:47], v[46:47], v[204:205]
	v_lshlrev_b32_e32 v202, 16, v188
	v_and_b32_e32 v203, 0xffff0000, v188
	v_lshlrev_b32_e32 v204, 16, v189
	v_and_b32_e32 v205, 0xffff0000, v189
	v_pk_add_f32 v[40:41], v[40:41], v[202:203]
	v_pk_add_f32 v[42:43], v[42:43], v[204:205]
	v_cvt_pk_bf16_f32 v186, v44, v45
	v_cvt_pk_bf16_f32 v187, v46, v47
	v_cvt_pk_bf16_f32 v188, v40, v41
	v_cvt_pk_bf16_f32 v189, v42, v43
	v_pk_mul_f32 v[138:139], v[44:45], v[44:45]
	global_store_dwordx4 v207, v[186:189], s[14:15]
	v_pk_fma_f32 v[138:139], v[46:47], v[46:47], v[138:139]
	v_pk_fma_f32 v[138:139], v[40:41], v[40:41], v[138:139]
	v_pk_fma_f32 v[138:139], v[42:43], v[42:43], v[138:139]
	v_lshlrev_b32_e32 v202, 16, v190
	v_and_b32_e32 v203, 0xffff0000, v190
	v_lshlrev_b32_e32 v204, 16, v191
	v_and_b32_e32 v205, 0xffff0000, v191
	v_pk_add_f32 v[36:37], v[36:37], v[202:203]
	v_pk_add_f32 v[38:39], v[38:39], v[204:205]
	v_lshlrev_b32_e32 v202, 16, v192
	v_and_b32_e32 v203, 0xffff0000, v192
	v_lshlrev_b32_e32 v204, 16, v193
	v_and_b32_e32 v205, 0xffff0000, v193
	v_pk_add_f32 v[32:33], v[32:33], v[202:203]
	v_pk_add_f32 v[34:35], v[34:35], v[204:205]
	v_cvt_pk_bf16_f32 v190, v36, v37
	v_cvt_pk_bf16_f32 v191, v38, v39
	v_cvt_pk_bf16_f32 v192, v32, v33
	v_cvt_pk_bf16_f32 v193, v34, v35
	v_pk_fma_f32 v[138:139], v[36:37], v[36:37], v[138:139]
	global_store_dwordx4 v207, v[190:193], s[14:15] offset:256
	v_pk_fma_f32 v[138:139], v[38:39], v[38:39], v[138:139]
	v_pk_fma_f32 v[138:139], v[32:33], v[32:33], v[138:139]
	v_pk_fma_f32 v[138:139], v[34:35], v[34:35], v[138:139]
	v_add_f32_e32 v214, v138, v139
	v_add_u32_e32 v207, 0x8000, v207
	v_mov_b32_e32 v215, v214
	s_nop 1
	v_permlane16_swap_b32_e32 v214, v215
	s_nop 0
	v_add_f32_e32 v214, v214, v215
	v_mov_b32_e32 v215, v214
	s_nop 1
	v_permlane32_swap_b32_e32 v214, v215
	s_nop 0
	v_add_f32_e32 v214, v214, v215
	s_and_saveexec_b64 s[22:23], s[4:5]
	global_store_dword v210, v214, s[16:17] offset:1024
	s_mov_b64 exec, s[22:23]
	s_waitcnt vmcnt(20)
	v_lshlrev_b32_e32 v202, 16, v194
	v_and_b32_e32 v203, 0xffff0000, v194
	v_lshlrev_b32_e32 v204, 16, v195
	v_and_b32_e32 v205, 0xffff0000, v195
	v_pk_add_f32 v[28:29], v[28:29], v[202:203]
	v_pk_add_f32 v[30:31], v[30:31], v[204:205]
	v_lshlrev_b32_e32 v202, 16, v196
	v_and_b32_e32 v203, 0xffff0000, v196
	v_lshlrev_b32_e32 v204, 16, v197
	v_and_b32_e32 v205, 0xffff0000, v197
	v_pk_add_f32 v[24:25], v[24:25], v[202:203]
	v_pk_add_f32 v[26:27], v[26:27], v[204:205]
	v_cvt_pk_bf16_f32 v194, v28, v29
	v_cvt_pk_bf16_f32 v195, v30, v31
	v_cvt_pk_bf16_f32 v196, v24, v25
	v_cvt_pk_bf16_f32 v197, v26, v27
	v_pk_mul_f32 v[138:139], v[28:29], v[28:29]
	global_store_dwordx4 v207, v[194:197], s[14:15]
	v_pk_fma_f32 v[138:139], v[30:31], v[30:31], v[138:139]
	v_pk_fma_f32 v[138:139], v[24:25], v[24:25], v[138:139]
	v_pk_fma_f32 v[138:139], v[26:27], v[26:27], v[138:139]
	v_lshlrev_b32_e32 v202, 16, v198
	v_and_b32_e32 v203, 0xffff0000, v198
	v_lshlrev_b32_e32 v204, 16, v199
	v_and_b32_e32 v205, 0xffff0000, v199
	v_pk_add_f32 v[20:21], v[20:21], v[202:203]
	v_pk_add_f32 v[22:23], v[22:23], v[204:205]
	v_lshlrev_b32_e32 v202, 16, v200
	v_and_b32_e32 v203, 0xffff0000, v200
	v_lshlrev_b32_e32 v204, 16, v201
	v_and_b32_e32 v205, 0xffff0000, v201
	v_pk_add_f32 v[16:17], v[16:17], v[202:203]
	v_pk_add_f32 v[18:19], v[18:19], v[204:205]
	v_cvt_pk_bf16_f32 v198, v20, v21
	v_cvt_pk_bf16_f32 v199, v22, v23
	v_cvt_pk_bf16_f32 v200, v16, v17
	v_cvt_pk_bf16_f32 v201, v18, v19
	v_pk_fma_f32 v[138:139], v[20:21], v[20:21], v[138:139]
	global_store_dwordx4 v207, v[198:201], s[14:15] offset:256
	v_pk_fma_f32 v[138:139], v[22:23], v[22:23], v[138:139]
	v_pk_fma_f32 v[138:139], v[16:17], v[16:17], v[138:139]
	v_pk_fma_f32 v[138:139], v[18:19], v[18:19], v[138:139]
	v_add_f32_e32 v214, v138, v139
	v_add_u32_e32 v207, 0x8000, v207
	v_mov_b32_e32 v215, v214
	s_nop 1
	v_permlane16_swap_b32_e32 v214, v215
	s_nop 0
	v_add_f32_e32 v214, v214, v215
	v_mov_b32_e32 v215, v214
	s_nop 1
	v_permlane32_swap_b32_e32 v214, v215
	s_nop 0
	v_add_f32_e32 v214, v214, v215
	s_and_saveexec_b64 s[22:23], s[4:5]
	global_store_dword v210, v214, s[16:17] offset:2048
	s_mov_b64 exec, s[22:23]
	s_waitcnt vmcnt(18)
	v_lshlrev_b32_e32 v202, 16, v146
	v_and_b32_e32 v203, 0xffff0000, v146
	v_lshlrev_b32_e32 v204, 16, v147
	v_and_b32_e32 v205, 0xffff0000, v147
	v_pk_add_f32 v[12:13], v[12:13], v[202:203]
	v_pk_add_f32 v[14:15], v[14:15], v[204:205]
	v_lshlrev_b32_e32 v202, 16, v148
	v_and_b32_e32 v203, 0xffff0000, v148
	v_lshlrev_b32_e32 v204, 16, v149
	v_and_b32_e32 v205, 0xffff0000, v149
	v_pk_add_f32 v[8:9], v[8:9], v[202:203]
	v_pk_add_f32 v[10:11], v[10:11], v[204:205]
	v_cvt_pk_bf16_f32 v146, v12, v13
	v_cvt_pk_bf16_f32 v147, v14, v15
	v_cvt_pk_bf16_f32 v148, v8, v9
	v_cvt_pk_bf16_f32 v149, v10, v11
	v_pk_mul_f32 v[138:139], v[12:13], v[12:13]
	global_store_dwordx4 v207, v[146:149], s[14:15]
	v_pk_fma_f32 v[138:139], v[14:15], v[14:15], v[138:139]
	v_pk_fma_f32 v[138:139], v[8:9], v[8:9], v[138:139]
	v_pk_fma_f32 v[138:139], v[10:11], v[10:11], v[138:139]
	v_lshlrev_b32_e32 v202, 16, v150
	v_and_b32_e32 v203, 0xffff0000, v150
	v_lshlrev_b32_e32 v204, 16, v151
	v_and_b32_e32 v205, 0xffff0000, v151
	v_pk_add_f32 v[4:5], v[4:5], v[202:203]
	v_pk_add_f32 v[6:7], v[6:7], v[204:205]
	v_lshlrev_b32_e32 v202, 16, v152
	v_and_b32_e32 v203, 0xffff0000, v152
	v_lshlrev_b32_e32 v204, 16, v153
	v_and_b32_e32 v205, 0xffff0000, v153
	v_pk_add_f32 v[0:1], v[0:1], v[202:203]
	v_pk_add_f32 v[2:3], v[2:3], v[204:205]
	v_cvt_pk_bf16_f32 v150, v4, v5
	v_cvt_pk_bf16_f32 v151, v6, v7
	v_cvt_pk_bf16_f32 v152, v0, v1
	v_cvt_pk_bf16_f32 v153, v2, v3
	v_pk_fma_f32 v[138:139], v[4:5], v[4:5], v[138:139]
	global_store_dwordx4 v207, v[150:153], s[14:15] offset:256
	v_pk_fma_f32 v[138:139], v[6:7], v[6:7], v[138:139]
	v_pk_fma_f32 v[138:139], v[0:1], v[0:1], v[138:139]
	v_pk_fma_f32 v[138:139], v[2:3], v[2:3], v[138:139]
	v_add_f32_e32 v214, v138, v139
	v_add_u32_e32 v207, 0x8000, v207
	v_mov_b32_e32 v215, v214
	s_nop 1
	v_permlane16_swap_b32_e32 v214, v215
	s_nop 0
	v_add_f32_e32 v214, v214, v215
	v_mov_b32_e32 v215, v214
	s_nop 1
	v_permlane32_swap_b32_e32 v214, v215
	s_nop 0
	v_add_f32_e32 v214, v214, v215
	s_and_saveexec_b64 s[22:23], s[4:5]
	global_store_dword v210, v214, s[16:17] offset:3072
	s_mov_b64 exec, s[22:23]
	s_branch .LBB0_1009
